# x-update rewrite + rs hoist + mixer stage-2 load batching (run 1)
# speedup vs baseline: 1.0085x; 1.0085x over previous
.LBB0_446:
	s_waitcnt lgkmcnt(0)
	v_cndmask_b32_e64 v0, 0, 1, s[24:25]
	v_cmp_ne_u32_e64 s[0:1], 1, v0
	s_andn2_b64 vcc, exec, s[24:25]
	s_nop 0
	v_writelane_b32 v235, s0, 52
	s_barrier
	s_nop 0
	v_writelane_b32 v235, s1, 53
	v_mbcnt_lo_u32_b32 v0, -1, 0
	v_mbcnt_hi_u32_b32 v0, -1, v0
	s_cbranch_vccnz .LBB0_465
	v_lshlrev_b32_e32 v2, 3, v0
	v_ashrrev_i32_e32 v3, 31, v2
	v_readlane_b32 s4, v235, 4
	v_lshlrev_b64 v[4:5], 1, v[2:3]
	v_lshlrev_b64 v[2:3], 2, v[2:3]
	v_readlane_b32 s5, v235, 5
	v_readlane_b32 s6, v235, 6
	v_readlane_b32 s7, v235, 7
	v_readlane_b32 s8, v235, 8
	v_readlane_b32 s9, v235, 9
	v_readlane_b32 s10, v235, 10
	v_readlane_b32 s11, v235, 11
	v_readlane_b32 s12, v235, 12
	v_readlane_b32 s13, v235, 13
	v_readlane_b32 s14, v235, 14
	v_readlane_b32 s15, v235, 15
	v_readlane_b32 s16, v235, 16
	v_readlane_b32 s17, v235, 17
	v_readlane_b32 s18, v235, 18
	v_readlane_b32 s19, v235, 19
	v_lshl_add_u64 v[60:61], s[86:87], 0, v[4:5]
	v_lshl_add_u64 v[62:63], s[90:91], 0, v[2:3]
	v_lshl_add_u64 v[64:65], s[54:55], 0, v[4:5]
	v_lshl_add_u64 v[66:67], s[14:15], 0, v[2:3]
	s_mov_b32 s1, 0
	v_cmp_eq_u32_e64 s[4:5], 0, v0
	s_mov_b64 s[6:7], 0x200000
	s_mov_b64 s[8:9], 0x200800
	s_mov_b64 s[10:11], 0x400000
	s_mov_b64 s[12:13], 0x400800
	s_mov_b64 s[14:15], 0x600000
	s_mov_b64 s[16:17], 0x600800
	s_mov_b64 s[18:19], 0x800000
	s_mov_b32 s48, 0x800000
	s_mov_b64 s[20:21], 0x800800
	s_mov_b64 s[22:23], 0xa00000
	s_mov_b64 s[24:25], 0xa00800
	s_mov_b64 s[26:27], 0xc00000
	s_mov_b64 s[28:29], 0xc00800
	s_mov_b64 s[34:35], 0xe00000
	s_mov_b64 s[36:37], 0xe00800
	v_mov_b32_e32 v104, 0
	v_mov_b32_e32 v105, 0x358637bd
	s_mov_b32 s40, s80
	v_mbcnt_lo_u32_b32 v176, -1, 0
	v_mbcnt_hi_u32_b32 v176, -1, v176
	v_readlane_b32 s98, v235, 49
	v_readlane_b32 s99, v235, 20
	v_readlane_b32 s100, v235, 14
	v_readlane_b32 s101, v235, 15
	s_nop 3
	s_lshr_b32 vcc_lo, s98, 3
	s_and_b32 vcc_hi, vcc_lo, 7
	s_lshr_b32 vcc_lo, vcc_lo, 3
	s_lshl_b32 vcc_lo, vcc_lo, 3
	s_add_i32 vcc_lo, vcc_lo, s99
	s_lshl_b32 s98, vcc_hi, 8
	s_add_i32 s98, s98, vcc_lo
	s_mov_b32 s99, s98
	v_mov_b32_e32 v183, s99
	v_lshlrev_b32_e32 v177, 4, v176
	s_lshl_b32 s99, s99, 11
	v_add_u32_e32 v177, s99, v177
	v_add_u32_e32 v178, 0x1800000, v177
	v_add_u32_e32 v179, 0x9e00000, v177
	v_lshlrev_b32_e32 v180, 5, v176
	global_load_dwordx4 v[128:131], v180, s[100:101]
	global_load_dwordx4 v[132:135], v180, s[100:101] offset:16
	global_load_dwordx4 v[136:139], v180, s[100:101] offset:2048
	global_load_dwordx4 v[140:143], v180, s[100:101] offset:2064
	v_mov_b32_e32 v182, 0x358637bd
	global_load_dwordx4 v[0:3], v178, s[78:79]
	global_load_dwordx4 v[4:7], v178, s[78:79] offset:1024
	global_load_dwordx4 v[8:11], v179, s[78:79]
	global_load_dwordx4 v[12:15], v179, s[78:79] offset:1024
	v_add_u32_e32 v178, 0x400000, v178
	v_add_u32_e32 v179, 0x400000, v179
	global_load_dwordx4 v[16:19], v178, s[78:79]
	global_load_dwordx4 v[20:23], v178, s[78:79] offset:1024
	global_load_dwordx4 v[24:27], v179, s[78:79]
	global_load_dwordx4 v[28:31], v179, s[78:79] offset:1024
	v_add_u32_e32 v178, 0x400000, v178
	v_add_u32_e32 v179, 0x400000, v179
	global_load_dwordx4 v[32:35], v178, s[78:79]
	global_load_dwordx4 v[36:39], v178, s[78:79] offset:1024
	global_load_dwordx4 v[40:43], v179, s[78:79]
	global_load_dwordx4 v[44:47], v179, s[78:79] offset:1024
	v_add_u32_e32 v178, 0x400000, v178
	v_add_u32_e32 v179, 0x400000, v179
	global_load_dwordx4 v[48:51], v178, s[78:79]
	global_load_dwordx4 v[52:55], v178, s[78:79] offset:1024
	global_load_dwordx4 v[56:59], v179, s[78:79]
	global_load_dwordx4 v[60:63], v179, s[78:79] offset:1024
	v_add_u32_e32 v178, 0x400000, v178
	v_add_u32_e32 v179, 0x400000, v179
	global_load_dwordx4 v[64:67], v178, s[78:79]
	global_load_dwordx4 v[68:71], v178, s[78:79] offset:1024
	global_load_dwordx4 v[72:75], v179, s[78:79]
	global_load_dwordx4 v[76:79], v179, s[78:79] offset:1024
	v_add_u32_e32 v178, 0x400000, v178
	v_add_u32_e32 v179, 0x400000, v179
	global_load_dwordx4 v[80:83], v178, s[78:79]
	global_load_dwordx4 v[84:87], v178, s[78:79] offset:1024
	global_load_dwordx4 v[88:91], v179, s[78:79]
	global_load_dwordx4 v[92:95], v179, s[78:79] offset:1024
	v_add_u32_e32 v178, 0x400000, v178
	v_add_u32_e32 v179, 0x400000, v179
	global_load_dwordx4 v[96:99], v178, s[78:79]
	global_load_dwordx4 v[100:103], v178, s[78:79] offset:1024
	global_load_dwordx4 v[104:107], v179, s[78:79]
	global_load_dwordx4 v[108:111], v179, s[78:79] offset:1024
	v_add_u32_e32 v178, 0x400000, v178
	v_add_u32_e32 v179, 0x400000, v179
	global_load_dwordx4 v[112:115], v178, s[78:79]
	global_load_dwordx4 v[116:119], v178, s[78:79] offset:1024
	global_load_dwordx4 v[120:123], v179, s[78:79]
	global_load_dwordx4 v[124:127], v179, s[78:79] offset:1024
	v_lshlrev_b32_e32 v237, 2, v183
	v_add_u32_e32 v237, 0x10000, v237
	v_mov_b32_e32 v179, s98
	s_waitcnt vmcnt(28)
	v_lshlrev_b32_e32 v144, 16, v0
	v_and_b32_e32 v145, 0xffff0000, v0
	v_lshlrev_b32_e32 v146, 16, v1
	v_and_b32_e32 v147, 0xffff0000, v1
	v_lshlrev_b32_e32 v148, 16, v2
	v_and_b32_e32 v149, 0xffff0000, v2
	v_lshlrev_b32_e32 v150, 16, v3
	v_and_b32_e32 v151, 0xffff0000, v3
	v_lshlrev_b32_e32 v152, 16, v4
	v_and_b32_e32 v153, 0xffff0000, v4
	v_lshlrev_b32_e32 v154, 16, v5
	v_and_b32_e32 v155, 0xffff0000, v5
	v_lshlrev_b32_e32 v156, 16, v6
	v_and_b32_e32 v157, 0xffff0000, v6
	v_lshlrev_b32_e32 v158, 16, v7
	v_and_b32_e32 v159, 0xffff0000, v7
	v_lshlrev_b32_e32 v160, 16, v8
	v_and_b32_e32 v161, 0xffff0000, v8
	v_lshlrev_b32_e32 v162, 16, v9
	v_and_b32_e32 v163, 0xffff0000, v9
	v_lshlrev_b32_e32 v164, 16, v10
	v_and_b32_e32 v165, 0xffff0000, v10
	v_lshlrev_b32_e32 v166, 16, v11
	v_and_b32_e32 v167, 0xffff0000, v11
	v_lshlrev_b32_e32 v168, 16, v12
	v_and_b32_e32 v169, 0xffff0000, v12
	v_lshlrev_b32_e32 v170, 16, v13
	v_and_b32_e32 v171, 0xffff0000, v13
	v_lshlrev_b32_e32 v172, 16, v14
	v_and_b32_e32 v173, 0xffff0000, v14
	v_lshlrev_b32_e32 v174, 16, v15
	v_and_b32_e32 v175, 0xffff0000, v15
	v_pk_mul_f32 v[252:253], v[160:161], v[160:161]
	v_pk_mul_f32 v[254:255], v[162:163], v[162:163]
	v_pk_fma_f32 v[252:253], v[164:165], v[164:165], v[252:253]
	v_pk_fma_f32 v[254:255], v[166:167], v[166:167], v[254:255]
	v_pk_fma_f32 v[252:253], v[168:169], v[168:169], v[252:253]
	v_pk_fma_f32 v[254:255], v[170:171], v[170:171], v[254:255]
	v_pk_fma_f32 v[252:253], v[172:173], v[172:173], v[252:253]
	v_pk_fma_f32 v[254:255], v[174:175], v[174:175], v[254:255]
	v_pk_add_f32 v[252:253], v[252:253], v[254:255]
	s_nop 0
	v_add_f32_e32 v183, v252, v253
	s_nop 1
	v_add_f32_dpp v183, v183, v183 quad_perm:[1,0,3,2] row_mask:0xf bank_mask:0xf bound_ctrl:1
	s_nop 1
	v_add_f32_dpp v183, v183, v183 quad_perm:[2,3,0,1] row_mask:0xf bank_mask:0xf bound_ctrl:1
	s_nop 1
	v_add_f32_dpp v183, v183, v183 row_half_mirror row_mask:0xf bank_mask:0xf bound_ctrl:1
	s_nop 1
	v_add_f32_dpp v183, v183, v183 row_mirror row_mask:0xf bank_mask:0xf bound_ctrl:1
	s_nop 1
	v_readlane_b32 s98, v183, 0
	v_readlane_b32 s99, v183, 16
	v_readlane_b32 s100, v183, 32
	v_readlane_b32 s101, v183, 48
	s_nop 1
	v_mov_b32_e32 v183, s98
	v_add_f32_e32 v183, s99, v183
	v_add_f32_e32 v183, s100, v183
	v_add_f32_e32 v183, s101, v183
	v_fmamk_f32 v183, v183, 0x3a800000, v182
	v_cmp_gt_f32_e32 vcc, 0x800000, v183
	v_mul_f32_e32 v181, 0x4b800000, v183
	s_nop 1
	v_cndmask_b32_e32 v183, v183, v181, vcc
	v_rsq_f32_e32 v183, v183
	s_nop 0
	v_mul_f32_e32 v181, 0x45800000, v183
	v_cndmask_b32_e32 v184, v183, v181, vcc
	v_mov_b32_e32 v185, v184
	v_pk_mul_f32 v[160:161], v[160:161], v[184:185]
	v_pk_mul_f32 v[162:163], v[162:163], v[184:185]
	v_pk_mul_f32 v[164:165], v[164:165], v[184:185]
	v_pk_mul_f32 v[166:167], v[166:167], v[184:185]
	v_pk_mul_f32 v[168:169], v[168:169], v[184:185]
	v_pk_mul_f32 v[170:171], v[170:171], v[184:185]
	v_pk_mul_f32 v[172:173], v[172:173], v[184:185]
	v_pk_mul_f32 v[174:175], v[174:175], v[184:185]
	v_pk_fma_f32 v[144:145], v[160:161], v[128:129], v[144:145]
	v_pk_fma_f32 v[146:147], v[162:163], v[130:131], v[146:147]
	v_pk_fma_f32 v[148:149], v[164:165], v[132:133], v[148:149]
	v_pk_fma_f32 v[150:151], v[166:167], v[134:135], v[150:151]
	v_pk_fma_f32 v[152:153], v[168:169], v[136:137], v[152:153]
	v_pk_fma_f32 v[154:155], v[170:171], v[138:139], v[154:155]
	v_pk_fma_f32 v[156:157], v[172:173], v[140:141], v[156:157]
	v_pk_fma_f32 v[158:159], v[174:175], v[142:143], v[158:159]
	v_pk_mul_f32 v[252:253], v[144:145], v[144:145]
	v_pk_mul_f32 v[254:255], v[146:147], v[146:147]
	v_pk_fma_f32 v[252:253], v[148:149], v[148:149], v[252:253]
	v_pk_fma_f32 v[254:255], v[150:151], v[150:151], v[254:255]
	v_pk_fma_f32 v[252:253], v[152:153], v[152:153], v[252:253]
	v_pk_fma_f32 v[254:255], v[154:155], v[154:155], v[254:255]
	v_pk_fma_f32 v[252:253], v[156:157], v[156:157], v[252:253]
	v_pk_fma_f32 v[254:255], v[158:159], v[158:159], v[254:255]
	v_pk_add_f32 v[252:253], v[252:253], v[254:255]
	s_nop 0
	v_add_f32_e32 v183, v252, v253
	s_nop 1
	v_add_f32_dpp v183, v183, v183 quad_perm:[1,0,3,2] row_mask:0xf bank_mask:0xf bound_ctrl:1
	s_nop 1
	v_add_f32_dpp v183, v183, v183 quad_perm:[2,3,0,1] row_mask:0xf bank_mask:0xf bound_ctrl:1
	s_nop 1
	v_add_f32_dpp v183, v183, v183 row_half_mirror row_mask:0xf bank_mask:0xf bound_ctrl:1
	s_nop 1
	v_add_f32_dpp v183, v183, v183 row_mirror row_mask:0xf bank_mask:0xf bound_ctrl:1
	s_nop 1
	v_readlane_b32 s98, v183, 0
	v_readlane_b32 s99, v183, 16
	v_readlane_b32 s100, v183, 32
	v_readlane_b32 s101, v183, 48
	s_nop 1
	v_mov_b32_e32 v183, s98
	v_add_f32_e32 v183, s99, v183
	v_add_f32_e32 v183, s100, v183
	v_add_f32_e32 v183, s101, v183
	v_fmamk_f32 v183, v183, 0x3a800000, v182
	v_cmp_gt_f32_e32 vcc, 0x800000, v183
	v_mul_f32_e32 v181, 0x4b800000, v183
	s_nop 1
	v_cndmask_b32_e32 v183, v183, v181, vcc
	v_rsq_f32_e32 v183, v183
	s_nop 0
	v_mul_f32_e32 v181, 0x45800000, v183
	v_cndmask_b32_e32 v184, v183, v181, vcc
	v_mov_b32_e32 v185, v184
	v_cvt_pk_bf16_f32 v0, v144, v145
	v_cvt_pk_bf16_f32 v1, v146, v147
	v_cvt_pk_bf16_f32 v2, v148, v149
	v_cvt_pk_bf16_f32 v3, v150, v151
	v_cvt_pk_bf16_f32 v4, v152, v153
	v_cvt_pk_bf16_f32 v5, v154, v155
	v_cvt_pk_bf16_f32 v6, v156, v157
	v_cvt_pk_bf16_f32 v7, v158, v159
	v_add_u32_e32 v181, 0x1800000, v177
	global_store_dwordx4 v181, v[0:3], s[78:79]
	global_store_dwordx4 v181, v[4:7], s[78:79] offset:1024
	v_add_u32_e32 v236, 0x0, v237
	s_mov_b64 exec, 1
	global_store_dword v236, v184, s[78:79]
	s_mov_b64 exec, -1
	s_waitcnt vmcnt(24)
	v_lshlrev_b32_e32 v144, 16, v16
	v_and_b32_e32 v145, 0xffff0000, v16
	v_lshlrev_b32_e32 v146, 16, v17
	v_and_b32_e32 v147, 0xffff0000, v17
	v_lshlrev_b32_e32 v148, 16, v18
	v_and_b32_e32 v149, 0xffff0000, v18
	v_lshlrev_b32_e32 v150, 16, v19
	v_and_b32_e32 v151, 0xffff0000, v19
	v_lshlrev_b32_e32 v152, 16, v20
	v_and_b32_e32 v153, 0xffff0000, v20
	v_lshlrev_b32_e32 v154, 16, v21
	v_and_b32_e32 v155, 0xffff0000, v21
	v_lshlrev_b32_e32 v156, 16, v22
	v_and_b32_e32 v157, 0xffff0000, v22
	v_lshlrev_b32_e32 v158, 16, v23
	v_and_b32_e32 v159, 0xffff0000, v23
	v_lshlrev_b32_e32 v160, 16, v24
	v_and_b32_e32 v161, 0xffff0000, v24
	v_lshlrev_b32_e32 v162, 16, v25
	v_and_b32_e32 v163, 0xffff0000, v25
	v_lshlrev_b32_e32 v164, 16, v26
	v_and_b32_e32 v165, 0xffff0000, v26
	v_lshlrev_b32_e32 v166, 16, v27
	v_and_b32_e32 v167, 0xffff0000, v27
	v_lshlrev_b32_e32 v168, 16, v28
	v_and_b32_e32 v169, 0xffff0000, v28
	v_lshlrev_b32_e32 v170, 16, v29
	v_and_b32_e32 v171, 0xffff0000, v29
	v_lshlrev_b32_e32 v172, 16, v30
	v_and_b32_e32 v173, 0xffff0000, v30
	v_lshlrev_b32_e32 v174, 16, v31
	v_and_b32_e32 v175, 0xffff0000, v31
	v_pk_mul_f32 v[252:253], v[160:161], v[160:161]
	v_pk_mul_f32 v[254:255], v[162:163], v[162:163]
	v_pk_fma_f32 v[252:253], v[164:165], v[164:165], v[252:253]
	v_pk_fma_f32 v[254:255], v[166:167], v[166:167], v[254:255]
	v_pk_fma_f32 v[252:253], v[168:169], v[168:169], v[252:253]
	v_pk_fma_f32 v[254:255], v[170:171], v[170:171], v[254:255]
	v_pk_fma_f32 v[252:253], v[172:173], v[172:173], v[252:253]
	v_pk_fma_f32 v[254:255], v[174:175], v[174:175], v[254:255]
	v_pk_add_f32 v[252:253], v[252:253], v[254:255]
	s_nop 0
	v_add_f32_e32 v183, v252, v253
	s_nop 1
	v_add_f32_dpp v183, v183, v183 quad_perm:[1,0,3,2] row_mask:0xf bank_mask:0xf bound_ctrl:1
	s_nop 1
	v_add_f32_dpp v183, v183, v183 quad_perm:[2,3,0,1] row_mask:0xf bank_mask:0xf bound_ctrl:1
	s_nop 1
	v_add_f32_dpp v183, v183, v183 row_half_mirror row_mask:0xf bank_mask:0xf bound_ctrl:1
	s_nop 1
	v_add_f32_dpp v183, v183, v183 row_mirror row_mask:0xf bank_mask:0xf bound_ctrl:1
	s_nop 1
	v_readlane_b32 s98, v183, 0
	v_readlane_b32 s99, v183, 16
	v_readlane_b32 s100, v183, 32
	v_readlane_b32 s101, v183, 48
	s_nop 1
	v_mov_b32_e32 v183, s98
	v_add_f32_e32 v183, s99, v183
	v_add_f32_e32 v183, s100, v183
	v_add_f32_e32 v183, s101, v183
	v_fmamk_f32 v183, v183, 0x3a800000, v182
	v_cmp_gt_f32_e32 vcc, 0x800000, v183
	v_mul_f32_e32 v181, 0x4b800000, v183
	s_nop 1
	v_cndmask_b32_e32 v183, v183, v181, vcc
	v_rsq_f32_e32 v183, v183
	s_nop 0
	v_mul_f32_e32 v181, 0x45800000, v183
	v_cndmask_b32_e32 v184, v183, v181, vcc
	v_mov_b32_e32 v185, v184
	v_pk_mul_f32 v[160:161], v[160:161], v[184:185]
	v_pk_mul_f32 v[162:163], v[162:163], v[184:185]
	v_pk_mul_f32 v[164:165], v[164:165], v[184:185]
	v_pk_mul_f32 v[166:167], v[166:167], v[184:185]
	v_pk_mul_f32 v[168:169], v[168:169], v[184:185]
	v_pk_mul_f32 v[170:171], v[170:171], v[184:185]
	v_pk_mul_f32 v[172:173], v[172:173], v[184:185]
	v_pk_mul_f32 v[174:175], v[174:175], v[184:185]
	v_pk_fma_f32 v[144:145], v[160:161], v[128:129], v[144:145]
	v_pk_fma_f32 v[146:147], v[162:163], v[130:131], v[146:147]
	v_pk_fma_f32 v[148:149], v[164:165], v[132:133], v[148:149]
	v_pk_fma_f32 v[150:151], v[166:167], v[134:135], v[150:151]
	v_pk_fma_f32 v[152:153], v[168:169], v[136:137], v[152:153]
	v_pk_fma_f32 v[154:155], v[170:171], v[138:139], v[154:155]
	v_pk_fma_f32 v[156:157], v[172:173], v[140:141], v[156:157]
	v_pk_fma_f32 v[158:159], v[174:175], v[142:143], v[158:159]
	v_pk_mul_f32 v[252:253], v[144:145], v[144:145]
	v_pk_mul_f32 v[254:255], v[146:147], v[146:147]
	v_pk_fma_f32 v[252:253], v[148:149], v[148:149], v[252:253]
	v_pk_fma_f32 v[254:255], v[150:151], v[150:151], v[254:255]
	v_pk_fma_f32 v[252:253], v[152:153], v[152:153], v[252:253]
	v_pk_fma_f32 v[254:255], v[154:155], v[154:155], v[254:255]
	v_pk_fma_f32 v[252:253], v[156:157], v[156:157], v[252:253]
	v_pk_fma_f32 v[254:255], v[158:159], v[158:159], v[254:255]
	v_pk_add_f32 v[252:253], v[252:253], v[254:255]
	s_nop 0
	v_add_f32_e32 v183, v252, v253
	s_nop 1
	v_add_f32_dpp v183, v183, v183 quad_perm:[1,0,3,2] row_mask:0xf bank_mask:0xf bound_ctrl:1
	s_nop 1
	v_add_f32_dpp v183, v183, v183 quad_perm:[2,3,0,1] row_mask:0xf bank_mask:0xf bound_ctrl:1
	s_nop 1
	v_add_f32_dpp v183, v183, v183 row_half_mirror row_mask:0xf bank_mask:0xf bound_ctrl:1
	s_nop 1
	v_add_f32_dpp v183, v183, v183 row_mirror row_mask:0xf bank_mask:0xf bound_ctrl:1
	s_nop 1
	v_readlane_b32 s98, v183, 0
	v_readlane_b32 s99, v183, 16
	v_readlane_b32 s100, v183, 32
	v_readlane_b32 s101, v183, 48
	s_nop 1
	v_mov_b32_e32 v183, s98
	v_add_f32_e32 v183, s99, v183
	v_add_f32_e32 v183, s100, v183
	v_add_f32_e32 v183, s101, v183
	v_fmamk_f32 v183, v183, 0x3a800000, v182
	v_cmp_gt_f32_e32 vcc, 0x800000, v183
	v_mul_f32_e32 v181, 0x4b800000, v183
	s_nop 1
	v_cndmask_b32_e32 v183, v183, v181, vcc
	v_rsq_f32_e32 v183, v183
	s_nop 0
	v_mul_f32_e32 v181, 0x45800000, v183
	v_cndmask_b32_e32 v184, v183, v181, vcc
	v_mov_b32_e32 v185, v184
	v_cvt_pk_bf16_f32 v16, v144, v145
	v_cvt_pk_bf16_f32 v17, v146, v147
	v_cvt_pk_bf16_f32 v18, v148, v149
	v_cvt_pk_bf16_f32 v19, v150, v151
	v_cvt_pk_bf16_f32 v20, v152, v153
	v_cvt_pk_bf16_f32 v21, v154, v155
	v_cvt_pk_bf16_f32 v22, v156, v157
	v_cvt_pk_bf16_f32 v23, v158, v159
	v_add_u32_e32 v181, 0x1c00000, v177
	global_store_dwordx4 v181, v[16:19], s[78:79]
	global_store_dwordx4 v181, v[20:23], s[78:79] offset:1024
	v_add_u32_e32 v236, 0x2000, v237
	s_mov_b64 exec, 1
	global_store_dword v236, v184, s[78:79]
	s_mov_b64 exec, -1
	s_waitcnt vmcnt(20)
	v_lshlrev_b32_e32 v144, 16, v32
	v_and_b32_e32 v145, 0xffff0000, v32
	v_lshlrev_b32_e32 v146, 16, v33
	v_and_b32_e32 v147, 0xffff0000, v33
	v_lshlrev_b32_e32 v148, 16, v34
	v_and_b32_e32 v149, 0xffff0000, v34
	v_lshlrev_b32_e32 v150, 16, v35
	v_and_b32_e32 v151, 0xffff0000, v35
	v_lshlrev_b32_e32 v152, 16, v36
	v_and_b32_e32 v153, 0xffff0000, v36
	v_lshlrev_b32_e32 v154, 16, v37
	v_and_b32_e32 v155, 0xffff0000, v37
	v_lshlrev_b32_e32 v156, 16, v38
	v_and_b32_e32 v157, 0xffff0000, v38
	v_lshlrev_b32_e32 v158, 16, v39
	v_and_b32_e32 v159, 0xffff0000, v39
	v_lshlrev_b32_e32 v160, 16, v40
	v_and_b32_e32 v161, 0xffff0000, v40
	v_lshlrev_b32_e32 v162, 16, v41
	v_and_b32_e32 v163, 0xffff0000, v41
	v_lshlrev_b32_e32 v164, 16, v42
	v_and_b32_e32 v165, 0xffff0000, v42
	v_lshlrev_b32_e32 v166, 16, v43
	v_and_b32_e32 v167, 0xffff0000, v43
	v_lshlrev_b32_e32 v168, 16, v44
	v_and_b32_e32 v169, 0xffff0000, v44
	v_lshlrev_b32_e32 v170, 16, v45
	v_and_b32_e32 v171, 0xffff0000, v45
	v_lshlrev_b32_e32 v172, 16, v46
	v_and_b32_e32 v173, 0xffff0000, v46
	v_lshlrev_b32_e32 v174, 16, v47
	v_and_b32_e32 v175, 0xffff0000, v47
	v_pk_mul_f32 v[252:253], v[160:161], v[160:161]
	v_pk_mul_f32 v[254:255], v[162:163], v[162:163]
	v_pk_fma_f32 v[252:253], v[164:165], v[164:165], v[252:253]
	v_pk_fma_f32 v[254:255], v[166:167], v[166:167], v[254:255]
	v_pk_fma_f32 v[252:253], v[168:169], v[168:169], v[252:253]
	v_pk_fma_f32 v[254:255], v[170:171], v[170:171], v[254:255]
	v_pk_fma_f32 v[252:253], v[172:173], v[172:173], v[252:253]
	v_pk_fma_f32 v[254:255], v[174:175], v[174:175], v[254:255]
	v_pk_add_f32 v[252:253], v[252:253], v[254:255]
	s_nop 0
	v_add_f32_e32 v183, v252, v253
	s_nop 1
	v_add_f32_dpp v183, v183, v183 quad_perm:[1,0,3,2] row_mask:0xf bank_mask:0xf bound_ctrl:1
	s_nop 1
	v_add_f32_dpp v183, v183, v183 quad_perm:[2,3,0,1] row_mask:0xf bank_mask:0xf bound_ctrl:1
	s_nop 1
	v_add_f32_dpp v183, v183, v183 row_half_mirror row_mask:0xf bank_mask:0xf bound_ctrl:1
	s_nop 1
	v_add_f32_dpp v183, v183, v183 row_mirror row_mask:0xf bank_mask:0xf bound_ctrl:1
	s_nop 1
	v_readlane_b32 s98, v183, 0
	v_readlane_b32 s99, v183, 16
	v_readlane_b32 s100, v183, 32
	v_readlane_b32 s101, v183, 48
	s_nop 1
	v_mov_b32_e32 v183, s98
	v_add_f32_e32 v183, s99, v183
	v_add_f32_e32 v183, s100, v183
	v_add_f32_e32 v183, s101, v183
	v_fmamk_f32 v183, v183, 0x3a800000, v182
	v_cmp_gt_f32_e32 vcc, 0x800000, v183
	v_mul_f32_e32 v181, 0x4b800000, v183
	s_nop 1
	v_cndmask_b32_e32 v183, v183, v181, vcc
	v_rsq_f32_e32 v183, v183
	s_nop 0
	v_mul_f32_e32 v181, 0x45800000, v183
	v_cndmask_b32_e32 v184, v183, v181, vcc
	v_mov_b32_e32 v185, v184
	v_pk_mul_f32 v[160:161], v[160:161], v[184:185]
	v_pk_mul_f32 v[162:163], v[162:163], v[184:185]
	v_pk_mul_f32 v[164:165], v[164:165], v[184:185]
	v_pk_mul_f32 v[166:167], v[166:167], v[184:185]
	v_pk_mul_f32 v[168:169], v[168:169], v[184:185]
	v_pk_mul_f32 v[170:171], v[170:171], v[184:185]
	v_pk_mul_f32 v[172:173], v[172:173], v[184:185]
	v_pk_mul_f32 v[174:175], v[174:175], v[184:185]
	v_pk_fma_f32 v[144:145], v[160:161], v[128:129], v[144:145]
	v_pk_fma_f32 v[146:147], v[162:163], v[130:131], v[146:147]
	v_pk_fma_f32 v[148:149], v[164:165], v[132:133], v[148:149]
	v_pk_fma_f32 v[150:151], v[166:167], v[134:135], v[150:151]
	v_pk_fma_f32 v[152:153], v[168:169], v[136:137], v[152:153]
	v_pk_fma_f32 v[154:155], v[170:171], v[138:139], v[154:155]
	v_pk_fma_f32 v[156:157], v[172:173], v[140:141], v[156:157]
	v_pk_fma_f32 v[158:159], v[174:175], v[142:143], v[158:159]
	v_pk_mul_f32 v[252:253], v[144:145], v[144:145]
	v_pk_mul_f32 v[254:255], v[146:147], v[146:147]
	v_pk_fma_f32 v[252:253], v[148:149], v[148:149], v[252:253]
	v_pk_fma_f32 v[254:255], v[150:151], v[150:151], v[254:255]
	v_pk_fma_f32 v[252:253], v[152:153], v[152:153], v[252:253]
	v_pk_fma_f32 v[254:255], v[154:155], v[154:155], v[254:255]
	v_pk_fma_f32 v[252:253], v[156:157], v[156:157], v[252:253]
	v_pk_fma_f32 v[254:255], v[158:159], v[158:159], v[254:255]
	v_pk_add_f32 v[252:253], v[252:253], v[254:255]
	s_nop 0
	v_add_f32_e32 v183, v252, v253
	s_nop 1
	v_add_f32_dpp v183, v183, v183 quad_perm:[1,0,3,2] row_mask:0xf bank_mask:0xf bound_ctrl:1
	s_nop 1
	v_add_f32_dpp v183, v183, v183 quad_perm:[2,3,0,1] row_mask:0xf bank_mask:0xf bound_ctrl:1
	s_nop 1
	v_add_f32_dpp v183, v183, v183 row_half_mirror row_mask:0xf bank_mask:0xf bound_ctrl:1
	s_nop 1
	v_add_f32_dpp v183, v183, v183 row_mirror row_mask:0xf bank_mask:0xf bound_ctrl:1
	s_nop 1
	v_readlane_b32 s98, v183, 0
	v_readlane_b32 s99, v183, 16
	v_readlane_b32 s100, v183, 32
	v_readlane_b32 s101, v183, 48
	s_nop 1
	v_mov_b32_e32 v183, s98
	v_add_f32_e32 v183, s99, v183
	v_add_f32_e32 v183, s100, v183
	v_add_f32_e32 v183, s101, v183
	v_fmamk_f32 v183, v183, 0x3a800000, v182
	v_cmp_gt_f32_e32 vcc, 0x800000, v183
	v_mul_f32_e32 v181, 0x4b800000, v183
	s_nop 1
	v_cndmask_b32_e32 v183, v183, v181, vcc
	v_rsq_f32_e32 v183, v183
	s_nop 0
	v_mul_f32_e32 v181, 0x45800000, v183
	v_cndmask_b32_e32 v184, v183, v181, vcc
	v_mov_b32_e32 v185, v184
	v_cvt_pk_bf16_f32 v32, v144, v145
	v_cvt_pk_bf16_f32 v33, v146, v147
	v_cvt_pk_bf16_f32 v34, v148, v149
	v_cvt_pk_bf16_f32 v35, v150, v151
	v_cvt_pk_bf16_f32 v36, v152, v153
	v_cvt_pk_bf16_f32 v37, v154, v155
	v_cvt_pk_bf16_f32 v38, v156, v157
	v_cvt_pk_bf16_f32 v39, v158, v159
	v_add_u32_e32 v181, 0x2000000, v177
	global_store_dwordx4 v181, v[32:35], s[78:79]
	global_store_dwordx4 v181, v[36:39], s[78:79] offset:1024
	v_add_u32_e32 v236, 0x4000, v237
	s_mov_b64 exec, 1
	global_store_dword v236, v184, s[78:79]
	s_mov_b64 exec, -1
	s_waitcnt vmcnt(16)
	v_lshlrev_b32_e32 v144, 16, v48
	v_and_b32_e32 v145, 0xffff0000, v48
	v_lshlrev_b32_e32 v146, 16, v49
	v_and_b32_e32 v147, 0xffff0000, v49
	v_lshlrev_b32_e32 v148, 16, v50
	v_and_b32_e32 v149, 0xffff0000, v50
	v_lshlrev_b32_e32 v150, 16, v51
	v_and_b32_e32 v151, 0xffff0000, v51
	v_lshlrev_b32_e32 v152, 16, v52
	v_and_b32_e32 v153, 0xffff0000, v52
	v_lshlrev_b32_e32 v154, 16, v53
	v_and_b32_e32 v155, 0xffff0000, v53
	v_lshlrev_b32_e32 v156, 16, v54
	v_and_b32_e32 v157, 0xffff0000, v54
	v_lshlrev_b32_e32 v158, 16, v55
	v_and_b32_e32 v159, 0xffff0000, v55
	v_lshlrev_b32_e32 v160, 16, v56
	v_and_b32_e32 v161, 0xffff0000, v56
	v_lshlrev_b32_e32 v162, 16, v57
	v_and_b32_e32 v163, 0xffff0000, v57
	v_lshlrev_b32_e32 v164, 16, v58
	v_and_b32_e32 v165, 0xffff0000, v58
	v_lshlrev_b32_e32 v166, 16, v59
	v_and_b32_e32 v167, 0xffff0000, v59
	v_lshlrev_b32_e32 v168, 16, v60
	v_and_b32_e32 v169, 0xffff0000, v60
	v_lshlrev_b32_e32 v170, 16, v61
	v_and_b32_e32 v171, 0xffff0000, v61
	v_lshlrev_b32_e32 v172, 16, v62
	v_and_b32_e32 v173, 0xffff0000, v62
	v_lshlrev_b32_e32 v174, 16, v63
	v_and_b32_e32 v175, 0xffff0000, v63
	v_pk_mul_f32 v[252:253], v[160:161], v[160:161]
	v_pk_mul_f32 v[254:255], v[162:163], v[162:163]
	v_pk_fma_f32 v[252:253], v[164:165], v[164:165], v[252:253]
	v_pk_fma_f32 v[254:255], v[166:167], v[166:167], v[254:255]
	v_pk_fma_f32 v[252:253], v[168:169], v[168:169], v[252:253]
	v_pk_fma_f32 v[254:255], v[170:171], v[170:171], v[254:255]
	v_pk_fma_f32 v[252:253], v[172:173], v[172:173], v[252:253]
	v_pk_fma_f32 v[254:255], v[174:175], v[174:175], v[254:255]
	v_pk_add_f32 v[252:253], v[252:253], v[254:255]
	s_nop 0
	v_add_f32_e32 v183, v252, v253
	s_nop 1
	v_add_f32_dpp v183, v183, v183 quad_perm:[1,0,3,2] row_mask:0xf bank_mask:0xf bound_ctrl:1
	s_nop 1
	v_add_f32_dpp v183, v183, v183 quad_perm:[2,3,0,1] row_mask:0xf bank_mask:0xf bound_ctrl:1
	s_nop 1
	v_add_f32_dpp v183, v183, v183 row_half_mirror row_mask:0xf bank_mask:0xf bound_ctrl:1
	s_nop 1
	v_add_f32_dpp v183, v183, v183 row_mirror row_mask:0xf bank_mask:0xf bound_ctrl:1
	s_nop 1
	v_readlane_b32 s98, v183, 0
	v_readlane_b32 s99, v183, 16
	v_readlane_b32 s100, v183, 32
	v_readlane_b32 s101, v183, 48
	s_nop 1
	v_mov_b32_e32 v183, s98
	v_add_f32_e32 v183, s99, v183
	v_add_f32_e32 v183, s100, v183
	v_add_f32_e32 v183, s101, v183
	v_fmamk_f32 v183, v183, 0x3a800000, v182
	v_cmp_gt_f32_e32 vcc, 0x800000, v183
	v_mul_f32_e32 v181, 0x4b800000, v183
	s_nop 1
	v_cndmask_b32_e32 v183, v183, v181, vcc
	v_rsq_f32_e32 v183, v183
	s_nop 0
	v_mul_f32_e32 v181, 0x45800000, v183
	v_cndmask_b32_e32 v184, v183, v181, vcc
	v_mov_b32_e32 v185, v184
	v_pk_mul_f32 v[160:161], v[160:161], v[184:185]
	v_pk_mul_f32 v[162:163], v[162:163], v[184:185]
	v_pk_mul_f32 v[164:165], v[164:165], v[184:185]
	v_pk_mul_f32 v[166:167], v[166:167], v[184:185]
	v_pk_mul_f32 v[168:169], v[168:169], v[184:185]
	v_pk_mul_f32 v[170:171], v[170:171], v[184:185]
	v_pk_mul_f32 v[172:173], v[172:173], v[184:185]
	v_pk_mul_f32 v[174:175], v[174:175], v[184:185]
	v_pk_fma_f32 v[144:145], v[160:161], v[128:129], v[144:145]
	v_pk_fma_f32 v[146:147], v[162:163], v[130:131], v[146:147]
	v_pk_fma_f32 v[148:149], v[164:165], v[132:133], v[148:149]
	v_pk_fma_f32 v[150:151], v[166:167], v[134:135], v[150:151]
	v_pk_fma_f32 v[152:153], v[168:169], v[136:137], v[152:153]
	v_pk_fma_f32 v[154:155], v[170:171], v[138:139], v[154:155]
	v_pk_fma_f32 v[156:157], v[172:173], v[140:141], v[156:157]
	v_pk_fma_f32 v[158:159], v[174:175], v[142:143], v[158:159]
	v_pk_mul_f32 v[252:253], v[144:145], v[144:145]
	v_pk_mul_f32 v[254:255], v[146:147], v[146:147]
	v_pk_fma_f32 v[252:253], v[148:149], v[148:149], v[252:253]
	v_pk_fma_f32 v[254:255], v[150:151], v[150:151], v[254:255]
	v_pk_fma_f32 v[252:253], v[152:153], v[152:153], v[252:253]
	v_pk_fma_f32 v[254:255], v[154:155], v[154:155], v[254:255]
	v_pk_fma_f32 v[252:253], v[156:157], v[156:157], v[252:253]
	v_pk_fma_f32 v[254:255], v[158:159], v[158:159], v[254:255]
	v_pk_add_f32 v[252:253], v[252:253], v[254:255]
	s_nop 0
	v_add_f32_e32 v183, v252, v253
	s_nop 1
	v_add_f32_dpp v183, v183, v183 quad_perm:[1,0,3,2] row_mask:0xf bank_mask:0xf bound_ctrl:1
	s_nop 1
	v_add_f32_dpp v183, v183, v183 quad_perm:[2,3,0,1] row_mask:0xf bank_mask:0xf bound_ctrl:1
	s_nop 1
	v_add_f32_dpp v183, v183, v183 row_half_mirror row_mask:0xf bank_mask:0xf bound_ctrl:1
	s_nop 1
	v_add_f32_dpp v183, v183, v183 row_mirror row_mask:0xf bank_mask:0xf bound_ctrl:1
	s_nop 1
	v_readlane_b32 s98, v183, 0
	v_readlane_b32 s99, v183, 16
	v_readlane_b32 s100, v183, 32
	v_readlane_b32 s101, v183, 48
	s_nop 1
	v_mov_b32_e32 v183, s98
	v_add_f32_e32 v183, s99, v183
	v_add_f32_e32 v183, s100, v183
	v_add_f32_e32 v183, s101, v183
	v_fmamk_f32 v183, v183, 0x3a800000, v182
	v_cmp_gt_f32_e32 vcc, 0x800000, v183
	v_mul_f32_e32 v181, 0x4b800000, v183
	s_nop 1
	v_cndmask_b32_e32 v183, v183, v181, vcc
	v_rsq_f32_e32 v183, v183
	s_nop 0
	v_mul_f32_e32 v181, 0x45800000, v183
	v_cndmask_b32_e32 v184, v183, v181, vcc
	v_mov_b32_e32 v185, v184
	v_cvt_pk_bf16_f32 v48, v144, v145
	v_cvt_pk_bf16_f32 v49, v146, v147
	v_cvt_pk_bf16_f32 v50, v148, v149
	v_cvt_pk_bf16_f32 v51, v150, v151
	v_cvt_pk_bf16_f32 v52, v152, v153
	v_cvt_pk_bf16_f32 v53, v154, v155
	v_cvt_pk_bf16_f32 v54, v156, v157
	v_cvt_pk_bf16_f32 v55, v158, v159
	v_add_u32_e32 v181, 0x2400000, v177
	global_store_dwordx4 v181, v[48:51], s[78:79]
	global_store_dwordx4 v181, v[52:55], s[78:79] offset:1024
	v_add_u32_e32 v236, 0x6000, v237
	s_mov_b64 exec, 1
	global_store_dword v236, v184, s[78:79]
	s_mov_b64 exec, -1
	s_waitcnt vmcnt(12)
	v_lshlrev_b32_e32 v144, 16, v64
	v_and_b32_e32 v145, 0xffff0000, v64
	v_lshlrev_b32_e32 v146, 16, v65
	v_and_b32_e32 v147, 0xffff0000, v65
	v_lshlrev_b32_e32 v148, 16, v66
	v_and_b32_e32 v149, 0xffff0000, v66
	v_lshlrev_b32_e32 v150, 16, v67
	v_and_b32_e32 v151, 0xffff0000, v67
	v_lshlrev_b32_e32 v152, 16, v68
	v_and_b32_e32 v153, 0xffff0000, v68
	v_lshlrev_b32_e32 v154, 16, v69
	v_and_b32_e32 v155, 0xffff0000, v69
	v_lshlrev_b32_e32 v156, 16, v70
	v_and_b32_e32 v157, 0xffff0000, v70
	v_lshlrev_b32_e32 v158, 16, v71
	v_and_b32_e32 v159, 0xffff0000, v71
	v_lshlrev_b32_e32 v160, 16, v72
	v_and_b32_e32 v161, 0xffff0000, v72
	v_lshlrev_b32_e32 v162, 16, v73
	v_and_b32_e32 v163, 0xffff0000, v73
	v_lshlrev_b32_e32 v164, 16, v74
	v_and_b32_e32 v165, 0xffff0000, v74
	v_lshlrev_b32_e32 v166, 16, v75
	v_and_b32_e32 v167, 0xffff0000, v75
	v_lshlrev_b32_e32 v168, 16, v76
	v_and_b32_e32 v169, 0xffff0000, v76
	v_lshlrev_b32_e32 v170, 16, v77
	v_and_b32_e32 v171, 0xffff0000, v77
	v_lshlrev_b32_e32 v172, 16, v78
	v_and_b32_e32 v173, 0xffff0000, v78
	v_lshlrev_b32_e32 v174, 16, v79
	v_and_b32_e32 v175, 0xffff0000, v79
	v_pk_mul_f32 v[252:253], v[160:161], v[160:161]
	v_pk_mul_f32 v[254:255], v[162:163], v[162:163]
	v_pk_fma_f32 v[252:253], v[164:165], v[164:165], v[252:253]
	v_pk_fma_f32 v[254:255], v[166:167], v[166:167], v[254:255]
	v_pk_fma_f32 v[252:253], v[168:169], v[168:169], v[252:253]
	v_pk_fma_f32 v[254:255], v[170:171], v[170:171], v[254:255]
	v_pk_fma_f32 v[252:253], v[172:173], v[172:173], v[252:253]
	v_pk_fma_f32 v[254:255], v[174:175], v[174:175], v[254:255]
	v_pk_add_f32 v[252:253], v[252:253], v[254:255]
	s_nop 0
	v_add_f32_e32 v183, v252, v253
	s_nop 1
	v_add_f32_dpp v183, v183, v183 quad_perm:[1,0,3,2] row_mask:0xf bank_mask:0xf bound_ctrl:1
	s_nop 1
	v_add_f32_dpp v183, v183, v183 quad_perm:[2,3,0,1] row_mask:0xf bank_mask:0xf bound_ctrl:1
	s_nop 1
	v_add_f32_dpp v183, v183, v183 row_half_mirror row_mask:0xf bank_mask:0xf bound_ctrl:1
	s_nop 1
	v_add_f32_dpp v183, v183, v183 row_mirror row_mask:0xf bank_mask:0xf bound_ctrl:1
	s_nop 1
	v_readlane_b32 s98, v183, 0
	v_readlane_b32 s99, v183, 16
	v_readlane_b32 s100, v183, 32
	v_readlane_b32 s101, v183, 48
	s_nop 1
	v_mov_b32_e32 v183, s98
	v_add_f32_e32 v183, s99, v183
	v_add_f32_e32 v183, s100, v183
	v_add_f32_e32 v183, s101, v183
	v_fmamk_f32 v183, v183, 0x3a800000, v182
	v_cmp_gt_f32_e32 vcc, 0x800000, v183
	v_mul_f32_e32 v181, 0x4b800000, v183
	s_nop 1
	v_cndmask_b32_e32 v183, v183, v181, vcc
	v_rsq_f32_e32 v183, v183
	s_nop 0
	v_mul_f32_e32 v181, 0x45800000, v183
	v_cndmask_b32_e32 v184, v183, v181, vcc
	v_mov_b32_e32 v185, v184
	v_pk_mul_f32 v[160:161], v[160:161], v[184:185]
	v_pk_mul_f32 v[162:163], v[162:163], v[184:185]
	v_pk_mul_f32 v[164:165], v[164:165], v[184:185]
	v_pk_mul_f32 v[166:167], v[166:167], v[184:185]
	v_pk_mul_f32 v[168:169], v[168:169], v[184:185]
	v_pk_mul_f32 v[170:171], v[170:171], v[184:185]
	v_pk_mul_f32 v[172:173], v[172:173], v[184:185]
	v_pk_mul_f32 v[174:175], v[174:175], v[184:185]
	v_pk_fma_f32 v[144:145], v[160:161], v[128:129], v[144:145]
	v_pk_fma_f32 v[146:147], v[162:163], v[130:131], v[146:147]
	v_pk_fma_f32 v[148:149], v[164:165], v[132:133], v[148:149]
	v_pk_fma_f32 v[150:151], v[166:167], v[134:135], v[150:151]
	v_pk_fma_f32 v[152:153], v[168:169], v[136:137], v[152:153]
	v_pk_fma_f32 v[154:155], v[170:171], v[138:139], v[154:155]
	v_pk_fma_f32 v[156:157], v[172:173], v[140:141], v[156:157]
	v_pk_fma_f32 v[158:159], v[174:175], v[142:143], v[158:159]
	v_pk_mul_f32 v[252:253], v[144:145], v[144:145]
	v_pk_mul_f32 v[254:255], v[146:147], v[146:147]
	v_pk_fma_f32 v[252:253], v[148:149], v[148:149], v[252:253]
	v_pk_fma_f32 v[254:255], v[150:151], v[150:151], v[254:255]
	v_pk_fma_f32 v[252:253], v[152:153], v[152:153], v[252:253]
	v_pk_fma_f32 v[254:255], v[154:155], v[154:155], v[254:255]
	v_pk_fma_f32 v[252:253], v[156:157], v[156:157], v[252:253]
	v_pk_fma_f32 v[254:255], v[158:159], v[158:159], v[254:255]
	v_pk_add_f32 v[252:253], v[252:253], v[254:255]
	s_nop 0
	v_add_f32_e32 v183, v252, v253
	s_nop 1
	v_add_f32_dpp v183, v183, v183 quad_perm:[1,0,3,2] row_mask:0xf bank_mask:0xf bound_ctrl:1
	s_nop 1
	v_add_f32_dpp v183, v183, v183 quad_perm:[2,3,0,1] row_mask:0xf bank_mask:0xf bound_ctrl:1
	s_nop 1
	v_add_f32_dpp v183, v183, v183 row_half_mirror row_mask:0xf bank_mask:0xf bound_ctrl:1
	s_nop 1
	v_add_f32_dpp v183, v183, v183 row_mirror row_mask:0xf bank_mask:0xf bound_ctrl:1
	s_nop 1
	v_readlane_b32 s98, v183, 0
	v_readlane_b32 s99, v183, 16
	v_readlane_b32 s100, v183, 32
	v_readlane_b32 s101, v183, 48
	s_nop 1
	v_mov_b32_e32 v183, s98
	v_add_f32_e32 v183, s99, v183
	v_add_f32_e32 v183, s100, v183
	v_add_f32_e32 v183, s101, v183
	v_fmamk_f32 v183, v183, 0x3a800000, v182
	v_cmp_gt_f32_e32 vcc, 0x800000, v183
	v_mul_f32_e32 v181, 0x4b800000, v183
	s_nop 1
	v_cndmask_b32_e32 v183, v183, v181, vcc
	v_rsq_f32_e32 v183, v183
	s_nop 0
	v_mul_f32_e32 v181, 0x45800000, v183
	v_cndmask_b32_e32 v184, v183, v181, vcc
	v_mov_b32_e32 v185, v184
	v_cvt_pk_bf16_f32 v64, v144, v145
	v_cvt_pk_bf16_f32 v65, v146, v147
	v_cvt_pk_bf16_f32 v66, v148, v149
	v_cvt_pk_bf16_f32 v67, v150, v151
	v_cvt_pk_bf16_f32 v68, v152, v153
	v_cvt_pk_bf16_f32 v69, v154, v155
	v_cvt_pk_bf16_f32 v70, v156, v157
	v_cvt_pk_bf16_f32 v71, v158, v159
	v_add_u32_e32 v181, 0x2800000, v177
	global_store_dwordx4 v181, v[64:67], s[78:79]
	global_store_dwordx4 v181, v[68:71], s[78:79] offset:1024
	v_add_u32_e32 v236, 0x8000, v237
	s_mov_b64 exec, 1
	global_store_dword v236, v184, s[78:79]
	s_mov_b64 exec, -1
	s_waitcnt vmcnt(8)
	v_lshlrev_b32_e32 v144, 16, v80
	v_and_b32_e32 v145, 0xffff0000, v80
	v_lshlrev_b32_e32 v146, 16, v81
	v_and_b32_e32 v147, 0xffff0000, v81
	v_lshlrev_b32_e32 v148, 16, v82
	v_and_b32_e32 v149, 0xffff0000, v82
	v_lshlrev_b32_e32 v150, 16, v83
	v_and_b32_e32 v151, 0xffff0000, v83
	v_lshlrev_b32_e32 v152, 16, v84
	v_and_b32_e32 v153, 0xffff0000, v84
	v_lshlrev_b32_e32 v154, 16, v85
	v_and_b32_e32 v155, 0xffff0000, v85
	v_lshlrev_b32_e32 v156, 16, v86
	v_and_b32_e32 v157, 0xffff0000, v86
	v_lshlrev_b32_e32 v158, 16, v87
	v_and_b32_e32 v159, 0xffff0000, v87
	v_lshlrev_b32_e32 v160, 16, v88
	v_and_b32_e32 v161, 0xffff0000, v88
	v_lshlrev_b32_e32 v162, 16, v89
	v_and_b32_e32 v163, 0xffff0000, v89
	v_lshlrev_b32_e32 v164, 16, v90
	v_and_b32_e32 v165, 0xffff0000, v90
	v_lshlrev_b32_e32 v166, 16, v91
	v_and_b32_e32 v167, 0xffff0000, v91
	v_lshlrev_b32_e32 v168, 16, v92
	v_and_b32_e32 v169, 0xffff0000, v92
	v_lshlrev_b32_e32 v170, 16, v93
	v_and_b32_e32 v171, 0xffff0000, v93
	v_lshlrev_b32_e32 v172, 16, v94
	v_and_b32_e32 v173, 0xffff0000, v94
	v_lshlrev_b32_e32 v174, 16, v95
	v_and_b32_e32 v175, 0xffff0000, v95
	v_pk_mul_f32 v[252:253], v[160:161], v[160:161]
	v_pk_mul_f32 v[254:255], v[162:163], v[162:163]
	v_pk_fma_f32 v[252:253], v[164:165], v[164:165], v[252:253]
	v_pk_fma_f32 v[254:255], v[166:167], v[166:167], v[254:255]
	v_pk_fma_f32 v[252:253], v[168:169], v[168:169], v[252:253]
	v_pk_fma_f32 v[254:255], v[170:171], v[170:171], v[254:255]
	v_pk_fma_f32 v[252:253], v[172:173], v[172:173], v[252:253]
	v_pk_fma_f32 v[254:255], v[174:175], v[174:175], v[254:255]
	v_pk_add_f32 v[252:253], v[252:253], v[254:255]
	s_nop 0
	v_add_f32_e32 v183, v252, v253
	s_nop 1
	v_add_f32_dpp v183, v183, v183 quad_perm:[1,0,3,2] row_mask:0xf bank_mask:0xf bound_ctrl:1
	s_nop 1
	v_add_f32_dpp v183, v183, v183 quad_perm:[2,3,0,1] row_mask:0xf bank_mask:0xf bound_ctrl:1
	s_nop 1
	v_add_f32_dpp v183, v183, v183 row_half_mirror row_mask:0xf bank_mask:0xf bound_ctrl:1
	s_nop 1
	v_add_f32_dpp v183, v183, v183 row_mirror row_mask:0xf bank_mask:0xf bound_ctrl:1
	s_nop 1
	v_readlane_b32 s98, v183, 0
	v_readlane_b32 s99, v183, 16
	v_readlane_b32 s100, v183, 32
	v_readlane_b32 s101, v183, 48
	s_nop 1
	v_mov_b32_e32 v183, s98
	v_add_f32_e32 v183, s99, v183
	v_add_f32_e32 v183, s100, v183
	v_add_f32_e32 v183, s101, v183
	v_fmamk_f32 v183, v183, 0x3a800000, v182
	v_cmp_gt_f32_e32 vcc, 0x800000, v183
	v_mul_f32_e32 v181, 0x4b800000, v183
	s_nop 1
	v_cndmask_b32_e32 v183, v183, v181, vcc
	v_rsq_f32_e32 v183, v183
	s_nop 0
	v_mul_f32_e32 v181, 0x45800000, v183
	v_cndmask_b32_e32 v184, v183, v181, vcc
	v_mov_b32_e32 v185, v184
	v_pk_mul_f32 v[160:161], v[160:161], v[184:185]
	v_pk_mul_f32 v[162:163], v[162:163], v[184:185]
	v_pk_mul_f32 v[164:165], v[164:165], v[184:185]
	v_pk_mul_f32 v[166:167], v[166:167], v[184:185]
	v_pk_mul_f32 v[168:169], v[168:169], v[184:185]
	v_pk_mul_f32 v[170:171], v[170:171], v[184:185]
	v_pk_mul_f32 v[172:173], v[172:173], v[184:185]
	v_pk_mul_f32 v[174:175], v[174:175], v[184:185]
	v_pk_fma_f32 v[144:145], v[160:161], v[128:129], v[144:145]
	v_pk_fma_f32 v[146:147], v[162:163], v[130:131], v[146:147]
	v_pk_fma_f32 v[148:149], v[164:165], v[132:133], v[148:149]
	v_pk_fma_f32 v[150:151], v[166:167], v[134:135], v[150:151]
	v_pk_fma_f32 v[152:153], v[168:169], v[136:137], v[152:153]
	v_pk_fma_f32 v[154:155], v[170:171], v[138:139], v[154:155]
	v_pk_fma_f32 v[156:157], v[172:173], v[140:141], v[156:157]
	v_pk_fma_f32 v[158:159], v[174:175], v[142:143], v[158:159]
	v_pk_mul_f32 v[252:253], v[144:145], v[144:145]
	v_pk_mul_f32 v[254:255], v[146:147], v[146:147]
	v_pk_fma_f32 v[252:253], v[148:149], v[148:149], v[252:253]
	v_pk_fma_f32 v[254:255], v[150:151], v[150:151], v[254:255]
	v_pk_fma_f32 v[252:253], v[152:153], v[152:153], v[252:253]
	v_pk_fma_f32 v[254:255], v[154:155], v[154:155], v[254:255]
	v_pk_fma_f32 v[252:253], v[156:157], v[156:157], v[252:253]
	v_pk_fma_f32 v[254:255], v[158:159], v[158:159], v[254:255]
	v_pk_add_f32 v[252:253], v[252:253], v[254:255]
	s_nop 0
	v_add_f32_e32 v183, v252, v253
	s_nop 1
	v_add_f32_dpp v183, v183, v183 quad_perm:[1,0,3,2] row_mask:0xf bank_mask:0xf bound_ctrl:1
	s_nop 1
	v_add_f32_dpp v183, v183, v183 quad_perm:[2,3,0,1] row_mask:0xf bank_mask:0xf bound_ctrl:1
	s_nop 1
	v_add_f32_dpp v183, v183, v183 row_half_mirror row_mask:0xf bank_mask:0xf bound_ctrl:1
	s_nop 1
	v_add_f32_dpp v183, v183, v183 row_mirror row_mask:0xf bank_mask:0xf bound_ctrl:1
	s_nop 1
	v_readlane_b32 s98, v183, 0
	v_readlane_b32 s99, v183, 16
	v_readlane_b32 s100, v183, 32
	v_readlane_b32 s101, v183, 48
	s_nop 1
	v_mov_b32_e32 v183, s98
	v_add_f32_e32 v183, s99, v183
	v_add_f32_e32 v183, s100, v183
	v_add_f32_e32 v183, s101, v183
	v_fmamk_f32 v183, v183, 0x3a800000, v182
	v_cmp_gt_f32_e32 vcc, 0x800000, v183
	v_mul_f32_e32 v181, 0x4b800000, v183
	s_nop 1
	v_cndmask_b32_e32 v183, v183, v181, vcc
	v_rsq_f32_e32 v183, v183
	s_nop 0
	v_mul_f32_e32 v181, 0x45800000, v183
	v_cndmask_b32_e32 v184, v183, v181, vcc
	v_mov_b32_e32 v185, v184
	v_cvt_pk_bf16_f32 v80, v144, v145
	v_cvt_pk_bf16_f32 v81, v146, v147
	v_cvt_pk_bf16_f32 v82, v148, v149
	v_cvt_pk_bf16_f32 v83, v150, v151
	v_cvt_pk_bf16_f32 v84, v152, v153
	v_cvt_pk_bf16_f32 v85, v154, v155
	v_cvt_pk_bf16_f32 v86, v156, v157
	v_cvt_pk_bf16_f32 v87, v158, v159
	v_add_u32_e32 v181, 0x2c00000, v177
	global_store_dwordx4 v181, v[80:83], s[78:79]
	global_store_dwordx4 v181, v[84:87], s[78:79] offset:1024
	v_add_u32_e32 v236, 0xa000, v237
	s_mov_b64 exec, 1
	global_store_dword v236, v184, s[78:79]
	s_mov_b64 exec, -1
	s_waitcnt vmcnt(4)
	v_lshlrev_b32_e32 v144, 16, v96
	v_and_b32_e32 v145, 0xffff0000, v96
	v_lshlrev_b32_e32 v146, 16, v97
	v_and_b32_e32 v147, 0xffff0000, v97
	v_lshlrev_b32_e32 v148, 16, v98
	v_and_b32_e32 v149, 0xffff0000, v98
	v_lshlrev_b32_e32 v150, 16, v99
	v_and_b32_e32 v151, 0xffff0000, v99
	v_lshlrev_b32_e32 v152, 16, v100
	v_and_b32_e32 v153, 0xffff0000, v100
	v_lshlrev_b32_e32 v154, 16, v101
	v_and_b32_e32 v155, 0xffff0000, v101
	v_lshlrev_b32_e32 v156, 16, v102
	v_and_b32_e32 v157, 0xffff0000, v102
	v_lshlrev_b32_e32 v158, 16, v103
	v_and_b32_e32 v159, 0xffff0000, v103
	v_lshlrev_b32_e32 v160, 16, v104
	v_and_b32_e32 v161, 0xffff0000, v104
	v_lshlrev_b32_e32 v162, 16, v105
	v_and_b32_e32 v163, 0xffff0000, v105
	v_lshlrev_b32_e32 v164, 16, v106
	v_and_b32_e32 v165, 0xffff0000, v106
	v_lshlrev_b32_e32 v166, 16, v107
	v_and_b32_e32 v167, 0xffff0000, v107
	v_lshlrev_b32_e32 v168, 16, v108
	v_and_b32_e32 v169, 0xffff0000, v108
	v_lshlrev_b32_e32 v170, 16, v109
	v_and_b32_e32 v171, 0xffff0000, v109
	v_lshlrev_b32_e32 v172, 16, v110
	v_and_b32_e32 v173, 0xffff0000, v110
	v_lshlrev_b32_e32 v174, 16, v111
	v_and_b32_e32 v175, 0xffff0000, v111
	v_pk_mul_f32 v[252:253], v[160:161], v[160:161]
	v_pk_mul_f32 v[254:255], v[162:163], v[162:163]
	v_pk_fma_f32 v[252:253], v[164:165], v[164:165], v[252:253]
	v_pk_fma_f32 v[254:255], v[166:167], v[166:167], v[254:255]
	v_pk_fma_f32 v[252:253], v[168:169], v[168:169], v[252:253]
	v_pk_fma_f32 v[254:255], v[170:171], v[170:171], v[254:255]
	v_pk_fma_f32 v[252:253], v[172:173], v[172:173], v[252:253]
	v_pk_fma_f32 v[254:255], v[174:175], v[174:175], v[254:255]
	v_pk_add_f32 v[252:253], v[252:253], v[254:255]
	s_nop 0
	v_add_f32_e32 v183, v252, v253
	s_nop 1
	v_add_f32_dpp v183, v183, v183 quad_perm:[1,0,3,2] row_mask:0xf bank_mask:0xf bound_ctrl:1
	s_nop 1
	v_add_f32_dpp v183, v183, v183 quad_perm:[2,3,0,1] row_mask:0xf bank_mask:0xf bound_ctrl:1
	s_nop 1
	v_add_f32_dpp v183, v183, v183 row_half_mirror row_mask:0xf bank_mask:0xf bound_ctrl:1
	s_nop 1
	v_add_f32_dpp v183, v183, v183 row_mirror row_mask:0xf bank_mask:0xf bound_ctrl:1
	s_nop 1
	v_readlane_b32 s98, v183, 0
	v_readlane_b32 s99, v183, 16
	v_readlane_b32 s100, v183, 32
	v_readlane_b32 s101, v183, 48
	s_nop 1
	v_mov_b32_e32 v183, s98
	v_add_f32_e32 v183, s99, v183
	v_add_f32_e32 v183, s100, v183
	v_add_f32_e32 v183, s101, v183
	v_fmamk_f32 v183, v183, 0x3a800000, v182
	v_cmp_gt_f32_e32 vcc, 0x800000, v183
	v_mul_f32_e32 v181, 0x4b800000, v183
	s_nop 1
	v_cndmask_b32_e32 v183, v183, v181, vcc
	v_rsq_f32_e32 v183, v183
	s_nop 0
	v_mul_f32_e32 v181, 0x45800000, v183
	v_cndmask_b32_e32 v184, v183, v181, vcc
	v_mov_b32_e32 v185, v184
	v_pk_mul_f32 v[160:161], v[160:161], v[184:185]
	v_pk_mul_f32 v[162:163], v[162:163], v[184:185]
	v_pk_mul_f32 v[164:165], v[164:165], v[184:185]
	v_pk_mul_f32 v[166:167], v[166:167], v[184:185]
	v_pk_mul_f32 v[168:169], v[168:169], v[184:185]
	v_pk_mul_f32 v[170:171], v[170:171], v[184:185]
	v_pk_mul_f32 v[172:173], v[172:173], v[184:185]
	v_pk_mul_f32 v[174:175], v[174:175], v[184:185]
	v_pk_fma_f32 v[144:145], v[160:161], v[128:129], v[144:145]
	v_pk_fma_f32 v[146:147], v[162:163], v[130:131], v[146:147]
	v_pk_fma_f32 v[148:149], v[164:165], v[132:133], v[148:149]
	v_pk_fma_f32 v[150:151], v[166:167], v[134:135], v[150:151]
	v_pk_fma_f32 v[152:153], v[168:169], v[136:137], v[152:153]
	v_pk_fma_f32 v[154:155], v[170:171], v[138:139], v[154:155]
	v_pk_fma_f32 v[156:157], v[172:173], v[140:141], v[156:157]
	v_pk_fma_f32 v[158:159], v[174:175], v[142:143], v[158:159]
	v_pk_mul_f32 v[252:253], v[144:145], v[144:145]
	v_pk_mul_f32 v[254:255], v[146:147], v[146:147]
	v_pk_fma_f32 v[252:253], v[148:149], v[148:149], v[252:253]
	v_pk_fma_f32 v[254:255], v[150:151], v[150:151], v[254:255]
	v_pk_fma_f32 v[252:253], v[152:153], v[152:153], v[252:253]
	v_pk_fma_f32 v[254:255], v[154:155], v[154:155], v[254:255]
	v_pk_fma_f32 v[252:253], v[156:157], v[156:157], v[252:253]
	v_pk_fma_f32 v[254:255], v[158:159], v[158:159], v[254:255]
	v_pk_add_f32 v[252:253], v[252:253], v[254:255]
	s_nop 0
	v_add_f32_e32 v183, v252, v253
	s_nop 1
	v_add_f32_dpp v183, v183, v183 quad_perm:[1,0,3,2] row_mask:0xf bank_mask:0xf bound_ctrl:1
	s_nop 1
	v_add_f32_dpp v183, v183, v183 quad_perm:[2,3,0,1] row_mask:0xf bank_mask:0xf bound_ctrl:1
	s_nop 1
	v_add_f32_dpp v183, v183, v183 row_half_mirror row_mask:0xf bank_mask:0xf bound_ctrl:1
	s_nop 1
	v_add_f32_dpp v183, v183, v183 row_mirror row_mask:0xf bank_mask:0xf bound_ctrl:1
	s_nop 1
	v_readlane_b32 s98, v183, 0
	v_readlane_b32 s99, v183, 16
	v_readlane_b32 s100, v183, 32
	v_readlane_b32 s101, v183, 48
	s_nop 1
	v_mov_b32_e32 v183, s98
	v_add_f32_e32 v183, s99, v183
	v_add_f32_e32 v183, s100, v183
	v_add_f32_e32 v183, s101, v183
	v_fmamk_f32 v183, v183, 0x3a800000, v182
	v_cmp_gt_f32_e32 vcc, 0x800000, v183
	v_mul_f32_e32 v181, 0x4b800000, v183
	s_nop 1
	v_cndmask_b32_e32 v183, v183, v181, vcc
	v_rsq_f32_e32 v183, v183
	s_nop 0
	v_mul_f32_e32 v181, 0x45800000, v183
	v_cndmask_b32_e32 v184, v183, v181, vcc
	v_mov_b32_e32 v185, v184
	v_cvt_pk_bf16_f32 v96, v144, v145
	v_cvt_pk_bf16_f32 v97, v146, v147
	v_cvt_pk_bf16_f32 v98, v148, v149
	v_cvt_pk_bf16_f32 v99, v150, v151
	v_cvt_pk_bf16_f32 v100, v152, v153
	v_cvt_pk_bf16_f32 v101, v154, v155
	v_cvt_pk_bf16_f32 v102, v156, v157
	v_cvt_pk_bf16_f32 v103, v158, v159
	v_add_u32_e32 v181, 0x3000000, v177
	global_store_dwordx4 v181, v[96:99], s[78:79]
	global_store_dwordx4 v181, v[100:103], s[78:79] offset:1024
	v_add_u32_e32 v236, 0xc000, v237
	s_mov_b64 exec, 1
	global_store_dword v236, v184, s[78:79]
	s_mov_b64 exec, -1
	s_waitcnt vmcnt(0)
	v_lshlrev_b32_e32 v144, 16, v112
	v_and_b32_e32 v145, 0xffff0000, v112
	v_lshlrev_b32_e32 v146, 16, v113
	v_and_b32_e32 v147, 0xffff0000, v113
	v_lshlrev_b32_e32 v148, 16, v114
	v_and_b32_e32 v149, 0xffff0000, v114
	v_lshlrev_b32_e32 v150, 16, v115
	v_and_b32_e32 v151, 0xffff0000, v115
	v_lshlrev_b32_e32 v152, 16, v116
	v_and_b32_e32 v153, 0xffff0000, v116
	v_lshlrev_b32_e32 v154, 16, v117
	v_and_b32_e32 v155, 0xffff0000, v117
	v_lshlrev_b32_e32 v156, 16, v118
	v_and_b32_e32 v157, 0xffff0000, v118
	v_lshlrev_b32_e32 v158, 16, v119
	v_and_b32_e32 v159, 0xffff0000, v119
	v_lshlrev_b32_e32 v160, 16, v120
	v_and_b32_e32 v161, 0xffff0000, v120
	v_lshlrev_b32_e32 v162, 16, v121
	v_and_b32_e32 v163, 0xffff0000, v121
	v_lshlrev_b32_e32 v164, 16, v122
	v_and_b32_e32 v165, 0xffff0000, v122
	v_lshlrev_b32_e32 v166, 16, v123
	v_and_b32_e32 v167, 0xffff0000, v123
	v_lshlrev_b32_e32 v168, 16, v124
	v_and_b32_e32 v169, 0xffff0000, v124
	v_lshlrev_b32_e32 v170, 16, v125
	v_and_b32_e32 v171, 0xffff0000, v125
	v_lshlrev_b32_e32 v172, 16, v126
	v_and_b32_e32 v173, 0xffff0000, v126
	v_lshlrev_b32_e32 v174, 16, v127
	v_and_b32_e32 v175, 0xffff0000, v127
	v_pk_mul_f32 v[252:253], v[160:161], v[160:161]
	v_pk_mul_f32 v[254:255], v[162:163], v[162:163]
	v_pk_fma_f32 v[252:253], v[164:165], v[164:165], v[252:253]
	v_pk_fma_f32 v[254:255], v[166:167], v[166:167], v[254:255]
	v_pk_fma_f32 v[252:253], v[168:169], v[168:169], v[252:253]
	v_pk_fma_f32 v[254:255], v[170:171], v[170:171], v[254:255]
	v_pk_fma_f32 v[252:253], v[172:173], v[172:173], v[252:253]
	v_pk_fma_f32 v[254:255], v[174:175], v[174:175], v[254:255]
	v_pk_add_f32 v[252:253], v[252:253], v[254:255]
	s_nop 0
	v_add_f32_e32 v183, v252, v253
	s_nop 1
	v_add_f32_dpp v183, v183, v183 quad_perm:[1,0,3,2] row_mask:0xf bank_mask:0xf bound_ctrl:1
	s_nop 1
	v_add_f32_dpp v183, v183, v183 quad_perm:[2,3,0,1] row_mask:0xf bank_mask:0xf bound_ctrl:1
	s_nop 1
	v_add_f32_dpp v183, v183, v183 row_half_mirror row_mask:0xf bank_mask:0xf bound_ctrl:1
	s_nop 1
	v_add_f32_dpp v183, v183, v183 row_mirror row_mask:0xf bank_mask:0xf bound_ctrl:1
	s_nop 1
	v_readlane_b32 s98, v183, 0
	v_readlane_b32 s99, v183, 16
	v_readlane_b32 s100, v183, 32
	v_readlane_b32 s101, v183, 48
	s_nop 1
	v_mov_b32_e32 v183, s98
	v_add_f32_e32 v183, s99, v183
	v_add_f32_e32 v183, s100, v183
	v_add_f32_e32 v183, s101, v183
	v_fmamk_f32 v183, v183, 0x3a800000, v182
	v_cmp_gt_f32_e32 vcc, 0x800000, v183
	v_mul_f32_e32 v181, 0x4b800000, v183
	s_nop 1
	v_cndmask_b32_e32 v183, v183, v181, vcc
	v_rsq_f32_e32 v183, v183
	s_nop 0
	v_mul_f32_e32 v181, 0x45800000, v183
	v_cndmask_b32_e32 v184, v183, v181, vcc
	v_mov_b32_e32 v185, v184
	v_pk_mul_f32 v[160:161], v[160:161], v[184:185]
	v_pk_mul_f32 v[162:163], v[162:163], v[184:185]
	v_pk_mul_f32 v[164:165], v[164:165], v[184:185]
	v_pk_mul_f32 v[166:167], v[166:167], v[184:185]
	v_pk_mul_f32 v[168:169], v[168:169], v[184:185]
	v_pk_mul_f32 v[170:171], v[170:171], v[184:185]
	v_pk_mul_f32 v[172:173], v[172:173], v[184:185]
	v_pk_mul_f32 v[174:175], v[174:175], v[184:185]
	v_pk_fma_f32 v[144:145], v[160:161], v[128:129], v[144:145]
	v_pk_fma_f32 v[146:147], v[162:163], v[130:131], v[146:147]
	v_pk_fma_f32 v[148:149], v[164:165], v[132:133], v[148:149]
	v_pk_fma_f32 v[150:151], v[166:167], v[134:135], v[150:151]
	v_pk_fma_f32 v[152:153], v[168:169], v[136:137], v[152:153]
	v_pk_fma_f32 v[154:155], v[170:171], v[138:139], v[154:155]
	v_pk_fma_f32 v[156:157], v[172:173], v[140:141], v[156:157]
	v_pk_fma_f32 v[158:159], v[174:175], v[142:143], v[158:159]
	v_pk_mul_f32 v[252:253], v[144:145], v[144:145]
	v_pk_mul_f32 v[254:255], v[146:147], v[146:147]
	v_pk_fma_f32 v[252:253], v[148:149], v[148:149], v[252:253]
	v_pk_fma_f32 v[254:255], v[150:151], v[150:151], v[254:255]
	v_pk_fma_f32 v[252:253], v[152:153], v[152:153], v[252:253]
	v_pk_fma_f32 v[254:255], v[154:155], v[154:155], v[254:255]
	v_pk_fma_f32 v[252:253], v[156:157], v[156:157], v[252:253]
	v_pk_fma_f32 v[254:255], v[158:159], v[158:159], v[254:255]
	v_pk_add_f32 v[252:253], v[252:253], v[254:255]
	s_nop 0
	v_add_f32_e32 v183, v252, v253
	s_nop 1
	v_add_f32_dpp v183, v183, v183 quad_perm:[1,0,3,2] row_mask:0xf bank_mask:0xf bound_ctrl:1
	s_nop 1
	v_add_f32_dpp v183, v183, v183 quad_perm:[2,3,0,1] row_mask:0xf bank_mask:0xf bound_ctrl:1
	s_nop 1
	v_add_f32_dpp v183, v183, v183 row_half_mirror row_mask:0xf bank_mask:0xf bound_ctrl:1
	s_nop 1
	v_add_f32_dpp v183, v183, v183 row_mirror row_mask:0xf bank_mask:0xf bound_ctrl:1
	s_nop 1
	v_readlane_b32 s98, v183, 0
	v_readlane_b32 s99, v183, 16
	v_readlane_b32 s100, v183, 32
	v_readlane_b32 s101, v183, 48
	s_nop 1
	v_mov_b32_e32 v183, s98
	v_add_f32_e32 v183, s99, v183
	v_add_f32_e32 v183, s100, v183
	v_add_f32_e32 v183, s101, v183
	v_fmamk_f32 v183, v183, 0x3a800000, v182
	v_cmp_gt_f32_e32 vcc, 0x800000, v183
	v_mul_f32_e32 v181, 0x4b800000, v183
	s_nop 1
	v_cndmask_b32_e32 v183, v183, v181, vcc
	v_rsq_f32_e32 v183, v183
	s_nop 0
	v_mul_f32_e32 v181, 0x45800000, v183
	v_cndmask_b32_e32 v184, v183, v181, vcc
	v_mov_b32_e32 v185, v184
	v_cvt_pk_bf16_f32 v112, v144, v145
	v_cvt_pk_bf16_f32 v113, v146, v147
	v_cvt_pk_bf16_f32 v114, v148, v149
	v_cvt_pk_bf16_f32 v115, v150, v151
	v_cvt_pk_bf16_f32 v116, v152, v153
	v_cvt_pk_bf16_f32 v117, v154, v155
	v_cvt_pk_bf16_f32 v118, v156, v157
	v_cvt_pk_bf16_f32 v119, v158, v159
	v_add_u32_e32 v181, 0x3400000, v177
	global_store_dwordx4 v181, v[112:115], s[78:79]
	global_store_dwordx4 v181, v[116:119], s[78:79] offset:1024
	v_add_u32_e32 v236, 0xe000, v237
	s_mov_b64 exec, 1
	global_store_dword v236, v184, s[78:79]
	s_mov_b64 exec, -1
	v_readfirstlane_b32 s98, v179
	s_nop 3
	s_cmp_ge_u32 s98, 512
	s_cbranch_scc1 .Lmyxupd_done_0
	v_lshlrev_b32_e32 v177, 4, v176
	v_lshl_add_u32 v177, v179, 11, v177
	v_lshlrev_b32_e32 v237, 2, v179
	v_add_u32_e32 v237, 0x10000, v237
	v_add_u32_e32 v181, 0x3800000, v177
	global_load_dwordx4 v[0:3], v181, s[78:79]
	global_load_dwordx4 v[4:7], v181, s[78:79] offset:1024
	v_lshl_add_u32 v183, v179, 12, v180
	v_add_u32_e32 v183, 0xbf00000, v183
	v_add_u32_e32 v181, 0x0, v183
	global_load_dwordx4 v[8:11], v181, s[78:79]
	global_load_dwordx4 v[12:15], v181, s[78:79] offset:16
	global_load_dwordx4 v[16:19], v181, s[78:79] offset:2048
	global_load_dwordx4 v[20:23], v181, s[78:79] offset:2064
	v_add_u32_e32 v181, 0x200000, v183
	global_load_dwordx4 v[24:27], v181, s[78:79]
	global_load_dwordx4 v[28:31], v181, s[78:79] offset:16
	global_load_dwordx4 v[32:35], v181, s[78:79] offset:2048
	global_load_dwordx4 v[36:39], v181, s[78:79] offset:2064
	v_add_u32_e32 v181, 0x400000, v183
	global_load_dwordx4 v[40:43], v181, s[78:79]
	global_load_dwordx4 v[44:47], v181, s[78:79] offset:16
	global_load_dwordx4 v[48:51], v181, s[78:79] offset:2048
	global_load_dwordx4 v[52:55], v181, s[78:79] offset:2064
	v_add_u32_e32 v181, 0x600000, v183
	global_load_dwordx4 v[56:59], v181, s[78:79]
	global_load_dwordx4 v[60:63], v181, s[78:79] offset:16
	global_load_dwordx4 v[64:67], v181, s[78:79] offset:2048
	global_load_dwordx4 v[68:71], v181, s[78:79] offset:2064
	v_add_u32_e32 v181, 0x800000, v183
	global_load_dwordx4 v[72:75], v181, s[78:79]
	global_load_dwordx4 v[76:79], v181, s[78:79] offset:16
	global_load_dwordx4 v[80:83], v181, s[78:79] offset:2048
	global_load_dwordx4 v[84:87], v181, s[78:79] offset:2064
	v_add_u32_e32 v181, 0xa00000, v183
	global_load_dwordx4 v[88:91], v181, s[78:79]
	global_load_dwordx4 v[92:95], v181, s[78:79] offset:16
	global_load_dwordx4 v[96:99], v181, s[78:79] offset:2048
	global_load_dwordx4 v[100:103], v181, s[78:79] offset:2064
	s_waitcnt vmcnt(20)
	v_pk_add_f32 v[160:161], v[8:9], 0 op_sel_hi:[1,0]
	v_pk_add_f32 v[162:163], v[10:11], 0 op_sel_hi:[1,0]
	v_pk_add_f32 v[164:165], v[12:13], 0 op_sel_hi:[1,0]
	v_pk_add_f32 v[166:167], v[14:15], 0 op_sel_hi:[1,0]
	v_pk_add_f32 v[168:169], v[16:17], 0 op_sel_hi:[1,0]
	v_pk_add_f32 v[170:171], v[18:19], 0 op_sel_hi:[1,0]
	v_pk_add_f32 v[172:173], v[20:21], 0 op_sel_hi:[1,0]
	v_pk_add_f32 v[174:175], v[22:23], 0 op_sel_hi:[1,0]
	s_waitcnt vmcnt(16)
	v_pk_add_f32 v[160:161], v[160:161], v[24:25]
	v_pk_add_f32 v[162:163], v[162:163], v[26:27]
	v_pk_add_f32 v[164:165], v[164:165], v[28:29]
	v_pk_add_f32 v[166:167], v[166:167], v[30:31]
	v_pk_add_f32 v[168:169], v[168:169], v[32:33]
	v_pk_add_f32 v[170:171], v[170:171], v[34:35]
	v_pk_add_f32 v[172:173], v[172:173], v[36:37]
	v_pk_add_f32 v[174:175], v[174:175], v[38:39]
	s_waitcnt vmcnt(12)
	v_pk_add_f32 v[160:161], v[160:161], v[40:41]
	v_pk_add_f32 v[162:163], v[162:163], v[42:43]
	v_pk_add_f32 v[164:165], v[164:165], v[44:45]
	v_pk_add_f32 v[166:167], v[166:167], v[46:47]
	v_pk_add_f32 v[168:169], v[168:169], v[48:49]
	v_pk_add_f32 v[170:171], v[170:171], v[50:51]
	v_pk_add_f32 v[172:173], v[172:173], v[52:53]
	v_pk_add_f32 v[174:175], v[174:175], v[54:55]
	s_waitcnt vmcnt(8)
	v_pk_add_f32 v[160:161], v[160:161], v[56:57]
	v_pk_add_f32 v[162:163], v[162:163], v[58:59]
	v_pk_add_f32 v[164:165], v[164:165], v[60:61]
	v_pk_add_f32 v[166:167], v[166:167], v[62:63]
	v_pk_add_f32 v[168:169], v[168:169], v[64:65]
	v_pk_add_f32 v[170:171], v[170:171], v[66:67]
	v_pk_add_f32 v[172:173], v[172:173], v[68:69]
	v_pk_add_f32 v[174:175], v[174:175], v[70:71]
	s_waitcnt vmcnt(4)
	v_pk_add_f32 v[160:161], v[160:161], v[72:73]
	v_pk_add_f32 v[162:163], v[162:163], v[74:75]
	v_pk_add_f32 v[164:165], v[164:165], v[76:77]
	v_pk_add_f32 v[166:167], v[166:167], v[78:79]
	v_pk_add_f32 v[168:169], v[168:169], v[80:81]
	v_pk_add_f32 v[170:171], v[170:171], v[82:83]
	v_pk_add_f32 v[172:173], v[172:173], v[84:85]
	v_pk_add_f32 v[174:175], v[174:175], v[86:87]
	s_waitcnt vmcnt(0)
	v_pk_add_f32 v[160:161], v[160:161], v[88:89]
	v_pk_add_f32 v[162:163], v[162:163], v[90:91]
	v_pk_add_f32 v[164:165], v[164:165], v[92:93]
	v_pk_add_f32 v[166:167], v[166:167], v[94:95]
	v_pk_add_f32 v[168:169], v[168:169], v[96:97]
	v_pk_add_f32 v[170:171], v[170:171], v[98:99]
	v_pk_add_f32 v[172:173], v[172:173], v[100:101]
	v_pk_add_f32 v[174:175], v[174:175], v[102:103]
	v_lshlrev_b32_e32 v144, 16, v0
	v_and_b32_e32 v145, 0xffff0000, v0
	v_lshlrev_b32_e32 v146, 16, v1
	v_and_b32_e32 v147, 0xffff0000, v1
	v_lshlrev_b32_e32 v148, 16, v2
	v_and_b32_e32 v149, 0xffff0000, v2
	v_lshlrev_b32_e32 v150, 16, v3
	v_and_b32_e32 v151, 0xffff0000, v3
	v_lshlrev_b32_e32 v152, 16, v4
	v_and_b32_e32 v153, 0xffff0000, v4
	v_lshlrev_b32_e32 v154, 16, v5
	v_and_b32_e32 v155, 0xffff0000, v5
	v_lshlrev_b32_e32 v156, 16, v6
	v_and_b32_e32 v157, 0xffff0000, v6
	v_lshlrev_b32_e32 v158, 16, v7
	v_and_b32_e32 v159, 0xffff0000, v7
	v_add_u32_e32 v181, 0xc00000, v183
	global_load_dwordx4 v[8:11], v181, s[78:79]
	global_load_dwordx4 v[12:15], v181, s[78:79] offset:16
	global_load_dwordx4 v[16:19], v181, s[78:79] offset:2048
	global_load_dwordx4 v[20:23], v181, s[78:79] offset:2064
	v_add_u32_e32 v181, 0xe00000, v183
	global_load_dwordx4 v[24:27], v181, s[78:79]
	global_load_dwordx4 v[28:31], v181, s[78:79] offset:16
	global_load_dwordx4 v[32:35], v181, s[78:79] offset:2048
	global_load_dwordx4 v[36:39], v181, s[78:79] offset:2064
	s_waitcnt vmcnt(4)
	v_pk_add_f32 v[160:161], v[160:161], v[8:9]
	v_pk_add_f32 v[162:163], v[162:163], v[10:11]
	v_pk_add_f32 v[164:165], v[164:165], v[12:13]
	v_pk_add_f32 v[166:167], v[166:167], v[14:15]
	v_pk_add_f32 v[168:169], v[168:169], v[16:17]
	v_pk_add_f32 v[170:171], v[170:171], v[18:19]
	v_pk_add_f32 v[172:173], v[172:173], v[20:21]
	v_pk_add_f32 v[174:175], v[174:175], v[22:23]
	s_waitcnt vmcnt(0)
	v_pk_add_f32 v[160:161], v[160:161], v[24:25]
	v_pk_add_f32 v[162:163], v[162:163], v[26:27]
	v_pk_add_f32 v[164:165], v[164:165], v[28:29]
	v_pk_add_f32 v[166:167], v[166:167], v[30:31]
	v_pk_add_f32 v[168:169], v[168:169], v[32:33]
	v_pk_add_f32 v[170:171], v[170:171], v[34:35]
	v_pk_add_f32 v[172:173], v[172:173], v[36:37]
	v_pk_add_f32 v[174:175], v[174:175], v[38:39]
	v_pk_mul_f32 v[252:253], v[160:161], v[160:161]
	v_pk_mul_f32 v[254:255], v[162:163], v[162:163]
	v_pk_fma_f32 v[252:253], v[164:165], v[164:165], v[252:253]
	v_pk_fma_f32 v[254:255], v[166:167], v[166:167], v[254:255]
	v_pk_fma_f32 v[252:253], v[168:169], v[168:169], v[252:253]
	v_pk_fma_f32 v[254:255], v[170:171], v[170:171], v[254:255]
	v_pk_fma_f32 v[252:253], v[172:173], v[172:173], v[252:253]
	v_pk_fma_f32 v[254:255], v[174:175], v[174:175], v[254:255]
	v_pk_add_f32 v[252:253], v[252:253], v[254:255]
	s_nop 0
	v_add_f32_e32 v183, v252, v253
	s_nop 1
	v_add_f32_dpp v183, v183, v183 quad_perm:[1,0,3,2] row_mask:0xf bank_mask:0xf bound_ctrl:1
	s_nop 1
	v_add_f32_dpp v183, v183, v183 quad_perm:[2,3,0,1] row_mask:0xf bank_mask:0xf bound_ctrl:1
	s_nop 1
	v_add_f32_dpp v183, v183, v183 row_half_mirror row_mask:0xf bank_mask:0xf bound_ctrl:1
	s_nop 1
	v_add_f32_dpp v183, v183, v183 row_mirror row_mask:0xf bank_mask:0xf bound_ctrl:1
	s_nop 1
	v_readlane_b32 s98, v183, 0
	v_readlane_b32 s99, v183, 16
	v_readlane_b32 s100, v183, 32
	v_readlane_b32 s101, v183, 48
	s_nop 1
	v_mov_b32_e32 v183, s98
	v_add_f32_e32 v183, s99, v183
	v_add_f32_e32 v183, s100, v183
	v_add_f32_e32 v183, s101, v183
	v_fmamk_f32 v183, v183, 0x3a800000, v182
	v_cmp_gt_f32_e32 vcc, 0x800000, v183
	v_mul_f32_e32 v181, 0x4b800000, v183
	s_nop 1
	v_cndmask_b32_e32 v183, v183, v181, vcc
	v_rsq_f32_e32 v183, v183
	s_nop 0
	v_mul_f32_e32 v181, 0x45800000, v183
	v_cndmask_b32_e32 v184, v183, v181, vcc
	v_mov_b32_e32 v185, v184
	v_pk_mul_f32 v[160:161], v[160:161], v[184:185]
	v_pk_mul_f32 v[162:163], v[162:163], v[184:185]
	v_pk_mul_f32 v[164:165], v[164:165], v[184:185]
	v_pk_mul_f32 v[166:167], v[166:167], v[184:185]
	v_pk_mul_f32 v[168:169], v[168:169], v[184:185]
	v_pk_mul_f32 v[170:171], v[170:171], v[184:185]
	v_pk_mul_f32 v[172:173], v[172:173], v[184:185]
	v_pk_mul_f32 v[174:175], v[174:175], v[184:185]
	v_pk_fma_f32 v[144:145], v[160:161], v[128:129], v[144:145]
	v_pk_fma_f32 v[146:147], v[162:163], v[130:131], v[146:147]
	v_pk_fma_f32 v[148:149], v[164:165], v[132:133], v[148:149]
	v_pk_fma_f32 v[150:151], v[166:167], v[134:135], v[150:151]
	v_pk_fma_f32 v[152:153], v[168:169], v[136:137], v[152:153]
	v_pk_fma_f32 v[154:155], v[170:171], v[138:139], v[154:155]
	v_pk_fma_f32 v[156:157], v[172:173], v[140:141], v[156:157]
	v_pk_fma_f32 v[158:159], v[174:175], v[142:143], v[158:159]
	v_pk_mul_f32 v[252:253], v[144:145], v[144:145]
	v_pk_mul_f32 v[254:255], v[146:147], v[146:147]
	v_pk_fma_f32 v[252:253], v[148:149], v[148:149], v[252:253]
	v_pk_fma_f32 v[254:255], v[150:151], v[150:151], v[254:255]
	v_pk_fma_f32 v[252:253], v[152:153], v[152:153], v[252:253]
	v_pk_fma_f32 v[254:255], v[154:155], v[154:155], v[254:255]
	v_pk_fma_f32 v[252:253], v[156:157], v[156:157], v[252:253]
	v_pk_fma_f32 v[254:255], v[158:159], v[158:159], v[254:255]
	v_pk_add_f32 v[252:253], v[252:253], v[254:255]
	s_nop 0
	v_add_f32_e32 v183, v252, v253
	s_nop 1
	v_add_f32_dpp v183, v183, v183 quad_perm:[1,0,3,2] row_mask:0xf bank_mask:0xf bound_ctrl:1
	s_nop 1
	v_add_f32_dpp v183, v183, v183 quad_perm:[2,3,0,1] row_mask:0xf bank_mask:0xf bound_ctrl:1
	s_nop 1
	v_add_f32_dpp v183, v183, v183 row_half_mirror row_mask:0xf bank_mask:0xf bound_ctrl:1
	s_nop 1
	v_add_f32_dpp v183, v183, v183 row_mirror row_mask:0xf bank_mask:0xf bound_ctrl:1
	s_nop 1
	v_readlane_b32 s98, v183, 0
	v_readlane_b32 s99, v183, 16
	v_readlane_b32 s100, v183, 32
	v_readlane_b32 s101, v183, 48
	s_nop 1
	v_mov_b32_e32 v183, s98
	v_add_f32_e32 v183, s99, v183
	v_add_f32_e32 v183, s100, v183
	v_add_f32_e32 v183, s101, v183
	v_fmamk_f32 v183, v183, 0x3a800000, v182
	v_cmp_gt_f32_e32 vcc, 0x800000, v183
	v_mul_f32_e32 v181, 0x4b800000, v183
	s_nop 1
	v_cndmask_b32_e32 v183, v183, v181, vcc
	v_rsq_f32_e32 v183, v183
	s_nop 0
	v_mul_f32_e32 v181, 0x45800000, v183
	v_cndmask_b32_e32 v184, v183, v181, vcc
	v_mov_b32_e32 v185, v184
	v_cvt_pk_bf16_f32 v0, v144, v145
	v_cvt_pk_bf16_f32 v1, v146, v147
	v_cvt_pk_bf16_f32 v2, v148, v149
	v_cvt_pk_bf16_f32 v3, v150, v151
	v_cvt_pk_bf16_f32 v4, v152, v153
	v_cvt_pk_bf16_f32 v5, v154, v155
	v_cvt_pk_bf16_f32 v6, v156, v157
	v_cvt_pk_bf16_f32 v7, v158, v159
	v_add_u32_e32 v181, 0x3800000, v177
	global_store_dwordx4 v181, v[0:3], s[78:79]
	global_store_dwordx4 v181, v[4:7], s[78:79] offset:1024
	v_add_u32_e32 v236, 0x10000, v237
	s_mov_b64 exec, 1
	global_store_dword v236, v184, s[78:79]
	s_mov_b64 exec, -1

.LBB0_721:
	v_readlane_b32 s0, v235, 52
	v_readlane_b32 s1, v235, 53
	s_and_b64 vcc, exec, s[0:1]
	s_waitcnt lgkmcnt(0)
	s_barrier
	v_mbcnt_lo_u32_b32 v0, -1, 0
	v_mbcnt_hi_u32_b32 v0, -1, v0
	v_writelane_b32 v234, s93, 4
	s_cbranch_vccnz .LBB0_741
	v_readlane_b32 s4, v235, 4
	v_readlane_b32 s8, v235, 8
	v_readlane_b32 s9, v235, 9
	v_readlane_b32 s6, v235, 6
	v_readlane_b32 s7, v235, 7
	v_readlane_b32 s12, v235, 12
	v_readlane_b32 s13, v235, 13
	v_readlane_b32 s8, v235, 61
	v_readlane_b32 s10, v235, 10
	v_readlane_b32 s6, v235, 0
	v_readlane_b32 s9, v235, 62
	s_mov_b32 s12, s8
	s_ashr_i32 s13, s8, 31
	v_lshlrev_b32_e32 v2, 3, v0
	v_readlane_b32 s11, v235, 11
	s_lshl_b32 s6, s6, 4
	s_add_i32 s0, s8, 0xffffc000
	s_lshl_b64 s[8:9], s[12:13], 2
	s_mov_b32 s10, s12
	v_ashrrev_i32_e32 v3, 31, v2
	v_readlane_b32 s5, v235, 5
	v_readlane_b32 s14, v235, 14
	v_readlane_b32 s15, v235, 15
	v_readlane_b32 s16, v235, 16
	v_readlane_b32 s17, v235, 17
	v_readlane_b32 s18, v235, 18
	v_readlane_b32 s19, v235, 19
	v_readlane_b32 s7, v235, 1
	s_add_u32 s80, s8, 0x10000
	v_writelane_b32 v235, s10, 61
	v_lshlrev_b64 v[4:5], 1, v[2:3]
	v_lshlrev_b64 v[2:3], 2, v[2:3]
	s_addc_u32 s14, s9, 0
	s_ashr_i32 s7, s6, 31
	v_writelane_b32 v235, s11, 62
	s_lshl_b64 s[10:11], s[12:13], 11
	v_lshl_add_u64 v[152:153], s[86:87], 0, v[4:5]
	v_lshl_add_u64 v[154:155], s[90:91], 0, v[2:3]
	v_lshl_add_u64 v[156:157], s[54:55], 0, v[4:5]
	v_lshl_add_u64 v[158:159], s[18:19], 0, v[2:3]
	s_mov_b32 s1, 0
	v_cmp_eq_u32_e64 s[4:5], 0, v0
	s_lshl_b64 s[8:9], s[6:7], 2
	v_lshl_add_u64 v[160:161], s[10:11], 0, v[4:5]
	s_lshl_b64 s[10:11], s[6:7], 11
	s_mov_b64 s[24:25], 0x600000
	s_mov_b64 s[26:27], 0x600800
	s_mov_b64 s[28:29], 0x800000
	s_mov_b32 s7, 0x800000
	s_mov_b64 s[36:37], 0x800800
	s_mov_b64 s[38:39], 0xa00000
	s_mov_b64 s[40:41], 0xa00800
	s_mov_b64 s[42:43], 0xc00000
	s_mov_b64 s[44:45], 0xc00800
	s_mov_b64 s[46:47], 0xe00000
	s_mov_b64 s[48:49], 0xe00800
	s_mov_b64 s[50:51], 0x1000000
	s_mov_b32 s15, 0x1000000
	s_mov_b64 s[12:13], 0x1000800
	s_mov_b64 s[82:83], 0x1200000
	s_mov_b32 s16, 0x1200000
	s_mov_b64 s[90:91], 0x1200800
	s_mov_b64 s[20:21], 0x1400000
	s_mov_b32 s17, 0x1400000
	s_mov_b64 s[22:23], 0x1400800
	v_mov_b32_e32 v215, 0
	v_mov_b32_e32 v216, 0x358637bd
	v_mbcnt_lo_u32_b32 v176, -1, 0
	v_mbcnt_hi_u32_b32 v176, -1, v176
	v_readlane_b32 s98, v235, 49
	v_readlane_b32 s99, v235, 20
	v_readlane_b32 s100, v235, 18
	v_readlane_b32 s101, v235, 19
	s_nop 3
	s_lshr_b32 vcc_lo, s98, 3
	s_and_b32 vcc_hi, vcc_lo, 7
	s_lshr_b32 vcc_lo, vcc_lo, 3
	s_lshl_b32 vcc_lo, vcc_lo, 3
	s_add_i32 vcc_lo, vcc_lo, s99
	s_lshl_b32 s98, vcc_hi, 8
	s_add_i32 s98, s98, vcc_lo
	s_mov_b32 s99, s98
	v_mov_b32_e32 v183, s99
	v_lshlrev_b32_e32 v177, 4, v176
	s_lshl_b32 s99, s99, 11
	v_add_u32_e32 v177, s99, v177
	v_add_u32_e32 v178, 0x1800000, v177
	v_add_u32_e32 v179, 0x9e00000, v177
	v_lshlrev_b32_e32 v180, 5, v176
	global_load_dwordx4 v[128:131], v180, s[100:101]
	global_load_dwordx4 v[132:135], v180, s[100:101] offset:16
	global_load_dwordx4 v[136:139], v180, s[100:101] offset:2048
	global_load_dwordx4 v[140:143], v180, s[100:101] offset:2064
	v_mov_b32_e32 v182, 0x358637bd
	global_load_dwordx4 v[0:3], v178, s[78:79]
	global_load_dwordx4 v[4:7], v178, s[78:79] offset:1024
	global_load_dwordx4 v[8:11], v179, s[78:79]
	global_load_dwordx4 v[12:15], v179, s[78:79] offset:1024
	v_add_u32_e32 v178, 0x400000, v178
	v_add_u32_e32 v179, 0x400000, v179
	global_load_dwordx4 v[16:19], v178, s[78:79]
	global_load_dwordx4 v[20:23], v178, s[78:79] offset:1024
	global_load_dwordx4 v[24:27], v179, s[78:79]
	global_load_dwordx4 v[28:31], v179, s[78:79] offset:1024
	v_add_u32_e32 v178, 0x400000, v178
	v_add_u32_e32 v179, 0x400000, v179
	global_load_dwordx4 v[32:35], v178, s[78:79]
	global_load_dwordx4 v[36:39], v178, s[78:79] offset:1024
	global_load_dwordx4 v[40:43], v179, s[78:79]
	global_load_dwordx4 v[44:47], v179, s[78:79] offset:1024
	v_add_u32_e32 v178, 0x400000, v178
	v_add_u32_e32 v179, 0x400000, v179
	global_load_dwordx4 v[48:51], v178, s[78:79]
	global_load_dwordx4 v[52:55], v178, s[78:79] offset:1024
	global_load_dwordx4 v[56:59], v179, s[78:79]
	global_load_dwordx4 v[60:63], v179, s[78:79] offset:1024
	v_add_u32_e32 v178, 0x400000, v178
	v_add_u32_e32 v179, 0x400000, v179
	global_load_dwordx4 v[64:67], v178, s[78:79]
	global_load_dwordx4 v[68:71], v178, s[78:79] offset:1024
	global_load_dwordx4 v[72:75], v179, s[78:79]
	global_load_dwordx4 v[76:79], v179, s[78:79] offset:1024
	v_add_u32_e32 v178, 0x400000, v178
	v_add_u32_e32 v179, 0x400000, v179
	global_load_dwordx4 v[80:83], v178, s[78:79]
	global_load_dwordx4 v[84:87], v178, s[78:79] offset:1024
	global_load_dwordx4 v[88:91], v179, s[78:79]
	global_load_dwordx4 v[92:95], v179, s[78:79] offset:1024
	v_add_u32_e32 v178, 0x400000, v178
	v_add_u32_e32 v179, 0x400000, v179
	global_load_dwordx4 v[96:99], v178, s[78:79]
	global_load_dwordx4 v[100:103], v178, s[78:79] offset:1024
	global_load_dwordx4 v[104:107], v179, s[78:79]
	global_load_dwordx4 v[108:111], v179, s[78:79] offset:1024
	v_add_u32_e32 v178, 0x400000, v178
	v_add_u32_e32 v179, 0x400000, v179
	global_load_dwordx4 v[112:115], v178, s[78:79]
	global_load_dwordx4 v[116:119], v178, s[78:79] offset:1024
	global_load_dwordx4 v[120:123], v179, s[78:79]
	global_load_dwordx4 v[124:127], v179, s[78:79] offset:1024
	v_lshlrev_b32_e32 v237, 2, v183
	v_add_u32_e32 v237, 0x10000, v237
	v_mov_b32_e32 v179, s98
	s_waitcnt vmcnt(28)
	v_lshlrev_b32_e32 v144, 16, v0
	v_and_b32_e32 v145, 0xffff0000, v0
	v_lshlrev_b32_e32 v146, 16, v1
	v_and_b32_e32 v147, 0xffff0000, v1
	v_lshlrev_b32_e32 v148, 16, v2
	v_and_b32_e32 v149, 0xffff0000, v2
	v_lshlrev_b32_e32 v150, 16, v3
	v_and_b32_e32 v151, 0xffff0000, v3
	v_lshlrev_b32_e32 v152, 16, v4
	v_and_b32_e32 v153, 0xffff0000, v4
	v_lshlrev_b32_e32 v154, 16, v5
	v_and_b32_e32 v155, 0xffff0000, v5
	v_lshlrev_b32_e32 v156, 16, v6
	v_and_b32_e32 v157, 0xffff0000, v6
	v_lshlrev_b32_e32 v158, 16, v7
	v_and_b32_e32 v159, 0xffff0000, v7
	v_lshlrev_b32_e32 v160, 16, v8
	v_and_b32_e32 v161, 0xffff0000, v8
	v_lshlrev_b32_e32 v162, 16, v9
	v_and_b32_e32 v163, 0xffff0000, v9
	v_lshlrev_b32_e32 v164, 16, v10
	v_and_b32_e32 v165, 0xffff0000, v10
	v_lshlrev_b32_e32 v166, 16, v11
	v_and_b32_e32 v167, 0xffff0000, v11
	v_lshlrev_b32_e32 v168, 16, v12
	v_and_b32_e32 v169, 0xffff0000, v12
	v_lshlrev_b32_e32 v170, 16, v13
	v_and_b32_e32 v171, 0xffff0000, v13
	v_lshlrev_b32_e32 v172, 16, v14
	v_and_b32_e32 v173, 0xffff0000, v14
	v_lshlrev_b32_e32 v174, 16, v15
	v_and_b32_e32 v175, 0xffff0000, v15
	v_pk_mul_f32 v[252:253], v[160:161], v[160:161]
	v_pk_mul_f32 v[254:255], v[162:163], v[162:163]
	v_pk_fma_f32 v[252:253], v[164:165], v[164:165], v[252:253]
	v_pk_fma_f32 v[254:255], v[166:167], v[166:167], v[254:255]
	v_pk_fma_f32 v[252:253], v[168:169], v[168:169], v[252:253]
	v_pk_fma_f32 v[254:255], v[170:171], v[170:171], v[254:255]
	v_pk_fma_f32 v[252:253], v[172:173], v[172:173], v[252:253]
	v_pk_fma_f32 v[254:255], v[174:175], v[174:175], v[254:255]
	v_pk_add_f32 v[252:253], v[252:253], v[254:255]
	s_nop 0
	v_add_f32_e32 v183, v252, v253
	s_nop 1
	v_add_f32_dpp v183, v183, v183 quad_perm:[1,0,3,2] row_mask:0xf bank_mask:0xf bound_ctrl:1
	s_nop 1
	v_add_f32_dpp v183, v183, v183 quad_perm:[2,3,0,1] row_mask:0xf bank_mask:0xf bound_ctrl:1
	s_nop 1
	v_add_f32_dpp v183, v183, v183 row_half_mirror row_mask:0xf bank_mask:0xf bound_ctrl:1
	s_nop 1
	v_add_f32_dpp v183, v183, v183 row_mirror row_mask:0xf bank_mask:0xf bound_ctrl:1
	s_nop 1
	v_readlane_b32 s98, v183, 0
	v_readlane_b32 s99, v183, 16
	v_readlane_b32 s100, v183, 32
	v_readlane_b32 s101, v183, 48
	s_nop 1
	v_mov_b32_e32 v183, s98
	v_add_f32_e32 v183, s99, v183
	v_add_f32_e32 v183, s100, v183
	v_add_f32_e32 v183, s101, v183
	v_fmamk_f32 v183, v183, 0x3a800000, v182
	v_cmp_gt_f32_e32 vcc, 0x800000, v183
	v_mul_f32_e32 v181, 0x4b800000, v183
	s_nop 1
	v_cndmask_b32_e32 v183, v183, v181, vcc
	v_rsq_f32_e32 v183, v183
	s_nop 0
	v_mul_f32_e32 v181, 0x45800000, v183
	v_cndmask_b32_e32 v184, v183, v181, vcc
	v_mov_b32_e32 v185, v184
	v_pk_mul_f32 v[160:161], v[160:161], v[184:185]
	v_pk_mul_f32 v[162:163], v[162:163], v[184:185]
	v_pk_mul_f32 v[164:165], v[164:165], v[184:185]
	v_pk_mul_f32 v[166:167], v[166:167], v[184:185]
	v_pk_mul_f32 v[168:169], v[168:169], v[184:185]
	v_pk_mul_f32 v[170:171], v[170:171], v[184:185]
	v_pk_mul_f32 v[172:173], v[172:173], v[184:185]
	v_pk_mul_f32 v[174:175], v[174:175], v[184:185]
	v_pk_fma_f32 v[144:145], v[160:161], v[128:129], v[144:145]
	v_pk_fma_f32 v[146:147], v[162:163], v[130:131], v[146:147]
	v_pk_fma_f32 v[148:149], v[164:165], v[132:133], v[148:149]
	v_pk_fma_f32 v[150:151], v[166:167], v[134:135], v[150:151]
	v_pk_fma_f32 v[152:153], v[168:169], v[136:137], v[152:153]
	v_pk_fma_f32 v[154:155], v[170:171], v[138:139], v[154:155]
	v_pk_fma_f32 v[156:157], v[172:173], v[140:141], v[156:157]
	v_pk_fma_f32 v[158:159], v[174:175], v[142:143], v[158:159]
	v_pk_mul_f32 v[252:253], v[144:145], v[144:145]
	v_pk_mul_f32 v[254:255], v[146:147], v[146:147]
	v_pk_fma_f32 v[252:253], v[148:149], v[148:149], v[252:253]
	v_pk_fma_f32 v[254:255], v[150:151], v[150:151], v[254:255]
	v_pk_fma_f32 v[252:253], v[152:153], v[152:153], v[252:253]
	v_pk_fma_f32 v[254:255], v[154:155], v[154:155], v[254:255]
	v_pk_fma_f32 v[252:253], v[156:157], v[156:157], v[252:253]
	v_pk_fma_f32 v[254:255], v[158:159], v[158:159], v[254:255]
	v_pk_add_f32 v[252:253], v[252:253], v[254:255]
	s_nop 0
	v_add_f32_e32 v183, v252, v253
	s_nop 1
	v_add_f32_dpp v183, v183, v183 quad_perm:[1,0,3,2] row_mask:0xf bank_mask:0xf bound_ctrl:1
	s_nop 1
	v_add_f32_dpp v183, v183, v183 quad_perm:[2,3,0,1] row_mask:0xf bank_mask:0xf bound_ctrl:1
	s_nop 1
	v_add_f32_dpp v183, v183, v183 row_half_mirror row_mask:0xf bank_mask:0xf bound_ctrl:1
	s_nop 1
	v_add_f32_dpp v183, v183, v183 row_mirror row_mask:0xf bank_mask:0xf bound_ctrl:1
	s_nop 1
	v_readlane_b32 s98, v183, 0
	v_readlane_b32 s99, v183, 16
	v_readlane_b32 s100, v183, 32
	v_readlane_b32 s101, v183, 48
	s_nop 1
	v_mov_b32_e32 v183, s98
	v_add_f32_e32 v183, s99, v183
	v_add_f32_e32 v183, s100, v183
	v_add_f32_e32 v183, s101, v183
	v_fmamk_f32 v183, v183, 0x3a800000, v182
	v_cmp_gt_f32_e32 vcc, 0x800000, v183
	v_mul_f32_e32 v181, 0x4b800000, v183
	s_nop 1
	v_cndmask_b32_e32 v183, v183, v181, vcc
	v_rsq_f32_e32 v183, v183
	s_nop 0
	v_mul_f32_e32 v181, 0x45800000, v183
	v_cndmask_b32_e32 v184, v183, v181, vcc
	v_mov_b32_e32 v185, v184
	v_cvt_pk_bf16_f32 v0, v144, v145
	v_cvt_pk_bf16_f32 v1, v146, v147
	v_cvt_pk_bf16_f32 v2, v148, v149
	v_cvt_pk_bf16_f32 v3, v150, v151
	v_cvt_pk_bf16_f32 v4, v152, v153
	v_cvt_pk_bf16_f32 v5, v154, v155
	v_cvt_pk_bf16_f32 v6, v156, v157
	v_cvt_pk_bf16_f32 v7, v158, v159
	v_add_u32_e32 v181, 0x1800000, v177
	global_store_dwordx4 v181, v[0:3], s[78:79]
	global_store_dwordx4 v181, v[4:7], s[78:79] offset:1024
	v_add_u32_e32 v236, 0x0, v237
	s_mov_b64 exec, 1
	global_store_dword v236, v184, s[78:79]
	s_mov_b64 exec, -1
	s_waitcnt vmcnt(24)
	v_lshlrev_b32_e32 v144, 16, v16
	v_and_b32_e32 v145, 0xffff0000, v16
	v_lshlrev_b32_e32 v146, 16, v17
	v_and_b32_e32 v147, 0xffff0000, v17
	v_lshlrev_b32_e32 v148, 16, v18
	v_and_b32_e32 v149, 0xffff0000, v18
	v_lshlrev_b32_e32 v150, 16, v19
	v_and_b32_e32 v151, 0xffff0000, v19
	v_lshlrev_b32_e32 v152, 16, v20
	v_and_b32_e32 v153, 0xffff0000, v20
	v_lshlrev_b32_e32 v154, 16, v21
	v_and_b32_e32 v155, 0xffff0000, v21
	v_lshlrev_b32_e32 v156, 16, v22
	v_and_b32_e32 v157, 0xffff0000, v22
	v_lshlrev_b32_e32 v158, 16, v23
	v_and_b32_e32 v159, 0xffff0000, v23
	v_lshlrev_b32_e32 v160, 16, v24
	v_and_b32_e32 v161, 0xffff0000, v24
	v_lshlrev_b32_e32 v162, 16, v25
	v_and_b32_e32 v163, 0xffff0000, v25
	v_lshlrev_b32_e32 v164, 16, v26
	v_and_b32_e32 v165, 0xffff0000, v26
	v_lshlrev_b32_e32 v166, 16, v27
	v_and_b32_e32 v167, 0xffff0000, v27
	v_lshlrev_b32_e32 v168, 16, v28
	v_and_b32_e32 v169, 0xffff0000, v28
	v_lshlrev_b32_e32 v170, 16, v29
	v_and_b32_e32 v171, 0xffff0000, v29
	v_lshlrev_b32_e32 v172, 16, v30
	v_and_b32_e32 v173, 0xffff0000, v30
	v_lshlrev_b32_e32 v174, 16, v31
	v_and_b32_e32 v175, 0xffff0000, v31
	v_pk_mul_f32 v[252:253], v[160:161], v[160:161]
	v_pk_mul_f32 v[254:255], v[162:163], v[162:163]
	v_pk_fma_f32 v[252:253], v[164:165], v[164:165], v[252:253]
	v_pk_fma_f32 v[254:255], v[166:167], v[166:167], v[254:255]
	v_pk_fma_f32 v[252:253], v[168:169], v[168:169], v[252:253]
	v_pk_fma_f32 v[254:255], v[170:171], v[170:171], v[254:255]
	v_pk_fma_f32 v[252:253], v[172:173], v[172:173], v[252:253]
	v_pk_fma_f32 v[254:255], v[174:175], v[174:175], v[254:255]
	v_pk_add_f32 v[252:253], v[252:253], v[254:255]
	s_nop 0
	v_add_f32_e32 v183, v252, v253
	s_nop 1
	v_add_f32_dpp v183, v183, v183 quad_perm:[1,0,3,2] row_mask:0xf bank_mask:0xf bound_ctrl:1
	s_nop 1
	v_add_f32_dpp v183, v183, v183 quad_perm:[2,3,0,1] row_mask:0xf bank_mask:0xf bound_ctrl:1
	s_nop 1
	v_add_f32_dpp v183, v183, v183 row_half_mirror row_mask:0xf bank_mask:0xf bound_ctrl:1
	s_nop 1
	v_add_f32_dpp v183, v183, v183 row_mirror row_mask:0xf bank_mask:0xf bound_ctrl:1
	s_nop 1
	v_readlane_b32 s98, v183, 0
	v_readlane_b32 s99, v183, 16
	v_readlane_b32 s100, v183, 32
	v_readlane_b32 s101, v183, 48
	s_nop 1
	v_mov_b32_e32 v183, s98
	v_add_f32_e32 v183, s99, v183
	v_add_f32_e32 v183, s100, v183
	v_add_f32_e32 v183, s101, v183
	v_fmamk_f32 v183, v183, 0x3a800000, v182
	v_cmp_gt_f32_e32 vcc, 0x800000, v183
	v_mul_f32_e32 v181, 0x4b800000, v183
	s_nop 1
	v_cndmask_b32_e32 v183, v183, v181, vcc
	v_rsq_f32_e32 v183, v183
	s_nop 0
	v_mul_f32_e32 v181, 0x45800000, v183
	v_cndmask_b32_e32 v184, v183, v181, vcc
	v_mov_b32_e32 v185, v184
	v_pk_mul_f32 v[160:161], v[160:161], v[184:185]
	v_pk_mul_f32 v[162:163], v[162:163], v[184:185]
	v_pk_mul_f32 v[164:165], v[164:165], v[184:185]
	v_pk_mul_f32 v[166:167], v[166:167], v[184:185]
	v_pk_mul_f32 v[168:169], v[168:169], v[184:185]
	v_pk_mul_f32 v[170:171], v[170:171], v[184:185]
	v_pk_mul_f32 v[172:173], v[172:173], v[184:185]
	v_pk_mul_f32 v[174:175], v[174:175], v[184:185]
	v_pk_fma_f32 v[144:145], v[160:161], v[128:129], v[144:145]
	v_pk_fma_f32 v[146:147], v[162:163], v[130:131], v[146:147]
	v_pk_fma_f32 v[148:149], v[164:165], v[132:133], v[148:149]
	v_pk_fma_f32 v[150:151], v[166:167], v[134:135], v[150:151]
	v_pk_fma_f32 v[152:153], v[168:169], v[136:137], v[152:153]
	v_pk_fma_f32 v[154:155], v[170:171], v[138:139], v[154:155]
	v_pk_fma_f32 v[156:157], v[172:173], v[140:141], v[156:157]
	v_pk_fma_f32 v[158:159], v[174:175], v[142:143], v[158:159]
	v_pk_mul_f32 v[252:253], v[144:145], v[144:145]
	v_pk_mul_f32 v[254:255], v[146:147], v[146:147]
	v_pk_fma_f32 v[252:253], v[148:149], v[148:149], v[252:253]
	v_pk_fma_f32 v[254:255], v[150:151], v[150:151], v[254:255]
	v_pk_fma_f32 v[252:253], v[152:153], v[152:153], v[252:253]
	v_pk_fma_f32 v[254:255], v[154:155], v[154:155], v[254:255]
	v_pk_fma_f32 v[252:253], v[156:157], v[156:157], v[252:253]
	v_pk_fma_f32 v[254:255], v[158:159], v[158:159], v[254:255]
	v_pk_add_f32 v[252:253], v[252:253], v[254:255]
	s_nop 0
	v_add_f32_e32 v183, v252, v253
	s_nop 1
	v_add_f32_dpp v183, v183, v183 quad_perm:[1,0,3,2] row_mask:0xf bank_mask:0xf bound_ctrl:1
	s_nop 1
	v_add_f32_dpp v183, v183, v183 quad_perm:[2,3,0,1] row_mask:0xf bank_mask:0xf bound_ctrl:1
	s_nop 1
	v_add_f32_dpp v183, v183, v183 row_half_mirror row_mask:0xf bank_mask:0xf bound_ctrl:1
	s_nop 1
	v_add_f32_dpp v183, v183, v183 row_mirror row_mask:0xf bank_mask:0xf bound_ctrl:1
	s_nop 1
	v_readlane_b32 s98, v183, 0
	v_readlane_b32 s99, v183, 16
	v_readlane_b32 s100, v183, 32
	v_readlane_b32 s101, v183, 48
	s_nop 1
	v_mov_b32_e32 v183, s98
	v_add_f32_e32 v183, s99, v183
	v_add_f32_e32 v183, s100, v183
	v_add_f32_e32 v183, s101, v183
	v_fmamk_f32 v183, v183, 0x3a800000, v182
	v_cmp_gt_f32_e32 vcc, 0x800000, v183
	v_mul_f32_e32 v181, 0x4b800000, v183
	s_nop 1
	v_cndmask_b32_e32 v183, v183, v181, vcc
	v_rsq_f32_e32 v183, v183
	s_nop 0
	v_mul_f32_e32 v181, 0x45800000, v183
	v_cndmask_b32_e32 v184, v183, v181, vcc
	v_mov_b32_e32 v185, v184
	v_cvt_pk_bf16_f32 v16, v144, v145
	v_cvt_pk_bf16_f32 v17, v146, v147
	v_cvt_pk_bf16_f32 v18, v148, v149
	v_cvt_pk_bf16_f32 v19, v150, v151
	v_cvt_pk_bf16_f32 v20, v152, v153
	v_cvt_pk_bf16_f32 v21, v154, v155
	v_cvt_pk_bf16_f32 v22, v156, v157
	v_cvt_pk_bf16_f32 v23, v158, v159
	v_add_u32_e32 v181, 0x1c00000, v177
	global_store_dwordx4 v181, v[16:19], s[78:79]
	global_store_dwordx4 v181, v[20:23], s[78:79] offset:1024
	v_add_u32_e32 v236, 0x2000, v237
	s_mov_b64 exec, 1
	global_store_dword v236, v184, s[78:79]
	s_mov_b64 exec, -1
	s_waitcnt vmcnt(20)
	v_lshlrev_b32_e32 v144, 16, v32
	v_and_b32_e32 v145, 0xffff0000, v32
	v_lshlrev_b32_e32 v146, 16, v33
	v_and_b32_e32 v147, 0xffff0000, v33
	v_lshlrev_b32_e32 v148, 16, v34
	v_and_b32_e32 v149, 0xffff0000, v34
	v_lshlrev_b32_e32 v150, 16, v35
	v_and_b32_e32 v151, 0xffff0000, v35
	v_lshlrev_b32_e32 v152, 16, v36
	v_and_b32_e32 v153, 0xffff0000, v36
	v_lshlrev_b32_e32 v154, 16, v37
	v_and_b32_e32 v155, 0xffff0000, v37
	v_lshlrev_b32_e32 v156, 16, v38
	v_and_b32_e32 v157, 0xffff0000, v38
	v_lshlrev_b32_e32 v158, 16, v39
	v_and_b32_e32 v159, 0xffff0000, v39
	v_lshlrev_b32_e32 v160, 16, v40
	v_and_b32_e32 v161, 0xffff0000, v40
	v_lshlrev_b32_e32 v162, 16, v41
	v_and_b32_e32 v163, 0xffff0000, v41
	v_lshlrev_b32_e32 v164, 16, v42
	v_and_b32_e32 v165, 0xffff0000, v42
	v_lshlrev_b32_e32 v166, 16, v43
	v_and_b32_e32 v167, 0xffff0000, v43
	v_lshlrev_b32_e32 v168, 16, v44
	v_and_b32_e32 v169, 0xffff0000, v44
	v_lshlrev_b32_e32 v170, 16, v45
	v_and_b32_e32 v171, 0xffff0000, v45
	v_lshlrev_b32_e32 v172, 16, v46
	v_and_b32_e32 v173, 0xffff0000, v46
	v_lshlrev_b32_e32 v174, 16, v47
	v_and_b32_e32 v175, 0xffff0000, v47
	v_pk_mul_f32 v[252:253], v[160:161], v[160:161]
	v_pk_mul_f32 v[254:255], v[162:163], v[162:163]
	v_pk_fma_f32 v[252:253], v[164:165], v[164:165], v[252:253]
	v_pk_fma_f32 v[254:255], v[166:167], v[166:167], v[254:255]
	v_pk_fma_f32 v[252:253], v[168:169], v[168:169], v[252:253]
	v_pk_fma_f32 v[254:255], v[170:171], v[170:171], v[254:255]
	v_pk_fma_f32 v[252:253], v[172:173], v[172:173], v[252:253]
	v_pk_fma_f32 v[254:255], v[174:175], v[174:175], v[254:255]
	v_pk_add_f32 v[252:253], v[252:253], v[254:255]
	s_nop 0
	v_add_f32_e32 v183, v252, v253
	s_nop 1
	v_add_f32_dpp v183, v183, v183 quad_perm:[1,0,3,2] row_mask:0xf bank_mask:0xf bound_ctrl:1
	s_nop 1
	v_add_f32_dpp v183, v183, v183 quad_perm:[2,3,0,1] row_mask:0xf bank_mask:0xf bound_ctrl:1
	s_nop 1
	v_add_f32_dpp v183, v183, v183 row_half_mirror row_mask:0xf bank_mask:0xf bound_ctrl:1
	s_nop 1
	v_add_f32_dpp v183, v183, v183 row_mirror row_mask:0xf bank_mask:0xf bound_ctrl:1
	s_nop 1
	v_readlane_b32 s98, v183, 0
	v_readlane_b32 s99, v183, 16
	v_readlane_b32 s100, v183, 32
	v_readlane_b32 s101, v183, 48
	s_nop 1
	v_mov_b32_e32 v183, s98
	v_add_f32_e32 v183, s99, v183
	v_add_f32_e32 v183, s100, v183
	v_add_f32_e32 v183, s101, v183
	v_fmamk_f32 v183, v183, 0x3a800000, v182
	v_cmp_gt_f32_e32 vcc, 0x800000, v183
	v_mul_f32_e32 v181, 0x4b800000, v183
	s_nop 1
	v_cndmask_b32_e32 v183, v183, v181, vcc
	v_rsq_f32_e32 v183, v183
	s_nop 0
	v_mul_f32_e32 v181, 0x45800000, v183
	v_cndmask_b32_e32 v184, v183, v181, vcc
	v_mov_b32_e32 v185, v184
	v_pk_mul_f32 v[160:161], v[160:161], v[184:185]
	v_pk_mul_f32 v[162:163], v[162:163], v[184:185]
	v_pk_mul_f32 v[164:165], v[164:165], v[184:185]
	v_pk_mul_f32 v[166:167], v[166:167], v[184:185]
	v_pk_mul_f32 v[168:169], v[168:169], v[184:185]
	v_pk_mul_f32 v[170:171], v[170:171], v[184:185]
	v_pk_mul_f32 v[172:173], v[172:173], v[184:185]
	v_pk_mul_f32 v[174:175], v[174:175], v[184:185]
	v_pk_fma_f32 v[144:145], v[160:161], v[128:129], v[144:145]
	v_pk_fma_f32 v[146:147], v[162:163], v[130:131], v[146:147]
	v_pk_fma_f32 v[148:149], v[164:165], v[132:133], v[148:149]
	v_pk_fma_f32 v[150:151], v[166:167], v[134:135], v[150:151]
	v_pk_fma_f32 v[152:153], v[168:169], v[136:137], v[152:153]
	v_pk_fma_f32 v[154:155], v[170:171], v[138:139], v[154:155]
	v_pk_fma_f32 v[156:157], v[172:173], v[140:141], v[156:157]
	v_pk_fma_f32 v[158:159], v[174:175], v[142:143], v[158:159]
	v_pk_mul_f32 v[252:253], v[144:145], v[144:145]
	v_pk_mul_f32 v[254:255], v[146:147], v[146:147]
	v_pk_fma_f32 v[252:253], v[148:149], v[148:149], v[252:253]
	v_pk_fma_f32 v[254:255], v[150:151], v[150:151], v[254:255]
	v_pk_fma_f32 v[252:253], v[152:153], v[152:153], v[252:253]
	v_pk_fma_f32 v[254:255], v[154:155], v[154:155], v[254:255]
	v_pk_fma_f32 v[252:253], v[156:157], v[156:157], v[252:253]
	v_pk_fma_f32 v[254:255], v[158:159], v[158:159], v[254:255]
	v_pk_add_f32 v[252:253], v[252:253], v[254:255]
	s_nop 0
	v_add_f32_e32 v183, v252, v253
	s_nop 1
	v_add_f32_dpp v183, v183, v183 quad_perm:[1,0,3,2] row_mask:0xf bank_mask:0xf bound_ctrl:1
	s_nop 1
	v_add_f32_dpp v183, v183, v183 quad_perm:[2,3,0,1] row_mask:0xf bank_mask:0xf bound_ctrl:1
	s_nop 1
	v_add_f32_dpp v183, v183, v183 row_half_mirror row_mask:0xf bank_mask:0xf bound_ctrl:1
	s_nop 1
	v_add_f32_dpp v183, v183, v183 row_mirror row_mask:0xf bank_mask:0xf bound_ctrl:1
	s_nop 1
	v_readlane_b32 s98, v183, 0
	v_readlane_b32 s99, v183, 16
	v_readlane_b32 s100, v183, 32
	v_readlane_b32 s101, v183, 48
	s_nop 1
	v_mov_b32_e32 v183, s98
	v_add_f32_e32 v183, s99, v183
	v_add_f32_e32 v183, s100, v183
	v_add_f32_e32 v183, s101, v183
	v_fmamk_f32 v183, v183, 0x3a800000, v182
	v_cmp_gt_f32_e32 vcc, 0x800000, v183
	v_mul_f32_e32 v181, 0x4b800000, v183
	s_nop 1
	v_cndmask_b32_e32 v183, v183, v181, vcc
	v_rsq_f32_e32 v183, v183
	s_nop 0
	v_mul_f32_e32 v181, 0x45800000, v183
	v_cndmask_b32_e32 v184, v183, v181, vcc
	v_mov_b32_e32 v185, v184
	v_cvt_pk_bf16_f32 v32, v144, v145
	v_cvt_pk_bf16_f32 v33, v146, v147
	v_cvt_pk_bf16_f32 v34, v148, v149
	v_cvt_pk_bf16_f32 v35, v150, v151
	v_cvt_pk_bf16_f32 v36, v152, v153
	v_cvt_pk_bf16_f32 v37, v154, v155
	v_cvt_pk_bf16_f32 v38, v156, v157
	v_cvt_pk_bf16_f32 v39, v158, v159
	v_add_u32_e32 v181, 0x2000000, v177
	global_store_dwordx4 v181, v[32:35], s[78:79]
	global_store_dwordx4 v181, v[36:39], s[78:79] offset:1024
	v_add_u32_e32 v236, 0x4000, v237
	s_mov_b64 exec, 1
	global_store_dword v236, v184, s[78:79]
	s_mov_b64 exec, -1
	s_waitcnt vmcnt(16)
	v_lshlrev_b32_e32 v144, 16, v48
	v_and_b32_e32 v145, 0xffff0000, v48
	v_lshlrev_b32_e32 v146, 16, v49
	v_and_b32_e32 v147, 0xffff0000, v49
	v_lshlrev_b32_e32 v148, 16, v50
	v_and_b32_e32 v149, 0xffff0000, v50
	v_lshlrev_b32_e32 v150, 16, v51
	v_and_b32_e32 v151, 0xffff0000, v51
	v_lshlrev_b32_e32 v152, 16, v52
	v_and_b32_e32 v153, 0xffff0000, v52
	v_lshlrev_b32_e32 v154, 16, v53
	v_and_b32_e32 v155, 0xffff0000, v53
	v_lshlrev_b32_e32 v156, 16, v54
	v_and_b32_e32 v157, 0xffff0000, v54
	v_lshlrev_b32_e32 v158, 16, v55
	v_and_b32_e32 v159, 0xffff0000, v55
	v_lshlrev_b32_e32 v160, 16, v56
	v_and_b32_e32 v161, 0xffff0000, v56
	v_lshlrev_b32_e32 v162, 16, v57
	v_and_b32_e32 v163, 0xffff0000, v57
	v_lshlrev_b32_e32 v164, 16, v58
	v_and_b32_e32 v165, 0xffff0000, v58
	v_lshlrev_b32_e32 v166, 16, v59
	v_and_b32_e32 v167, 0xffff0000, v59
	v_lshlrev_b32_e32 v168, 16, v60
	v_and_b32_e32 v169, 0xffff0000, v60
	v_lshlrev_b32_e32 v170, 16, v61
	v_and_b32_e32 v171, 0xffff0000, v61
	v_lshlrev_b32_e32 v172, 16, v62
	v_and_b32_e32 v173, 0xffff0000, v62
	v_lshlrev_b32_e32 v174, 16, v63
	v_and_b32_e32 v175, 0xffff0000, v63
	v_pk_mul_f32 v[252:253], v[160:161], v[160:161]
	v_pk_mul_f32 v[254:255], v[162:163], v[162:163]
	v_pk_fma_f32 v[252:253], v[164:165], v[164:165], v[252:253]
	v_pk_fma_f32 v[254:255], v[166:167], v[166:167], v[254:255]
	v_pk_fma_f32 v[252:253], v[168:169], v[168:169], v[252:253]
	v_pk_fma_f32 v[254:255], v[170:171], v[170:171], v[254:255]
	v_pk_fma_f32 v[252:253], v[172:173], v[172:173], v[252:253]
	v_pk_fma_f32 v[254:255], v[174:175], v[174:175], v[254:255]
	v_pk_add_f32 v[252:253], v[252:253], v[254:255]
	s_nop 0
	v_add_f32_e32 v183, v252, v253
	s_nop 1
	v_add_f32_dpp v183, v183, v183 quad_perm:[1,0,3,2] row_mask:0xf bank_mask:0xf bound_ctrl:1
	s_nop 1
	v_add_f32_dpp v183, v183, v183 quad_perm:[2,3,0,1] row_mask:0xf bank_mask:0xf bound_ctrl:1
	s_nop 1
	v_add_f32_dpp v183, v183, v183 row_half_mirror row_mask:0xf bank_mask:0xf bound_ctrl:1
	s_nop 1
	v_add_f32_dpp v183, v183, v183 row_mirror row_mask:0xf bank_mask:0xf bound_ctrl:1
	s_nop 1
	v_readlane_b32 s98, v183, 0
	v_readlane_b32 s99, v183, 16
	v_readlane_b32 s100, v183, 32
	v_readlane_b32 s101, v183, 48
	s_nop 1
	v_mov_b32_e32 v183, s98
	v_add_f32_e32 v183, s99, v183
	v_add_f32_e32 v183, s100, v183
	v_add_f32_e32 v183, s101, v183
	v_fmamk_f32 v183, v183, 0x3a800000, v182
	v_cmp_gt_f32_e32 vcc, 0x800000, v183
	v_mul_f32_e32 v181, 0x4b800000, v183
	s_nop 1
	v_cndmask_b32_e32 v183, v183, v181, vcc
	v_rsq_f32_e32 v183, v183
	s_nop 0
	v_mul_f32_e32 v181, 0x45800000, v183
	v_cndmask_b32_e32 v184, v183, v181, vcc
	v_mov_b32_e32 v185, v184
	v_pk_mul_f32 v[160:161], v[160:161], v[184:185]
	v_pk_mul_f32 v[162:163], v[162:163], v[184:185]
	v_pk_mul_f32 v[164:165], v[164:165], v[184:185]
	v_pk_mul_f32 v[166:167], v[166:167], v[184:185]
	v_pk_mul_f32 v[168:169], v[168:169], v[184:185]
	v_pk_mul_f32 v[170:171], v[170:171], v[184:185]
	v_pk_mul_f32 v[172:173], v[172:173], v[184:185]
	v_pk_mul_f32 v[174:175], v[174:175], v[184:185]
	v_pk_fma_f32 v[144:145], v[160:161], v[128:129], v[144:145]
	v_pk_fma_f32 v[146:147], v[162:163], v[130:131], v[146:147]
	v_pk_fma_f32 v[148:149], v[164:165], v[132:133], v[148:149]
	v_pk_fma_f32 v[150:151], v[166:167], v[134:135], v[150:151]
	v_pk_fma_f32 v[152:153], v[168:169], v[136:137], v[152:153]
	v_pk_fma_f32 v[154:155], v[170:171], v[138:139], v[154:155]
	v_pk_fma_f32 v[156:157], v[172:173], v[140:141], v[156:157]
	v_pk_fma_f32 v[158:159], v[174:175], v[142:143], v[158:159]
	v_pk_mul_f32 v[252:253], v[144:145], v[144:145]
	v_pk_mul_f32 v[254:255], v[146:147], v[146:147]
	v_pk_fma_f32 v[252:253], v[148:149], v[148:149], v[252:253]
	v_pk_fma_f32 v[254:255], v[150:151], v[150:151], v[254:255]
	v_pk_fma_f32 v[252:253], v[152:153], v[152:153], v[252:253]
	v_pk_fma_f32 v[254:255], v[154:155], v[154:155], v[254:255]
	v_pk_fma_f32 v[252:253], v[156:157], v[156:157], v[252:253]
	v_pk_fma_f32 v[254:255], v[158:159], v[158:159], v[254:255]
	v_pk_add_f32 v[252:253], v[252:253], v[254:255]
	s_nop 0
	v_add_f32_e32 v183, v252, v253
	s_nop 1
	v_add_f32_dpp v183, v183, v183 quad_perm:[1,0,3,2] row_mask:0xf bank_mask:0xf bound_ctrl:1
	s_nop 1
	v_add_f32_dpp v183, v183, v183 quad_perm:[2,3,0,1] row_mask:0xf bank_mask:0xf bound_ctrl:1
	s_nop 1
	v_add_f32_dpp v183, v183, v183 row_half_mirror row_mask:0xf bank_mask:0xf bound_ctrl:1
	s_nop 1
	v_add_f32_dpp v183, v183, v183 row_mirror row_mask:0xf bank_mask:0xf bound_ctrl:1
	s_nop 1
	v_readlane_b32 s98, v183, 0
	v_readlane_b32 s99, v183, 16
	v_readlane_b32 s100, v183, 32
	v_readlane_b32 s101, v183, 48
	s_nop 1
	v_mov_b32_e32 v183, s98
	v_add_f32_e32 v183, s99, v183
	v_add_f32_e32 v183, s100, v183
	v_add_f32_e32 v183, s101, v183
	v_fmamk_f32 v183, v183, 0x3a800000, v182
	v_cmp_gt_f32_e32 vcc, 0x800000, v183
	v_mul_f32_e32 v181, 0x4b800000, v183
	s_nop 1
	v_cndmask_b32_e32 v183, v183, v181, vcc
	v_rsq_f32_e32 v183, v183
	s_nop 0
	v_mul_f32_e32 v181, 0x45800000, v183
	v_cndmask_b32_e32 v184, v183, v181, vcc
	v_mov_b32_e32 v185, v184
	v_cvt_pk_bf16_f32 v48, v144, v145
	v_cvt_pk_bf16_f32 v49, v146, v147
	v_cvt_pk_bf16_f32 v50, v148, v149
	v_cvt_pk_bf16_f32 v51, v150, v151
	v_cvt_pk_bf16_f32 v52, v152, v153
	v_cvt_pk_bf16_f32 v53, v154, v155
	v_cvt_pk_bf16_f32 v54, v156, v157
	v_cvt_pk_bf16_f32 v55, v158, v159
	v_add_u32_e32 v181, 0x2400000, v177
	global_store_dwordx4 v181, v[48:51], s[78:79]
	global_store_dwordx4 v181, v[52:55], s[78:79] offset:1024
	v_add_u32_e32 v236, 0x6000, v237
	s_mov_b64 exec, 1
	global_store_dword v236, v184, s[78:79]
	s_mov_b64 exec, -1
	s_waitcnt vmcnt(12)
	v_lshlrev_b32_e32 v144, 16, v64
	v_and_b32_e32 v145, 0xffff0000, v64
	v_lshlrev_b32_e32 v146, 16, v65
	v_and_b32_e32 v147, 0xffff0000, v65
	v_lshlrev_b32_e32 v148, 16, v66
	v_and_b32_e32 v149, 0xffff0000, v66
	v_lshlrev_b32_e32 v150, 16, v67
	v_and_b32_e32 v151, 0xffff0000, v67
	v_lshlrev_b32_e32 v152, 16, v68
	v_and_b32_e32 v153, 0xffff0000, v68
	v_lshlrev_b32_e32 v154, 16, v69
	v_and_b32_e32 v155, 0xffff0000, v69
	v_lshlrev_b32_e32 v156, 16, v70
	v_and_b32_e32 v157, 0xffff0000, v70
	v_lshlrev_b32_e32 v158, 16, v71
	v_and_b32_e32 v159, 0xffff0000, v71
	v_lshlrev_b32_e32 v160, 16, v72
	v_and_b32_e32 v161, 0xffff0000, v72
	v_lshlrev_b32_e32 v162, 16, v73
	v_and_b32_e32 v163, 0xffff0000, v73
	v_lshlrev_b32_e32 v164, 16, v74
	v_and_b32_e32 v165, 0xffff0000, v74
	v_lshlrev_b32_e32 v166, 16, v75
	v_and_b32_e32 v167, 0xffff0000, v75
	v_lshlrev_b32_e32 v168, 16, v76
	v_and_b32_e32 v169, 0xffff0000, v76
	v_lshlrev_b32_e32 v170, 16, v77
	v_and_b32_e32 v171, 0xffff0000, v77
	v_lshlrev_b32_e32 v172, 16, v78
	v_and_b32_e32 v173, 0xffff0000, v78
	v_lshlrev_b32_e32 v174, 16, v79
	v_and_b32_e32 v175, 0xffff0000, v79
	v_pk_mul_f32 v[252:253], v[160:161], v[160:161]
	v_pk_mul_f32 v[254:255], v[162:163], v[162:163]
	v_pk_fma_f32 v[252:253], v[164:165], v[164:165], v[252:253]
	v_pk_fma_f32 v[254:255], v[166:167], v[166:167], v[254:255]
	v_pk_fma_f32 v[252:253], v[168:169], v[168:169], v[252:253]
	v_pk_fma_f32 v[254:255], v[170:171], v[170:171], v[254:255]
	v_pk_fma_f32 v[252:253], v[172:173], v[172:173], v[252:253]
	v_pk_fma_f32 v[254:255], v[174:175], v[174:175], v[254:255]
	v_pk_add_f32 v[252:253], v[252:253], v[254:255]
	s_nop 0
	v_add_f32_e32 v183, v252, v253
	s_nop 1
	v_add_f32_dpp v183, v183, v183 quad_perm:[1,0,3,2] row_mask:0xf bank_mask:0xf bound_ctrl:1
	s_nop 1
	v_add_f32_dpp v183, v183, v183 quad_perm:[2,3,0,1] row_mask:0xf bank_mask:0xf bound_ctrl:1
	s_nop 1
	v_add_f32_dpp v183, v183, v183 row_half_mirror row_mask:0xf bank_mask:0xf bound_ctrl:1
	s_nop 1
	v_add_f32_dpp v183, v183, v183 row_mirror row_mask:0xf bank_mask:0xf bound_ctrl:1
	s_nop 1
	v_readlane_b32 s98, v183, 0
	v_readlane_b32 s99, v183, 16
	v_readlane_b32 s100, v183, 32
	v_readlane_b32 s101, v183, 48
	s_nop 1
	v_mov_b32_e32 v183, s98
	v_add_f32_e32 v183, s99, v183
	v_add_f32_e32 v183, s100, v183
	v_add_f32_e32 v183, s101, v183
	v_fmamk_f32 v183, v183, 0x3a800000, v182
	v_cmp_gt_f32_e32 vcc, 0x800000, v183
	v_mul_f32_e32 v181, 0x4b800000, v183
	s_nop 1
	v_cndmask_b32_e32 v183, v183, v181, vcc
	v_rsq_f32_e32 v183, v183
	s_nop 0
	v_mul_f32_e32 v181, 0x45800000, v183
	v_cndmask_b32_e32 v184, v183, v181, vcc
	v_mov_b32_e32 v185, v184
	v_pk_mul_f32 v[160:161], v[160:161], v[184:185]
	v_pk_mul_f32 v[162:163], v[162:163], v[184:185]
	v_pk_mul_f32 v[164:165], v[164:165], v[184:185]
	v_pk_mul_f32 v[166:167], v[166:167], v[184:185]
	v_pk_mul_f32 v[168:169], v[168:169], v[184:185]
	v_pk_mul_f32 v[170:171], v[170:171], v[184:185]
	v_pk_mul_f32 v[172:173], v[172:173], v[184:185]
	v_pk_mul_f32 v[174:175], v[174:175], v[184:185]
	v_pk_fma_f32 v[144:145], v[160:161], v[128:129], v[144:145]
	v_pk_fma_f32 v[146:147], v[162:163], v[130:131], v[146:147]
	v_pk_fma_f32 v[148:149], v[164:165], v[132:133], v[148:149]
	v_pk_fma_f32 v[150:151], v[166:167], v[134:135], v[150:151]
	v_pk_fma_f32 v[152:153], v[168:169], v[136:137], v[152:153]
	v_pk_fma_f32 v[154:155], v[170:171], v[138:139], v[154:155]
	v_pk_fma_f32 v[156:157], v[172:173], v[140:141], v[156:157]
	v_pk_fma_f32 v[158:159], v[174:175], v[142:143], v[158:159]
	v_pk_mul_f32 v[252:253], v[144:145], v[144:145]
	v_pk_mul_f32 v[254:255], v[146:147], v[146:147]
	v_pk_fma_f32 v[252:253], v[148:149], v[148:149], v[252:253]
	v_pk_fma_f32 v[254:255], v[150:151], v[150:151], v[254:255]
	v_pk_fma_f32 v[252:253], v[152:153], v[152:153], v[252:253]
	v_pk_fma_f32 v[254:255], v[154:155], v[154:155], v[254:255]
	v_pk_fma_f32 v[252:253], v[156:157], v[156:157], v[252:253]
	v_pk_fma_f32 v[254:255], v[158:159], v[158:159], v[254:255]
	v_pk_add_f32 v[252:253], v[252:253], v[254:255]
	s_nop 0
	v_add_f32_e32 v183, v252, v253
	s_nop 1
	v_add_f32_dpp v183, v183, v183 quad_perm:[1,0,3,2] row_mask:0xf bank_mask:0xf bound_ctrl:1
	s_nop 1
	v_add_f32_dpp v183, v183, v183 quad_perm:[2,3,0,1] row_mask:0xf bank_mask:0xf bound_ctrl:1
	s_nop 1
	v_add_f32_dpp v183, v183, v183 row_half_mirror row_mask:0xf bank_mask:0xf bound_ctrl:1
	s_nop 1
	v_add_f32_dpp v183, v183, v183 row_mirror row_mask:0xf bank_mask:0xf bound_ctrl:1
	s_nop 1
	v_readlane_b32 s98, v183, 0
	v_readlane_b32 s99, v183, 16
	v_readlane_b32 s100, v183, 32
	v_readlane_b32 s101, v183, 48
	s_nop 1
	v_mov_b32_e32 v183, s98
	v_add_f32_e32 v183, s99, v183
	v_add_f32_e32 v183, s100, v183
	v_add_f32_e32 v183, s101, v183
	v_fmamk_f32 v183, v183, 0x3a800000, v182
	v_cmp_gt_f32_e32 vcc, 0x800000, v183
	v_mul_f32_e32 v181, 0x4b800000, v183
	s_nop 1
	v_cndmask_b32_e32 v183, v183, v181, vcc
	v_rsq_f32_e32 v183, v183
	s_nop 0
	v_mul_f32_e32 v181, 0x45800000, v183
	v_cndmask_b32_e32 v184, v183, v181, vcc
	v_mov_b32_e32 v185, v184
	v_cvt_pk_bf16_f32 v64, v144, v145
	v_cvt_pk_bf16_f32 v65, v146, v147
	v_cvt_pk_bf16_f32 v66, v148, v149
	v_cvt_pk_bf16_f32 v67, v150, v151
	v_cvt_pk_bf16_f32 v68, v152, v153
	v_cvt_pk_bf16_f32 v69, v154, v155
	v_cvt_pk_bf16_f32 v70, v156, v157
	v_cvt_pk_bf16_f32 v71, v158, v159
	v_add_u32_e32 v181, 0x2800000, v177
	global_store_dwordx4 v181, v[64:67], s[78:79]
	global_store_dwordx4 v181, v[68:71], s[78:79] offset:1024
	v_add_u32_e32 v236, 0x8000, v237
	s_mov_b64 exec, 1
	global_store_dword v236, v184, s[78:79]
	s_mov_b64 exec, -1
	s_waitcnt vmcnt(8)
	v_lshlrev_b32_e32 v144, 16, v80
	v_and_b32_e32 v145, 0xffff0000, v80
	v_lshlrev_b32_e32 v146, 16, v81
	v_and_b32_e32 v147, 0xffff0000, v81
	v_lshlrev_b32_e32 v148, 16, v82
	v_and_b32_e32 v149, 0xffff0000, v82
	v_lshlrev_b32_e32 v150, 16, v83
	v_and_b32_e32 v151, 0xffff0000, v83
	v_lshlrev_b32_e32 v152, 16, v84
	v_and_b32_e32 v153, 0xffff0000, v84
	v_lshlrev_b32_e32 v154, 16, v85
	v_and_b32_e32 v155, 0xffff0000, v85
	v_lshlrev_b32_e32 v156, 16, v86
	v_and_b32_e32 v157, 0xffff0000, v86
	v_lshlrev_b32_e32 v158, 16, v87
	v_and_b32_e32 v159, 0xffff0000, v87
	v_lshlrev_b32_e32 v160, 16, v88
	v_and_b32_e32 v161, 0xffff0000, v88
	v_lshlrev_b32_e32 v162, 16, v89
	v_and_b32_e32 v163, 0xffff0000, v89
	v_lshlrev_b32_e32 v164, 16, v90
	v_and_b32_e32 v165, 0xffff0000, v90
	v_lshlrev_b32_e32 v166, 16, v91
	v_and_b32_e32 v167, 0xffff0000, v91
	v_lshlrev_b32_e32 v168, 16, v92
	v_and_b32_e32 v169, 0xffff0000, v92
	v_lshlrev_b32_e32 v170, 16, v93
	v_and_b32_e32 v171, 0xffff0000, v93
	v_lshlrev_b32_e32 v172, 16, v94
	v_and_b32_e32 v173, 0xffff0000, v94
	v_lshlrev_b32_e32 v174, 16, v95
	v_and_b32_e32 v175, 0xffff0000, v95
	v_pk_mul_f32 v[252:253], v[160:161], v[160:161]
	v_pk_mul_f32 v[254:255], v[162:163], v[162:163]
	v_pk_fma_f32 v[252:253], v[164:165], v[164:165], v[252:253]
	v_pk_fma_f32 v[254:255], v[166:167], v[166:167], v[254:255]
	v_pk_fma_f32 v[252:253], v[168:169], v[168:169], v[252:253]
	v_pk_fma_f32 v[254:255], v[170:171], v[170:171], v[254:255]
	v_pk_fma_f32 v[252:253], v[172:173], v[172:173], v[252:253]
	v_pk_fma_f32 v[254:255], v[174:175], v[174:175], v[254:255]
	v_pk_add_f32 v[252:253], v[252:253], v[254:255]
	s_nop 0
	v_add_f32_e32 v183, v252, v253
	s_nop 1
	v_add_f32_dpp v183, v183, v183 quad_perm:[1,0,3,2] row_mask:0xf bank_mask:0xf bound_ctrl:1
	s_nop 1
	v_add_f32_dpp v183, v183, v183 quad_perm:[2,3,0,1] row_mask:0xf bank_mask:0xf bound_ctrl:1
	s_nop 1
	v_add_f32_dpp v183, v183, v183 row_half_mirror row_mask:0xf bank_mask:0xf bound_ctrl:1
	s_nop 1
	v_add_f32_dpp v183, v183, v183 row_mirror row_mask:0xf bank_mask:0xf bound_ctrl:1
	s_nop 1
	v_readlane_b32 s98, v183, 0
	v_readlane_b32 s99, v183, 16
	v_readlane_b32 s100, v183, 32
	v_readlane_b32 s101, v183, 48
	s_nop 1
	v_mov_b32_e32 v183, s98
	v_add_f32_e32 v183, s99, v183
	v_add_f32_e32 v183, s100, v183
	v_add_f32_e32 v183, s101, v183
	v_fmamk_f32 v183, v183, 0x3a800000, v182
	v_cmp_gt_f32_e32 vcc, 0x800000, v183
	v_mul_f32_e32 v181, 0x4b800000, v183
	s_nop 1
	v_cndmask_b32_e32 v183, v183, v181, vcc
	v_rsq_f32_e32 v183, v183
	s_nop 0
	v_mul_f32_e32 v181, 0x45800000, v183
	v_cndmask_b32_e32 v184, v183, v181, vcc
	v_mov_b32_e32 v185, v184
	v_pk_mul_f32 v[160:161], v[160:161], v[184:185]
	v_pk_mul_f32 v[162:163], v[162:163], v[184:185]
	v_pk_mul_f32 v[164:165], v[164:165], v[184:185]
	v_pk_mul_f32 v[166:167], v[166:167], v[184:185]
	v_pk_mul_f32 v[168:169], v[168:169], v[184:185]
	v_pk_mul_f32 v[170:171], v[170:171], v[184:185]
	v_pk_mul_f32 v[172:173], v[172:173], v[184:185]
	v_pk_mul_f32 v[174:175], v[174:175], v[184:185]
	v_pk_fma_f32 v[144:145], v[160:161], v[128:129], v[144:145]
	v_pk_fma_f32 v[146:147], v[162:163], v[130:131], v[146:147]
	v_pk_fma_f32 v[148:149], v[164:165], v[132:133], v[148:149]
	v_pk_fma_f32 v[150:151], v[166:167], v[134:135], v[150:151]
	v_pk_fma_f32 v[152:153], v[168:169], v[136:137], v[152:153]
	v_pk_fma_f32 v[154:155], v[170:171], v[138:139], v[154:155]
	v_pk_fma_f32 v[156:157], v[172:173], v[140:141], v[156:157]
	v_pk_fma_f32 v[158:159], v[174:175], v[142:143], v[158:159]
	v_pk_mul_f32 v[252:253], v[144:145], v[144:145]
	v_pk_mul_f32 v[254:255], v[146:147], v[146:147]
	v_pk_fma_f32 v[252:253], v[148:149], v[148:149], v[252:253]
	v_pk_fma_f32 v[254:255], v[150:151], v[150:151], v[254:255]
	v_pk_fma_f32 v[252:253], v[152:153], v[152:153], v[252:253]
	v_pk_fma_f32 v[254:255], v[154:155], v[154:155], v[254:255]
	v_pk_fma_f32 v[252:253], v[156:157], v[156:157], v[252:253]
	v_pk_fma_f32 v[254:255], v[158:159], v[158:159], v[254:255]
	v_pk_add_f32 v[252:253], v[252:253], v[254:255]
	s_nop 0
	v_add_f32_e32 v183, v252, v253
	s_nop 1
	v_add_f32_dpp v183, v183, v183 quad_perm:[1,0,3,2] row_mask:0xf bank_mask:0xf bound_ctrl:1
	s_nop 1
	v_add_f32_dpp v183, v183, v183 quad_perm:[2,3,0,1] row_mask:0xf bank_mask:0xf bound_ctrl:1
	s_nop 1
	v_add_f32_dpp v183, v183, v183 row_half_mirror row_mask:0xf bank_mask:0xf bound_ctrl:1
	s_nop 1
	v_add_f32_dpp v183, v183, v183 row_mirror row_mask:0xf bank_mask:0xf bound_ctrl:1
	s_nop 1
	v_readlane_b32 s98, v183, 0
	v_readlane_b32 s99, v183, 16
	v_readlane_b32 s100, v183, 32
	v_readlane_b32 s101, v183, 48
	s_nop 1
	v_mov_b32_e32 v183, s98
	v_add_f32_e32 v183, s99, v183
	v_add_f32_e32 v183, s100, v183
	v_add_f32_e32 v183, s101, v183
	v_fmamk_f32 v183, v183, 0x3a800000, v182
	v_cmp_gt_f32_e32 vcc, 0x800000, v183
	v_mul_f32_e32 v181, 0x4b800000, v183
	s_nop 1
	v_cndmask_b32_e32 v183, v183, v181, vcc
	v_rsq_f32_e32 v183, v183
	s_nop 0
	v_mul_f32_e32 v181, 0x45800000, v183
	v_cndmask_b32_e32 v184, v183, v181, vcc
	v_mov_b32_e32 v185, v184
	v_cvt_pk_bf16_f32 v80, v144, v145
	v_cvt_pk_bf16_f32 v81, v146, v147
	v_cvt_pk_bf16_f32 v82, v148, v149
	v_cvt_pk_bf16_f32 v83, v150, v151
	v_cvt_pk_bf16_f32 v84, v152, v153
	v_cvt_pk_bf16_f32 v85, v154, v155
	v_cvt_pk_bf16_f32 v86, v156, v157
	v_cvt_pk_bf16_f32 v87, v158, v159
	v_add_u32_e32 v181, 0x2c00000, v177
	global_store_dwordx4 v181, v[80:83], s[78:79]
	global_store_dwordx4 v181, v[84:87], s[78:79] offset:1024
	v_add_u32_e32 v236, 0xa000, v237
	s_mov_b64 exec, 1
	global_store_dword v236, v184, s[78:79]
	s_mov_b64 exec, -1
	s_waitcnt vmcnt(4)
	v_lshlrev_b32_e32 v144, 16, v96
	v_and_b32_e32 v145, 0xffff0000, v96
	v_lshlrev_b32_e32 v146, 16, v97
	v_and_b32_e32 v147, 0xffff0000, v97
	v_lshlrev_b32_e32 v148, 16, v98
	v_and_b32_e32 v149, 0xffff0000, v98
	v_lshlrev_b32_e32 v150, 16, v99
	v_and_b32_e32 v151, 0xffff0000, v99
	v_lshlrev_b32_e32 v152, 16, v100
	v_and_b32_e32 v153, 0xffff0000, v100
	v_lshlrev_b32_e32 v154, 16, v101
	v_and_b32_e32 v155, 0xffff0000, v101
	v_lshlrev_b32_e32 v156, 16, v102
	v_and_b32_e32 v157, 0xffff0000, v102
	v_lshlrev_b32_e32 v158, 16, v103
	v_and_b32_e32 v159, 0xffff0000, v103
	v_lshlrev_b32_e32 v160, 16, v104
	v_and_b32_e32 v161, 0xffff0000, v104
	v_lshlrev_b32_e32 v162, 16, v105
	v_and_b32_e32 v163, 0xffff0000, v105
	v_lshlrev_b32_e32 v164, 16, v106
	v_and_b32_e32 v165, 0xffff0000, v106
	v_lshlrev_b32_e32 v166, 16, v107
	v_and_b32_e32 v167, 0xffff0000, v107
	v_lshlrev_b32_e32 v168, 16, v108
	v_and_b32_e32 v169, 0xffff0000, v108
	v_lshlrev_b32_e32 v170, 16, v109
	v_and_b32_e32 v171, 0xffff0000, v109
	v_lshlrev_b32_e32 v172, 16, v110
	v_and_b32_e32 v173, 0xffff0000, v110
	v_lshlrev_b32_e32 v174, 16, v111
	v_and_b32_e32 v175, 0xffff0000, v111
	v_pk_mul_f32 v[252:253], v[160:161], v[160:161]
	v_pk_mul_f32 v[254:255], v[162:163], v[162:163]
	v_pk_fma_f32 v[252:253], v[164:165], v[164:165], v[252:253]
	v_pk_fma_f32 v[254:255], v[166:167], v[166:167], v[254:255]
	v_pk_fma_f32 v[252:253], v[168:169], v[168:169], v[252:253]
	v_pk_fma_f32 v[254:255], v[170:171], v[170:171], v[254:255]
	v_pk_fma_f32 v[252:253], v[172:173], v[172:173], v[252:253]
	v_pk_fma_f32 v[254:255], v[174:175], v[174:175], v[254:255]
	v_pk_add_f32 v[252:253], v[252:253], v[254:255]
	s_nop 0
	v_add_f32_e32 v183, v252, v253
	s_nop 1
	v_add_f32_dpp v183, v183, v183 quad_perm:[1,0,3,2] row_mask:0xf bank_mask:0xf bound_ctrl:1
	s_nop 1
	v_add_f32_dpp v183, v183, v183 quad_perm:[2,3,0,1] row_mask:0xf bank_mask:0xf bound_ctrl:1
	s_nop 1
	v_add_f32_dpp v183, v183, v183 row_half_mirror row_mask:0xf bank_mask:0xf bound_ctrl:1
	s_nop 1
	v_add_f32_dpp v183, v183, v183 row_mirror row_mask:0xf bank_mask:0xf bound_ctrl:1
	s_nop 1
	v_readlane_b32 s98, v183, 0
	v_readlane_b32 s99, v183, 16
	v_readlane_b32 s100, v183, 32
	v_readlane_b32 s101, v183, 48
	s_nop 1
	v_mov_b32_e32 v183, s98
	v_add_f32_e32 v183, s99, v183
	v_add_f32_e32 v183, s100, v183
	v_add_f32_e32 v183, s101, v183
	v_fmamk_f32 v183, v183, 0x3a800000, v182
	v_cmp_gt_f32_e32 vcc, 0x800000, v183
	v_mul_f32_e32 v181, 0x4b800000, v183
	s_nop 1
	v_cndmask_b32_e32 v183, v183, v181, vcc
	v_rsq_f32_e32 v183, v183
	s_nop 0
	v_mul_f32_e32 v181, 0x45800000, v183
	v_cndmask_b32_e32 v184, v183, v181, vcc
	v_mov_b32_e32 v185, v184
	v_pk_mul_f32 v[160:161], v[160:161], v[184:185]
	v_pk_mul_f32 v[162:163], v[162:163], v[184:185]
	v_pk_mul_f32 v[164:165], v[164:165], v[184:185]
	v_pk_mul_f32 v[166:167], v[166:167], v[184:185]
	v_pk_mul_f32 v[168:169], v[168:169], v[184:185]
	v_pk_mul_f32 v[170:171], v[170:171], v[184:185]
	v_pk_mul_f32 v[172:173], v[172:173], v[184:185]
	v_pk_mul_f32 v[174:175], v[174:175], v[184:185]
	v_pk_fma_f32 v[144:145], v[160:161], v[128:129], v[144:145]
	v_pk_fma_f32 v[146:147], v[162:163], v[130:131], v[146:147]
	v_pk_fma_f32 v[148:149], v[164:165], v[132:133], v[148:149]
	v_pk_fma_f32 v[150:151], v[166:167], v[134:135], v[150:151]
	v_pk_fma_f32 v[152:153], v[168:169], v[136:137], v[152:153]
	v_pk_fma_f32 v[154:155], v[170:171], v[138:139], v[154:155]
	v_pk_fma_f32 v[156:157], v[172:173], v[140:141], v[156:157]
	v_pk_fma_f32 v[158:159], v[174:175], v[142:143], v[158:159]
	v_pk_mul_f32 v[252:253], v[144:145], v[144:145]
	v_pk_mul_f32 v[254:255], v[146:147], v[146:147]
	v_pk_fma_f32 v[252:253], v[148:149], v[148:149], v[252:253]
	v_pk_fma_f32 v[254:255], v[150:151], v[150:151], v[254:255]
	v_pk_fma_f32 v[252:253], v[152:153], v[152:153], v[252:253]
	v_pk_fma_f32 v[254:255], v[154:155], v[154:155], v[254:255]
	v_pk_fma_f32 v[252:253], v[156:157], v[156:157], v[252:253]
	v_pk_fma_f32 v[254:255], v[158:159], v[158:159], v[254:255]
	v_pk_add_f32 v[252:253], v[252:253], v[254:255]
	s_nop 0
	v_add_f32_e32 v183, v252, v253
	s_nop 1
	v_add_f32_dpp v183, v183, v183 quad_perm:[1,0,3,2] row_mask:0xf bank_mask:0xf bound_ctrl:1
	s_nop 1
	v_add_f32_dpp v183, v183, v183 quad_perm:[2,3,0,1] row_mask:0xf bank_mask:0xf bound_ctrl:1
	s_nop 1
	v_add_f32_dpp v183, v183, v183 row_half_mirror row_mask:0xf bank_mask:0xf bound_ctrl:1
	s_nop 1
	v_add_f32_dpp v183, v183, v183 row_mirror row_mask:0xf bank_mask:0xf bound_ctrl:1
	s_nop 1
	v_readlane_b32 s98, v183, 0
	v_readlane_b32 s99, v183, 16
	v_readlane_b32 s100, v183, 32
	v_readlane_b32 s101, v183, 48
	s_nop 1
	v_mov_b32_e32 v183, s98
	v_add_f32_e32 v183, s99, v183
	v_add_f32_e32 v183, s100, v183
	v_add_f32_e32 v183, s101, v183
	v_fmamk_f32 v183, v183, 0x3a800000, v182
	v_cmp_gt_f32_e32 vcc, 0x800000, v183
	v_mul_f32_e32 v181, 0x4b800000, v183
	s_nop 1
	v_cndmask_b32_e32 v183, v183, v181, vcc
	v_rsq_f32_e32 v183, v183
	s_nop 0
	v_mul_f32_e32 v181, 0x45800000, v183
	v_cndmask_b32_e32 v184, v183, v181, vcc
	v_mov_b32_e32 v185, v184
	v_cvt_pk_bf16_f32 v96, v144, v145
	v_cvt_pk_bf16_f32 v97, v146, v147
	v_cvt_pk_bf16_f32 v98, v148, v149
	v_cvt_pk_bf16_f32 v99, v150, v151
	v_cvt_pk_bf16_f32 v100, v152, v153
	v_cvt_pk_bf16_f32 v101, v154, v155
	v_cvt_pk_bf16_f32 v102, v156, v157
	v_cvt_pk_bf16_f32 v103, v158, v159
	v_add_u32_e32 v181, 0x3000000, v177
	global_store_dwordx4 v181, v[96:99], s[78:79]
	global_store_dwordx4 v181, v[100:103], s[78:79] offset:1024
	v_add_u32_e32 v236, 0xc000, v237
	s_mov_b64 exec, 1
	global_store_dword v236, v184, s[78:79]
	s_mov_b64 exec, -1
	s_waitcnt vmcnt(0)
	v_lshlrev_b32_e32 v144, 16, v112
	v_and_b32_e32 v145, 0xffff0000, v112
	v_lshlrev_b32_e32 v146, 16, v113
	v_and_b32_e32 v147, 0xffff0000, v113
	v_lshlrev_b32_e32 v148, 16, v114
	v_and_b32_e32 v149, 0xffff0000, v114
	v_lshlrev_b32_e32 v150, 16, v115
	v_and_b32_e32 v151, 0xffff0000, v115
	v_lshlrev_b32_e32 v152, 16, v116
	v_and_b32_e32 v153, 0xffff0000, v116
	v_lshlrev_b32_e32 v154, 16, v117
	v_and_b32_e32 v155, 0xffff0000, v117
	v_lshlrev_b32_e32 v156, 16, v118
	v_and_b32_e32 v157, 0xffff0000, v118
	v_lshlrev_b32_e32 v158, 16, v119
	v_and_b32_e32 v159, 0xffff0000, v119
	v_lshlrev_b32_e32 v160, 16, v120
	v_and_b32_e32 v161, 0xffff0000, v120
	v_lshlrev_b32_e32 v162, 16, v121
	v_and_b32_e32 v163, 0xffff0000, v121
	v_lshlrev_b32_e32 v164, 16, v122
	v_and_b32_e32 v165, 0xffff0000, v122
	v_lshlrev_b32_e32 v166, 16, v123
	v_and_b32_e32 v167, 0xffff0000, v123
	v_lshlrev_b32_e32 v168, 16, v124
	v_and_b32_e32 v169, 0xffff0000, v124
	v_lshlrev_b32_e32 v170, 16, v125
	v_and_b32_e32 v171, 0xffff0000, v125
	v_lshlrev_b32_e32 v172, 16, v126
	v_and_b32_e32 v173, 0xffff0000, v126
	v_lshlrev_b32_e32 v174, 16, v127
	v_and_b32_e32 v175, 0xffff0000, v127
	v_pk_mul_f32 v[252:253], v[160:161], v[160:161]
	v_pk_mul_f32 v[254:255], v[162:163], v[162:163]
	v_pk_fma_f32 v[252:253], v[164:165], v[164:165], v[252:253]
	v_pk_fma_f32 v[254:255], v[166:167], v[166:167], v[254:255]
	v_pk_fma_f32 v[252:253], v[168:169], v[168:169], v[252:253]
	v_pk_fma_f32 v[254:255], v[170:171], v[170:171], v[254:255]
	v_pk_fma_f32 v[252:253], v[172:173], v[172:173], v[252:253]
	v_pk_fma_f32 v[254:255], v[174:175], v[174:175], v[254:255]
	v_pk_add_f32 v[252:253], v[252:253], v[254:255]
	s_nop 0
	v_add_f32_e32 v183, v252, v253
	s_nop 1
	v_add_f32_dpp v183, v183, v183 quad_perm:[1,0,3,2] row_mask:0xf bank_mask:0xf bound_ctrl:1
	s_nop 1
	v_add_f32_dpp v183, v183, v183 quad_perm:[2,3,0,1] row_mask:0xf bank_mask:0xf bound_ctrl:1
	s_nop 1
	v_add_f32_dpp v183, v183, v183 row_half_mirror row_mask:0xf bank_mask:0xf bound_ctrl:1
	s_nop 1
	v_add_f32_dpp v183, v183, v183 row_mirror row_mask:0xf bank_mask:0xf bound_ctrl:1
	s_nop 1
	v_readlane_b32 s98, v183, 0
	v_readlane_b32 s99, v183, 16
	v_readlane_b32 s100, v183, 32
	v_readlane_b32 s101, v183, 48
	s_nop 1
	v_mov_b32_e32 v183, s98
	v_add_f32_e32 v183, s99, v183
	v_add_f32_e32 v183, s100, v183
	v_add_f32_e32 v183, s101, v183
	v_fmamk_f32 v183, v183, 0x3a800000, v182
	v_cmp_gt_f32_e32 vcc, 0x800000, v183
	v_mul_f32_e32 v181, 0x4b800000, v183
	s_nop 1
	v_cndmask_b32_e32 v183, v183, v181, vcc
	v_rsq_f32_e32 v183, v183
	s_nop 0
	v_mul_f32_e32 v181, 0x45800000, v183
	v_cndmask_b32_e32 v184, v183, v181, vcc
	v_mov_b32_e32 v185, v184
	v_pk_mul_f32 v[160:161], v[160:161], v[184:185]
	v_pk_mul_f32 v[162:163], v[162:163], v[184:185]
	v_pk_mul_f32 v[164:165], v[164:165], v[184:185]
	v_pk_mul_f32 v[166:167], v[166:167], v[184:185]
	v_pk_mul_f32 v[168:169], v[168:169], v[184:185]
	v_pk_mul_f32 v[170:171], v[170:171], v[184:185]
	v_pk_mul_f32 v[172:173], v[172:173], v[184:185]
	v_pk_mul_f32 v[174:175], v[174:175], v[184:185]
	v_pk_fma_f32 v[144:145], v[160:161], v[128:129], v[144:145]
	v_pk_fma_f32 v[146:147], v[162:163], v[130:131], v[146:147]
	v_pk_fma_f32 v[148:149], v[164:165], v[132:133], v[148:149]
	v_pk_fma_f32 v[150:151], v[166:167], v[134:135], v[150:151]
	v_pk_fma_f32 v[152:153], v[168:169], v[136:137], v[152:153]
	v_pk_fma_f32 v[154:155], v[170:171], v[138:139], v[154:155]
	v_pk_fma_f32 v[156:157], v[172:173], v[140:141], v[156:157]
	v_pk_fma_f32 v[158:159], v[174:175], v[142:143], v[158:159]
	v_pk_mul_f32 v[252:253], v[144:145], v[144:145]
	v_pk_mul_f32 v[254:255], v[146:147], v[146:147]
	v_pk_fma_f32 v[252:253], v[148:149], v[148:149], v[252:253]
	v_pk_fma_f32 v[254:255], v[150:151], v[150:151], v[254:255]
	v_pk_fma_f32 v[252:253], v[152:153], v[152:153], v[252:253]
	v_pk_fma_f32 v[254:255], v[154:155], v[154:155], v[254:255]
	v_pk_fma_f32 v[252:253], v[156:157], v[156:157], v[252:253]
	v_pk_fma_f32 v[254:255], v[158:159], v[158:159], v[254:255]
	v_pk_add_f32 v[252:253], v[252:253], v[254:255]
	s_nop 0
	v_add_f32_e32 v183, v252, v253
	s_nop 1
	v_add_f32_dpp v183, v183, v183 quad_perm:[1,0,3,2] row_mask:0xf bank_mask:0xf bound_ctrl:1
	s_nop 1
	v_add_f32_dpp v183, v183, v183 quad_perm:[2,3,0,1] row_mask:0xf bank_mask:0xf bound_ctrl:1
	s_nop 1
	v_add_f32_dpp v183, v183, v183 row_half_mirror row_mask:0xf bank_mask:0xf bound_ctrl:1
	s_nop 1
	v_add_f32_dpp v183, v183, v183 row_mirror row_mask:0xf bank_mask:0xf bound_ctrl:1
	s_nop 1
	v_readlane_b32 s98, v183, 0
	v_readlane_b32 s99, v183, 16
	v_readlane_b32 s100, v183, 32
	v_readlane_b32 s101, v183, 48
	s_nop 1
	v_mov_b32_e32 v183, s98
	v_add_f32_e32 v183, s99, v183
	v_add_f32_e32 v183, s100, v183
	v_add_f32_e32 v183, s101, v183
	v_fmamk_f32 v183, v183, 0x3a800000, v182
	v_cmp_gt_f32_e32 vcc, 0x800000, v183
	v_mul_f32_e32 v181, 0x4b800000, v183
	s_nop 1
	v_cndmask_b32_e32 v183, v183, v181, vcc
	v_rsq_f32_e32 v183, v183
	s_nop 0
	v_mul_f32_e32 v181, 0x45800000, v183
	v_cndmask_b32_e32 v184, v183, v181, vcc
	v_mov_b32_e32 v185, v184
	v_cvt_pk_bf16_f32 v112, v144, v145
	v_cvt_pk_bf16_f32 v113, v146, v147
	v_cvt_pk_bf16_f32 v114, v148, v149
	v_cvt_pk_bf16_f32 v115, v150, v151
	v_cvt_pk_bf16_f32 v116, v152, v153
	v_cvt_pk_bf16_f32 v117, v154, v155
	v_cvt_pk_bf16_f32 v118, v156, v157
	v_cvt_pk_bf16_f32 v119, v158, v159
	v_add_u32_e32 v181, 0x3400000, v177
	global_store_dwordx4 v181, v[112:115], s[78:79]
	global_store_dwordx4 v181, v[116:119], s[78:79] offset:1024
	v_add_u32_e32 v236, 0xe000, v237
	s_mov_b64 exec, 1
	global_store_dword v236, v184, s[78:79]
	s_mov_b64 exec, -1
	v_readfirstlane_b32 s98, v179
	s_nop 3
	s_cmp_ge_u32 s98, 512
	s_cbranch_scc1 .Lmyxupd_done_1
	v_lshlrev_b32_e32 v177, 4, v176
	v_lshl_add_u32 v177, v179, 11, v177
	v_lshlrev_b32_e32 v237, 2, v179
	v_add_u32_e32 v237, 0x10000, v237
	v_add_u32_e32 v181, 0x3800000, v177
	global_load_dwordx4 v[0:3], v181, s[78:79]
	global_load_dwordx4 v[4:7], v181, s[78:79] offset:1024
	v_lshl_add_u32 v183, v179, 12, v180
	v_add_u32_e32 v183, 0xbf00000, v183
	v_add_u32_e32 v181, 0x0, v183
	global_load_dwordx4 v[8:11], v181, s[78:79]
	global_load_dwordx4 v[12:15], v181, s[78:79] offset:16
	global_load_dwordx4 v[16:19], v181, s[78:79] offset:2048
	global_load_dwordx4 v[20:23], v181, s[78:79] offset:2064
	v_add_u32_e32 v181, 0x200000, v183
	global_load_dwordx4 v[24:27], v181, s[78:79]
	global_load_dwordx4 v[28:31], v181, s[78:79] offset:16
	global_load_dwordx4 v[32:35], v181, s[78:79] offset:2048
	global_load_dwordx4 v[36:39], v181, s[78:79] offset:2064
	v_add_u32_e32 v181, 0x400000, v183
	global_load_dwordx4 v[40:43], v181, s[78:79]
	global_load_dwordx4 v[44:47], v181, s[78:79] offset:16
	global_load_dwordx4 v[48:51], v181, s[78:79] offset:2048
	global_load_dwordx4 v[52:55], v181, s[78:79] offset:2064
	v_add_u32_e32 v181, 0x600000, v183
	global_load_dwordx4 v[56:59], v181, s[78:79]
	global_load_dwordx4 v[60:63], v181, s[78:79] offset:16
	global_load_dwordx4 v[64:67], v181, s[78:79] offset:2048
	global_load_dwordx4 v[68:71], v181, s[78:79] offset:2064
	v_add_u32_e32 v181, 0x800000, v183
	global_load_dwordx4 v[72:75], v181, s[78:79]
	global_load_dwordx4 v[76:79], v181, s[78:79] offset:16
	global_load_dwordx4 v[80:83], v181, s[78:79] offset:2048
	global_load_dwordx4 v[84:87], v181, s[78:79] offset:2064
	v_add_u32_e32 v181, 0xa00000, v183
	global_load_dwordx4 v[88:91], v181, s[78:79]
	global_load_dwordx4 v[92:95], v181, s[78:79] offset:16
	global_load_dwordx4 v[96:99], v181, s[78:79] offset:2048
	global_load_dwordx4 v[100:103], v181, s[78:79] offset:2064
	s_waitcnt vmcnt(20)
	v_pk_add_f32 v[160:161], v[8:9], 0 op_sel_hi:[1,0]
	v_pk_add_f32 v[162:163], v[10:11], 0 op_sel_hi:[1,0]
	v_pk_add_f32 v[164:165], v[12:13], 0 op_sel_hi:[1,0]
	v_pk_add_f32 v[166:167], v[14:15], 0 op_sel_hi:[1,0]
	v_pk_add_f32 v[168:169], v[16:17], 0 op_sel_hi:[1,0]
	v_pk_add_f32 v[170:171], v[18:19], 0 op_sel_hi:[1,0]
	v_pk_add_f32 v[172:173], v[20:21], 0 op_sel_hi:[1,0]
	v_pk_add_f32 v[174:175], v[22:23], 0 op_sel_hi:[1,0]
	s_waitcnt vmcnt(16)
	v_pk_add_f32 v[160:161], v[160:161], v[24:25]
	v_pk_add_f32 v[162:163], v[162:163], v[26:27]
	v_pk_add_f32 v[164:165], v[164:165], v[28:29]
	v_pk_add_f32 v[166:167], v[166:167], v[30:31]
	v_pk_add_f32 v[168:169], v[168:169], v[32:33]
	v_pk_add_f32 v[170:171], v[170:171], v[34:35]
	v_pk_add_f32 v[172:173], v[172:173], v[36:37]
	v_pk_add_f32 v[174:175], v[174:175], v[38:39]
	s_waitcnt vmcnt(12)
	v_pk_add_f32 v[160:161], v[160:161], v[40:41]
	v_pk_add_f32 v[162:163], v[162:163], v[42:43]
	v_pk_add_f32 v[164:165], v[164:165], v[44:45]
	v_pk_add_f32 v[166:167], v[166:167], v[46:47]
	v_pk_add_f32 v[168:169], v[168:169], v[48:49]
	v_pk_add_f32 v[170:171], v[170:171], v[50:51]
	v_pk_add_f32 v[172:173], v[172:173], v[52:53]
	v_pk_add_f32 v[174:175], v[174:175], v[54:55]
	s_waitcnt vmcnt(8)
	v_pk_add_f32 v[160:161], v[160:161], v[56:57]
	v_pk_add_f32 v[162:163], v[162:163], v[58:59]
	v_pk_add_f32 v[164:165], v[164:165], v[60:61]
	v_pk_add_f32 v[166:167], v[166:167], v[62:63]
	v_pk_add_f32 v[168:169], v[168:169], v[64:65]
	v_pk_add_f32 v[170:171], v[170:171], v[66:67]
	v_pk_add_f32 v[172:173], v[172:173], v[68:69]
	v_pk_add_f32 v[174:175], v[174:175], v[70:71]
	s_waitcnt vmcnt(4)
	v_pk_add_f32 v[160:161], v[160:161], v[72:73]
	v_pk_add_f32 v[162:163], v[162:163], v[74:75]
	v_pk_add_f32 v[164:165], v[164:165], v[76:77]
	v_pk_add_f32 v[166:167], v[166:167], v[78:79]
	v_pk_add_f32 v[168:169], v[168:169], v[80:81]
	v_pk_add_f32 v[170:171], v[170:171], v[82:83]
	v_pk_add_f32 v[172:173], v[172:173], v[84:85]
	v_pk_add_f32 v[174:175], v[174:175], v[86:87]
	s_waitcnt vmcnt(0)
	v_pk_add_f32 v[160:161], v[160:161], v[88:89]
	v_pk_add_f32 v[162:163], v[162:163], v[90:91]
	v_pk_add_f32 v[164:165], v[164:165], v[92:93]
	v_pk_add_f32 v[166:167], v[166:167], v[94:95]
	v_pk_add_f32 v[168:169], v[168:169], v[96:97]
	v_pk_add_f32 v[170:171], v[170:171], v[98:99]
	v_pk_add_f32 v[172:173], v[172:173], v[100:101]
	v_pk_add_f32 v[174:175], v[174:175], v[102:103]
	v_lshlrev_b32_e32 v144, 16, v0
	v_and_b32_e32 v145, 0xffff0000, v0
	v_lshlrev_b32_e32 v146, 16, v1
	v_and_b32_e32 v147, 0xffff0000, v1
	v_lshlrev_b32_e32 v148, 16, v2
	v_and_b32_e32 v149, 0xffff0000, v2
	v_lshlrev_b32_e32 v150, 16, v3
	v_and_b32_e32 v151, 0xffff0000, v3
	v_lshlrev_b32_e32 v152, 16, v4
	v_and_b32_e32 v153, 0xffff0000, v4
	v_lshlrev_b32_e32 v154, 16, v5
	v_and_b32_e32 v155, 0xffff0000, v5
	v_lshlrev_b32_e32 v156, 16, v6
	v_and_b32_e32 v157, 0xffff0000, v6
	v_lshlrev_b32_e32 v158, 16, v7
	v_and_b32_e32 v159, 0xffff0000, v7
	v_add_u32_e32 v181, 0xc00000, v183
	global_load_dwordx4 v[8:11], v181, s[78:79]
	global_load_dwordx4 v[12:15], v181, s[78:79] offset:16
	global_load_dwordx4 v[16:19], v181, s[78:79] offset:2048
	global_load_dwordx4 v[20:23], v181, s[78:79] offset:2064
	v_add_u32_e32 v181, 0xe00000, v183
	global_load_dwordx4 v[24:27], v181, s[78:79]
	global_load_dwordx4 v[28:31], v181, s[78:79] offset:16
	global_load_dwordx4 v[32:35], v181, s[78:79] offset:2048
	global_load_dwordx4 v[36:39], v181, s[78:79] offset:2064
	v_add_u32_e32 v181, 0x1000000, v183
	global_load_dwordx4 v[40:43], v181, s[78:79]
	global_load_dwordx4 v[44:47], v181, s[78:79] offset:16
	global_load_dwordx4 v[48:51], v181, s[78:79] offset:2048
	global_load_dwordx4 v[52:55], v181, s[78:79] offset:2064
	v_add_u32_e32 v181, 0x1200000, v183
	global_load_dwordx4 v[56:59], v181, s[78:79]
	global_load_dwordx4 v[60:63], v181, s[78:79] offset:16
	global_load_dwordx4 v[64:67], v181, s[78:79] offset:2048
	global_load_dwordx4 v[68:71], v181, s[78:79] offset:2064
	v_add_u32_e32 v181, 0x1400000, v183
	global_load_dwordx4 v[72:75], v181, s[78:79]
	global_load_dwordx4 v[76:79], v181, s[78:79] offset:16
	global_load_dwordx4 v[80:83], v181, s[78:79] offset:2048
	global_load_dwordx4 v[84:87], v181, s[78:79] offset:2064
	s_waitcnt vmcnt(16)
	v_pk_add_f32 v[160:161], v[160:161], v[8:9]
	v_pk_add_f32 v[162:163], v[162:163], v[10:11]
	v_pk_add_f32 v[164:165], v[164:165], v[12:13]
	v_pk_add_f32 v[166:167], v[166:167], v[14:15]
	v_pk_add_f32 v[168:169], v[168:169], v[16:17]
	v_pk_add_f32 v[170:171], v[170:171], v[18:19]
	v_pk_add_f32 v[172:173], v[172:173], v[20:21]
	v_pk_add_f32 v[174:175], v[174:175], v[22:23]
	s_waitcnt vmcnt(12)
	v_pk_add_f32 v[160:161], v[160:161], v[24:25]
	v_pk_add_f32 v[162:163], v[162:163], v[26:27]
	v_pk_add_f32 v[164:165], v[164:165], v[28:29]
	v_pk_add_f32 v[166:167], v[166:167], v[30:31]
	v_pk_add_f32 v[168:169], v[168:169], v[32:33]
	v_pk_add_f32 v[170:171], v[170:171], v[34:35]
	v_pk_add_f32 v[172:173], v[172:173], v[36:37]
	v_pk_add_f32 v[174:175], v[174:175], v[38:39]
	s_waitcnt vmcnt(8)
	v_pk_add_f32 v[160:161], v[160:161], v[40:41]
	v_pk_add_f32 v[162:163], v[162:163], v[42:43]
	v_pk_add_f32 v[164:165], v[164:165], v[44:45]
	v_pk_add_f32 v[166:167], v[166:167], v[46:47]
	v_pk_add_f32 v[168:169], v[168:169], v[48:49]
	v_pk_add_f32 v[170:171], v[170:171], v[50:51]
	v_pk_add_f32 v[172:173], v[172:173], v[52:53]
	v_pk_add_f32 v[174:175], v[174:175], v[54:55]
	s_waitcnt vmcnt(4)
	v_pk_add_f32 v[160:161], v[160:161], v[56:57]
	v_pk_add_f32 v[162:163], v[162:163], v[58:59]
	v_pk_add_f32 v[164:165], v[164:165], v[60:61]
	v_pk_add_f32 v[166:167], v[166:167], v[62:63]
	v_pk_add_f32 v[168:169], v[168:169], v[64:65]
	v_pk_add_f32 v[170:171], v[170:171], v[66:67]
	v_pk_add_f32 v[172:173], v[172:173], v[68:69]
	v_pk_add_f32 v[174:175], v[174:175], v[70:71]
	s_waitcnt vmcnt(0)
	v_pk_add_f32 v[160:161], v[160:161], v[72:73]
	v_pk_add_f32 v[162:163], v[162:163], v[74:75]
	v_pk_add_f32 v[164:165], v[164:165], v[76:77]
	v_pk_add_f32 v[166:167], v[166:167], v[78:79]
	v_pk_add_f32 v[168:169], v[168:169], v[80:81]
	v_pk_add_f32 v[170:171], v[170:171], v[82:83]
	v_pk_add_f32 v[172:173], v[172:173], v[84:85]
	v_pk_add_f32 v[174:175], v[174:175], v[86:87]
	v_pk_mul_f32 v[252:253], v[160:161], v[160:161]
	v_pk_mul_f32 v[254:255], v[162:163], v[162:163]
	v_pk_fma_f32 v[252:253], v[164:165], v[164:165], v[252:253]
	v_pk_fma_f32 v[254:255], v[166:167], v[166:167], v[254:255]
	v_pk_fma_f32 v[252:253], v[168:169], v[168:169], v[252:253]
	v_pk_fma_f32 v[254:255], v[170:171], v[170:171], v[254:255]
	v_pk_fma_f32 v[252:253], v[172:173], v[172:173], v[252:253]
	v_pk_fma_f32 v[254:255], v[174:175], v[174:175], v[254:255]
	v_pk_add_f32 v[252:253], v[252:253], v[254:255]
	s_nop 0
	v_add_f32_e32 v183, v252, v253
	s_nop 1
	v_add_f32_dpp v183, v183, v183 quad_perm:[1,0,3,2] row_mask:0xf bank_mask:0xf bound_ctrl:1
	s_nop 1
	v_add_f32_dpp v183, v183, v183 quad_perm:[2,3,0,1] row_mask:0xf bank_mask:0xf bound_ctrl:1
	s_nop 1
	v_add_f32_dpp v183, v183, v183 row_half_mirror row_mask:0xf bank_mask:0xf bound_ctrl:1
	s_nop 1
	v_add_f32_dpp v183, v183, v183 row_mirror row_mask:0xf bank_mask:0xf bound_ctrl:1
	s_nop 1
	v_readlane_b32 s98, v183, 0
	v_readlane_b32 s99, v183, 16
	v_readlane_b32 s100, v183, 32
	v_readlane_b32 s101, v183, 48
	s_nop 1
	v_mov_b32_e32 v183, s98
	v_add_f32_e32 v183, s99, v183
	v_add_f32_e32 v183, s100, v183
	v_add_f32_e32 v183, s101, v183
	v_fmamk_f32 v183, v183, 0x3a800000, v182
	v_cmp_gt_f32_e32 vcc, 0x800000, v183
	v_mul_f32_e32 v181, 0x4b800000, v183
	s_nop 1
	v_cndmask_b32_e32 v183, v183, v181, vcc
	v_rsq_f32_e32 v183, v183
	s_nop 0
	v_mul_f32_e32 v181, 0x45800000, v183
	v_cndmask_b32_e32 v184, v183, v181, vcc
	v_mov_b32_e32 v185, v184
	v_pk_mul_f32 v[160:161], v[160:161], v[184:185]
	v_pk_mul_f32 v[162:163], v[162:163], v[184:185]
	v_pk_mul_f32 v[164:165], v[164:165], v[184:185]
	v_pk_mul_f32 v[166:167], v[166:167], v[184:185]
	v_pk_mul_f32 v[168:169], v[168:169], v[184:185]
	v_pk_mul_f32 v[170:171], v[170:171], v[184:185]
	v_pk_mul_f32 v[172:173], v[172:173], v[184:185]
	v_pk_mul_f32 v[174:175], v[174:175], v[184:185]
	v_pk_fma_f32 v[144:145], v[160:161], v[128:129], v[144:145]
	v_pk_fma_f32 v[146:147], v[162:163], v[130:131], v[146:147]
	v_pk_fma_f32 v[148:149], v[164:165], v[132:133], v[148:149]
	v_pk_fma_f32 v[150:151], v[166:167], v[134:135], v[150:151]
	v_pk_fma_f32 v[152:153], v[168:169], v[136:137], v[152:153]
	v_pk_fma_f32 v[154:155], v[170:171], v[138:139], v[154:155]
	v_pk_fma_f32 v[156:157], v[172:173], v[140:141], v[156:157]
	v_pk_fma_f32 v[158:159], v[174:175], v[142:143], v[158:159]
	v_pk_mul_f32 v[252:253], v[144:145], v[144:145]
	v_pk_mul_f32 v[254:255], v[146:147], v[146:147]
	v_pk_fma_f32 v[252:253], v[148:149], v[148:149], v[252:253]
	v_pk_fma_f32 v[254:255], v[150:151], v[150:151], v[254:255]
	v_pk_fma_f32 v[252:253], v[152:153], v[152:153], v[252:253]
	v_pk_fma_f32 v[254:255], v[154:155], v[154:155], v[254:255]
	v_pk_fma_f32 v[252:253], v[156:157], v[156:157], v[252:253]
	v_pk_fma_f32 v[254:255], v[158:159], v[158:159], v[254:255]
	v_pk_add_f32 v[252:253], v[252:253], v[254:255]
	s_nop 0
	v_add_f32_e32 v183, v252, v253
	s_nop 1
	v_add_f32_dpp v183, v183, v183 quad_perm:[1,0,3,2] row_mask:0xf bank_mask:0xf bound_ctrl:1
	s_nop 1
	v_add_f32_dpp v183, v183, v183 quad_perm:[2,3,0,1] row_mask:0xf bank_mask:0xf bound_ctrl:1
	s_nop 1
	v_add_f32_dpp v183, v183, v183 row_half_mirror row_mask:0xf bank_mask:0xf bound_ctrl:1
	s_nop 1
	v_add_f32_dpp v183, v183, v183 row_mirror row_mask:0xf bank_mask:0xf bound_ctrl:1
	s_nop 1
	v_readlane_b32 s98, v183, 0
	v_readlane_b32 s99, v183, 16
	v_readlane_b32 s100, v183, 32
	v_readlane_b32 s101, v183, 48
	s_nop 1
	v_mov_b32_e32 v183, s98
	v_add_f32_e32 v183, s99, v183
	v_add_f32_e32 v183, s100, v183
	v_add_f32_e32 v183, s101, v183
	v_fmamk_f32 v183, v183, 0x3a800000, v182
	v_cmp_gt_f32_e32 vcc, 0x800000, v183
	v_mul_f32_e32 v181, 0x4b800000, v183
	s_nop 1
	v_cndmask_b32_e32 v183, v183, v181, vcc
	v_rsq_f32_e32 v183, v183
	s_nop 0
	v_mul_f32_e32 v181, 0x45800000, v183
	v_cndmask_b32_e32 v184, v183, v181, vcc
	v_mov_b32_e32 v185, v184
	v_cvt_pk_bf16_f32 v0, v144, v145
	v_cvt_pk_bf16_f32 v1, v146, v147
	v_cvt_pk_bf16_f32 v2, v148, v149
	v_cvt_pk_bf16_f32 v3, v150, v151
	v_cvt_pk_bf16_f32 v4, v152, v153
	v_cvt_pk_bf16_f32 v5, v154, v155
	v_cvt_pk_bf16_f32 v6, v156, v157
	v_cvt_pk_bf16_f32 v7, v158, v159
	v_add_u32_e32 v181, 0x3800000, v177
	global_store_dwordx4 v181, v[0:3], s[78:79]
	global_store_dwordx4 v181, v[4:7], s[78:79] offset:1024
	v_add_u32_e32 v236, 0x10000, v237
	s_mov_b64 exec, 1
	global_store_dword v236, v184, s[78:79]
	s_mov_b64 exec, -1

.LBB0_1154:
	v_readlane_b32 s0, v235, 52
	v_readlane_b32 s1, v235, 53
	s_and_b64 vcc, exec, s[0:1]
	s_waitcnt lgkmcnt(0)
	s_barrier
	v_mbcnt_lo_u32_b32 v0, -1, 0
	v_mbcnt_hi_u32_b32 v0, -1, v0
	s_cbranch_vccnz .LBB0_1174
	v_lshlrev_b32_e32 v2, 3, v0
	v_ashrrev_i32_e32 v3, 31, v2
	v_readlane_b32 s4, v235, 4
	v_lshlrev_b64 v[4:5], 1, v[2:3]
	v_lshlrev_b64 v[2:3], 2, v[2:3]
	v_readlane_b32 s14, v235, 14
	v_readlane_b32 s15, v235, 15
	v_lshl_add_u64 v[62:63], s[90:91], 0, v[2:3]
	v_readlane_b32 s5, v235, 5
	v_readlane_b32 s6, v235, 6
	v_readlane_b32 s7, v235, 7
	v_readlane_b32 s8, v235, 8
	v_readlane_b32 s9, v235, 9
	v_readlane_b32 s10, v235, 10
	v_readlane_b32 s11, v235, 11
	v_readlane_b32 s12, v235, 12
	v_readlane_b32 s13, v235, 13
	v_readlane_b32 s16, v235, 16
	v_readlane_b32 s17, v235, 17
	v_readlane_b32 s18, v235, 18
	v_readlane_b32 s19, v235, 19
	v_lshl_add_u64 v[2:3], s[14:15], 0, v[2:3]
	s_mov_b64 s[0:1], 0x1000
	v_lshl_add_u64 v[60:61], s[86:87], 0, v[4:5]
	v_lshl_add_u64 v[64:65], s[54:55], 0, v[4:5]
	v_lshl_add_u64 v[66:67], v[2:3], 0, s[0:1]
	s_mov_b32 s1, 0
	v_cmp_eq_u32_e64 s[12:13], 0, v0
	s_mov_b64 s[4:5], 0x200000
	s_mov_b64 s[6:7], 0x200800
	s_mov_b64 s[8:9], 0x400000
	s_mov_b64 s[10:11], 0x400800
	s_mov_b64 s[14:15], 0x600000
	s_mov_b64 s[16:17], 0x600800
	s_mov_b64 s[18:19], 0x800000
	s_mov_b32 s48, 0x800000
	s_mov_b64 s[20:21], 0x800800
	s_mov_b64 s[22:23], 0xa00000
	s_mov_b64 s[24:25], 0xa00800
	s_mov_b64 s[26:27], 0xc00000
	s_mov_b64 s[28:29], 0xc00800
	s_mov_b64 s[36:37], 0xe00000
	s_mov_b64 s[38:39], 0xe00800
	v_mov_b32_e32 v104, 0
	v_mov_b32_e32 v105, 0x358637bd
	v_readlane_b32 s42, v235, 61
	v_readlane_b32 s43, v235, 62
	v_mbcnt_lo_u32_b32 v176, -1, 0
	v_mbcnt_hi_u32_b32 v176, -1, v176
	v_readlane_b32 s98, v235, 49
	v_readlane_b32 s99, v235, 20
	v_readlane_b32 s100, v235, 14
	v_readlane_b32 s101, v235, 15
	s_nop 3
	s_lshr_b32 vcc_lo, s98, 3
	s_and_b32 vcc_hi, vcc_lo, 7
	s_lshr_b32 vcc_lo, vcc_lo, 3
	s_lshl_b32 vcc_lo, vcc_lo, 3
	s_add_i32 vcc_lo, vcc_lo, s99
	s_lshl_b32 s98, vcc_hi, 8
	s_add_i32 s98, s98, vcc_lo
	s_mov_b32 s99, s98
	v_mov_b32_e32 v183, s99
	v_lshlrev_b32_e32 v177, 4, v176
	s_lshl_b32 s99, s99, 11
	v_add_u32_e32 v177, s99, v177
	v_add_u32_e32 v178, 0x1800000, v177
	v_add_u32_e32 v179, 0x9e00000, v177
	v_lshlrev_b32_e32 v180, 5, v176
	v_add_u32_e32 v181, 0x1000, v180
	global_load_dwordx4 v[128:131], v181, s[100:101]
	global_load_dwordx4 v[132:135], v181, s[100:101] offset:16
	global_load_dwordx4 v[136:139], v181, s[100:101] offset:2048
	global_load_dwordx4 v[140:143], v181, s[100:101] offset:2064
	v_mov_b32_e32 v182, 0x358637bd
	global_load_dwordx4 v[0:3], v178, s[78:79]
	global_load_dwordx4 v[4:7], v178, s[78:79] offset:1024
	global_load_dwordx4 v[8:11], v179, s[78:79]
	global_load_dwordx4 v[12:15], v179, s[78:79] offset:1024
	v_add_u32_e32 v178, 0x400000, v178
	v_add_u32_e32 v179, 0x400000, v179
	global_load_dwordx4 v[16:19], v178, s[78:79]
	global_load_dwordx4 v[20:23], v178, s[78:79] offset:1024
	global_load_dwordx4 v[24:27], v179, s[78:79]
	global_load_dwordx4 v[28:31], v179, s[78:79] offset:1024
	v_add_u32_e32 v178, 0x400000, v178
	v_add_u32_e32 v179, 0x400000, v179
	global_load_dwordx4 v[32:35], v178, s[78:79]
	global_load_dwordx4 v[36:39], v178, s[78:79] offset:1024
	global_load_dwordx4 v[40:43], v179, s[78:79]
	global_load_dwordx4 v[44:47], v179, s[78:79] offset:1024
	v_add_u32_e32 v178, 0x400000, v178
	v_add_u32_e32 v179, 0x400000, v179
	global_load_dwordx4 v[48:51], v178, s[78:79]
	global_load_dwordx4 v[52:55], v178, s[78:79] offset:1024
	global_load_dwordx4 v[56:59], v179, s[78:79]
	global_load_dwordx4 v[60:63], v179, s[78:79] offset:1024
	v_add_u32_e32 v178, 0x400000, v178
	v_add_u32_e32 v179, 0x400000, v179
	global_load_dwordx4 v[64:67], v178, s[78:79]
	global_load_dwordx4 v[68:71], v178, s[78:79] offset:1024
	global_load_dwordx4 v[72:75], v179, s[78:79]
	global_load_dwordx4 v[76:79], v179, s[78:79] offset:1024
	v_add_u32_e32 v178, 0x400000, v178
	v_add_u32_e32 v179, 0x400000, v179
	global_load_dwordx4 v[80:83], v178, s[78:79]
	global_load_dwordx4 v[84:87], v178, s[78:79] offset:1024
	global_load_dwordx4 v[88:91], v179, s[78:79]
	global_load_dwordx4 v[92:95], v179, s[78:79] offset:1024
	v_add_u32_e32 v178, 0x400000, v178
	v_add_u32_e32 v179, 0x400000, v179
	global_load_dwordx4 v[96:99], v178, s[78:79]
	global_load_dwordx4 v[100:103], v178, s[78:79] offset:1024
	global_load_dwordx4 v[104:107], v179, s[78:79]
	global_load_dwordx4 v[108:111], v179, s[78:79] offset:1024
	v_add_u32_e32 v178, 0x400000, v178
	v_add_u32_e32 v179, 0x400000, v179
	global_load_dwordx4 v[112:115], v178, s[78:79]
	global_load_dwordx4 v[116:119], v178, s[78:79] offset:1024
	global_load_dwordx4 v[120:123], v179, s[78:79]
	global_load_dwordx4 v[124:127], v179, s[78:79] offset:1024
	v_lshlrev_b32_e32 v237, 2, v183
	v_add_u32_e32 v237, 0x10000, v237
	v_mov_b32_e32 v179, s98
	s_waitcnt vmcnt(28)
	v_lshlrev_b32_e32 v144, 16, v0
	v_and_b32_e32 v145, 0xffff0000, v0
	v_lshlrev_b32_e32 v146, 16, v1
	v_and_b32_e32 v147, 0xffff0000, v1
	v_lshlrev_b32_e32 v148, 16, v2
	v_and_b32_e32 v149, 0xffff0000, v2
	v_lshlrev_b32_e32 v150, 16, v3
	v_and_b32_e32 v151, 0xffff0000, v3
	v_lshlrev_b32_e32 v152, 16, v4
	v_and_b32_e32 v153, 0xffff0000, v4
	v_lshlrev_b32_e32 v154, 16, v5
	v_and_b32_e32 v155, 0xffff0000, v5
	v_lshlrev_b32_e32 v156, 16, v6
	v_and_b32_e32 v157, 0xffff0000, v6
	v_lshlrev_b32_e32 v158, 16, v7
	v_and_b32_e32 v159, 0xffff0000, v7
	v_lshlrev_b32_e32 v160, 16, v8
	v_and_b32_e32 v161, 0xffff0000, v8
	v_lshlrev_b32_e32 v162, 16, v9
	v_and_b32_e32 v163, 0xffff0000, v9
	v_lshlrev_b32_e32 v164, 16, v10
	v_and_b32_e32 v165, 0xffff0000, v10
	v_lshlrev_b32_e32 v166, 16, v11
	v_and_b32_e32 v167, 0xffff0000, v11
	v_lshlrev_b32_e32 v168, 16, v12
	v_and_b32_e32 v169, 0xffff0000, v12
	v_lshlrev_b32_e32 v170, 16, v13
	v_and_b32_e32 v171, 0xffff0000, v13
	v_lshlrev_b32_e32 v172, 16, v14
	v_and_b32_e32 v173, 0xffff0000, v14
	v_lshlrev_b32_e32 v174, 16, v15
	v_and_b32_e32 v175, 0xffff0000, v15
	v_pk_mul_f32 v[252:253], v[160:161], v[160:161]
	v_pk_mul_f32 v[254:255], v[162:163], v[162:163]
	v_pk_fma_f32 v[252:253], v[164:165], v[164:165], v[252:253]
	v_pk_fma_f32 v[254:255], v[166:167], v[166:167], v[254:255]
	v_pk_fma_f32 v[252:253], v[168:169], v[168:169], v[252:253]
	v_pk_fma_f32 v[254:255], v[170:171], v[170:171], v[254:255]
	v_pk_fma_f32 v[252:253], v[172:173], v[172:173], v[252:253]
	v_pk_fma_f32 v[254:255], v[174:175], v[174:175], v[254:255]
	v_pk_add_f32 v[252:253], v[252:253], v[254:255]
	s_nop 0
	v_add_f32_e32 v183, v252, v253
	s_nop 1
	v_add_f32_dpp v183, v183, v183 quad_perm:[1,0,3,2] row_mask:0xf bank_mask:0xf bound_ctrl:1
	s_nop 1
	v_add_f32_dpp v183, v183, v183 quad_perm:[2,3,0,1] row_mask:0xf bank_mask:0xf bound_ctrl:1
	s_nop 1
	v_add_f32_dpp v183, v183, v183 row_half_mirror row_mask:0xf bank_mask:0xf bound_ctrl:1
	s_nop 1
	v_add_f32_dpp v183, v183, v183 row_mirror row_mask:0xf bank_mask:0xf bound_ctrl:1
	s_nop 1
	v_readlane_b32 s98, v183, 0
	v_readlane_b32 s99, v183, 16
	v_readlane_b32 s100, v183, 32
	v_readlane_b32 s101, v183, 48
	s_nop 1
	v_mov_b32_e32 v183, s98
	v_add_f32_e32 v183, s99, v183
	v_add_f32_e32 v183, s100, v183
	v_add_f32_e32 v183, s101, v183
	v_fmamk_f32 v183, v183, 0x3a800000, v182
	v_cmp_gt_f32_e32 vcc, 0x800000, v183
	v_mul_f32_e32 v181, 0x4b800000, v183
	s_nop 1
	v_cndmask_b32_e32 v183, v183, v181, vcc
	v_rsq_f32_e32 v183, v183
	s_nop 0
	v_mul_f32_e32 v181, 0x45800000, v183
	v_cndmask_b32_e32 v184, v183, v181, vcc
	v_mov_b32_e32 v185, v184
	v_pk_mul_f32 v[160:161], v[160:161], v[184:185]
	v_pk_mul_f32 v[162:163], v[162:163], v[184:185]
	v_pk_mul_f32 v[164:165], v[164:165], v[184:185]
	v_pk_mul_f32 v[166:167], v[166:167], v[184:185]
	v_pk_mul_f32 v[168:169], v[168:169], v[184:185]
	v_pk_mul_f32 v[170:171], v[170:171], v[184:185]
	v_pk_mul_f32 v[172:173], v[172:173], v[184:185]
	v_pk_mul_f32 v[174:175], v[174:175], v[184:185]
	v_pk_fma_f32 v[144:145], v[160:161], v[128:129], v[144:145]
	v_pk_fma_f32 v[146:147], v[162:163], v[130:131], v[146:147]
	v_pk_fma_f32 v[148:149], v[164:165], v[132:133], v[148:149]
	v_pk_fma_f32 v[150:151], v[166:167], v[134:135], v[150:151]
	v_pk_fma_f32 v[152:153], v[168:169], v[136:137], v[152:153]
	v_pk_fma_f32 v[154:155], v[170:171], v[138:139], v[154:155]
	v_pk_fma_f32 v[156:157], v[172:173], v[140:141], v[156:157]
	v_pk_fma_f32 v[158:159], v[174:175], v[142:143], v[158:159]
	v_pk_mul_f32 v[252:253], v[144:145], v[144:145]
	v_pk_mul_f32 v[254:255], v[146:147], v[146:147]
	v_pk_fma_f32 v[252:253], v[148:149], v[148:149], v[252:253]
	v_pk_fma_f32 v[254:255], v[150:151], v[150:151], v[254:255]
	v_pk_fma_f32 v[252:253], v[152:153], v[152:153], v[252:253]
	v_pk_fma_f32 v[254:255], v[154:155], v[154:155], v[254:255]
	v_pk_fma_f32 v[252:253], v[156:157], v[156:157], v[252:253]
	v_pk_fma_f32 v[254:255], v[158:159], v[158:159], v[254:255]
	v_pk_add_f32 v[252:253], v[252:253], v[254:255]
	s_nop 0
	v_add_f32_e32 v183, v252, v253
	s_nop 1
	v_add_f32_dpp v183, v183, v183 quad_perm:[1,0,3,2] row_mask:0xf bank_mask:0xf bound_ctrl:1
	s_nop 1
	v_add_f32_dpp v183, v183, v183 quad_perm:[2,3,0,1] row_mask:0xf bank_mask:0xf bound_ctrl:1
	s_nop 1
	v_add_f32_dpp v183, v183, v183 row_half_mirror row_mask:0xf bank_mask:0xf bound_ctrl:1
	s_nop 1
	v_add_f32_dpp v183, v183, v183 row_mirror row_mask:0xf bank_mask:0xf bound_ctrl:1
	s_nop 1
	v_readlane_b32 s98, v183, 0
	v_readlane_b32 s99, v183, 16
	v_readlane_b32 s100, v183, 32
	v_readlane_b32 s101, v183, 48
	s_nop 1
	v_mov_b32_e32 v183, s98
	v_add_f32_e32 v183, s99, v183
	v_add_f32_e32 v183, s100, v183
	v_add_f32_e32 v183, s101, v183
	v_fmamk_f32 v183, v183, 0x3a800000, v182
	v_cmp_gt_f32_e32 vcc, 0x800000, v183
	v_mul_f32_e32 v181, 0x4b800000, v183
	s_nop 1
	v_cndmask_b32_e32 v183, v183, v181, vcc
	v_rsq_f32_e32 v183, v183
	s_nop 0
	v_mul_f32_e32 v181, 0x45800000, v183
	v_cndmask_b32_e32 v184, v183, v181, vcc
	v_mov_b32_e32 v185, v184
	v_cvt_pk_bf16_f32 v0, v144, v145
	v_cvt_pk_bf16_f32 v1, v146, v147
	v_cvt_pk_bf16_f32 v2, v148, v149
	v_cvt_pk_bf16_f32 v3, v150, v151
	v_cvt_pk_bf16_f32 v4, v152, v153
	v_cvt_pk_bf16_f32 v5, v154, v155
	v_cvt_pk_bf16_f32 v6, v156, v157
	v_cvt_pk_bf16_f32 v7, v158, v159
	v_add_u32_e32 v181, 0x1800000, v177
	global_store_dwordx4 v181, v[0:3], s[78:79]
	global_store_dwordx4 v181, v[4:7], s[78:79] offset:1024
	v_add_u32_e32 v236, 0x0, v237
	s_mov_b64 exec, 1
	global_store_dword v236, v184, s[78:79]
	s_mov_b64 exec, -1
	s_waitcnt vmcnt(24)
	v_lshlrev_b32_e32 v144, 16, v16
	v_and_b32_e32 v145, 0xffff0000, v16
	v_lshlrev_b32_e32 v146, 16, v17
	v_and_b32_e32 v147, 0xffff0000, v17
	v_lshlrev_b32_e32 v148, 16, v18
	v_and_b32_e32 v149, 0xffff0000, v18
	v_lshlrev_b32_e32 v150, 16, v19
	v_and_b32_e32 v151, 0xffff0000, v19
	v_lshlrev_b32_e32 v152, 16, v20
	v_and_b32_e32 v153, 0xffff0000, v20
	v_lshlrev_b32_e32 v154, 16, v21
	v_and_b32_e32 v155, 0xffff0000, v21
	v_lshlrev_b32_e32 v156, 16, v22
	v_and_b32_e32 v157, 0xffff0000, v22
	v_lshlrev_b32_e32 v158, 16, v23
	v_and_b32_e32 v159, 0xffff0000, v23
	v_lshlrev_b32_e32 v160, 16, v24
	v_and_b32_e32 v161, 0xffff0000, v24
	v_lshlrev_b32_e32 v162, 16, v25
	v_and_b32_e32 v163, 0xffff0000, v25
	v_lshlrev_b32_e32 v164, 16, v26
	v_and_b32_e32 v165, 0xffff0000, v26
	v_lshlrev_b32_e32 v166, 16, v27
	v_and_b32_e32 v167, 0xffff0000, v27
	v_lshlrev_b32_e32 v168, 16, v28
	v_and_b32_e32 v169, 0xffff0000, v28
	v_lshlrev_b32_e32 v170, 16, v29
	v_and_b32_e32 v171, 0xffff0000, v29
	v_lshlrev_b32_e32 v172, 16, v30
	v_and_b32_e32 v173, 0xffff0000, v30
	v_lshlrev_b32_e32 v174, 16, v31
	v_and_b32_e32 v175, 0xffff0000, v31
	v_pk_mul_f32 v[252:253], v[160:161], v[160:161]
	v_pk_mul_f32 v[254:255], v[162:163], v[162:163]
	v_pk_fma_f32 v[252:253], v[164:165], v[164:165], v[252:253]
	v_pk_fma_f32 v[254:255], v[166:167], v[166:167], v[254:255]
	v_pk_fma_f32 v[252:253], v[168:169], v[168:169], v[252:253]
	v_pk_fma_f32 v[254:255], v[170:171], v[170:171], v[254:255]
	v_pk_fma_f32 v[252:253], v[172:173], v[172:173], v[252:253]
	v_pk_fma_f32 v[254:255], v[174:175], v[174:175], v[254:255]
	v_pk_add_f32 v[252:253], v[252:253], v[254:255]
	s_nop 0
	v_add_f32_e32 v183, v252, v253
	s_nop 1
	v_add_f32_dpp v183, v183, v183 quad_perm:[1,0,3,2] row_mask:0xf bank_mask:0xf bound_ctrl:1
	s_nop 1
	v_add_f32_dpp v183, v183, v183 quad_perm:[2,3,0,1] row_mask:0xf bank_mask:0xf bound_ctrl:1
	s_nop 1
	v_add_f32_dpp v183, v183, v183 row_half_mirror row_mask:0xf bank_mask:0xf bound_ctrl:1
	s_nop 1
	v_add_f32_dpp v183, v183, v183 row_mirror row_mask:0xf bank_mask:0xf bound_ctrl:1
	s_nop 1
	v_readlane_b32 s98, v183, 0
	v_readlane_b32 s99, v183, 16
	v_readlane_b32 s100, v183, 32
	v_readlane_b32 s101, v183, 48
	s_nop 1
	v_mov_b32_e32 v183, s98
	v_add_f32_e32 v183, s99, v183
	v_add_f32_e32 v183, s100, v183
	v_add_f32_e32 v183, s101, v183
	v_fmamk_f32 v183, v183, 0x3a800000, v182
	v_cmp_gt_f32_e32 vcc, 0x800000, v183
	v_mul_f32_e32 v181, 0x4b800000, v183
	s_nop 1
	v_cndmask_b32_e32 v183, v183, v181, vcc
	v_rsq_f32_e32 v183, v183
	s_nop 0
	v_mul_f32_e32 v181, 0x45800000, v183
	v_cndmask_b32_e32 v184, v183, v181, vcc
	v_mov_b32_e32 v185, v184
	v_pk_mul_f32 v[160:161], v[160:161], v[184:185]
	v_pk_mul_f32 v[162:163], v[162:163], v[184:185]
	v_pk_mul_f32 v[164:165], v[164:165], v[184:185]
	v_pk_mul_f32 v[166:167], v[166:167], v[184:185]
	v_pk_mul_f32 v[168:169], v[168:169], v[184:185]
	v_pk_mul_f32 v[170:171], v[170:171], v[184:185]
	v_pk_mul_f32 v[172:173], v[172:173], v[184:185]
	v_pk_mul_f32 v[174:175], v[174:175], v[184:185]
	v_pk_fma_f32 v[144:145], v[160:161], v[128:129], v[144:145]
	v_pk_fma_f32 v[146:147], v[162:163], v[130:131], v[146:147]
	v_pk_fma_f32 v[148:149], v[164:165], v[132:133], v[148:149]
	v_pk_fma_f32 v[150:151], v[166:167], v[134:135], v[150:151]
	v_pk_fma_f32 v[152:153], v[168:169], v[136:137], v[152:153]
	v_pk_fma_f32 v[154:155], v[170:171], v[138:139], v[154:155]
	v_pk_fma_f32 v[156:157], v[172:173], v[140:141], v[156:157]
	v_pk_fma_f32 v[158:159], v[174:175], v[142:143], v[158:159]
	v_pk_mul_f32 v[252:253], v[144:145], v[144:145]
	v_pk_mul_f32 v[254:255], v[146:147], v[146:147]
	v_pk_fma_f32 v[252:253], v[148:149], v[148:149], v[252:253]
	v_pk_fma_f32 v[254:255], v[150:151], v[150:151], v[254:255]
	v_pk_fma_f32 v[252:253], v[152:153], v[152:153], v[252:253]
	v_pk_fma_f32 v[254:255], v[154:155], v[154:155], v[254:255]
	v_pk_fma_f32 v[252:253], v[156:157], v[156:157], v[252:253]
	v_pk_fma_f32 v[254:255], v[158:159], v[158:159], v[254:255]
	v_pk_add_f32 v[252:253], v[252:253], v[254:255]
	s_nop 0
	v_add_f32_e32 v183, v252, v253
	s_nop 1
	v_add_f32_dpp v183, v183, v183 quad_perm:[1,0,3,2] row_mask:0xf bank_mask:0xf bound_ctrl:1
	s_nop 1
	v_add_f32_dpp v183, v183, v183 quad_perm:[2,3,0,1] row_mask:0xf bank_mask:0xf bound_ctrl:1
	s_nop 1
	v_add_f32_dpp v183, v183, v183 row_half_mirror row_mask:0xf bank_mask:0xf bound_ctrl:1
	s_nop 1
	v_add_f32_dpp v183, v183, v183 row_mirror row_mask:0xf bank_mask:0xf bound_ctrl:1
	s_nop 1
	v_readlane_b32 s98, v183, 0
	v_readlane_b32 s99, v183, 16
	v_readlane_b32 s100, v183, 32
	v_readlane_b32 s101, v183, 48
	s_nop 1
	v_mov_b32_e32 v183, s98
	v_add_f32_e32 v183, s99, v183
	v_add_f32_e32 v183, s100, v183
	v_add_f32_e32 v183, s101, v183
	v_fmamk_f32 v183, v183, 0x3a800000, v182
	v_cmp_gt_f32_e32 vcc, 0x800000, v183
	v_mul_f32_e32 v181, 0x4b800000, v183
	s_nop 1
	v_cndmask_b32_e32 v183, v183, v181, vcc
	v_rsq_f32_e32 v183, v183
	s_nop 0
	v_mul_f32_e32 v181, 0x45800000, v183
	v_cndmask_b32_e32 v184, v183, v181, vcc
	v_mov_b32_e32 v185, v184
	v_cvt_pk_bf16_f32 v16, v144, v145
	v_cvt_pk_bf16_f32 v17, v146, v147
	v_cvt_pk_bf16_f32 v18, v148, v149
	v_cvt_pk_bf16_f32 v19, v150, v151
	v_cvt_pk_bf16_f32 v20, v152, v153
	v_cvt_pk_bf16_f32 v21, v154, v155
	v_cvt_pk_bf16_f32 v22, v156, v157
	v_cvt_pk_bf16_f32 v23, v158, v159
	v_add_u32_e32 v181, 0x1c00000, v177
	global_store_dwordx4 v181, v[16:19], s[78:79]
	global_store_dwordx4 v181, v[20:23], s[78:79] offset:1024
	v_add_u32_e32 v236, 0x2000, v237
	s_mov_b64 exec, 1
	global_store_dword v236, v184, s[78:79]
	s_mov_b64 exec, -1
	s_waitcnt vmcnt(20)
	v_lshlrev_b32_e32 v144, 16, v32
	v_and_b32_e32 v145, 0xffff0000, v32
	v_lshlrev_b32_e32 v146, 16, v33
	v_and_b32_e32 v147, 0xffff0000, v33
	v_lshlrev_b32_e32 v148, 16, v34
	v_and_b32_e32 v149, 0xffff0000, v34
	v_lshlrev_b32_e32 v150, 16, v35
	v_and_b32_e32 v151, 0xffff0000, v35
	v_lshlrev_b32_e32 v152, 16, v36
	v_and_b32_e32 v153, 0xffff0000, v36
	v_lshlrev_b32_e32 v154, 16, v37
	v_and_b32_e32 v155, 0xffff0000, v37
	v_lshlrev_b32_e32 v156, 16, v38
	v_and_b32_e32 v157, 0xffff0000, v38
	v_lshlrev_b32_e32 v158, 16, v39
	v_and_b32_e32 v159, 0xffff0000, v39
	v_lshlrev_b32_e32 v160, 16, v40
	v_and_b32_e32 v161, 0xffff0000, v40
	v_lshlrev_b32_e32 v162, 16, v41
	v_and_b32_e32 v163, 0xffff0000, v41
	v_lshlrev_b32_e32 v164, 16, v42
	v_and_b32_e32 v165, 0xffff0000, v42
	v_lshlrev_b32_e32 v166, 16, v43
	v_and_b32_e32 v167, 0xffff0000, v43
	v_lshlrev_b32_e32 v168, 16, v44
	v_and_b32_e32 v169, 0xffff0000, v44
	v_lshlrev_b32_e32 v170, 16, v45
	v_and_b32_e32 v171, 0xffff0000, v45
	v_lshlrev_b32_e32 v172, 16, v46
	v_and_b32_e32 v173, 0xffff0000, v46
	v_lshlrev_b32_e32 v174, 16, v47
	v_and_b32_e32 v175, 0xffff0000, v47
	v_pk_mul_f32 v[252:253], v[160:161], v[160:161]
	v_pk_mul_f32 v[254:255], v[162:163], v[162:163]
	v_pk_fma_f32 v[252:253], v[164:165], v[164:165], v[252:253]
	v_pk_fma_f32 v[254:255], v[166:167], v[166:167], v[254:255]
	v_pk_fma_f32 v[252:253], v[168:169], v[168:169], v[252:253]
	v_pk_fma_f32 v[254:255], v[170:171], v[170:171], v[254:255]
	v_pk_fma_f32 v[252:253], v[172:173], v[172:173], v[252:253]
	v_pk_fma_f32 v[254:255], v[174:175], v[174:175], v[254:255]
	v_pk_add_f32 v[252:253], v[252:253], v[254:255]
	s_nop 0
	v_add_f32_e32 v183, v252, v253
	s_nop 1
	v_add_f32_dpp v183, v183, v183 quad_perm:[1,0,3,2] row_mask:0xf bank_mask:0xf bound_ctrl:1
	s_nop 1
	v_add_f32_dpp v183, v183, v183 quad_perm:[2,3,0,1] row_mask:0xf bank_mask:0xf bound_ctrl:1
	s_nop 1
	v_add_f32_dpp v183, v183, v183 row_half_mirror row_mask:0xf bank_mask:0xf bound_ctrl:1
	s_nop 1
	v_add_f32_dpp v183, v183, v183 row_mirror row_mask:0xf bank_mask:0xf bound_ctrl:1
	s_nop 1
	v_readlane_b32 s98, v183, 0
	v_readlane_b32 s99, v183, 16
	v_readlane_b32 s100, v183, 32
	v_readlane_b32 s101, v183, 48
	s_nop 1
	v_mov_b32_e32 v183, s98
	v_add_f32_e32 v183, s99, v183
	v_add_f32_e32 v183, s100, v183
	v_add_f32_e32 v183, s101, v183
	v_fmamk_f32 v183, v183, 0x3a800000, v182
	v_cmp_gt_f32_e32 vcc, 0x800000, v183
	v_mul_f32_e32 v181, 0x4b800000, v183
	s_nop 1
	v_cndmask_b32_e32 v183, v183, v181, vcc
	v_rsq_f32_e32 v183, v183
	s_nop 0
	v_mul_f32_e32 v181, 0x45800000, v183
	v_cndmask_b32_e32 v184, v183, v181, vcc
	v_mov_b32_e32 v185, v184
	v_pk_mul_f32 v[160:161], v[160:161], v[184:185]
	v_pk_mul_f32 v[162:163], v[162:163], v[184:185]
	v_pk_mul_f32 v[164:165], v[164:165], v[184:185]
	v_pk_mul_f32 v[166:167], v[166:167], v[184:185]
	v_pk_mul_f32 v[168:169], v[168:169], v[184:185]
	v_pk_mul_f32 v[170:171], v[170:171], v[184:185]
	v_pk_mul_f32 v[172:173], v[172:173], v[184:185]
	v_pk_mul_f32 v[174:175], v[174:175], v[184:185]
	v_pk_fma_f32 v[144:145], v[160:161], v[128:129], v[144:145]
	v_pk_fma_f32 v[146:147], v[162:163], v[130:131], v[146:147]
	v_pk_fma_f32 v[148:149], v[164:165], v[132:133], v[148:149]
	v_pk_fma_f32 v[150:151], v[166:167], v[134:135], v[150:151]
	v_pk_fma_f32 v[152:153], v[168:169], v[136:137], v[152:153]
	v_pk_fma_f32 v[154:155], v[170:171], v[138:139], v[154:155]
	v_pk_fma_f32 v[156:157], v[172:173], v[140:141], v[156:157]
	v_pk_fma_f32 v[158:159], v[174:175], v[142:143], v[158:159]
	v_pk_mul_f32 v[252:253], v[144:145], v[144:145]
	v_pk_mul_f32 v[254:255], v[146:147], v[146:147]
	v_pk_fma_f32 v[252:253], v[148:149], v[148:149], v[252:253]
	v_pk_fma_f32 v[254:255], v[150:151], v[150:151], v[254:255]
	v_pk_fma_f32 v[252:253], v[152:153], v[152:153], v[252:253]
	v_pk_fma_f32 v[254:255], v[154:155], v[154:155], v[254:255]
	v_pk_fma_f32 v[252:253], v[156:157], v[156:157], v[252:253]
	v_pk_fma_f32 v[254:255], v[158:159], v[158:159], v[254:255]
	v_pk_add_f32 v[252:253], v[252:253], v[254:255]
	s_nop 0
	v_add_f32_e32 v183, v252, v253
	s_nop 1
	v_add_f32_dpp v183, v183, v183 quad_perm:[1,0,3,2] row_mask:0xf bank_mask:0xf bound_ctrl:1
	s_nop 1
	v_add_f32_dpp v183, v183, v183 quad_perm:[2,3,0,1] row_mask:0xf bank_mask:0xf bound_ctrl:1
	s_nop 1
	v_add_f32_dpp v183, v183, v183 row_half_mirror row_mask:0xf bank_mask:0xf bound_ctrl:1
	s_nop 1
	v_add_f32_dpp v183, v183, v183 row_mirror row_mask:0xf bank_mask:0xf bound_ctrl:1
	s_nop 1
	v_readlane_b32 s98, v183, 0
	v_readlane_b32 s99, v183, 16
	v_readlane_b32 s100, v183, 32
	v_readlane_b32 s101, v183, 48
	s_nop 1
	v_mov_b32_e32 v183, s98
	v_add_f32_e32 v183, s99, v183
	v_add_f32_e32 v183, s100, v183
	v_add_f32_e32 v183, s101, v183
	v_fmamk_f32 v183, v183, 0x3a800000, v182
	v_cmp_gt_f32_e32 vcc, 0x800000, v183
	v_mul_f32_e32 v181, 0x4b800000, v183
	s_nop 1
	v_cndmask_b32_e32 v183, v183, v181, vcc
	v_rsq_f32_e32 v183, v183
	s_nop 0
	v_mul_f32_e32 v181, 0x45800000, v183
	v_cndmask_b32_e32 v184, v183, v181, vcc
	v_mov_b32_e32 v185, v184
	v_cvt_pk_bf16_f32 v32, v144, v145
	v_cvt_pk_bf16_f32 v33, v146, v147
	v_cvt_pk_bf16_f32 v34, v148, v149
	v_cvt_pk_bf16_f32 v35, v150, v151
	v_cvt_pk_bf16_f32 v36, v152, v153
	v_cvt_pk_bf16_f32 v37, v154, v155
	v_cvt_pk_bf16_f32 v38, v156, v157
	v_cvt_pk_bf16_f32 v39, v158, v159
	v_add_u32_e32 v181, 0x2000000, v177
	global_store_dwordx4 v181, v[32:35], s[78:79]
	global_store_dwordx4 v181, v[36:39], s[78:79] offset:1024
	v_add_u32_e32 v236, 0x4000, v237
	s_mov_b64 exec, 1
	global_store_dword v236, v184, s[78:79]
	s_mov_b64 exec, -1
	s_waitcnt vmcnt(16)
	v_lshlrev_b32_e32 v144, 16, v48
	v_and_b32_e32 v145, 0xffff0000, v48
	v_lshlrev_b32_e32 v146, 16, v49
	v_and_b32_e32 v147, 0xffff0000, v49
	v_lshlrev_b32_e32 v148, 16, v50
	v_and_b32_e32 v149, 0xffff0000, v50
	v_lshlrev_b32_e32 v150, 16, v51
	v_and_b32_e32 v151, 0xffff0000, v51
	v_lshlrev_b32_e32 v152, 16, v52
	v_and_b32_e32 v153, 0xffff0000, v52
	v_lshlrev_b32_e32 v154, 16, v53
	v_and_b32_e32 v155, 0xffff0000, v53
	v_lshlrev_b32_e32 v156, 16, v54
	v_and_b32_e32 v157, 0xffff0000, v54
	v_lshlrev_b32_e32 v158, 16, v55
	v_and_b32_e32 v159, 0xffff0000, v55
	v_lshlrev_b32_e32 v160, 16, v56
	v_and_b32_e32 v161, 0xffff0000, v56
	v_lshlrev_b32_e32 v162, 16, v57
	v_and_b32_e32 v163, 0xffff0000, v57
	v_lshlrev_b32_e32 v164, 16, v58
	v_and_b32_e32 v165, 0xffff0000, v58
	v_lshlrev_b32_e32 v166, 16, v59
	v_and_b32_e32 v167, 0xffff0000, v59
	v_lshlrev_b32_e32 v168, 16, v60
	v_and_b32_e32 v169, 0xffff0000, v60
	v_lshlrev_b32_e32 v170, 16, v61
	v_and_b32_e32 v171, 0xffff0000, v61
	v_lshlrev_b32_e32 v172, 16, v62
	v_and_b32_e32 v173, 0xffff0000, v62
	v_lshlrev_b32_e32 v174, 16, v63
	v_and_b32_e32 v175, 0xffff0000, v63
	v_pk_mul_f32 v[252:253], v[160:161], v[160:161]
	v_pk_mul_f32 v[254:255], v[162:163], v[162:163]
	v_pk_fma_f32 v[252:253], v[164:165], v[164:165], v[252:253]
	v_pk_fma_f32 v[254:255], v[166:167], v[166:167], v[254:255]
	v_pk_fma_f32 v[252:253], v[168:169], v[168:169], v[252:253]
	v_pk_fma_f32 v[254:255], v[170:171], v[170:171], v[254:255]
	v_pk_fma_f32 v[252:253], v[172:173], v[172:173], v[252:253]
	v_pk_fma_f32 v[254:255], v[174:175], v[174:175], v[254:255]
	v_pk_add_f32 v[252:253], v[252:253], v[254:255]
	s_nop 0
	v_add_f32_e32 v183, v252, v253
	s_nop 1
	v_add_f32_dpp v183, v183, v183 quad_perm:[1,0,3,2] row_mask:0xf bank_mask:0xf bound_ctrl:1
	s_nop 1
	v_add_f32_dpp v183, v183, v183 quad_perm:[2,3,0,1] row_mask:0xf bank_mask:0xf bound_ctrl:1
	s_nop 1
	v_add_f32_dpp v183, v183, v183 row_half_mirror row_mask:0xf bank_mask:0xf bound_ctrl:1
	s_nop 1
	v_add_f32_dpp v183, v183, v183 row_mirror row_mask:0xf bank_mask:0xf bound_ctrl:1
	s_nop 1
	v_readlane_b32 s98, v183, 0
	v_readlane_b32 s99, v183, 16
	v_readlane_b32 s100, v183, 32
	v_readlane_b32 s101, v183, 48
	s_nop 1
	v_mov_b32_e32 v183, s98
	v_add_f32_e32 v183, s99, v183
	v_add_f32_e32 v183, s100, v183
	v_add_f32_e32 v183, s101, v183
	v_fmamk_f32 v183, v183, 0x3a800000, v182
	v_cmp_gt_f32_e32 vcc, 0x800000, v183
	v_mul_f32_e32 v181, 0x4b800000, v183
	s_nop 1
	v_cndmask_b32_e32 v183, v183, v181, vcc
	v_rsq_f32_e32 v183, v183
	s_nop 0
	v_mul_f32_e32 v181, 0x45800000, v183
	v_cndmask_b32_e32 v184, v183, v181, vcc
	v_mov_b32_e32 v185, v184
	v_pk_mul_f32 v[160:161], v[160:161], v[184:185]
	v_pk_mul_f32 v[162:163], v[162:163], v[184:185]
	v_pk_mul_f32 v[164:165], v[164:165], v[184:185]
	v_pk_mul_f32 v[166:167], v[166:167], v[184:185]
	v_pk_mul_f32 v[168:169], v[168:169], v[184:185]
	v_pk_mul_f32 v[170:171], v[170:171], v[184:185]
	v_pk_mul_f32 v[172:173], v[172:173], v[184:185]
	v_pk_mul_f32 v[174:175], v[174:175], v[184:185]
	v_pk_fma_f32 v[144:145], v[160:161], v[128:129], v[144:145]
	v_pk_fma_f32 v[146:147], v[162:163], v[130:131], v[146:147]
	v_pk_fma_f32 v[148:149], v[164:165], v[132:133], v[148:149]
	v_pk_fma_f32 v[150:151], v[166:167], v[134:135], v[150:151]
	v_pk_fma_f32 v[152:153], v[168:169], v[136:137], v[152:153]
	v_pk_fma_f32 v[154:155], v[170:171], v[138:139], v[154:155]
	v_pk_fma_f32 v[156:157], v[172:173], v[140:141], v[156:157]
	v_pk_fma_f32 v[158:159], v[174:175], v[142:143], v[158:159]
	v_pk_mul_f32 v[252:253], v[144:145], v[144:145]
	v_pk_mul_f32 v[254:255], v[146:147], v[146:147]
	v_pk_fma_f32 v[252:253], v[148:149], v[148:149], v[252:253]
	v_pk_fma_f32 v[254:255], v[150:151], v[150:151], v[254:255]
	v_pk_fma_f32 v[252:253], v[152:153], v[152:153], v[252:253]
	v_pk_fma_f32 v[254:255], v[154:155], v[154:155], v[254:255]
	v_pk_fma_f32 v[252:253], v[156:157], v[156:157], v[252:253]
	v_pk_fma_f32 v[254:255], v[158:159], v[158:159], v[254:255]
	v_pk_add_f32 v[252:253], v[252:253], v[254:255]
	s_nop 0
	v_add_f32_e32 v183, v252, v253
	s_nop 1
	v_add_f32_dpp v183, v183, v183 quad_perm:[1,0,3,2] row_mask:0xf bank_mask:0xf bound_ctrl:1
	s_nop 1
	v_add_f32_dpp v183, v183, v183 quad_perm:[2,3,0,1] row_mask:0xf bank_mask:0xf bound_ctrl:1
	s_nop 1
	v_add_f32_dpp v183, v183, v183 row_half_mirror row_mask:0xf bank_mask:0xf bound_ctrl:1
	s_nop 1
	v_add_f32_dpp v183, v183, v183 row_mirror row_mask:0xf bank_mask:0xf bound_ctrl:1
	s_nop 1
	v_readlane_b32 s98, v183, 0
	v_readlane_b32 s99, v183, 16
	v_readlane_b32 s100, v183, 32
	v_readlane_b32 s101, v183, 48
	s_nop 1
	v_mov_b32_e32 v183, s98
	v_add_f32_e32 v183, s99, v183
	v_add_f32_e32 v183, s100, v183
	v_add_f32_e32 v183, s101, v183
	v_fmamk_f32 v183, v183, 0x3a800000, v182
	v_cmp_gt_f32_e32 vcc, 0x800000, v183
	v_mul_f32_e32 v181, 0x4b800000, v183
	s_nop 1
	v_cndmask_b32_e32 v183, v183, v181, vcc
	v_rsq_f32_e32 v183, v183
	s_nop 0
	v_mul_f32_e32 v181, 0x45800000, v183
	v_cndmask_b32_e32 v184, v183, v181, vcc
	v_mov_b32_e32 v185, v184
	v_cvt_pk_bf16_f32 v48, v144, v145
	v_cvt_pk_bf16_f32 v49, v146, v147
	v_cvt_pk_bf16_f32 v50, v148, v149
	v_cvt_pk_bf16_f32 v51, v150, v151
	v_cvt_pk_bf16_f32 v52, v152, v153
	v_cvt_pk_bf16_f32 v53, v154, v155
	v_cvt_pk_bf16_f32 v54, v156, v157
	v_cvt_pk_bf16_f32 v55, v158, v159
	v_add_u32_e32 v181, 0x2400000, v177
	global_store_dwordx4 v181, v[48:51], s[78:79]
	global_store_dwordx4 v181, v[52:55], s[78:79] offset:1024
	v_add_u32_e32 v236, 0x6000, v237
	s_mov_b64 exec, 1
	global_store_dword v236, v184, s[78:79]
	s_mov_b64 exec, -1
	s_waitcnt vmcnt(12)
	v_lshlrev_b32_e32 v144, 16, v64
	v_and_b32_e32 v145, 0xffff0000, v64
	v_lshlrev_b32_e32 v146, 16, v65
	v_and_b32_e32 v147, 0xffff0000, v65
	v_lshlrev_b32_e32 v148, 16, v66
	v_and_b32_e32 v149, 0xffff0000, v66
	v_lshlrev_b32_e32 v150, 16, v67
	v_and_b32_e32 v151, 0xffff0000, v67
	v_lshlrev_b32_e32 v152, 16, v68
	v_and_b32_e32 v153, 0xffff0000, v68
	v_lshlrev_b32_e32 v154, 16, v69
	v_and_b32_e32 v155, 0xffff0000, v69
	v_lshlrev_b32_e32 v156, 16, v70
	v_and_b32_e32 v157, 0xffff0000, v70
	v_lshlrev_b32_e32 v158, 16, v71
	v_and_b32_e32 v159, 0xffff0000, v71
	v_lshlrev_b32_e32 v160, 16, v72
	v_and_b32_e32 v161, 0xffff0000, v72
	v_lshlrev_b32_e32 v162, 16, v73
	v_and_b32_e32 v163, 0xffff0000, v73
	v_lshlrev_b32_e32 v164, 16, v74
	v_and_b32_e32 v165, 0xffff0000, v74
	v_lshlrev_b32_e32 v166, 16, v75
	v_and_b32_e32 v167, 0xffff0000, v75
	v_lshlrev_b32_e32 v168, 16, v76
	v_and_b32_e32 v169, 0xffff0000, v76
	v_lshlrev_b32_e32 v170, 16, v77
	v_and_b32_e32 v171, 0xffff0000, v77
	v_lshlrev_b32_e32 v172, 16, v78
	v_and_b32_e32 v173, 0xffff0000, v78
	v_lshlrev_b32_e32 v174, 16, v79
	v_and_b32_e32 v175, 0xffff0000, v79
	v_pk_mul_f32 v[252:253], v[160:161], v[160:161]
	v_pk_mul_f32 v[254:255], v[162:163], v[162:163]
	v_pk_fma_f32 v[252:253], v[164:165], v[164:165], v[252:253]
	v_pk_fma_f32 v[254:255], v[166:167], v[166:167], v[254:255]
	v_pk_fma_f32 v[252:253], v[168:169], v[168:169], v[252:253]
	v_pk_fma_f32 v[254:255], v[170:171], v[170:171], v[254:255]
	v_pk_fma_f32 v[252:253], v[172:173], v[172:173], v[252:253]
	v_pk_fma_f32 v[254:255], v[174:175], v[174:175], v[254:255]
	v_pk_add_f32 v[252:253], v[252:253], v[254:255]
	s_nop 0
	v_add_f32_e32 v183, v252, v253
	s_nop 1
	v_add_f32_dpp v183, v183, v183 quad_perm:[1,0,3,2] row_mask:0xf bank_mask:0xf bound_ctrl:1
	s_nop 1
	v_add_f32_dpp v183, v183, v183 quad_perm:[2,3,0,1] row_mask:0xf bank_mask:0xf bound_ctrl:1
	s_nop 1
	v_add_f32_dpp v183, v183, v183 row_half_mirror row_mask:0xf bank_mask:0xf bound_ctrl:1
	s_nop 1
	v_add_f32_dpp v183, v183, v183 row_mirror row_mask:0xf bank_mask:0xf bound_ctrl:1
	s_nop 1
	v_readlane_b32 s98, v183, 0
	v_readlane_b32 s99, v183, 16
	v_readlane_b32 s100, v183, 32
	v_readlane_b32 s101, v183, 48
	s_nop 1
	v_mov_b32_e32 v183, s98
	v_add_f32_e32 v183, s99, v183
	v_add_f32_e32 v183, s100, v183
	v_add_f32_e32 v183, s101, v183
	v_fmamk_f32 v183, v183, 0x3a800000, v182
	v_cmp_gt_f32_e32 vcc, 0x800000, v183
	v_mul_f32_e32 v181, 0x4b800000, v183
	s_nop 1
	v_cndmask_b32_e32 v183, v183, v181, vcc
	v_rsq_f32_e32 v183, v183
	s_nop 0
	v_mul_f32_e32 v181, 0x45800000, v183
	v_cndmask_b32_e32 v184, v183, v181, vcc
	v_mov_b32_e32 v185, v184
	v_pk_mul_f32 v[160:161], v[160:161], v[184:185]
	v_pk_mul_f32 v[162:163], v[162:163], v[184:185]
	v_pk_mul_f32 v[164:165], v[164:165], v[184:185]
	v_pk_mul_f32 v[166:167], v[166:167], v[184:185]
	v_pk_mul_f32 v[168:169], v[168:169], v[184:185]
	v_pk_mul_f32 v[170:171], v[170:171], v[184:185]
	v_pk_mul_f32 v[172:173], v[172:173], v[184:185]
	v_pk_mul_f32 v[174:175], v[174:175], v[184:185]
	v_pk_fma_f32 v[144:145], v[160:161], v[128:129], v[144:145]
	v_pk_fma_f32 v[146:147], v[162:163], v[130:131], v[146:147]
	v_pk_fma_f32 v[148:149], v[164:165], v[132:133], v[148:149]
	v_pk_fma_f32 v[150:151], v[166:167], v[134:135], v[150:151]
	v_pk_fma_f32 v[152:153], v[168:169], v[136:137], v[152:153]
	v_pk_fma_f32 v[154:155], v[170:171], v[138:139], v[154:155]
	v_pk_fma_f32 v[156:157], v[172:173], v[140:141], v[156:157]
	v_pk_fma_f32 v[158:159], v[174:175], v[142:143], v[158:159]
	v_pk_mul_f32 v[252:253], v[144:145], v[144:145]
	v_pk_mul_f32 v[254:255], v[146:147], v[146:147]
	v_pk_fma_f32 v[252:253], v[148:149], v[148:149], v[252:253]
	v_pk_fma_f32 v[254:255], v[150:151], v[150:151], v[254:255]
	v_pk_fma_f32 v[252:253], v[152:153], v[152:153], v[252:253]
	v_pk_fma_f32 v[254:255], v[154:155], v[154:155], v[254:255]
	v_pk_fma_f32 v[252:253], v[156:157], v[156:157], v[252:253]
	v_pk_fma_f32 v[254:255], v[158:159], v[158:159], v[254:255]
	v_pk_add_f32 v[252:253], v[252:253], v[254:255]
	s_nop 0
	v_add_f32_e32 v183, v252, v253
	s_nop 1
	v_add_f32_dpp v183, v183, v183 quad_perm:[1,0,3,2] row_mask:0xf bank_mask:0xf bound_ctrl:1
	s_nop 1
	v_add_f32_dpp v183, v183, v183 quad_perm:[2,3,0,1] row_mask:0xf bank_mask:0xf bound_ctrl:1
	s_nop 1
	v_add_f32_dpp v183, v183, v183 row_half_mirror row_mask:0xf bank_mask:0xf bound_ctrl:1
	s_nop 1
	v_add_f32_dpp v183, v183, v183 row_mirror row_mask:0xf bank_mask:0xf bound_ctrl:1
	s_nop 1
	v_readlane_b32 s98, v183, 0
	v_readlane_b32 s99, v183, 16
	v_readlane_b32 s100, v183, 32
	v_readlane_b32 s101, v183, 48
	s_nop 1
	v_mov_b32_e32 v183, s98
	v_add_f32_e32 v183, s99, v183
	v_add_f32_e32 v183, s100, v183
	v_add_f32_e32 v183, s101, v183
	v_fmamk_f32 v183, v183, 0x3a800000, v182
	v_cmp_gt_f32_e32 vcc, 0x800000, v183
	v_mul_f32_e32 v181, 0x4b800000, v183
	s_nop 1
	v_cndmask_b32_e32 v183, v183, v181, vcc
	v_rsq_f32_e32 v183, v183
	s_nop 0
	v_mul_f32_e32 v181, 0x45800000, v183
	v_cndmask_b32_e32 v184, v183, v181, vcc
	v_mov_b32_e32 v185, v184
	v_cvt_pk_bf16_f32 v64, v144, v145
	v_cvt_pk_bf16_f32 v65, v146, v147
	v_cvt_pk_bf16_f32 v66, v148, v149
	v_cvt_pk_bf16_f32 v67, v150, v151
	v_cvt_pk_bf16_f32 v68, v152, v153
	v_cvt_pk_bf16_f32 v69, v154, v155
	v_cvt_pk_bf16_f32 v70, v156, v157
	v_cvt_pk_bf16_f32 v71, v158, v159
	v_add_u32_e32 v181, 0x2800000, v177
	global_store_dwordx4 v181, v[64:67], s[78:79]
	global_store_dwordx4 v181, v[68:71], s[78:79] offset:1024
	v_add_u32_e32 v236, 0x8000, v237
	s_mov_b64 exec, 1
	global_store_dword v236, v184, s[78:79]
	s_mov_b64 exec, -1
	s_waitcnt vmcnt(8)
	v_lshlrev_b32_e32 v144, 16, v80
	v_and_b32_e32 v145, 0xffff0000, v80
	v_lshlrev_b32_e32 v146, 16, v81
	v_and_b32_e32 v147, 0xffff0000, v81
	v_lshlrev_b32_e32 v148, 16, v82
	v_and_b32_e32 v149, 0xffff0000, v82
	v_lshlrev_b32_e32 v150, 16, v83
	v_and_b32_e32 v151, 0xffff0000, v83
	v_lshlrev_b32_e32 v152, 16, v84
	v_and_b32_e32 v153, 0xffff0000, v84
	v_lshlrev_b32_e32 v154, 16, v85
	v_and_b32_e32 v155, 0xffff0000, v85
	v_lshlrev_b32_e32 v156, 16, v86
	v_and_b32_e32 v157, 0xffff0000, v86
	v_lshlrev_b32_e32 v158, 16, v87
	v_and_b32_e32 v159, 0xffff0000, v87
	v_lshlrev_b32_e32 v160, 16, v88
	v_and_b32_e32 v161, 0xffff0000, v88
	v_lshlrev_b32_e32 v162, 16, v89
	v_and_b32_e32 v163, 0xffff0000, v89
	v_lshlrev_b32_e32 v164, 16, v90
	v_and_b32_e32 v165, 0xffff0000, v90
	v_lshlrev_b32_e32 v166, 16, v91
	v_and_b32_e32 v167, 0xffff0000, v91
	v_lshlrev_b32_e32 v168, 16, v92
	v_and_b32_e32 v169, 0xffff0000, v92
	v_lshlrev_b32_e32 v170, 16, v93
	v_and_b32_e32 v171, 0xffff0000, v93
	v_lshlrev_b32_e32 v172, 16, v94
	v_and_b32_e32 v173, 0xffff0000, v94
	v_lshlrev_b32_e32 v174, 16, v95
	v_and_b32_e32 v175, 0xffff0000, v95
	v_pk_mul_f32 v[252:253], v[160:161], v[160:161]
	v_pk_mul_f32 v[254:255], v[162:163], v[162:163]
	v_pk_fma_f32 v[252:253], v[164:165], v[164:165], v[252:253]
	v_pk_fma_f32 v[254:255], v[166:167], v[166:167], v[254:255]
	v_pk_fma_f32 v[252:253], v[168:169], v[168:169], v[252:253]
	v_pk_fma_f32 v[254:255], v[170:171], v[170:171], v[254:255]
	v_pk_fma_f32 v[252:253], v[172:173], v[172:173], v[252:253]
	v_pk_fma_f32 v[254:255], v[174:175], v[174:175], v[254:255]
	v_pk_add_f32 v[252:253], v[252:253], v[254:255]
	s_nop 0
	v_add_f32_e32 v183, v252, v253
	s_nop 1
	v_add_f32_dpp v183, v183, v183 quad_perm:[1,0,3,2] row_mask:0xf bank_mask:0xf bound_ctrl:1
	s_nop 1
	v_add_f32_dpp v183, v183, v183 quad_perm:[2,3,0,1] row_mask:0xf bank_mask:0xf bound_ctrl:1
	s_nop 1
	v_add_f32_dpp v183, v183, v183 row_half_mirror row_mask:0xf bank_mask:0xf bound_ctrl:1
	s_nop 1
	v_add_f32_dpp v183, v183, v183 row_mirror row_mask:0xf bank_mask:0xf bound_ctrl:1
	s_nop 1
	v_readlane_b32 s98, v183, 0
	v_readlane_b32 s99, v183, 16
	v_readlane_b32 s100, v183, 32
	v_readlane_b32 s101, v183, 48
	s_nop 1
	v_mov_b32_e32 v183, s98
	v_add_f32_e32 v183, s99, v183
	v_add_f32_e32 v183, s100, v183
	v_add_f32_e32 v183, s101, v183
	v_fmamk_f32 v183, v183, 0x3a800000, v182
	v_cmp_gt_f32_e32 vcc, 0x800000, v183
	v_mul_f32_e32 v181, 0x4b800000, v183
	s_nop 1
	v_cndmask_b32_e32 v183, v183, v181, vcc
	v_rsq_f32_e32 v183, v183
	s_nop 0
	v_mul_f32_e32 v181, 0x45800000, v183
	v_cndmask_b32_e32 v184, v183, v181, vcc
	v_mov_b32_e32 v185, v184
	v_pk_mul_f32 v[160:161], v[160:161], v[184:185]
	v_pk_mul_f32 v[162:163], v[162:163], v[184:185]
	v_pk_mul_f32 v[164:165], v[164:165], v[184:185]
	v_pk_mul_f32 v[166:167], v[166:167], v[184:185]
	v_pk_mul_f32 v[168:169], v[168:169], v[184:185]
	v_pk_mul_f32 v[170:171], v[170:171], v[184:185]
	v_pk_mul_f32 v[172:173], v[172:173], v[184:185]
	v_pk_mul_f32 v[174:175], v[174:175], v[184:185]
	v_pk_fma_f32 v[144:145], v[160:161], v[128:129], v[144:145]
	v_pk_fma_f32 v[146:147], v[162:163], v[130:131], v[146:147]
	v_pk_fma_f32 v[148:149], v[164:165], v[132:133], v[148:149]
	v_pk_fma_f32 v[150:151], v[166:167], v[134:135], v[150:151]
	v_pk_fma_f32 v[152:153], v[168:169], v[136:137], v[152:153]
	v_pk_fma_f32 v[154:155], v[170:171], v[138:139], v[154:155]
	v_pk_fma_f32 v[156:157], v[172:173], v[140:141], v[156:157]
	v_pk_fma_f32 v[158:159], v[174:175], v[142:143], v[158:159]
	v_pk_mul_f32 v[252:253], v[144:145], v[144:145]
	v_pk_mul_f32 v[254:255], v[146:147], v[146:147]
	v_pk_fma_f32 v[252:253], v[148:149], v[148:149], v[252:253]
	v_pk_fma_f32 v[254:255], v[150:151], v[150:151], v[254:255]
	v_pk_fma_f32 v[252:253], v[152:153], v[152:153], v[252:253]
	v_pk_fma_f32 v[254:255], v[154:155], v[154:155], v[254:255]
	v_pk_fma_f32 v[252:253], v[156:157], v[156:157], v[252:253]
	v_pk_fma_f32 v[254:255], v[158:159], v[158:159], v[254:255]
	v_pk_add_f32 v[252:253], v[252:253], v[254:255]
	s_nop 0
	v_add_f32_e32 v183, v252, v253
	s_nop 1
	v_add_f32_dpp v183, v183, v183 quad_perm:[1,0,3,2] row_mask:0xf bank_mask:0xf bound_ctrl:1
	s_nop 1
	v_add_f32_dpp v183, v183, v183 quad_perm:[2,3,0,1] row_mask:0xf bank_mask:0xf bound_ctrl:1
	s_nop 1
	v_add_f32_dpp v183, v183, v183 row_half_mirror row_mask:0xf bank_mask:0xf bound_ctrl:1
	s_nop 1
	v_add_f32_dpp v183, v183, v183 row_mirror row_mask:0xf bank_mask:0xf bound_ctrl:1
	s_nop 1
	v_readlane_b32 s98, v183, 0
	v_readlane_b32 s99, v183, 16
	v_readlane_b32 s100, v183, 32
	v_readlane_b32 s101, v183, 48
	s_nop 1
	v_mov_b32_e32 v183, s98
	v_add_f32_e32 v183, s99, v183
	v_add_f32_e32 v183, s100, v183
	v_add_f32_e32 v183, s101, v183
	v_fmamk_f32 v183, v183, 0x3a800000, v182
	v_cmp_gt_f32_e32 vcc, 0x800000, v183
	v_mul_f32_e32 v181, 0x4b800000, v183
	s_nop 1
	v_cndmask_b32_e32 v183, v183, v181, vcc
	v_rsq_f32_e32 v183, v183
	s_nop 0
	v_mul_f32_e32 v181, 0x45800000, v183
	v_cndmask_b32_e32 v184, v183, v181, vcc
	v_mov_b32_e32 v185, v184
	v_cvt_pk_bf16_f32 v80, v144, v145
	v_cvt_pk_bf16_f32 v81, v146, v147
	v_cvt_pk_bf16_f32 v82, v148, v149
	v_cvt_pk_bf16_f32 v83, v150, v151
	v_cvt_pk_bf16_f32 v84, v152, v153
	v_cvt_pk_bf16_f32 v85, v154, v155
	v_cvt_pk_bf16_f32 v86, v156, v157
	v_cvt_pk_bf16_f32 v87, v158, v159
	v_add_u32_e32 v181, 0x2c00000, v177
	global_store_dwordx4 v181, v[80:83], s[78:79]
	global_store_dwordx4 v181, v[84:87], s[78:79] offset:1024
	v_add_u32_e32 v236, 0xa000, v237
	s_mov_b64 exec, 1
	global_store_dword v236, v184, s[78:79]
	s_mov_b64 exec, -1
	s_waitcnt vmcnt(4)
	v_lshlrev_b32_e32 v144, 16, v96
	v_and_b32_e32 v145, 0xffff0000, v96
	v_lshlrev_b32_e32 v146, 16, v97
	v_and_b32_e32 v147, 0xffff0000, v97
	v_lshlrev_b32_e32 v148, 16, v98
	v_and_b32_e32 v149, 0xffff0000, v98
	v_lshlrev_b32_e32 v150, 16, v99
	v_and_b32_e32 v151, 0xffff0000, v99
	v_lshlrev_b32_e32 v152, 16, v100
	v_and_b32_e32 v153, 0xffff0000, v100
	v_lshlrev_b32_e32 v154, 16, v101
	v_and_b32_e32 v155, 0xffff0000, v101
	v_lshlrev_b32_e32 v156, 16, v102
	v_and_b32_e32 v157, 0xffff0000, v102
	v_lshlrev_b32_e32 v158, 16, v103
	v_and_b32_e32 v159, 0xffff0000, v103
	v_lshlrev_b32_e32 v160, 16, v104
	v_and_b32_e32 v161, 0xffff0000, v104
	v_lshlrev_b32_e32 v162, 16, v105
	v_and_b32_e32 v163, 0xffff0000, v105
	v_lshlrev_b32_e32 v164, 16, v106
	v_and_b32_e32 v165, 0xffff0000, v106
	v_lshlrev_b32_e32 v166, 16, v107
	v_and_b32_e32 v167, 0xffff0000, v107
	v_lshlrev_b32_e32 v168, 16, v108
	v_and_b32_e32 v169, 0xffff0000, v108
	v_lshlrev_b32_e32 v170, 16, v109
	v_and_b32_e32 v171, 0xffff0000, v109
	v_lshlrev_b32_e32 v172, 16, v110
	v_and_b32_e32 v173, 0xffff0000, v110
	v_lshlrev_b32_e32 v174, 16, v111
	v_and_b32_e32 v175, 0xffff0000, v111
	v_pk_mul_f32 v[252:253], v[160:161], v[160:161]
	v_pk_mul_f32 v[254:255], v[162:163], v[162:163]
	v_pk_fma_f32 v[252:253], v[164:165], v[164:165], v[252:253]
	v_pk_fma_f32 v[254:255], v[166:167], v[166:167], v[254:255]
	v_pk_fma_f32 v[252:253], v[168:169], v[168:169], v[252:253]
	v_pk_fma_f32 v[254:255], v[170:171], v[170:171], v[254:255]
	v_pk_fma_f32 v[252:253], v[172:173], v[172:173], v[252:253]
	v_pk_fma_f32 v[254:255], v[174:175], v[174:175], v[254:255]
	v_pk_add_f32 v[252:253], v[252:253], v[254:255]
	s_nop 0
	v_add_f32_e32 v183, v252, v253
	s_nop 1
	v_add_f32_dpp v183, v183, v183 quad_perm:[1,0,3,2] row_mask:0xf bank_mask:0xf bound_ctrl:1
	s_nop 1
	v_add_f32_dpp v183, v183, v183 quad_perm:[2,3,0,1] row_mask:0xf bank_mask:0xf bound_ctrl:1
	s_nop 1
	v_add_f32_dpp v183, v183, v183 row_half_mirror row_mask:0xf bank_mask:0xf bound_ctrl:1
	s_nop 1
	v_add_f32_dpp v183, v183, v183 row_mirror row_mask:0xf bank_mask:0xf bound_ctrl:1
	s_nop 1
	v_readlane_b32 s98, v183, 0
	v_readlane_b32 s99, v183, 16
	v_readlane_b32 s100, v183, 32
	v_readlane_b32 s101, v183, 48
	s_nop 1
	v_mov_b32_e32 v183, s98
	v_add_f32_e32 v183, s99, v183
	v_add_f32_e32 v183, s100, v183
	v_add_f32_e32 v183, s101, v183
	v_fmamk_f32 v183, v183, 0x3a800000, v182
	v_cmp_gt_f32_e32 vcc, 0x800000, v183
	v_mul_f32_e32 v181, 0x4b800000, v183
	s_nop 1
	v_cndmask_b32_e32 v183, v183, v181, vcc
	v_rsq_f32_e32 v183, v183
	s_nop 0
	v_mul_f32_e32 v181, 0x45800000, v183
	v_cndmask_b32_e32 v184, v183, v181, vcc
	v_mov_b32_e32 v185, v184
	v_pk_mul_f32 v[160:161], v[160:161], v[184:185]
	v_pk_mul_f32 v[162:163], v[162:163], v[184:185]
	v_pk_mul_f32 v[164:165], v[164:165], v[184:185]
	v_pk_mul_f32 v[166:167], v[166:167], v[184:185]
	v_pk_mul_f32 v[168:169], v[168:169], v[184:185]
	v_pk_mul_f32 v[170:171], v[170:171], v[184:185]
	v_pk_mul_f32 v[172:173], v[172:173], v[184:185]
	v_pk_mul_f32 v[174:175], v[174:175], v[184:185]
	v_pk_fma_f32 v[144:145], v[160:161], v[128:129], v[144:145]
	v_pk_fma_f32 v[146:147], v[162:163], v[130:131], v[146:147]
	v_pk_fma_f32 v[148:149], v[164:165], v[132:133], v[148:149]
	v_pk_fma_f32 v[150:151], v[166:167], v[134:135], v[150:151]
	v_pk_fma_f32 v[152:153], v[168:169], v[136:137], v[152:153]
	v_pk_fma_f32 v[154:155], v[170:171], v[138:139], v[154:155]
	v_pk_fma_f32 v[156:157], v[172:173], v[140:141], v[156:157]
	v_pk_fma_f32 v[158:159], v[174:175], v[142:143], v[158:159]
	v_pk_mul_f32 v[252:253], v[144:145], v[144:145]
	v_pk_mul_f32 v[254:255], v[146:147], v[146:147]
	v_pk_fma_f32 v[252:253], v[148:149], v[148:149], v[252:253]
	v_pk_fma_f32 v[254:255], v[150:151], v[150:151], v[254:255]
	v_pk_fma_f32 v[252:253], v[152:153], v[152:153], v[252:253]
	v_pk_fma_f32 v[254:255], v[154:155], v[154:155], v[254:255]
	v_pk_fma_f32 v[252:253], v[156:157], v[156:157], v[252:253]
	v_pk_fma_f32 v[254:255], v[158:159], v[158:159], v[254:255]
	v_pk_add_f32 v[252:253], v[252:253], v[254:255]
	s_nop 0
	v_add_f32_e32 v183, v252, v253
	s_nop 1
	v_add_f32_dpp v183, v183, v183 quad_perm:[1,0,3,2] row_mask:0xf bank_mask:0xf bound_ctrl:1
	s_nop 1
	v_add_f32_dpp v183, v183, v183 quad_perm:[2,3,0,1] row_mask:0xf bank_mask:0xf bound_ctrl:1
	s_nop 1
	v_add_f32_dpp v183, v183, v183 row_half_mirror row_mask:0xf bank_mask:0xf bound_ctrl:1
	s_nop 1
	v_add_f32_dpp v183, v183, v183 row_mirror row_mask:0xf bank_mask:0xf bound_ctrl:1
	s_nop 1
	v_readlane_b32 s98, v183, 0
	v_readlane_b32 s99, v183, 16
	v_readlane_b32 s100, v183, 32
	v_readlane_b32 s101, v183, 48
	s_nop 1
	v_mov_b32_e32 v183, s98
	v_add_f32_e32 v183, s99, v183
	v_add_f32_e32 v183, s100, v183
	v_add_f32_e32 v183, s101, v183
	v_fmamk_f32 v183, v183, 0x3a800000, v182
	v_cmp_gt_f32_e32 vcc, 0x800000, v183
	v_mul_f32_e32 v181, 0x4b800000, v183
	s_nop 1
	v_cndmask_b32_e32 v183, v183, v181, vcc
	v_rsq_f32_e32 v183, v183
	s_nop 0
	v_mul_f32_e32 v181, 0x45800000, v183
	v_cndmask_b32_e32 v184, v183, v181, vcc
	v_mov_b32_e32 v185, v184
	v_cvt_pk_bf16_f32 v96, v144, v145
	v_cvt_pk_bf16_f32 v97, v146, v147
	v_cvt_pk_bf16_f32 v98, v148, v149
	v_cvt_pk_bf16_f32 v99, v150, v151
	v_cvt_pk_bf16_f32 v100, v152, v153
	v_cvt_pk_bf16_f32 v101, v154, v155
	v_cvt_pk_bf16_f32 v102, v156, v157
	v_cvt_pk_bf16_f32 v103, v158, v159
	v_add_u32_e32 v181, 0x3000000, v177
	global_store_dwordx4 v181, v[96:99], s[78:79]
	global_store_dwordx4 v181, v[100:103], s[78:79] offset:1024
	v_add_u32_e32 v236, 0xc000, v237
	s_mov_b64 exec, 1
	global_store_dword v236, v184, s[78:79]
	s_mov_b64 exec, -1
	s_waitcnt vmcnt(0)
	v_lshlrev_b32_e32 v144, 16, v112
	v_and_b32_e32 v145, 0xffff0000, v112
	v_lshlrev_b32_e32 v146, 16, v113
	v_and_b32_e32 v147, 0xffff0000, v113
	v_lshlrev_b32_e32 v148, 16, v114
	v_and_b32_e32 v149, 0xffff0000, v114
	v_lshlrev_b32_e32 v150, 16, v115
	v_and_b32_e32 v151, 0xffff0000, v115
	v_lshlrev_b32_e32 v152, 16, v116
	v_and_b32_e32 v153, 0xffff0000, v116
	v_lshlrev_b32_e32 v154, 16, v117
	v_and_b32_e32 v155, 0xffff0000, v117
	v_lshlrev_b32_e32 v156, 16, v118
	v_and_b32_e32 v157, 0xffff0000, v118
	v_lshlrev_b32_e32 v158, 16, v119
	v_and_b32_e32 v159, 0xffff0000, v119
	v_lshlrev_b32_e32 v160, 16, v120
	v_and_b32_e32 v161, 0xffff0000, v120
	v_lshlrev_b32_e32 v162, 16, v121
	v_and_b32_e32 v163, 0xffff0000, v121
	v_lshlrev_b32_e32 v164, 16, v122
	v_and_b32_e32 v165, 0xffff0000, v122
	v_lshlrev_b32_e32 v166, 16, v123
	v_and_b32_e32 v167, 0xffff0000, v123
	v_lshlrev_b32_e32 v168, 16, v124
	v_and_b32_e32 v169, 0xffff0000, v124
	v_lshlrev_b32_e32 v170, 16, v125
	v_and_b32_e32 v171, 0xffff0000, v125
	v_lshlrev_b32_e32 v172, 16, v126
	v_and_b32_e32 v173, 0xffff0000, v126
	v_lshlrev_b32_e32 v174, 16, v127
	v_and_b32_e32 v175, 0xffff0000, v127
	v_pk_mul_f32 v[252:253], v[160:161], v[160:161]
	v_pk_mul_f32 v[254:255], v[162:163], v[162:163]
	v_pk_fma_f32 v[252:253], v[164:165], v[164:165], v[252:253]
	v_pk_fma_f32 v[254:255], v[166:167], v[166:167], v[254:255]
	v_pk_fma_f32 v[252:253], v[168:169], v[168:169], v[252:253]
	v_pk_fma_f32 v[254:255], v[170:171], v[170:171], v[254:255]
	v_pk_fma_f32 v[252:253], v[172:173], v[172:173], v[252:253]
	v_pk_fma_f32 v[254:255], v[174:175], v[174:175], v[254:255]
	v_pk_add_f32 v[252:253], v[252:253], v[254:255]
	s_nop 0
	v_add_f32_e32 v183, v252, v253
	s_nop 1
	v_add_f32_dpp v183, v183, v183 quad_perm:[1,0,3,2] row_mask:0xf bank_mask:0xf bound_ctrl:1
	s_nop 1
	v_add_f32_dpp v183, v183, v183 quad_perm:[2,3,0,1] row_mask:0xf bank_mask:0xf bound_ctrl:1
	s_nop 1
	v_add_f32_dpp v183, v183, v183 row_half_mirror row_mask:0xf bank_mask:0xf bound_ctrl:1
	s_nop 1
	v_add_f32_dpp v183, v183, v183 row_mirror row_mask:0xf bank_mask:0xf bound_ctrl:1
	s_nop 1
	v_readlane_b32 s98, v183, 0
	v_readlane_b32 s99, v183, 16
	v_readlane_b32 s100, v183, 32
	v_readlane_b32 s101, v183, 48
	s_nop 1
	v_mov_b32_e32 v183, s98
	v_add_f32_e32 v183, s99, v183
	v_add_f32_e32 v183, s100, v183
	v_add_f32_e32 v183, s101, v183
	v_fmamk_f32 v183, v183, 0x3a800000, v182
	v_cmp_gt_f32_e32 vcc, 0x800000, v183
	v_mul_f32_e32 v181, 0x4b800000, v183
	s_nop 1
	v_cndmask_b32_e32 v183, v183, v181, vcc
	v_rsq_f32_e32 v183, v183
	s_nop 0
	v_mul_f32_e32 v181, 0x45800000, v183
	v_cndmask_b32_e32 v184, v183, v181, vcc
	v_mov_b32_e32 v185, v184
	v_pk_mul_f32 v[160:161], v[160:161], v[184:185]
	v_pk_mul_f32 v[162:163], v[162:163], v[184:185]
	v_pk_mul_f32 v[164:165], v[164:165], v[184:185]
	v_pk_mul_f32 v[166:167], v[166:167], v[184:185]
	v_pk_mul_f32 v[168:169], v[168:169], v[184:185]
	v_pk_mul_f32 v[170:171], v[170:171], v[184:185]
	v_pk_mul_f32 v[172:173], v[172:173], v[184:185]
	v_pk_mul_f32 v[174:175], v[174:175], v[184:185]
	v_pk_fma_f32 v[144:145], v[160:161], v[128:129], v[144:145]
	v_pk_fma_f32 v[146:147], v[162:163], v[130:131], v[146:147]
	v_pk_fma_f32 v[148:149], v[164:165], v[132:133], v[148:149]
	v_pk_fma_f32 v[150:151], v[166:167], v[134:135], v[150:151]
	v_pk_fma_f32 v[152:153], v[168:169], v[136:137], v[152:153]
	v_pk_fma_f32 v[154:155], v[170:171], v[138:139], v[154:155]
	v_pk_fma_f32 v[156:157], v[172:173], v[140:141], v[156:157]
	v_pk_fma_f32 v[158:159], v[174:175], v[142:143], v[158:159]
	v_pk_mul_f32 v[252:253], v[144:145], v[144:145]
	v_pk_mul_f32 v[254:255], v[146:147], v[146:147]
	v_pk_fma_f32 v[252:253], v[148:149], v[148:149], v[252:253]
	v_pk_fma_f32 v[254:255], v[150:151], v[150:151], v[254:255]
	v_pk_fma_f32 v[252:253], v[152:153], v[152:153], v[252:253]
	v_pk_fma_f32 v[254:255], v[154:155], v[154:155], v[254:255]
	v_pk_fma_f32 v[252:253], v[156:157], v[156:157], v[252:253]
	v_pk_fma_f32 v[254:255], v[158:159], v[158:159], v[254:255]
	v_pk_add_f32 v[252:253], v[252:253], v[254:255]
	s_nop 0
	v_add_f32_e32 v183, v252, v253
	s_nop 1
	v_add_f32_dpp v183, v183, v183 quad_perm:[1,0,3,2] row_mask:0xf bank_mask:0xf bound_ctrl:1
	s_nop 1
	v_add_f32_dpp v183, v183, v183 quad_perm:[2,3,0,1] row_mask:0xf bank_mask:0xf bound_ctrl:1
	s_nop 1
	v_add_f32_dpp v183, v183, v183 row_half_mirror row_mask:0xf bank_mask:0xf bound_ctrl:1
	s_nop 1
	v_add_f32_dpp v183, v183, v183 row_mirror row_mask:0xf bank_mask:0xf bound_ctrl:1
	s_nop 1
	v_readlane_b32 s98, v183, 0
	v_readlane_b32 s99, v183, 16
	v_readlane_b32 s100, v183, 32
	v_readlane_b32 s101, v183, 48
	s_nop 1
	v_mov_b32_e32 v183, s98
	v_add_f32_e32 v183, s99, v183
	v_add_f32_e32 v183, s100, v183
	v_add_f32_e32 v183, s101, v183
	v_fmamk_f32 v183, v183, 0x3a800000, v182
	v_cmp_gt_f32_e32 vcc, 0x800000, v183
	v_mul_f32_e32 v181, 0x4b800000, v183
	s_nop 1
	v_cndmask_b32_e32 v183, v183, v181, vcc
	v_rsq_f32_e32 v183, v183
	s_nop 0
	v_mul_f32_e32 v181, 0x45800000, v183
	v_cndmask_b32_e32 v184, v183, v181, vcc
	v_mov_b32_e32 v185, v184
	v_cvt_pk_bf16_f32 v112, v144, v145
	v_cvt_pk_bf16_f32 v113, v146, v147
	v_cvt_pk_bf16_f32 v114, v148, v149
	v_cvt_pk_bf16_f32 v115, v150, v151
	v_cvt_pk_bf16_f32 v116, v152, v153
	v_cvt_pk_bf16_f32 v117, v154, v155
	v_cvt_pk_bf16_f32 v118, v156, v157
	v_cvt_pk_bf16_f32 v119, v158, v159
	v_add_u32_e32 v181, 0x3400000, v177
	global_store_dwordx4 v181, v[112:115], s[78:79]
	global_store_dwordx4 v181, v[116:119], s[78:79] offset:1024
	v_add_u32_e32 v236, 0xe000, v237
	s_mov_b64 exec, 1
	global_store_dword v236, v184, s[78:79]
	s_mov_b64 exec, -1
	v_readfirstlane_b32 s98, v179
	s_nop 3
	s_cmp_ge_u32 s98, 512
	s_cbranch_scc1 .Lmyxupd_done_2
	v_lshlrev_b32_e32 v177, 4, v176
	v_lshl_add_u32 v177, v179, 11, v177
	v_lshlrev_b32_e32 v237, 2, v179
	v_add_u32_e32 v237, 0x10000, v237
	v_add_u32_e32 v181, 0x3800000, v177
	global_load_dwordx4 v[0:3], v181, s[78:79]
	global_load_dwordx4 v[4:7], v181, s[78:79] offset:1024
	v_lshl_add_u32 v183, v179, 12, v180
	v_add_u32_e32 v183, 0xbf00000, v183
	v_add_u32_e32 v181, 0x0, v183
	global_load_dwordx4 v[8:11], v181, s[78:79]
	global_load_dwordx4 v[12:15], v181, s[78:79] offset:16
	global_load_dwordx4 v[16:19], v181, s[78:79] offset:2048
	global_load_dwordx4 v[20:23], v181, s[78:79] offset:2064
	v_add_u32_e32 v181, 0x200000, v183
	global_load_dwordx4 v[24:27], v181, s[78:79]
	global_load_dwordx4 v[28:31], v181, s[78:79] offset:16
	global_load_dwordx4 v[32:35], v181, s[78:79] offset:2048
	global_load_dwordx4 v[36:39], v181, s[78:79] offset:2064
	v_add_u32_e32 v181, 0x400000, v183
	global_load_dwordx4 v[40:43], v181, s[78:79]
	global_load_dwordx4 v[44:47], v181, s[78:79] offset:16
	global_load_dwordx4 v[48:51], v181, s[78:79] offset:2048
	global_load_dwordx4 v[52:55], v181, s[78:79] offset:2064
	v_add_u32_e32 v181, 0x600000, v183
	global_load_dwordx4 v[56:59], v181, s[78:79]
	global_load_dwordx4 v[60:63], v181, s[78:79] offset:16
	global_load_dwordx4 v[64:67], v181, s[78:79] offset:2048
	global_load_dwordx4 v[68:71], v181, s[78:79] offset:2064
	v_add_u32_e32 v181, 0x800000, v183
	global_load_dwordx4 v[72:75], v181, s[78:79]
	global_load_dwordx4 v[76:79], v181, s[78:79] offset:16
	global_load_dwordx4 v[80:83], v181, s[78:79] offset:2048
	global_load_dwordx4 v[84:87], v181, s[78:79] offset:2064
	v_add_u32_e32 v181, 0xa00000, v183
	global_load_dwordx4 v[88:91], v181, s[78:79]
	global_load_dwordx4 v[92:95], v181, s[78:79] offset:16
	global_load_dwordx4 v[96:99], v181, s[78:79] offset:2048
	global_load_dwordx4 v[100:103], v181, s[78:79] offset:2064
	s_waitcnt vmcnt(20)
	v_pk_add_f32 v[160:161], v[8:9], 0 op_sel_hi:[1,0]
	v_pk_add_f32 v[162:163], v[10:11], 0 op_sel_hi:[1,0]
	v_pk_add_f32 v[164:165], v[12:13], 0 op_sel_hi:[1,0]
	v_pk_add_f32 v[166:167], v[14:15], 0 op_sel_hi:[1,0]
	v_pk_add_f32 v[168:169], v[16:17], 0 op_sel_hi:[1,0]
	v_pk_add_f32 v[170:171], v[18:19], 0 op_sel_hi:[1,0]
	v_pk_add_f32 v[172:173], v[20:21], 0 op_sel_hi:[1,0]
	v_pk_add_f32 v[174:175], v[22:23], 0 op_sel_hi:[1,0]
	s_waitcnt vmcnt(16)
	v_pk_add_f32 v[160:161], v[160:161], v[24:25]
	v_pk_add_f32 v[162:163], v[162:163], v[26:27]
	v_pk_add_f32 v[164:165], v[164:165], v[28:29]
	v_pk_add_f32 v[166:167], v[166:167], v[30:31]
	v_pk_add_f32 v[168:169], v[168:169], v[32:33]
	v_pk_add_f32 v[170:171], v[170:171], v[34:35]
	v_pk_add_f32 v[172:173], v[172:173], v[36:37]
	v_pk_add_f32 v[174:175], v[174:175], v[38:39]
	s_waitcnt vmcnt(12)
	v_pk_add_f32 v[160:161], v[160:161], v[40:41]
	v_pk_add_f32 v[162:163], v[162:163], v[42:43]
	v_pk_add_f32 v[164:165], v[164:165], v[44:45]
	v_pk_add_f32 v[166:167], v[166:167], v[46:47]
	v_pk_add_f32 v[168:169], v[168:169], v[48:49]
	v_pk_add_f32 v[170:171], v[170:171], v[50:51]
	v_pk_add_f32 v[172:173], v[172:173], v[52:53]
	v_pk_add_f32 v[174:175], v[174:175], v[54:55]
	s_waitcnt vmcnt(8)
	v_pk_add_f32 v[160:161], v[160:161], v[56:57]
	v_pk_add_f32 v[162:163], v[162:163], v[58:59]
	v_pk_add_f32 v[164:165], v[164:165], v[60:61]
	v_pk_add_f32 v[166:167], v[166:167], v[62:63]
	v_pk_add_f32 v[168:169], v[168:169], v[64:65]
	v_pk_add_f32 v[170:171], v[170:171], v[66:67]
	v_pk_add_f32 v[172:173], v[172:173], v[68:69]
	v_pk_add_f32 v[174:175], v[174:175], v[70:71]
	s_waitcnt vmcnt(4)
	v_pk_add_f32 v[160:161], v[160:161], v[72:73]
	v_pk_add_f32 v[162:163], v[162:163], v[74:75]
	v_pk_add_f32 v[164:165], v[164:165], v[76:77]
	v_pk_add_f32 v[166:167], v[166:167], v[78:79]
	v_pk_add_f32 v[168:169], v[168:169], v[80:81]
	v_pk_add_f32 v[170:171], v[170:171], v[82:83]
	v_pk_add_f32 v[172:173], v[172:173], v[84:85]
	v_pk_add_f32 v[174:175], v[174:175], v[86:87]
	s_waitcnt vmcnt(0)
	v_pk_add_f32 v[160:161], v[160:161], v[88:89]
	v_pk_add_f32 v[162:163], v[162:163], v[90:91]
	v_pk_add_f32 v[164:165], v[164:165], v[92:93]
	v_pk_add_f32 v[166:167], v[166:167], v[94:95]
	v_pk_add_f32 v[168:169], v[168:169], v[96:97]
	v_pk_add_f32 v[170:171], v[170:171], v[98:99]
	v_pk_add_f32 v[172:173], v[172:173], v[100:101]
	v_pk_add_f32 v[174:175], v[174:175], v[102:103]
	v_lshlrev_b32_e32 v144, 16, v0
	v_and_b32_e32 v145, 0xffff0000, v0
	v_lshlrev_b32_e32 v146, 16, v1
	v_and_b32_e32 v147, 0xffff0000, v1
	v_lshlrev_b32_e32 v148, 16, v2
	v_and_b32_e32 v149, 0xffff0000, v2
	v_lshlrev_b32_e32 v150, 16, v3
	v_and_b32_e32 v151, 0xffff0000, v3
	v_lshlrev_b32_e32 v152, 16, v4
	v_and_b32_e32 v153, 0xffff0000, v4
	v_lshlrev_b32_e32 v154, 16, v5
	v_and_b32_e32 v155, 0xffff0000, v5
	v_lshlrev_b32_e32 v156, 16, v6
	v_and_b32_e32 v157, 0xffff0000, v6
	v_lshlrev_b32_e32 v158, 16, v7
	v_and_b32_e32 v159, 0xffff0000, v7
	v_add_u32_e32 v181, 0xc00000, v183
	global_load_dwordx4 v[8:11], v181, s[78:79]
	global_load_dwordx4 v[12:15], v181, s[78:79] offset:16
	global_load_dwordx4 v[16:19], v181, s[78:79] offset:2048
	global_load_dwordx4 v[20:23], v181, s[78:79] offset:2064
	v_add_u32_e32 v181, 0xe00000, v183
	global_load_dwordx4 v[24:27], v181, s[78:79]
	global_load_dwordx4 v[28:31], v181, s[78:79] offset:16
	global_load_dwordx4 v[32:35], v181, s[78:79] offset:2048
	global_load_dwordx4 v[36:39], v181, s[78:79] offset:2064
	s_waitcnt vmcnt(4)
	v_pk_add_f32 v[160:161], v[160:161], v[8:9]
	v_pk_add_f32 v[162:163], v[162:163], v[10:11]
	v_pk_add_f32 v[164:165], v[164:165], v[12:13]
	v_pk_add_f32 v[166:167], v[166:167], v[14:15]
	v_pk_add_f32 v[168:169], v[168:169], v[16:17]
	v_pk_add_f32 v[170:171], v[170:171], v[18:19]
	v_pk_add_f32 v[172:173], v[172:173], v[20:21]
	v_pk_add_f32 v[174:175], v[174:175], v[22:23]
	s_waitcnt vmcnt(0)
	v_pk_add_f32 v[160:161], v[160:161], v[24:25]
	v_pk_add_f32 v[162:163], v[162:163], v[26:27]
	v_pk_add_f32 v[164:165], v[164:165], v[28:29]
	v_pk_add_f32 v[166:167], v[166:167], v[30:31]
	v_pk_add_f32 v[168:169], v[168:169], v[32:33]
	v_pk_add_f32 v[170:171], v[170:171], v[34:35]
	v_pk_add_f32 v[172:173], v[172:173], v[36:37]
	v_pk_add_f32 v[174:175], v[174:175], v[38:39]
	v_pk_mul_f32 v[252:253], v[160:161], v[160:161]
	v_pk_mul_f32 v[254:255], v[162:163], v[162:163]
	v_pk_fma_f32 v[252:253], v[164:165], v[164:165], v[252:253]
	v_pk_fma_f32 v[254:255], v[166:167], v[166:167], v[254:255]
	v_pk_fma_f32 v[252:253], v[168:169], v[168:169], v[252:253]
	v_pk_fma_f32 v[254:255], v[170:171], v[170:171], v[254:255]
	v_pk_fma_f32 v[252:253], v[172:173], v[172:173], v[252:253]
	v_pk_fma_f32 v[254:255], v[174:175], v[174:175], v[254:255]
	v_pk_add_f32 v[252:253], v[252:253], v[254:255]
	s_nop 0
	v_add_f32_e32 v183, v252, v253
	s_nop 1
	v_add_f32_dpp v183, v183, v183 quad_perm:[1,0,3,2] row_mask:0xf bank_mask:0xf bound_ctrl:1
	s_nop 1
	v_add_f32_dpp v183, v183, v183 quad_perm:[2,3,0,1] row_mask:0xf bank_mask:0xf bound_ctrl:1
	s_nop 1
	v_add_f32_dpp v183, v183, v183 row_half_mirror row_mask:0xf bank_mask:0xf bound_ctrl:1
	s_nop 1
	v_add_f32_dpp v183, v183, v183 row_mirror row_mask:0xf bank_mask:0xf bound_ctrl:1
	s_nop 1
	v_readlane_b32 s98, v183, 0
	v_readlane_b32 s99, v183, 16
	v_readlane_b32 s100, v183, 32
	v_readlane_b32 s101, v183, 48
	s_nop 1
	v_mov_b32_e32 v183, s98
	v_add_f32_e32 v183, s99, v183
	v_add_f32_e32 v183, s100, v183
	v_add_f32_e32 v183, s101, v183
	v_fmamk_f32 v183, v183, 0x3a800000, v182
	v_cmp_gt_f32_e32 vcc, 0x800000, v183
	v_mul_f32_e32 v181, 0x4b800000, v183
	s_nop 1
	v_cndmask_b32_e32 v183, v183, v181, vcc
	v_rsq_f32_e32 v183, v183
	s_nop 0
	v_mul_f32_e32 v181, 0x45800000, v183
	v_cndmask_b32_e32 v184, v183, v181, vcc
	v_mov_b32_e32 v185, v184
	v_pk_mul_f32 v[160:161], v[160:161], v[184:185]
	v_pk_mul_f32 v[162:163], v[162:163], v[184:185]
	v_pk_mul_f32 v[164:165], v[164:165], v[184:185]
	v_pk_mul_f32 v[166:167], v[166:167], v[184:185]
	v_pk_mul_f32 v[168:169], v[168:169], v[184:185]
	v_pk_mul_f32 v[170:171], v[170:171], v[184:185]
	v_pk_mul_f32 v[172:173], v[172:173], v[184:185]
	v_pk_mul_f32 v[174:175], v[174:175], v[184:185]
	v_pk_fma_f32 v[144:145], v[160:161], v[128:129], v[144:145]
	v_pk_fma_f32 v[146:147], v[162:163], v[130:131], v[146:147]
	v_pk_fma_f32 v[148:149], v[164:165], v[132:133], v[148:149]
	v_pk_fma_f32 v[150:151], v[166:167], v[134:135], v[150:151]
	v_pk_fma_f32 v[152:153], v[168:169], v[136:137], v[152:153]
	v_pk_fma_f32 v[154:155], v[170:171], v[138:139], v[154:155]
	v_pk_fma_f32 v[156:157], v[172:173], v[140:141], v[156:157]
	v_pk_fma_f32 v[158:159], v[174:175], v[142:143], v[158:159]
	v_pk_mul_f32 v[252:253], v[144:145], v[144:145]
	v_pk_mul_f32 v[254:255], v[146:147], v[146:147]
	v_pk_fma_f32 v[252:253], v[148:149], v[148:149], v[252:253]
	v_pk_fma_f32 v[254:255], v[150:151], v[150:151], v[254:255]
	v_pk_fma_f32 v[252:253], v[152:153], v[152:153], v[252:253]
	v_pk_fma_f32 v[254:255], v[154:155], v[154:155], v[254:255]
	v_pk_fma_f32 v[252:253], v[156:157], v[156:157], v[252:253]
	v_pk_fma_f32 v[254:255], v[158:159], v[158:159], v[254:255]
	v_pk_add_f32 v[252:253], v[252:253], v[254:255]
	s_nop 0
	v_add_f32_e32 v183, v252, v253
	s_nop 1
	v_add_f32_dpp v183, v183, v183 quad_perm:[1,0,3,2] row_mask:0xf bank_mask:0xf bound_ctrl:1
	s_nop 1
	v_add_f32_dpp v183, v183, v183 quad_perm:[2,3,0,1] row_mask:0xf bank_mask:0xf bound_ctrl:1
	s_nop 1
	v_add_f32_dpp v183, v183, v183 row_half_mirror row_mask:0xf bank_mask:0xf bound_ctrl:1
	s_nop 1
	v_add_f32_dpp v183, v183, v183 row_mirror row_mask:0xf bank_mask:0xf bound_ctrl:1
	s_nop 1
	v_readlane_b32 s98, v183, 0
	v_readlane_b32 s99, v183, 16
	v_readlane_b32 s100, v183, 32
	v_readlane_b32 s101, v183, 48
	s_nop 1
	v_mov_b32_e32 v183, s98
	v_add_f32_e32 v183, s99, v183
	v_add_f32_e32 v183, s100, v183
	v_add_f32_e32 v183, s101, v183
	v_fmamk_f32 v183, v183, 0x3a800000, v182
	v_cmp_gt_f32_e32 vcc, 0x800000, v183
	v_mul_f32_e32 v181, 0x4b800000, v183
	s_nop 1
	v_cndmask_b32_e32 v183, v183, v181, vcc
	v_rsq_f32_e32 v183, v183
	s_nop 0
	v_mul_f32_e32 v181, 0x45800000, v183
	v_cndmask_b32_e32 v184, v183, v181, vcc
	v_mov_b32_e32 v185, v184
	v_cvt_pk_bf16_f32 v0, v144, v145
	v_cvt_pk_bf16_f32 v1, v146, v147
	v_cvt_pk_bf16_f32 v2, v148, v149
	v_cvt_pk_bf16_f32 v3, v150, v151
	v_cvt_pk_bf16_f32 v4, v152, v153
	v_cvt_pk_bf16_f32 v5, v154, v155
	v_cvt_pk_bf16_f32 v6, v156, v157
	v_cvt_pk_bf16_f32 v7, v158, v159
	v_add_u32_e32 v181, 0x3800000, v177
	global_store_dwordx4 v181, v[0:3], s[78:79]
	global_store_dwordx4 v181, v[4:7], s[78:79] offset:1024
	v_add_u32_e32 v236, 0x10000, v237
	s_mov_b64 exec, 1
	global_store_dword v236, v184, s[78:79]
	s_mov_b64 exec, -1

.LBB0_1430:
	v_readlane_b32 s0, v235, 52
	v_readlane_b32 s1, v235, 53
	s_and_b64 vcc, exec, s[0:1]
	s_waitcnt lgkmcnt(0)
	s_barrier
	v_mbcnt_lo_u32_b32 v0, -1, 0
	v_mbcnt_hi_u32_b32 v0, -1, v0
	s_cbranch_vccnz .LBB0_1450
	v_lshlrev_b32_e32 v2, 3, v0
	v_readlane_b32 s4, v235, 4
	v_ashrrev_i32_e32 v3, 31, v2
	v_readlane_b32 s6, v235, 6
	v_readlane_b32 s7, v235, 7
	v_lshlrev_b64 v[4:5], 1, v[2:3]
	v_lshlrev_b64 v[2:3], 2, v[2:3]
	v_readlane_b32 s5, v235, 5
	v_readlane_b32 s10, v235, 10
	v_readlane_b32 s11, v235, 11
	v_readlane_b32 s18, v235, 18
	v_readlane_b32 s19, v235, 19
	v_readlane_b32 s6, v235, 61
	v_lshl_add_u64 v[154:155], s[90:91], 0, v[2:3]
	v_readlane_b32 s8, v235, 8
	v_lshl_add_u64 v[2:3], s[18:19], 0, v[2:3]
	s_mov_b64 s[0:1], 0x1000
	v_readlane_b32 s4, v235, 0
	v_readlane_b32 s7, v235, 62
	s_mov_b32 s10, s6
	s_ashr_i32 s11, s6, 31
	v_readlane_b32 s9, v235, 9
	v_lshl_add_u64 v[158:159], v[2:3], 0, s[0:1]
	s_lshl_b32 s4, s4, 4
	s_add_i32 s0, s6, 0xffffc000
	s_lshl_b64 s[6:7], s[10:11], 2
	s_mov_b32 s8, s10
	v_readlane_b32 s12, v235, 12
	v_readlane_b32 s13, v235, 13
	v_readlane_b32 s14, v235, 14
	v_readlane_b32 s15, v235, 15
	v_readlane_b32 s16, v235, 16
	v_readlane_b32 s17, v235, 17
	v_readlane_b32 s5, v235, 1
	s_add_u32 s80, s6, 0x10000
	v_writelane_b32 v235, s8, 61
	s_addc_u32 s12, s7, 0
	s_ashr_i32 s5, s4, 31
	v_writelane_b32 v235, s9, 62
	s_lshl_b64 s[8:9], s[10:11], 11
	v_lshl_add_u64 v[152:153], s[86:87], 0, v[4:5]
	v_lshl_add_u64 v[156:157], s[54:55], 0, v[4:5]
	s_mov_b32 s1, 0
	v_cmp_eq_u32_e64 s[16:17], 0, v0
	s_lshl_b64 s[6:7], s[4:5], 2
	v_lshl_add_u64 v[160:161], s[8:9], 0, v[4:5]
	s_lshl_b64 s[8:9], s[4:5], 11
	s_mov_b64 s[20:21], 0x600000
	s_mov_b64 s[22:23], 0x600800
	s_mov_b64 s[24:25], 0x800000
	s_mov_b32 s5, 0x800000
	s_mov_b64 s[26:27], 0x800800
	s_mov_b64 s[28:29], 0xa00000
	s_mov_b64 s[36:37], 0xa00800
	s_mov_b64 s[38:39], 0xc00000
	s_mov_b64 s[40:41], 0xc00800
	s_mov_b64 s[42:43], 0xe00000
	s_mov_b64 s[44:45], 0xe00800
	s_mov_b64 s[46:47], 0x1000000
	s_mov_b32 s13, 0x1000000
	s_mov_b64 s[48:49], 0x1000800
	s_mov_b64 s[50:51], 0x1200000
	s_mov_b32 s14, 0x1200000
	s_mov_b64 s[10:11], 0x1200800
	s_mov_b64 s[82:83], 0x1400000
	s_mov_b32 s15, 0x1400000
	s_mov_b64 s[90:91], 0x1400800
	v_mov_b32_e32 v215, 0
	v_mov_b32_e32 v216, 0x358637bd
	v_mbcnt_lo_u32_b32 v176, -1, 0
	v_mbcnt_hi_u32_b32 v176, -1, v176
	v_readlane_b32 s98, v235, 49
	v_readlane_b32 s99, v235, 20
	v_readlane_b32 s100, v235, 18
	v_readlane_b32 s101, v235, 19
	s_nop 3
	s_lshr_b32 vcc_lo, s98, 3
	s_and_b32 vcc_hi, vcc_lo, 7
	s_lshr_b32 vcc_lo, vcc_lo, 3
	s_lshl_b32 vcc_lo, vcc_lo, 3
	s_add_i32 vcc_lo, vcc_lo, s99
	s_lshl_b32 s98, vcc_hi, 8
	s_add_i32 s98, s98, vcc_lo
	s_mov_b32 s99, s98
	v_mov_b32_e32 v183, s99
	v_lshlrev_b32_e32 v177, 4, v176
	s_lshl_b32 s99, s99, 11
	v_add_u32_e32 v177, s99, v177
	v_add_u32_e32 v178, 0x1800000, v177
	v_add_u32_e32 v179, 0x9e00000, v177
	v_lshlrev_b32_e32 v180, 5, v176
	v_add_u32_e32 v181, 0x1000, v180
	global_load_dwordx4 v[128:131], v181, s[100:101]
	global_load_dwordx4 v[132:135], v181, s[100:101] offset:16
	global_load_dwordx4 v[136:139], v181, s[100:101] offset:2048
	global_load_dwordx4 v[140:143], v181, s[100:101] offset:2064
	v_mov_b32_e32 v182, 0x358637bd
	global_load_dwordx4 v[0:3], v178, s[78:79]
	global_load_dwordx4 v[4:7], v178, s[78:79] offset:1024
	global_load_dwordx4 v[8:11], v179, s[78:79]
	global_load_dwordx4 v[12:15], v179, s[78:79] offset:1024
	v_add_u32_e32 v178, 0x400000, v178
	v_add_u32_e32 v179, 0x400000, v179
	global_load_dwordx4 v[16:19], v178, s[78:79]
	global_load_dwordx4 v[20:23], v178, s[78:79] offset:1024
	global_load_dwordx4 v[24:27], v179, s[78:79]
	global_load_dwordx4 v[28:31], v179, s[78:79] offset:1024
	v_add_u32_e32 v178, 0x400000, v178
	v_add_u32_e32 v179, 0x400000, v179
	global_load_dwordx4 v[32:35], v178, s[78:79]
	global_load_dwordx4 v[36:39], v178, s[78:79] offset:1024
	global_load_dwordx4 v[40:43], v179, s[78:79]
	global_load_dwordx4 v[44:47], v179, s[78:79] offset:1024
	v_add_u32_e32 v178, 0x400000, v178
	v_add_u32_e32 v179, 0x400000, v179
	global_load_dwordx4 v[48:51], v178, s[78:79]
	global_load_dwordx4 v[52:55], v178, s[78:79] offset:1024
	global_load_dwordx4 v[56:59], v179, s[78:79]
	global_load_dwordx4 v[60:63], v179, s[78:79] offset:1024
	v_add_u32_e32 v178, 0x400000, v178
	v_add_u32_e32 v179, 0x400000, v179
	global_load_dwordx4 v[64:67], v178, s[78:79]
	global_load_dwordx4 v[68:71], v178, s[78:79] offset:1024
	global_load_dwordx4 v[72:75], v179, s[78:79]
	global_load_dwordx4 v[76:79], v179, s[78:79] offset:1024
	v_add_u32_e32 v178, 0x400000, v178
	v_add_u32_e32 v179, 0x400000, v179
	global_load_dwordx4 v[80:83], v178, s[78:79]
	global_load_dwordx4 v[84:87], v178, s[78:79] offset:1024
	global_load_dwordx4 v[88:91], v179, s[78:79]
	global_load_dwordx4 v[92:95], v179, s[78:79] offset:1024
	v_add_u32_e32 v178, 0x400000, v178
	v_add_u32_e32 v179, 0x400000, v179
	global_load_dwordx4 v[96:99], v178, s[78:79]
	global_load_dwordx4 v[100:103], v178, s[78:79] offset:1024
	global_load_dwordx4 v[104:107], v179, s[78:79]
	global_load_dwordx4 v[108:111], v179, s[78:79] offset:1024
	v_add_u32_e32 v178, 0x400000, v178
	v_add_u32_e32 v179, 0x400000, v179
	global_load_dwordx4 v[112:115], v178, s[78:79]
	global_load_dwordx4 v[116:119], v178, s[78:79] offset:1024
	global_load_dwordx4 v[120:123], v179, s[78:79]
	global_load_dwordx4 v[124:127], v179, s[78:79] offset:1024
	v_lshlrev_b32_e32 v237, 2, v183
	v_add_u32_e32 v237, 0x10000, v237
	v_mov_b32_e32 v179, s98
	s_waitcnt vmcnt(28)
	v_lshlrev_b32_e32 v144, 16, v0
	v_and_b32_e32 v145, 0xffff0000, v0
	v_lshlrev_b32_e32 v146, 16, v1
	v_and_b32_e32 v147, 0xffff0000, v1
	v_lshlrev_b32_e32 v148, 16, v2
	v_and_b32_e32 v149, 0xffff0000, v2
	v_lshlrev_b32_e32 v150, 16, v3
	v_and_b32_e32 v151, 0xffff0000, v3
	v_lshlrev_b32_e32 v152, 16, v4
	v_and_b32_e32 v153, 0xffff0000, v4
	v_lshlrev_b32_e32 v154, 16, v5
	v_and_b32_e32 v155, 0xffff0000, v5
	v_lshlrev_b32_e32 v156, 16, v6
	v_and_b32_e32 v157, 0xffff0000, v6
	v_lshlrev_b32_e32 v158, 16, v7
	v_and_b32_e32 v159, 0xffff0000, v7
	v_lshlrev_b32_e32 v160, 16, v8
	v_and_b32_e32 v161, 0xffff0000, v8
	v_lshlrev_b32_e32 v162, 16, v9
	v_and_b32_e32 v163, 0xffff0000, v9
	v_lshlrev_b32_e32 v164, 16, v10
	v_and_b32_e32 v165, 0xffff0000, v10
	v_lshlrev_b32_e32 v166, 16, v11
	v_and_b32_e32 v167, 0xffff0000, v11
	v_lshlrev_b32_e32 v168, 16, v12
	v_and_b32_e32 v169, 0xffff0000, v12
	v_lshlrev_b32_e32 v170, 16, v13
	v_and_b32_e32 v171, 0xffff0000, v13
	v_lshlrev_b32_e32 v172, 16, v14
	v_and_b32_e32 v173, 0xffff0000, v14
	v_lshlrev_b32_e32 v174, 16, v15
	v_and_b32_e32 v175, 0xffff0000, v15
	v_pk_mul_f32 v[252:253], v[160:161], v[160:161]
	v_pk_mul_f32 v[254:255], v[162:163], v[162:163]
	v_pk_fma_f32 v[252:253], v[164:165], v[164:165], v[252:253]
	v_pk_fma_f32 v[254:255], v[166:167], v[166:167], v[254:255]
	v_pk_fma_f32 v[252:253], v[168:169], v[168:169], v[252:253]
	v_pk_fma_f32 v[254:255], v[170:171], v[170:171], v[254:255]
	v_pk_fma_f32 v[252:253], v[172:173], v[172:173], v[252:253]
	v_pk_fma_f32 v[254:255], v[174:175], v[174:175], v[254:255]
	v_pk_add_f32 v[252:253], v[252:253], v[254:255]
	s_nop 0
	v_add_f32_e32 v183, v252, v253
	s_nop 1
	v_add_f32_dpp v183, v183, v183 quad_perm:[1,0,3,2] row_mask:0xf bank_mask:0xf bound_ctrl:1
	s_nop 1
	v_add_f32_dpp v183, v183, v183 quad_perm:[2,3,0,1] row_mask:0xf bank_mask:0xf bound_ctrl:1
	s_nop 1
	v_add_f32_dpp v183, v183, v183 row_half_mirror row_mask:0xf bank_mask:0xf bound_ctrl:1
	s_nop 1
	v_add_f32_dpp v183, v183, v183 row_mirror row_mask:0xf bank_mask:0xf bound_ctrl:1
	s_nop 1
	v_readlane_b32 s98, v183, 0
	v_readlane_b32 s99, v183, 16
	v_readlane_b32 s100, v183, 32
	v_readlane_b32 s101, v183, 48
	s_nop 1
	v_mov_b32_e32 v183, s98
	v_add_f32_e32 v183, s99, v183
	v_add_f32_e32 v183, s100, v183
	v_add_f32_e32 v183, s101, v183
	v_fmamk_f32 v183, v183, 0x3a800000, v182
	v_cmp_gt_f32_e32 vcc, 0x800000, v183
	v_mul_f32_e32 v181, 0x4b800000, v183
	s_nop 1
	v_cndmask_b32_e32 v183, v183, v181, vcc
	v_rsq_f32_e32 v183, v183
	s_nop 0
	v_mul_f32_e32 v181, 0x45800000, v183
	v_cndmask_b32_e32 v184, v183, v181, vcc
	v_mov_b32_e32 v185, v184
	v_pk_mul_f32 v[160:161], v[160:161], v[184:185]
	v_pk_mul_f32 v[162:163], v[162:163], v[184:185]
	v_pk_mul_f32 v[164:165], v[164:165], v[184:185]
	v_pk_mul_f32 v[166:167], v[166:167], v[184:185]
	v_pk_mul_f32 v[168:169], v[168:169], v[184:185]
	v_pk_mul_f32 v[170:171], v[170:171], v[184:185]
	v_pk_mul_f32 v[172:173], v[172:173], v[184:185]
	v_pk_mul_f32 v[174:175], v[174:175], v[184:185]
	v_pk_fma_f32 v[144:145], v[160:161], v[128:129], v[144:145]
	v_pk_fma_f32 v[146:147], v[162:163], v[130:131], v[146:147]
	v_pk_fma_f32 v[148:149], v[164:165], v[132:133], v[148:149]
	v_pk_fma_f32 v[150:151], v[166:167], v[134:135], v[150:151]
	v_pk_fma_f32 v[152:153], v[168:169], v[136:137], v[152:153]
	v_pk_fma_f32 v[154:155], v[170:171], v[138:139], v[154:155]
	v_pk_fma_f32 v[156:157], v[172:173], v[140:141], v[156:157]
	v_pk_fma_f32 v[158:159], v[174:175], v[142:143], v[158:159]
	v_pk_mul_f32 v[252:253], v[144:145], v[144:145]
	v_pk_mul_f32 v[254:255], v[146:147], v[146:147]
	v_pk_fma_f32 v[252:253], v[148:149], v[148:149], v[252:253]
	v_pk_fma_f32 v[254:255], v[150:151], v[150:151], v[254:255]
	v_pk_fma_f32 v[252:253], v[152:153], v[152:153], v[252:253]
	v_pk_fma_f32 v[254:255], v[154:155], v[154:155], v[254:255]
	v_pk_fma_f32 v[252:253], v[156:157], v[156:157], v[252:253]
	v_pk_fma_f32 v[254:255], v[158:159], v[158:159], v[254:255]
	v_pk_add_f32 v[252:253], v[252:253], v[254:255]
	s_nop 0
	v_add_f32_e32 v183, v252, v253
	s_nop 1
	v_add_f32_dpp v183, v183, v183 quad_perm:[1,0,3,2] row_mask:0xf bank_mask:0xf bound_ctrl:1
	s_nop 1
	v_add_f32_dpp v183, v183, v183 quad_perm:[2,3,0,1] row_mask:0xf bank_mask:0xf bound_ctrl:1
	s_nop 1
	v_add_f32_dpp v183, v183, v183 row_half_mirror row_mask:0xf bank_mask:0xf bound_ctrl:1
	s_nop 1
	v_add_f32_dpp v183, v183, v183 row_mirror row_mask:0xf bank_mask:0xf bound_ctrl:1
	s_nop 1
	v_readlane_b32 s98, v183, 0
	v_readlane_b32 s99, v183, 16
	v_readlane_b32 s100, v183, 32
	v_readlane_b32 s101, v183, 48
	s_nop 1
	v_mov_b32_e32 v183, s98
	v_add_f32_e32 v183, s99, v183
	v_add_f32_e32 v183, s100, v183
	v_add_f32_e32 v183, s101, v183
	v_fmamk_f32 v183, v183, 0x3a800000, v182
	v_cmp_gt_f32_e32 vcc, 0x800000, v183
	v_mul_f32_e32 v181, 0x4b800000, v183
	s_nop 1
	v_cndmask_b32_e32 v183, v183, v181, vcc
	v_rsq_f32_e32 v183, v183
	s_nop 0
	v_mul_f32_e32 v181, 0x45800000, v183
	v_cndmask_b32_e32 v184, v183, v181, vcc
	v_mov_b32_e32 v185, v184
	v_cvt_pk_bf16_f32 v0, v144, v145
	v_cvt_pk_bf16_f32 v1, v146, v147
	v_cvt_pk_bf16_f32 v2, v148, v149
	v_cvt_pk_bf16_f32 v3, v150, v151
	v_cvt_pk_bf16_f32 v4, v152, v153
	v_cvt_pk_bf16_f32 v5, v154, v155
	v_cvt_pk_bf16_f32 v6, v156, v157
	v_cvt_pk_bf16_f32 v7, v158, v159
	v_add_u32_e32 v181, 0x1800000, v177
	global_store_dwordx4 v181, v[0:3], s[78:79]
	global_store_dwordx4 v181, v[4:7], s[78:79] offset:1024
	v_add_u32_e32 v236, 0x0, v237
	s_mov_b64 exec, 1
	global_store_dword v236, v184, s[78:79]
	s_mov_b64 exec, -1
	s_waitcnt vmcnt(24)
	v_lshlrev_b32_e32 v144, 16, v16
	v_and_b32_e32 v145, 0xffff0000, v16
	v_lshlrev_b32_e32 v146, 16, v17
	v_and_b32_e32 v147, 0xffff0000, v17
	v_lshlrev_b32_e32 v148, 16, v18
	v_and_b32_e32 v149, 0xffff0000, v18
	v_lshlrev_b32_e32 v150, 16, v19
	v_and_b32_e32 v151, 0xffff0000, v19
	v_lshlrev_b32_e32 v152, 16, v20
	v_and_b32_e32 v153, 0xffff0000, v20
	v_lshlrev_b32_e32 v154, 16, v21
	v_and_b32_e32 v155, 0xffff0000, v21
	v_lshlrev_b32_e32 v156, 16, v22
	v_and_b32_e32 v157, 0xffff0000, v22
	v_lshlrev_b32_e32 v158, 16, v23
	v_and_b32_e32 v159, 0xffff0000, v23
	v_lshlrev_b32_e32 v160, 16, v24
	v_and_b32_e32 v161, 0xffff0000, v24
	v_lshlrev_b32_e32 v162, 16, v25
	v_and_b32_e32 v163, 0xffff0000, v25
	v_lshlrev_b32_e32 v164, 16, v26
	v_and_b32_e32 v165, 0xffff0000, v26
	v_lshlrev_b32_e32 v166, 16, v27
	v_and_b32_e32 v167, 0xffff0000, v27
	v_lshlrev_b32_e32 v168, 16, v28
	v_and_b32_e32 v169, 0xffff0000, v28
	v_lshlrev_b32_e32 v170, 16, v29
	v_and_b32_e32 v171, 0xffff0000, v29
	v_lshlrev_b32_e32 v172, 16, v30
	v_and_b32_e32 v173, 0xffff0000, v30
	v_lshlrev_b32_e32 v174, 16, v31
	v_and_b32_e32 v175, 0xffff0000, v31
	v_pk_mul_f32 v[252:253], v[160:161], v[160:161]
	v_pk_mul_f32 v[254:255], v[162:163], v[162:163]
	v_pk_fma_f32 v[252:253], v[164:165], v[164:165], v[252:253]
	v_pk_fma_f32 v[254:255], v[166:167], v[166:167], v[254:255]
	v_pk_fma_f32 v[252:253], v[168:169], v[168:169], v[252:253]
	v_pk_fma_f32 v[254:255], v[170:171], v[170:171], v[254:255]
	v_pk_fma_f32 v[252:253], v[172:173], v[172:173], v[252:253]
	v_pk_fma_f32 v[254:255], v[174:175], v[174:175], v[254:255]
	v_pk_add_f32 v[252:253], v[252:253], v[254:255]
	s_nop 0
	v_add_f32_e32 v183, v252, v253
	s_nop 1
	v_add_f32_dpp v183, v183, v183 quad_perm:[1,0,3,2] row_mask:0xf bank_mask:0xf bound_ctrl:1
	s_nop 1
	v_add_f32_dpp v183, v183, v183 quad_perm:[2,3,0,1] row_mask:0xf bank_mask:0xf bound_ctrl:1
	s_nop 1
	v_add_f32_dpp v183, v183, v183 row_half_mirror row_mask:0xf bank_mask:0xf bound_ctrl:1
	s_nop 1
	v_add_f32_dpp v183, v183, v183 row_mirror row_mask:0xf bank_mask:0xf bound_ctrl:1
	s_nop 1
	v_readlane_b32 s98, v183, 0
	v_readlane_b32 s99, v183, 16
	v_readlane_b32 s100, v183, 32
	v_readlane_b32 s101, v183, 48
	s_nop 1
	v_mov_b32_e32 v183, s98
	v_add_f32_e32 v183, s99, v183
	v_add_f32_e32 v183, s100, v183
	v_add_f32_e32 v183, s101, v183
	v_fmamk_f32 v183, v183, 0x3a800000, v182
	v_cmp_gt_f32_e32 vcc, 0x800000, v183
	v_mul_f32_e32 v181, 0x4b800000, v183
	s_nop 1
	v_cndmask_b32_e32 v183, v183, v181, vcc
	v_rsq_f32_e32 v183, v183
	s_nop 0
	v_mul_f32_e32 v181, 0x45800000, v183
	v_cndmask_b32_e32 v184, v183, v181, vcc
	v_mov_b32_e32 v185, v184
	v_pk_mul_f32 v[160:161], v[160:161], v[184:185]
	v_pk_mul_f32 v[162:163], v[162:163], v[184:185]
	v_pk_mul_f32 v[164:165], v[164:165], v[184:185]
	v_pk_mul_f32 v[166:167], v[166:167], v[184:185]
	v_pk_mul_f32 v[168:169], v[168:169], v[184:185]
	v_pk_mul_f32 v[170:171], v[170:171], v[184:185]
	v_pk_mul_f32 v[172:173], v[172:173], v[184:185]
	v_pk_mul_f32 v[174:175], v[174:175], v[184:185]
	v_pk_fma_f32 v[144:145], v[160:161], v[128:129], v[144:145]
	v_pk_fma_f32 v[146:147], v[162:163], v[130:131], v[146:147]
	v_pk_fma_f32 v[148:149], v[164:165], v[132:133], v[148:149]
	v_pk_fma_f32 v[150:151], v[166:167], v[134:135], v[150:151]
	v_pk_fma_f32 v[152:153], v[168:169], v[136:137], v[152:153]
	v_pk_fma_f32 v[154:155], v[170:171], v[138:139], v[154:155]
	v_pk_fma_f32 v[156:157], v[172:173], v[140:141], v[156:157]
	v_pk_fma_f32 v[158:159], v[174:175], v[142:143], v[158:159]
	v_pk_mul_f32 v[252:253], v[144:145], v[144:145]
	v_pk_mul_f32 v[254:255], v[146:147], v[146:147]
	v_pk_fma_f32 v[252:253], v[148:149], v[148:149], v[252:253]
	v_pk_fma_f32 v[254:255], v[150:151], v[150:151], v[254:255]
	v_pk_fma_f32 v[252:253], v[152:153], v[152:153], v[252:253]
	v_pk_fma_f32 v[254:255], v[154:155], v[154:155], v[254:255]
	v_pk_fma_f32 v[252:253], v[156:157], v[156:157], v[252:253]
	v_pk_fma_f32 v[254:255], v[158:159], v[158:159], v[254:255]
	v_pk_add_f32 v[252:253], v[252:253], v[254:255]
	s_nop 0
	v_add_f32_e32 v183, v252, v253
	s_nop 1
	v_add_f32_dpp v183, v183, v183 quad_perm:[1,0,3,2] row_mask:0xf bank_mask:0xf bound_ctrl:1
	s_nop 1
	v_add_f32_dpp v183, v183, v183 quad_perm:[2,3,0,1] row_mask:0xf bank_mask:0xf bound_ctrl:1
	s_nop 1
	v_add_f32_dpp v183, v183, v183 row_half_mirror row_mask:0xf bank_mask:0xf bound_ctrl:1
	s_nop 1
	v_add_f32_dpp v183, v183, v183 row_mirror row_mask:0xf bank_mask:0xf bound_ctrl:1
	s_nop 1
	v_readlane_b32 s98, v183, 0
	v_readlane_b32 s99, v183, 16
	v_readlane_b32 s100, v183, 32
	v_readlane_b32 s101, v183, 48
	s_nop 1
	v_mov_b32_e32 v183, s98
	v_add_f32_e32 v183, s99, v183
	v_add_f32_e32 v183, s100, v183
	v_add_f32_e32 v183, s101, v183
	v_fmamk_f32 v183, v183, 0x3a800000, v182
	v_cmp_gt_f32_e32 vcc, 0x800000, v183
	v_mul_f32_e32 v181, 0x4b800000, v183
	s_nop 1
	v_cndmask_b32_e32 v183, v183, v181, vcc
	v_rsq_f32_e32 v183, v183
	s_nop 0
	v_mul_f32_e32 v181, 0x45800000, v183
	v_cndmask_b32_e32 v184, v183, v181, vcc
	v_mov_b32_e32 v185, v184
	v_cvt_pk_bf16_f32 v16, v144, v145
	v_cvt_pk_bf16_f32 v17, v146, v147
	v_cvt_pk_bf16_f32 v18, v148, v149
	v_cvt_pk_bf16_f32 v19, v150, v151
	v_cvt_pk_bf16_f32 v20, v152, v153
	v_cvt_pk_bf16_f32 v21, v154, v155
	v_cvt_pk_bf16_f32 v22, v156, v157
	v_cvt_pk_bf16_f32 v23, v158, v159
	v_add_u32_e32 v181, 0x1c00000, v177
	global_store_dwordx4 v181, v[16:19], s[78:79]
	global_store_dwordx4 v181, v[20:23], s[78:79] offset:1024
	v_add_u32_e32 v236, 0x2000, v237
	s_mov_b64 exec, 1
	global_store_dword v236, v184, s[78:79]
	s_mov_b64 exec, -1
	s_waitcnt vmcnt(20)
	v_lshlrev_b32_e32 v144, 16, v32
	v_and_b32_e32 v145, 0xffff0000, v32
	v_lshlrev_b32_e32 v146, 16, v33
	v_and_b32_e32 v147, 0xffff0000, v33
	v_lshlrev_b32_e32 v148, 16, v34
	v_and_b32_e32 v149, 0xffff0000, v34
	v_lshlrev_b32_e32 v150, 16, v35
	v_and_b32_e32 v151, 0xffff0000, v35
	v_lshlrev_b32_e32 v152, 16, v36
	v_and_b32_e32 v153, 0xffff0000, v36
	v_lshlrev_b32_e32 v154, 16, v37
	v_and_b32_e32 v155, 0xffff0000, v37
	v_lshlrev_b32_e32 v156, 16, v38
	v_and_b32_e32 v157, 0xffff0000, v38
	v_lshlrev_b32_e32 v158, 16, v39
	v_and_b32_e32 v159, 0xffff0000, v39
	v_lshlrev_b32_e32 v160, 16, v40
	v_and_b32_e32 v161, 0xffff0000, v40
	v_lshlrev_b32_e32 v162, 16, v41
	v_and_b32_e32 v163, 0xffff0000, v41
	v_lshlrev_b32_e32 v164, 16, v42
	v_and_b32_e32 v165, 0xffff0000, v42
	v_lshlrev_b32_e32 v166, 16, v43
	v_and_b32_e32 v167, 0xffff0000, v43
	v_lshlrev_b32_e32 v168, 16, v44
	v_and_b32_e32 v169, 0xffff0000, v44
	v_lshlrev_b32_e32 v170, 16, v45
	v_and_b32_e32 v171, 0xffff0000, v45
	v_lshlrev_b32_e32 v172, 16, v46
	v_and_b32_e32 v173, 0xffff0000, v46
	v_lshlrev_b32_e32 v174, 16, v47
	v_and_b32_e32 v175, 0xffff0000, v47
	v_pk_mul_f32 v[252:253], v[160:161], v[160:161]
	v_pk_mul_f32 v[254:255], v[162:163], v[162:163]
	v_pk_fma_f32 v[252:253], v[164:165], v[164:165], v[252:253]
	v_pk_fma_f32 v[254:255], v[166:167], v[166:167], v[254:255]
	v_pk_fma_f32 v[252:253], v[168:169], v[168:169], v[252:253]
	v_pk_fma_f32 v[254:255], v[170:171], v[170:171], v[254:255]
	v_pk_fma_f32 v[252:253], v[172:173], v[172:173], v[252:253]
	v_pk_fma_f32 v[254:255], v[174:175], v[174:175], v[254:255]
	v_pk_add_f32 v[252:253], v[252:253], v[254:255]
	s_nop 0
	v_add_f32_e32 v183, v252, v253
	s_nop 1
	v_add_f32_dpp v183, v183, v183 quad_perm:[1,0,3,2] row_mask:0xf bank_mask:0xf bound_ctrl:1
	s_nop 1
	v_add_f32_dpp v183, v183, v183 quad_perm:[2,3,0,1] row_mask:0xf bank_mask:0xf bound_ctrl:1
	s_nop 1
	v_add_f32_dpp v183, v183, v183 row_half_mirror row_mask:0xf bank_mask:0xf bound_ctrl:1
	s_nop 1
	v_add_f32_dpp v183, v183, v183 row_mirror row_mask:0xf bank_mask:0xf bound_ctrl:1
	s_nop 1
	v_readlane_b32 s98, v183, 0
	v_readlane_b32 s99, v183, 16
	v_readlane_b32 s100, v183, 32
	v_readlane_b32 s101, v183, 48
	s_nop 1
	v_mov_b32_e32 v183, s98
	v_add_f32_e32 v183, s99, v183
	v_add_f32_e32 v183, s100, v183
	v_add_f32_e32 v183, s101, v183
	v_fmamk_f32 v183, v183, 0x3a800000, v182
	v_cmp_gt_f32_e32 vcc, 0x800000, v183
	v_mul_f32_e32 v181, 0x4b800000, v183
	s_nop 1
	v_cndmask_b32_e32 v183, v183, v181, vcc
	v_rsq_f32_e32 v183, v183
	s_nop 0
	v_mul_f32_e32 v181, 0x45800000, v183
	v_cndmask_b32_e32 v184, v183, v181, vcc
	v_mov_b32_e32 v185, v184
	v_pk_mul_f32 v[160:161], v[160:161], v[184:185]
	v_pk_mul_f32 v[162:163], v[162:163], v[184:185]
	v_pk_mul_f32 v[164:165], v[164:165], v[184:185]
	v_pk_mul_f32 v[166:167], v[166:167], v[184:185]
	v_pk_mul_f32 v[168:169], v[168:169], v[184:185]
	v_pk_mul_f32 v[170:171], v[170:171], v[184:185]
	v_pk_mul_f32 v[172:173], v[172:173], v[184:185]
	v_pk_mul_f32 v[174:175], v[174:175], v[184:185]
	v_pk_fma_f32 v[144:145], v[160:161], v[128:129], v[144:145]
	v_pk_fma_f32 v[146:147], v[162:163], v[130:131], v[146:147]
	v_pk_fma_f32 v[148:149], v[164:165], v[132:133], v[148:149]
	v_pk_fma_f32 v[150:151], v[166:167], v[134:135], v[150:151]
	v_pk_fma_f32 v[152:153], v[168:169], v[136:137], v[152:153]
	v_pk_fma_f32 v[154:155], v[170:171], v[138:139], v[154:155]
	v_pk_fma_f32 v[156:157], v[172:173], v[140:141], v[156:157]
	v_pk_fma_f32 v[158:159], v[174:175], v[142:143], v[158:159]
	v_pk_mul_f32 v[252:253], v[144:145], v[144:145]
	v_pk_mul_f32 v[254:255], v[146:147], v[146:147]
	v_pk_fma_f32 v[252:253], v[148:149], v[148:149], v[252:253]
	v_pk_fma_f32 v[254:255], v[150:151], v[150:151], v[254:255]
	v_pk_fma_f32 v[252:253], v[152:153], v[152:153], v[252:253]
	v_pk_fma_f32 v[254:255], v[154:155], v[154:155], v[254:255]
	v_pk_fma_f32 v[252:253], v[156:157], v[156:157], v[252:253]
	v_pk_fma_f32 v[254:255], v[158:159], v[158:159], v[254:255]
	v_pk_add_f32 v[252:253], v[252:253], v[254:255]
	s_nop 0
	v_add_f32_e32 v183, v252, v253
	s_nop 1
	v_add_f32_dpp v183, v183, v183 quad_perm:[1,0,3,2] row_mask:0xf bank_mask:0xf bound_ctrl:1
	s_nop 1
	v_add_f32_dpp v183, v183, v183 quad_perm:[2,3,0,1] row_mask:0xf bank_mask:0xf bound_ctrl:1
	s_nop 1
	v_add_f32_dpp v183, v183, v183 row_half_mirror row_mask:0xf bank_mask:0xf bound_ctrl:1
	s_nop 1
	v_add_f32_dpp v183, v183, v183 row_mirror row_mask:0xf bank_mask:0xf bound_ctrl:1
	s_nop 1
	v_readlane_b32 s98, v183, 0
	v_readlane_b32 s99, v183, 16
	v_readlane_b32 s100, v183, 32
	v_readlane_b32 s101, v183, 48
	s_nop 1
	v_mov_b32_e32 v183, s98
	v_add_f32_e32 v183, s99, v183
	v_add_f32_e32 v183, s100, v183
	v_add_f32_e32 v183, s101, v183
	v_fmamk_f32 v183, v183, 0x3a800000, v182
	v_cmp_gt_f32_e32 vcc, 0x800000, v183
	v_mul_f32_e32 v181, 0x4b800000, v183
	s_nop 1
	v_cndmask_b32_e32 v183, v183, v181, vcc
	v_rsq_f32_e32 v183, v183
	s_nop 0
	v_mul_f32_e32 v181, 0x45800000, v183
	v_cndmask_b32_e32 v184, v183, v181, vcc
	v_mov_b32_e32 v185, v184
	v_cvt_pk_bf16_f32 v32, v144, v145
	v_cvt_pk_bf16_f32 v33, v146, v147
	v_cvt_pk_bf16_f32 v34, v148, v149
	v_cvt_pk_bf16_f32 v35, v150, v151
	v_cvt_pk_bf16_f32 v36, v152, v153
	v_cvt_pk_bf16_f32 v37, v154, v155
	v_cvt_pk_bf16_f32 v38, v156, v157
	v_cvt_pk_bf16_f32 v39, v158, v159
	v_add_u32_e32 v181, 0x2000000, v177
	global_store_dwordx4 v181, v[32:35], s[78:79]
	global_store_dwordx4 v181, v[36:39], s[78:79] offset:1024
	v_add_u32_e32 v236, 0x4000, v237
	s_mov_b64 exec, 1
	global_store_dword v236, v184, s[78:79]
	s_mov_b64 exec, -1
	s_waitcnt vmcnt(16)
	v_lshlrev_b32_e32 v144, 16, v48
	v_and_b32_e32 v145, 0xffff0000, v48
	v_lshlrev_b32_e32 v146, 16, v49
	v_and_b32_e32 v147, 0xffff0000, v49
	v_lshlrev_b32_e32 v148, 16, v50
	v_and_b32_e32 v149, 0xffff0000, v50
	v_lshlrev_b32_e32 v150, 16, v51
	v_and_b32_e32 v151, 0xffff0000, v51
	v_lshlrev_b32_e32 v152, 16, v52
	v_and_b32_e32 v153, 0xffff0000, v52
	v_lshlrev_b32_e32 v154, 16, v53
	v_and_b32_e32 v155, 0xffff0000, v53
	v_lshlrev_b32_e32 v156, 16, v54
	v_and_b32_e32 v157, 0xffff0000, v54
	v_lshlrev_b32_e32 v158, 16, v55
	v_and_b32_e32 v159, 0xffff0000, v55
	v_lshlrev_b32_e32 v160, 16, v56
	v_and_b32_e32 v161, 0xffff0000, v56
	v_lshlrev_b32_e32 v162, 16, v57
	v_and_b32_e32 v163, 0xffff0000, v57
	v_lshlrev_b32_e32 v164, 16, v58
	v_and_b32_e32 v165, 0xffff0000, v58
	v_lshlrev_b32_e32 v166, 16, v59
	v_and_b32_e32 v167, 0xffff0000, v59
	v_lshlrev_b32_e32 v168, 16, v60
	v_and_b32_e32 v169, 0xffff0000, v60
	v_lshlrev_b32_e32 v170, 16, v61
	v_and_b32_e32 v171, 0xffff0000, v61
	v_lshlrev_b32_e32 v172, 16, v62
	v_and_b32_e32 v173, 0xffff0000, v62
	v_lshlrev_b32_e32 v174, 16, v63
	v_and_b32_e32 v175, 0xffff0000, v63
	v_pk_mul_f32 v[252:253], v[160:161], v[160:161]
	v_pk_mul_f32 v[254:255], v[162:163], v[162:163]
	v_pk_fma_f32 v[252:253], v[164:165], v[164:165], v[252:253]
	v_pk_fma_f32 v[254:255], v[166:167], v[166:167], v[254:255]
	v_pk_fma_f32 v[252:253], v[168:169], v[168:169], v[252:253]
	v_pk_fma_f32 v[254:255], v[170:171], v[170:171], v[254:255]
	v_pk_fma_f32 v[252:253], v[172:173], v[172:173], v[252:253]
	v_pk_fma_f32 v[254:255], v[174:175], v[174:175], v[254:255]
	v_pk_add_f32 v[252:253], v[252:253], v[254:255]
	s_nop 0
	v_add_f32_e32 v183, v252, v253
	s_nop 1
	v_add_f32_dpp v183, v183, v183 quad_perm:[1,0,3,2] row_mask:0xf bank_mask:0xf bound_ctrl:1
	s_nop 1
	v_add_f32_dpp v183, v183, v183 quad_perm:[2,3,0,1] row_mask:0xf bank_mask:0xf bound_ctrl:1
	s_nop 1
	v_add_f32_dpp v183, v183, v183 row_half_mirror row_mask:0xf bank_mask:0xf bound_ctrl:1
	s_nop 1
	v_add_f32_dpp v183, v183, v183 row_mirror row_mask:0xf bank_mask:0xf bound_ctrl:1
	s_nop 1
	v_readlane_b32 s98, v183, 0
	v_readlane_b32 s99, v183, 16
	v_readlane_b32 s100, v183, 32
	v_readlane_b32 s101, v183, 48
	s_nop 1
	v_mov_b32_e32 v183, s98
	v_add_f32_e32 v183, s99, v183
	v_add_f32_e32 v183, s100, v183
	v_add_f32_e32 v183, s101, v183
	v_fmamk_f32 v183, v183, 0x3a800000, v182
	v_cmp_gt_f32_e32 vcc, 0x800000, v183
	v_mul_f32_e32 v181, 0x4b800000, v183
	s_nop 1
	v_cndmask_b32_e32 v183, v183, v181, vcc
	v_rsq_f32_e32 v183, v183
	s_nop 0
	v_mul_f32_e32 v181, 0x45800000, v183
	v_cndmask_b32_e32 v184, v183, v181, vcc
	v_mov_b32_e32 v185, v184
	v_pk_mul_f32 v[160:161], v[160:161], v[184:185]
	v_pk_mul_f32 v[162:163], v[162:163], v[184:185]
	v_pk_mul_f32 v[164:165], v[164:165], v[184:185]
	v_pk_mul_f32 v[166:167], v[166:167], v[184:185]
	v_pk_mul_f32 v[168:169], v[168:169], v[184:185]
	v_pk_mul_f32 v[170:171], v[170:171], v[184:185]
	v_pk_mul_f32 v[172:173], v[172:173], v[184:185]
	v_pk_mul_f32 v[174:175], v[174:175], v[184:185]
	v_pk_fma_f32 v[144:145], v[160:161], v[128:129], v[144:145]
	v_pk_fma_f32 v[146:147], v[162:163], v[130:131], v[146:147]
	v_pk_fma_f32 v[148:149], v[164:165], v[132:133], v[148:149]
	v_pk_fma_f32 v[150:151], v[166:167], v[134:135], v[150:151]
	v_pk_fma_f32 v[152:153], v[168:169], v[136:137], v[152:153]
	v_pk_fma_f32 v[154:155], v[170:171], v[138:139], v[154:155]
	v_pk_fma_f32 v[156:157], v[172:173], v[140:141], v[156:157]
	v_pk_fma_f32 v[158:159], v[174:175], v[142:143], v[158:159]
	v_pk_mul_f32 v[252:253], v[144:145], v[144:145]
	v_pk_mul_f32 v[254:255], v[146:147], v[146:147]
	v_pk_fma_f32 v[252:253], v[148:149], v[148:149], v[252:253]
	v_pk_fma_f32 v[254:255], v[150:151], v[150:151], v[254:255]
	v_pk_fma_f32 v[252:253], v[152:153], v[152:153], v[252:253]
	v_pk_fma_f32 v[254:255], v[154:155], v[154:155], v[254:255]
	v_pk_fma_f32 v[252:253], v[156:157], v[156:157], v[252:253]
	v_pk_fma_f32 v[254:255], v[158:159], v[158:159], v[254:255]
	v_pk_add_f32 v[252:253], v[252:253], v[254:255]
	s_nop 0
	v_add_f32_e32 v183, v252, v253
	s_nop 1
	v_add_f32_dpp v183, v183, v183 quad_perm:[1,0,3,2] row_mask:0xf bank_mask:0xf bound_ctrl:1
	s_nop 1
	v_add_f32_dpp v183, v183, v183 quad_perm:[2,3,0,1] row_mask:0xf bank_mask:0xf bound_ctrl:1
	s_nop 1
	v_add_f32_dpp v183, v183, v183 row_half_mirror row_mask:0xf bank_mask:0xf bound_ctrl:1
	s_nop 1
	v_add_f32_dpp v183, v183, v183 row_mirror row_mask:0xf bank_mask:0xf bound_ctrl:1
	s_nop 1
	v_readlane_b32 s98, v183, 0
	v_readlane_b32 s99, v183, 16
	v_readlane_b32 s100, v183, 32
	v_readlane_b32 s101, v183, 48
	s_nop 1
	v_mov_b32_e32 v183, s98
	v_add_f32_e32 v183, s99, v183
	v_add_f32_e32 v183, s100, v183
	v_add_f32_e32 v183, s101, v183
	v_fmamk_f32 v183, v183, 0x3a800000, v182
	v_cmp_gt_f32_e32 vcc, 0x800000, v183
	v_mul_f32_e32 v181, 0x4b800000, v183
	s_nop 1
	v_cndmask_b32_e32 v183, v183, v181, vcc
	v_rsq_f32_e32 v183, v183
	s_nop 0
	v_mul_f32_e32 v181, 0x45800000, v183
	v_cndmask_b32_e32 v184, v183, v181, vcc
	v_mov_b32_e32 v185, v184
	v_cvt_pk_bf16_f32 v48, v144, v145
	v_cvt_pk_bf16_f32 v49, v146, v147
	v_cvt_pk_bf16_f32 v50, v148, v149
	v_cvt_pk_bf16_f32 v51, v150, v151
	v_cvt_pk_bf16_f32 v52, v152, v153
	v_cvt_pk_bf16_f32 v53, v154, v155
	v_cvt_pk_bf16_f32 v54, v156, v157
	v_cvt_pk_bf16_f32 v55, v158, v159
	v_add_u32_e32 v181, 0x2400000, v177
	global_store_dwordx4 v181, v[48:51], s[78:79]
	global_store_dwordx4 v181, v[52:55], s[78:79] offset:1024
	v_add_u32_e32 v236, 0x6000, v237
	s_mov_b64 exec, 1
	global_store_dword v236, v184, s[78:79]
	s_mov_b64 exec, -1
	s_waitcnt vmcnt(12)
	v_lshlrev_b32_e32 v144, 16, v64
	v_and_b32_e32 v145, 0xffff0000, v64
	v_lshlrev_b32_e32 v146, 16, v65
	v_and_b32_e32 v147, 0xffff0000, v65
	v_lshlrev_b32_e32 v148, 16, v66
	v_and_b32_e32 v149, 0xffff0000, v66
	v_lshlrev_b32_e32 v150, 16, v67
	v_and_b32_e32 v151, 0xffff0000, v67
	v_lshlrev_b32_e32 v152, 16, v68
	v_and_b32_e32 v153, 0xffff0000, v68
	v_lshlrev_b32_e32 v154, 16, v69
	v_and_b32_e32 v155, 0xffff0000, v69
	v_lshlrev_b32_e32 v156, 16, v70
	v_and_b32_e32 v157, 0xffff0000, v70
	v_lshlrev_b32_e32 v158, 16, v71
	v_and_b32_e32 v159, 0xffff0000, v71
	v_lshlrev_b32_e32 v160, 16, v72
	v_and_b32_e32 v161, 0xffff0000, v72
	v_lshlrev_b32_e32 v162, 16, v73
	v_and_b32_e32 v163, 0xffff0000, v73
	v_lshlrev_b32_e32 v164, 16, v74
	v_and_b32_e32 v165, 0xffff0000, v74
	v_lshlrev_b32_e32 v166, 16, v75
	v_and_b32_e32 v167, 0xffff0000, v75
	v_lshlrev_b32_e32 v168, 16, v76
	v_and_b32_e32 v169, 0xffff0000, v76
	v_lshlrev_b32_e32 v170, 16, v77
	v_and_b32_e32 v171, 0xffff0000, v77
	v_lshlrev_b32_e32 v172, 16, v78
	v_and_b32_e32 v173, 0xffff0000, v78
	v_lshlrev_b32_e32 v174, 16, v79
	v_and_b32_e32 v175, 0xffff0000, v79
	v_pk_mul_f32 v[252:253], v[160:161], v[160:161]
	v_pk_mul_f32 v[254:255], v[162:163], v[162:163]
	v_pk_fma_f32 v[252:253], v[164:165], v[164:165], v[252:253]
	v_pk_fma_f32 v[254:255], v[166:167], v[166:167], v[254:255]
	v_pk_fma_f32 v[252:253], v[168:169], v[168:169], v[252:253]
	v_pk_fma_f32 v[254:255], v[170:171], v[170:171], v[254:255]
	v_pk_fma_f32 v[252:253], v[172:173], v[172:173], v[252:253]
	v_pk_fma_f32 v[254:255], v[174:175], v[174:175], v[254:255]
	v_pk_add_f32 v[252:253], v[252:253], v[254:255]
	s_nop 0
	v_add_f32_e32 v183, v252, v253
	s_nop 1
	v_add_f32_dpp v183, v183, v183 quad_perm:[1,0,3,2] row_mask:0xf bank_mask:0xf bound_ctrl:1
	s_nop 1
	v_add_f32_dpp v183, v183, v183 quad_perm:[2,3,0,1] row_mask:0xf bank_mask:0xf bound_ctrl:1
	s_nop 1
	v_add_f32_dpp v183, v183, v183 row_half_mirror row_mask:0xf bank_mask:0xf bound_ctrl:1
	s_nop 1
	v_add_f32_dpp v183, v183, v183 row_mirror row_mask:0xf bank_mask:0xf bound_ctrl:1
	s_nop 1
	v_readlane_b32 s98, v183, 0
	v_readlane_b32 s99, v183, 16
	v_readlane_b32 s100, v183, 32
	v_readlane_b32 s101, v183, 48
	s_nop 1
	v_mov_b32_e32 v183, s98
	v_add_f32_e32 v183, s99, v183
	v_add_f32_e32 v183, s100, v183
	v_add_f32_e32 v183, s101, v183
	v_fmamk_f32 v183, v183, 0x3a800000, v182
	v_cmp_gt_f32_e32 vcc, 0x800000, v183
	v_mul_f32_e32 v181, 0x4b800000, v183
	s_nop 1
	v_cndmask_b32_e32 v183, v183, v181, vcc
	v_rsq_f32_e32 v183, v183
	s_nop 0
	v_mul_f32_e32 v181, 0x45800000, v183
	v_cndmask_b32_e32 v184, v183, v181, vcc
	v_mov_b32_e32 v185, v184
	v_pk_mul_f32 v[160:161], v[160:161], v[184:185]
	v_pk_mul_f32 v[162:163], v[162:163], v[184:185]
	v_pk_mul_f32 v[164:165], v[164:165], v[184:185]
	v_pk_mul_f32 v[166:167], v[166:167], v[184:185]
	v_pk_mul_f32 v[168:169], v[168:169], v[184:185]
	v_pk_mul_f32 v[170:171], v[170:171], v[184:185]
	v_pk_mul_f32 v[172:173], v[172:173], v[184:185]
	v_pk_mul_f32 v[174:175], v[174:175], v[184:185]
	v_pk_fma_f32 v[144:145], v[160:161], v[128:129], v[144:145]
	v_pk_fma_f32 v[146:147], v[162:163], v[130:131], v[146:147]
	v_pk_fma_f32 v[148:149], v[164:165], v[132:133], v[148:149]
	v_pk_fma_f32 v[150:151], v[166:167], v[134:135], v[150:151]
	v_pk_fma_f32 v[152:153], v[168:169], v[136:137], v[152:153]
	v_pk_fma_f32 v[154:155], v[170:171], v[138:139], v[154:155]
	v_pk_fma_f32 v[156:157], v[172:173], v[140:141], v[156:157]
	v_pk_fma_f32 v[158:159], v[174:175], v[142:143], v[158:159]
	v_pk_mul_f32 v[252:253], v[144:145], v[144:145]
	v_pk_mul_f32 v[254:255], v[146:147], v[146:147]
	v_pk_fma_f32 v[252:253], v[148:149], v[148:149], v[252:253]
	v_pk_fma_f32 v[254:255], v[150:151], v[150:151], v[254:255]
	v_pk_fma_f32 v[252:253], v[152:153], v[152:153], v[252:253]
	v_pk_fma_f32 v[254:255], v[154:155], v[154:155], v[254:255]
	v_pk_fma_f32 v[252:253], v[156:157], v[156:157], v[252:253]
	v_pk_fma_f32 v[254:255], v[158:159], v[158:159], v[254:255]
	v_pk_add_f32 v[252:253], v[252:253], v[254:255]
	s_nop 0
	v_add_f32_e32 v183, v252, v253
	s_nop 1
	v_add_f32_dpp v183, v183, v183 quad_perm:[1,0,3,2] row_mask:0xf bank_mask:0xf bound_ctrl:1
	s_nop 1
	v_add_f32_dpp v183, v183, v183 quad_perm:[2,3,0,1] row_mask:0xf bank_mask:0xf bound_ctrl:1
	s_nop 1
	v_add_f32_dpp v183, v183, v183 row_half_mirror row_mask:0xf bank_mask:0xf bound_ctrl:1
	s_nop 1
	v_add_f32_dpp v183, v183, v183 row_mirror row_mask:0xf bank_mask:0xf bound_ctrl:1
	s_nop 1
	v_readlane_b32 s98, v183, 0
	v_readlane_b32 s99, v183, 16
	v_readlane_b32 s100, v183, 32
	v_readlane_b32 s101, v183, 48
	s_nop 1
	v_mov_b32_e32 v183, s98
	v_add_f32_e32 v183, s99, v183
	v_add_f32_e32 v183, s100, v183
	v_add_f32_e32 v183, s101, v183
	v_fmamk_f32 v183, v183, 0x3a800000, v182
	v_cmp_gt_f32_e32 vcc, 0x800000, v183
	v_mul_f32_e32 v181, 0x4b800000, v183
	s_nop 1
	v_cndmask_b32_e32 v183, v183, v181, vcc
	v_rsq_f32_e32 v183, v183
	s_nop 0
	v_mul_f32_e32 v181, 0x45800000, v183
	v_cndmask_b32_e32 v184, v183, v181, vcc
	v_mov_b32_e32 v185, v184
	v_cvt_pk_bf16_f32 v64, v144, v145
	v_cvt_pk_bf16_f32 v65, v146, v147
	v_cvt_pk_bf16_f32 v66, v148, v149
	v_cvt_pk_bf16_f32 v67, v150, v151
	v_cvt_pk_bf16_f32 v68, v152, v153
	v_cvt_pk_bf16_f32 v69, v154, v155
	v_cvt_pk_bf16_f32 v70, v156, v157
	v_cvt_pk_bf16_f32 v71, v158, v159
	v_add_u32_e32 v181, 0x2800000, v177
	global_store_dwordx4 v181, v[64:67], s[78:79]
	global_store_dwordx4 v181, v[68:71], s[78:79] offset:1024
	v_add_u32_e32 v236, 0x8000, v237
	s_mov_b64 exec, 1
	global_store_dword v236, v184, s[78:79]
	s_mov_b64 exec, -1
	s_waitcnt vmcnt(8)
	v_lshlrev_b32_e32 v144, 16, v80
	v_and_b32_e32 v145, 0xffff0000, v80
	v_lshlrev_b32_e32 v146, 16, v81
	v_and_b32_e32 v147, 0xffff0000, v81
	v_lshlrev_b32_e32 v148, 16, v82
	v_and_b32_e32 v149, 0xffff0000, v82
	v_lshlrev_b32_e32 v150, 16, v83
	v_and_b32_e32 v151, 0xffff0000, v83
	v_lshlrev_b32_e32 v152, 16, v84
	v_and_b32_e32 v153, 0xffff0000, v84
	v_lshlrev_b32_e32 v154, 16, v85
	v_and_b32_e32 v155, 0xffff0000, v85
	v_lshlrev_b32_e32 v156, 16, v86
	v_and_b32_e32 v157, 0xffff0000, v86
	v_lshlrev_b32_e32 v158, 16, v87
	v_and_b32_e32 v159, 0xffff0000, v87
	v_lshlrev_b32_e32 v160, 16, v88
	v_and_b32_e32 v161, 0xffff0000, v88
	v_lshlrev_b32_e32 v162, 16, v89
	v_and_b32_e32 v163, 0xffff0000, v89
	v_lshlrev_b32_e32 v164, 16, v90
	v_and_b32_e32 v165, 0xffff0000, v90
	v_lshlrev_b32_e32 v166, 16, v91
	v_and_b32_e32 v167, 0xffff0000, v91
	v_lshlrev_b32_e32 v168, 16, v92
	v_and_b32_e32 v169, 0xffff0000, v92
	v_lshlrev_b32_e32 v170, 16, v93
	v_and_b32_e32 v171, 0xffff0000, v93
	v_lshlrev_b32_e32 v172, 16, v94
	v_and_b32_e32 v173, 0xffff0000, v94
	v_lshlrev_b32_e32 v174, 16, v95
	v_and_b32_e32 v175, 0xffff0000, v95
	v_pk_mul_f32 v[252:253], v[160:161], v[160:161]
	v_pk_mul_f32 v[254:255], v[162:163], v[162:163]
	v_pk_fma_f32 v[252:253], v[164:165], v[164:165], v[252:253]
	v_pk_fma_f32 v[254:255], v[166:167], v[166:167], v[254:255]
	v_pk_fma_f32 v[252:253], v[168:169], v[168:169], v[252:253]
	v_pk_fma_f32 v[254:255], v[170:171], v[170:171], v[254:255]
	v_pk_fma_f32 v[252:253], v[172:173], v[172:173], v[252:253]
	v_pk_fma_f32 v[254:255], v[174:175], v[174:175], v[254:255]
	v_pk_add_f32 v[252:253], v[252:253], v[254:255]
	s_nop 0
	v_add_f32_e32 v183, v252, v253
	s_nop 1
	v_add_f32_dpp v183, v183, v183 quad_perm:[1,0,3,2] row_mask:0xf bank_mask:0xf bound_ctrl:1
	s_nop 1
	v_add_f32_dpp v183, v183, v183 quad_perm:[2,3,0,1] row_mask:0xf bank_mask:0xf bound_ctrl:1
	s_nop 1
	v_add_f32_dpp v183, v183, v183 row_half_mirror row_mask:0xf bank_mask:0xf bound_ctrl:1
	s_nop 1
	v_add_f32_dpp v183, v183, v183 row_mirror row_mask:0xf bank_mask:0xf bound_ctrl:1
	s_nop 1
	v_readlane_b32 s98, v183, 0
	v_readlane_b32 s99, v183, 16
	v_readlane_b32 s100, v183, 32
	v_readlane_b32 s101, v183, 48
	s_nop 1
	v_mov_b32_e32 v183, s98
	v_add_f32_e32 v183, s99, v183
	v_add_f32_e32 v183, s100, v183
	v_add_f32_e32 v183, s101, v183
	v_fmamk_f32 v183, v183, 0x3a800000, v182
	v_cmp_gt_f32_e32 vcc, 0x800000, v183
	v_mul_f32_e32 v181, 0x4b800000, v183
	s_nop 1
	v_cndmask_b32_e32 v183, v183, v181, vcc
	v_rsq_f32_e32 v183, v183
	s_nop 0
	v_mul_f32_e32 v181, 0x45800000, v183
	v_cndmask_b32_e32 v184, v183, v181, vcc
	v_mov_b32_e32 v185, v184
	v_pk_mul_f32 v[160:161], v[160:161], v[184:185]
	v_pk_mul_f32 v[162:163], v[162:163], v[184:185]
	v_pk_mul_f32 v[164:165], v[164:165], v[184:185]
	v_pk_mul_f32 v[166:167], v[166:167], v[184:185]
	v_pk_mul_f32 v[168:169], v[168:169], v[184:185]
	v_pk_mul_f32 v[170:171], v[170:171], v[184:185]
	v_pk_mul_f32 v[172:173], v[172:173], v[184:185]
	v_pk_mul_f32 v[174:175], v[174:175], v[184:185]
	v_pk_fma_f32 v[144:145], v[160:161], v[128:129], v[144:145]
	v_pk_fma_f32 v[146:147], v[162:163], v[130:131], v[146:147]
	v_pk_fma_f32 v[148:149], v[164:165], v[132:133], v[148:149]
	v_pk_fma_f32 v[150:151], v[166:167], v[134:135], v[150:151]
	v_pk_fma_f32 v[152:153], v[168:169], v[136:137], v[152:153]
	v_pk_fma_f32 v[154:155], v[170:171], v[138:139], v[154:155]
	v_pk_fma_f32 v[156:157], v[172:173], v[140:141], v[156:157]
	v_pk_fma_f32 v[158:159], v[174:175], v[142:143], v[158:159]
	v_pk_mul_f32 v[252:253], v[144:145], v[144:145]
	v_pk_mul_f32 v[254:255], v[146:147], v[146:147]
	v_pk_fma_f32 v[252:253], v[148:149], v[148:149], v[252:253]
	v_pk_fma_f32 v[254:255], v[150:151], v[150:151], v[254:255]
	v_pk_fma_f32 v[252:253], v[152:153], v[152:153], v[252:253]
	v_pk_fma_f32 v[254:255], v[154:155], v[154:155], v[254:255]
	v_pk_fma_f32 v[252:253], v[156:157], v[156:157], v[252:253]
	v_pk_fma_f32 v[254:255], v[158:159], v[158:159], v[254:255]
	v_pk_add_f32 v[252:253], v[252:253], v[254:255]
	s_nop 0
	v_add_f32_e32 v183, v252, v253
	s_nop 1
	v_add_f32_dpp v183, v183, v183 quad_perm:[1,0,3,2] row_mask:0xf bank_mask:0xf bound_ctrl:1
	s_nop 1
	v_add_f32_dpp v183, v183, v183 quad_perm:[2,3,0,1] row_mask:0xf bank_mask:0xf bound_ctrl:1
	s_nop 1
	v_add_f32_dpp v183, v183, v183 row_half_mirror row_mask:0xf bank_mask:0xf bound_ctrl:1
	s_nop 1
	v_add_f32_dpp v183, v183, v183 row_mirror row_mask:0xf bank_mask:0xf bound_ctrl:1
	s_nop 1
	v_readlane_b32 s98, v183, 0
	v_readlane_b32 s99, v183, 16
	v_readlane_b32 s100, v183, 32
	v_readlane_b32 s101, v183, 48
	s_nop 1
	v_mov_b32_e32 v183, s98
	v_add_f32_e32 v183, s99, v183
	v_add_f32_e32 v183, s100, v183
	v_add_f32_e32 v183, s101, v183
	v_fmamk_f32 v183, v183, 0x3a800000, v182
	v_cmp_gt_f32_e32 vcc, 0x800000, v183
	v_mul_f32_e32 v181, 0x4b800000, v183
	s_nop 1
	v_cndmask_b32_e32 v183, v183, v181, vcc
	v_rsq_f32_e32 v183, v183
	s_nop 0
	v_mul_f32_e32 v181, 0x45800000, v183
	v_cndmask_b32_e32 v184, v183, v181, vcc
	v_mov_b32_e32 v185, v184
	v_cvt_pk_bf16_f32 v80, v144, v145
	v_cvt_pk_bf16_f32 v81, v146, v147
	v_cvt_pk_bf16_f32 v82, v148, v149
	v_cvt_pk_bf16_f32 v83, v150, v151
	v_cvt_pk_bf16_f32 v84, v152, v153
	v_cvt_pk_bf16_f32 v85, v154, v155
	v_cvt_pk_bf16_f32 v86, v156, v157
	v_cvt_pk_bf16_f32 v87, v158, v159
	v_add_u32_e32 v181, 0x2c00000, v177
	global_store_dwordx4 v181, v[80:83], s[78:79]
	global_store_dwordx4 v181, v[84:87], s[78:79] offset:1024
	v_add_u32_e32 v236, 0xa000, v237
	s_mov_b64 exec, 1
	global_store_dword v236, v184, s[78:79]
	s_mov_b64 exec, -1
	s_waitcnt vmcnt(4)
	v_lshlrev_b32_e32 v144, 16, v96
	v_and_b32_e32 v145, 0xffff0000, v96
	v_lshlrev_b32_e32 v146, 16, v97
	v_and_b32_e32 v147, 0xffff0000, v97
	v_lshlrev_b32_e32 v148, 16, v98
	v_and_b32_e32 v149, 0xffff0000, v98
	v_lshlrev_b32_e32 v150, 16, v99
	v_and_b32_e32 v151, 0xffff0000, v99
	v_lshlrev_b32_e32 v152, 16, v100
	v_and_b32_e32 v153, 0xffff0000, v100
	v_lshlrev_b32_e32 v154, 16, v101
	v_and_b32_e32 v155, 0xffff0000, v101
	v_lshlrev_b32_e32 v156, 16, v102
	v_and_b32_e32 v157, 0xffff0000, v102
	v_lshlrev_b32_e32 v158, 16, v103
	v_and_b32_e32 v159, 0xffff0000, v103
	v_lshlrev_b32_e32 v160, 16, v104
	v_and_b32_e32 v161, 0xffff0000, v104
	v_lshlrev_b32_e32 v162, 16, v105
	v_and_b32_e32 v163, 0xffff0000, v105
	v_lshlrev_b32_e32 v164, 16, v106
	v_and_b32_e32 v165, 0xffff0000, v106
	v_lshlrev_b32_e32 v166, 16, v107
	v_and_b32_e32 v167, 0xffff0000, v107
	v_lshlrev_b32_e32 v168, 16, v108
	v_and_b32_e32 v169, 0xffff0000, v108
	v_lshlrev_b32_e32 v170, 16, v109
	v_and_b32_e32 v171, 0xffff0000, v109
	v_lshlrev_b32_e32 v172, 16, v110
	v_and_b32_e32 v173, 0xffff0000, v110
	v_lshlrev_b32_e32 v174, 16, v111
	v_and_b32_e32 v175, 0xffff0000, v111
	v_pk_mul_f32 v[252:253], v[160:161], v[160:161]
	v_pk_mul_f32 v[254:255], v[162:163], v[162:163]
	v_pk_fma_f32 v[252:253], v[164:165], v[164:165], v[252:253]
	v_pk_fma_f32 v[254:255], v[166:167], v[166:167], v[254:255]
	v_pk_fma_f32 v[252:253], v[168:169], v[168:169], v[252:253]
	v_pk_fma_f32 v[254:255], v[170:171], v[170:171], v[254:255]
	v_pk_fma_f32 v[252:253], v[172:173], v[172:173], v[252:253]
	v_pk_fma_f32 v[254:255], v[174:175], v[174:175], v[254:255]
	v_pk_add_f32 v[252:253], v[252:253], v[254:255]
	s_nop 0
	v_add_f32_e32 v183, v252, v253
	s_nop 1
	v_add_f32_dpp v183, v183, v183 quad_perm:[1,0,3,2] row_mask:0xf bank_mask:0xf bound_ctrl:1
	s_nop 1
	v_add_f32_dpp v183, v183, v183 quad_perm:[2,3,0,1] row_mask:0xf bank_mask:0xf bound_ctrl:1
	s_nop 1
	v_add_f32_dpp v183, v183, v183 row_half_mirror row_mask:0xf bank_mask:0xf bound_ctrl:1
	s_nop 1
	v_add_f32_dpp v183, v183, v183 row_mirror row_mask:0xf bank_mask:0xf bound_ctrl:1
	s_nop 1
	v_readlane_b32 s98, v183, 0
	v_readlane_b32 s99, v183, 16
	v_readlane_b32 s100, v183, 32
	v_readlane_b32 s101, v183, 48
	s_nop 1
	v_mov_b32_e32 v183, s98
	v_add_f32_e32 v183, s99, v183
	v_add_f32_e32 v183, s100, v183
	v_add_f32_e32 v183, s101, v183
	v_fmamk_f32 v183, v183, 0x3a800000, v182
	v_cmp_gt_f32_e32 vcc, 0x800000, v183
	v_mul_f32_e32 v181, 0x4b800000, v183
	s_nop 1
	v_cndmask_b32_e32 v183, v183, v181, vcc
	v_rsq_f32_e32 v183, v183
	s_nop 0
	v_mul_f32_e32 v181, 0x45800000, v183
	v_cndmask_b32_e32 v184, v183, v181, vcc
	v_mov_b32_e32 v185, v184
	v_pk_mul_f32 v[160:161], v[160:161], v[184:185]
	v_pk_mul_f32 v[162:163], v[162:163], v[184:185]
	v_pk_mul_f32 v[164:165], v[164:165], v[184:185]
	v_pk_mul_f32 v[166:167], v[166:167], v[184:185]
	v_pk_mul_f32 v[168:169], v[168:169], v[184:185]
	v_pk_mul_f32 v[170:171], v[170:171], v[184:185]
	v_pk_mul_f32 v[172:173], v[172:173], v[184:185]
	v_pk_mul_f32 v[174:175], v[174:175], v[184:185]
	v_pk_fma_f32 v[144:145], v[160:161], v[128:129], v[144:145]
	v_pk_fma_f32 v[146:147], v[162:163], v[130:131], v[146:147]
	v_pk_fma_f32 v[148:149], v[164:165], v[132:133], v[148:149]
	v_pk_fma_f32 v[150:151], v[166:167], v[134:135], v[150:151]
	v_pk_fma_f32 v[152:153], v[168:169], v[136:137], v[152:153]
	v_pk_fma_f32 v[154:155], v[170:171], v[138:139], v[154:155]
	v_pk_fma_f32 v[156:157], v[172:173], v[140:141], v[156:157]
	v_pk_fma_f32 v[158:159], v[174:175], v[142:143], v[158:159]
	v_pk_mul_f32 v[252:253], v[144:145], v[144:145]
	v_pk_mul_f32 v[254:255], v[146:147], v[146:147]
	v_pk_fma_f32 v[252:253], v[148:149], v[148:149], v[252:253]
	v_pk_fma_f32 v[254:255], v[150:151], v[150:151], v[254:255]
	v_pk_fma_f32 v[252:253], v[152:153], v[152:153], v[252:253]
	v_pk_fma_f32 v[254:255], v[154:155], v[154:155], v[254:255]
	v_pk_fma_f32 v[252:253], v[156:157], v[156:157], v[252:253]
	v_pk_fma_f32 v[254:255], v[158:159], v[158:159], v[254:255]
	v_pk_add_f32 v[252:253], v[252:253], v[254:255]
	s_nop 0
	v_add_f32_e32 v183, v252, v253
	s_nop 1
	v_add_f32_dpp v183, v183, v183 quad_perm:[1,0,3,2] row_mask:0xf bank_mask:0xf bound_ctrl:1
	s_nop 1
	v_add_f32_dpp v183, v183, v183 quad_perm:[2,3,0,1] row_mask:0xf bank_mask:0xf bound_ctrl:1
	s_nop 1
	v_add_f32_dpp v183, v183, v183 row_half_mirror row_mask:0xf bank_mask:0xf bound_ctrl:1
	s_nop 1
	v_add_f32_dpp v183, v183, v183 row_mirror row_mask:0xf bank_mask:0xf bound_ctrl:1
	s_nop 1
	v_readlane_b32 s98, v183, 0
	v_readlane_b32 s99, v183, 16
	v_readlane_b32 s100, v183, 32
	v_readlane_b32 s101, v183, 48
	s_nop 1
	v_mov_b32_e32 v183, s98
	v_add_f32_e32 v183, s99, v183
	v_add_f32_e32 v183, s100, v183
	v_add_f32_e32 v183, s101, v183
	v_fmamk_f32 v183, v183, 0x3a800000, v182
	v_cmp_gt_f32_e32 vcc, 0x800000, v183
	v_mul_f32_e32 v181, 0x4b800000, v183
	s_nop 1
	v_cndmask_b32_e32 v183, v183, v181, vcc
	v_rsq_f32_e32 v183, v183
	s_nop 0
	v_mul_f32_e32 v181, 0x45800000, v183
	v_cndmask_b32_e32 v184, v183, v181, vcc
	v_mov_b32_e32 v185, v184
	v_cvt_pk_bf16_f32 v96, v144, v145
	v_cvt_pk_bf16_f32 v97, v146, v147
	v_cvt_pk_bf16_f32 v98, v148, v149
	v_cvt_pk_bf16_f32 v99, v150, v151
	v_cvt_pk_bf16_f32 v100, v152, v153
	v_cvt_pk_bf16_f32 v101, v154, v155
	v_cvt_pk_bf16_f32 v102, v156, v157
	v_cvt_pk_bf16_f32 v103, v158, v159
	v_add_u32_e32 v181, 0x3000000, v177
	global_store_dwordx4 v181, v[96:99], s[78:79]
	global_store_dwordx4 v181, v[100:103], s[78:79] offset:1024
	v_add_u32_e32 v236, 0xc000, v237
	s_mov_b64 exec, 1
	global_store_dword v236, v184, s[78:79]
	s_mov_b64 exec, -1
	s_waitcnt vmcnt(0)
	v_lshlrev_b32_e32 v144, 16, v112
	v_and_b32_e32 v145, 0xffff0000, v112
	v_lshlrev_b32_e32 v146, 16, v113
	v_and_b32_e32 v147, 0xffff0000, v113
	v_lshlrev_b32_e32 v148, 16, v114
	v_and_b32_e32 v149, 0xffff0000, v114
	v_lshlrev_b32_e32 v150, 16, v115
	v_and_b32_e32 v151, 0xffff0000, v115
	v_lshlrev_b32_e32 v152, 16, v116
	v_and_b32_e32 v153, 0xffff0000, v116
	v_lshlrev_b32_e32 v154, 16, v117
	v_and_b32_e32 v155, 0xffff0000, v117
	v_lshlrev_b32_e32 v156, 16, v118
	v_and_b32_e32 v157, 0xffff0000, v118
	v_lshlrev_b32_e32 v158, 16, v119
	v_and_b32_e32 v159, 0xffff0000, v119
	v_lshlrev_b32_e32 v160, 16, v120
	v_and_b32_e32 v161, 0xffff0000, v120
	v_lshlrev_b32_e32 v162, 16, v121
	v_and_b32_e32 v163, 0xffff0000, v121
	v_lshlrev_b32_e32 v164, 16, v122
	v_and_b32_e32 v165, 0xffff0000, v122
	v_lshlrev_b32_e32 v166, 16, v123
	v_and_b32_e32 v167, 0xffff0000, v123
	v_lshlrev_b32_e32 v168, 16, v124
	v_and_b32_e32 v169, 0xffff0000, v124
	v_lshlrev_b32_e32 v170, 16, v125
	v_and_b32_e32 v171, 0xffff0000, v125
	v_lshlrev_b32_e32 v172, 16, v126
	v_and_b32_e32 v173, 0xffff0000, v126
	v_lshlrev_b32_e32 v174, 16, v127
	v_and_b32_e32 v175, 0xffff0000, v127
	v_pk_mul_f32 v[252:253], v[160:161], v[160:161]
	v_pk_mul_f32 v[254:255], v[162:163], v[162:163]
	v_pk_fma_f32 v[252:253], v[164:165], v[164:165], v[252:253]
	v_pk_fma_f32 v[254:255], v[166:167], v[166:167], v[254:255]
	v_pk_fma_f32 v[252:253], v[168:169], v[168:169], v[252:253]
	v_pk_fma_f32 v[254:255], v[170:171], v[170:171], v[254:255]
	v_pk_fma_f32 v[252:253], v[172:173], v[172:173], v[252:253]
	v_pk_fma_f32 v[254:255], v[174:175], v[174:175], v[254:255]
	v_pk_add_f32 v[252:253], v[252:253], v[254:255]
	s_nop 0
	v_add_f32_e32 v183, v252, v253
	s_nop 1
	v_add_f32_dpp v183, v183, v183 quad_perm:[1,0,3,2] row_mask:0xf bank_mask:0xf bound_ctrl:1
	s_nop 1
	v_add_f32_dpp v183, v183, v183 quad_perm:[2,3,0,1] row_mask:0xf bank_mask:0xf bound_ctrl:1
	s_nop 1
	v_add_f32_dpp v183, v183, v183 row_half_mirror row_mask:0xf bank_mask:0xf bound_ctrl:1
	s_nop 1
	v_add_f32_dpp v183, v183, v183 row_mirror row_mask:0xf bank_mask:0xf bound_ctrl:1
	s_nop 1
	v_readlane_b32 s98, v183, 0
	v_readlane_b32 s99, v183, 16
	v_readlane_b32 s100, v183, 32
	v_readlane_b32 s101, v183, 48
	s_nop 1
	v_mov_b32_e32 v183, s98
	v_add_f32_e32 v183, s99, v183
	v_add_f32_e32 v183, s100, v183
	v_add_f32_e32 v183, s101, v183
	v_fmamk_f32 v183, v183, 0x3a800000, v182
	v_cmp_gt_f32_e32 vcc, 0x800000, v183
	v_mul_f32_e32 v181, 0x4b800000, v183
	s_nop 1
	v_cndmask_b32_e32 v183, v183, v181, vcc
	v_rsq_f32_e32 v183, v183
	s_nop 0
	v_mul_f32_e32 v181, 0x45800000, v183
	v_cndmask_b32_e32 v184, v183, v181, vcc
	v_mov_b32_e32 v185, v184
	v_pk_mul_f32 v[160:161], v[160:161], v[184:185]
	v_pk_mul_f32 v[162:163], v[162:163], v[184:185]
	v_pk_mul_f32 v[164:165], v[164:165], v[184:185]
	v_pk_mul_f32 v[166:167], v[166:167], v[184:185]
	v_pk_mul_f32 v[168:169], v[168:169], v[184:185]
	v_pk_mul_f32 v[170:171], v[170:171], v[184:185]
	v_pk_mul_f32 v[172:173], v[172:173], v[184:185]
	v_pk_mul_f32 v[174:175], v[174:175], v[184:185]
	v_pk_fma_f32 v[144:145], v[160:161], v[128:129], v[144:145]
	v_pk_fma_f32 v[146:147], v[162:163], v[130:131], v[146:147]
	v_pk_fma_f32 v[148:149], v[164:165], v[132:133], v[148:149]
	v_pk_fma_f32 v[150:151], v[166:167], v[134:135], v[150:151]
	v_pk_fma_f32 v[152:153], v[168:169], v[136:137], v[152:153]
	v_pk_fma_f32 v[154:155], v[170:171], v[138:139], v[154:155]
	v_pk_fma_f32 v[156:157], v[172:173], v[140:141], v[156:157]
	v_pk_fma_f32 v[158:159], v[174:175], v[142:143], v[158:159]
	v_pk_mul_f32 v[252:253], v[144:145], v[144:145]
	v_pk_mul_f32 v[254:255], v[146:147], v[146:147]
	v_pk_fma_f32 v[252:253], v[148:149], v[148:149], v[252:253]
	v_pk_fma_f32 v[254:255], v[150:151], v[150:151], v[254:255]
	v_pk_fma_f32 v[252:253], v[152:153], v[152:153], v[252:253]
	v_pk_fma_f32 v[254:255], v[154:155], v[154:155], v[254:255]
	v_pk_fma_f32 v[252:253], v[156:157], v[156:157], v[252:253]
	v_pk_fma_f32 v[254:255], v[158:159], v[158:159], v[254:255]
	v_pk_add_f32 v[252:253], v[252:253], v[254:255]
	s_nop 0
	v_add_f32_e32 v183, v252, v253
	s_nop 1
	v_add_f32_dpp v183, v183, v183 quad_perm:[1,0,3,2] row_mask:0xf bank_mask:0xf bound_ctrl:1
	s_nop 1
	v_add_f32_dpp v183, v183, v183 quad_perm:[2,3,0,1] row_mask:0xf bank_mask:0xf bound_ctrl:1
	s_nop 1
	v_add_f32_dpp v183, v183, v183 row_half_mirror row_mask:0xf bank_mask:0xf bound_ctrl:1
	s_nop 1
	v_add_f32_dpp v183, v183, v183 row_mirror row_mask:0xf bank_mask:0xf bound_ctrl:1
	s_nop 1
	v_readlane_b32 s98, v183, 0
	v_readlane_b32 s99, v183, 16
	v_readlane_b32 s100, v183, 32
	v_readlane_b32 s101, v183, 48
	s_nop 1
	v_mov_b32_e32 v183, s98
	v_add_f32_e32 v183, s99, v183
	v_add_f32_e32 v183, s100, v183
	v_add_f32_e32 v183, s101, v183
	v_fmamk_f32 v183, v183, 0x3a800000, v182
	v_cmp_gt_f32_e32 vcc, 0x800000, v183
	v_mul_f32_e32 v181, 0x4b800000, v183
	s_nop 1
	v_cndmask_b32_e32 v183, v183, v181, vcc
	v_rsq_f32_e32 v183, v183
	s_nop 0
	v_mul_f32_e32 v181, 0x45800000, v183
	v_cndmask_b32_e32 v184, v183, v181, vcc
	v_mov_b32_e32 v185, v184
	v_cvt_pk_bf16_f32 v112, v144, v145
	v_cvt_pk_bf16_f32 v113, v146, v147
	v_cvt_pk_bf16_f32 v114, v148, v149
	v_cvt_pk_bf16_f32 v115, v150, v151
	v_cvt_pk_bf16_f32 v116, v152, v153
	v_cvt_pk_bf16_f32 v117, v154, v155
	v_cvt_pk_bf16_f32 v118, v156, v157
	v_cvt_pk_bf16_f32 v119, v158, v159
	v_add_u32_e32 v181, 0x3400000, v177
	global_store_dwordx4 v181, v[112:115], s[78:79]
	global_store_dwordx4 v181, v[116:119], s[78:79] offset:1024
	v_add_u32_e32 v236, 0xe000, v237
	s_mov_b64 exec, 1
	global_store_dword v236, v184, s[78:79]
	s_mov_b64 exec, -1
	v_readfirstlane_b32 s98, v179
	s_nop 3
	s_cmp_ge_u32 s98, 512
	s_cbranch_scc1 .Lmyxupd_done_3
	v_lshlrev_b32_e32 v177, 4, v176
	v_lshl_add_u32 v177, v179, 11, v177
	v_lshlrev_b32_e32 v237, 2, v179
	v_add_u32_e32 v237, 0x10000, v237
	v_add_u32_e32 v181, 0x3800000, v177
	global_load_dwordx4 v[0:3], v181, s[78:79]
	global_load_dwordx4 v[4:7], v181, s[78:79] offset:1024
	v_lshl_add_u32 v183, v179, 12, v180
	v_add_u32_e32 v183, 0xbf00000, v183
	v_add_u32_e32 v181, 0x0, v183
	global_load_dwordx4 v[8:11], v181, s[78:79]
	global_load_dwordx4 v[12:15], v181, s[78:79] offset:16
	global_load_dwordx4 v[16:19], v181, s[78:79] offset:2048
	global_load_dwordx4 v[20:23], v181, s[78:79] offset:2064
	v_add_u32_e32 v181, 0x200000, v183
	global_load_dwordx4 v[24:27], v181, s[78:79]
	global_load_dwordx4 v[28:31], v181, s[78:79] offset:16
	global_load_dwordx4 v[32:35], v181, s[78:79] offset:2048
	global_load_dwordx4 v[36:39], v181, s[78:79] offset:2064
	v_add_u32_e32 v181, 0x400000, v183
	global_load_dwordx4 v[40:43], v181, s[78:79]
	global_load_dwordx4 v[44:47], v181, s[78:79] offset:16
	global_load_dwordx4 v[48:51], v181, s[78:79] offset:2048
	global_load_dwordx4 v[52:55], v181, s[78:79] offset:2064
	v_add_u32_e32 v181, 0x600000, v183
	global_load_dwordx4 v[56:59], v181, s[78:79]
	global_load_dwordx4 v[60:63], v181, s[78:79] offset:16
	global_load_dwordx4 v[64:67], v181, s[78:79] offset:2048
	global_load_dwordx4 v[68:71], v181, s[78:79] offset:2064
	v_add_u32_e32 v181, 0x800000, v183
	global_load_dwordx4 v[72:75], v181, s[78:79]
	global_load_dwordx4 v[76:79], v181, s[78:79] offset:16
	global_load_dwordx4 v[80:83], v181, s[78:79] offset:2048
	global_load_dwordx4 v[84:87], v181, s[78:79] offset:2064
	v_add_u32_e32 v181, 0xa00000, v183
	global_load_dwordx4 v[88:91], v181, s[78:79]
	global_load_dwordx4 v[92:95], v181, s[78:79] offset:16
	global_load_dwordx4 v[96:99], v181, s[78:79] offset:2048
	global_load_dwordx4 v[100:103], v181, s[78:79] offset:2064
	s_waitcnt vmcnt(20)
	v_pk_add_f32 v[160:161], v[8:9], 0 op_sel_hi:[1,0]
	v_pk_add_f32 v[162:163], v[10:11], 0 op_sel_hi:[1,0]
	v_pk_add_f32 v[164:165], v[12:13], 0 op_sel_hi:[1,0]
	v_pk_add_f32 v[166:167], v[14:15], 0 op_sel_hi:[1,0]
	v_pk_add_f32 v[168:169], v[16:17], 0 op_sel_hi:[1,0]
	v_pk_add_f32 v[170:171], v[18:19], 0 op_sel_hi:[1,0]
	v_pk_add_f32 v[172:173], v[20:21], 0 op_sel_hi:[1,0]
	v_pk_add_f32 v[174:175], v[22:23], 0 op_sel_hi:[1,0]
	s_waitcnt vmcnt(16)
	v_pk_add_f32 v[160:161], v[160:161], v[24:25]
	v_pk_add_f32 v[162:163], v[162:163], v[26:27]
	v_pk_add_f32 v[164:165], v[164:165], v[28:29]
	v_pk_add_f32 v[166:167], v[166:167], v[30:31]
	v_pk_add_f32 v[168:169], v[168:169], v[32:33]
	v_pk_add_f32 v[170:171], v[170:171], v[34:35]
	v_pk_add_f32 v[172:173], v[172:173], v[36:37]
	v_pk_add_f32 v[174:175], v[174:175], v[38:39]
	s_waitcnt vmcnt(12)
	v_pk_add_f32 v[160:161], v[160:161], v[40:41]
	v_pk_add_f32 v[162:163], v[162:163], v[42:43]
	v_pk_add_f32 v[164:165], v[164:165], v[44:45]
	v_pk_add_f32 v[166:167], v[166:167], v[46:47]
	v_pk_add_f32 v[168:169], v[168:169], v[48:49]
	v_pk_add_f32 v[170:171], v[170:171], v[50:51]
	v_pk_add_f32 v[172:173], v[172:173], v[52:53]
	v_pk_add_f32 v[174:175], v[174:175], v[54:55]
	s_waitcnt vmcnt(8)
	v_pk_add_f32 v[160:161], v[160:161], v[56:57]
	v_pk_add_f32 v[162:163], v[162:163], v[58:59]
	v_pk_add_f32 v[164:165], v[164:165], v[60:61]
	v_pk_add_f32 v[166:167], v[166:167], v[62:63]
	v_pk_add_f32 v[168:169], v[168:169], v[64:65]
	v_pk_add_f32 v[170:171], v[170:171], v[66:67]
	v_pk_add_f32 v[172:173], v[172:173], v[68:69]
	v_pk_add_f32 v[174:175], v[174:175], v[70:71]
	s_waitcnt vmcnt(4)
	v_pk_add_f32 v[160:161], v[160:161], v[72:73]
	v_pk_add_f32 v[162:163], v[162:163], v[74:75]
	v_pk_add_f32 v[164:165], v[164:165], v[76:77]
	v_pk_add_f32 v[166:167], v[166:167], v[78:79]
	v_pk_add_f32 v[168:169], v[168:169], v[80:81]
	v_pk_add_f32 v[170:171], v[170:171], v[82:83]
	v_pk_add_f32 v[172:173], v[172:173], v[84:85]
	v_pk_add_f32 v[174:175], v[174:175], v[86:87]
	s_waitcnt vmcnt(0)
	v_pk_add_f32 v[160:161], v[160:161], v[88:89]
	v_pk_add_f32 v[162:163], v[162:163], v[90:91]
	v_pk_add_f32 v[164:165], v[164:165], v[92:93]
	v_pk_add_f32 v[166:167], v[166:167], v[94:95]
	v_pk_add_f32 v[168:169], v[168:169], v[96:97]
	v_pk_add_f32 v[170:171], v[170:171], v[98:99]
	v_pk_add_f32 v[172:173], v[172:173], v[100:101]
	v_pk_add_f32 v[174:175], v[174:175], v[102:103]
	v_lshlrev_b32_e32 v144, 16, v0
	v_and_b32_e32 v145, 0xffff0000, v0
	v_lshlrev_b32_e32 v146, 16, v1
	v_and_b32_e32 v147, 0xffff0000, v1
	v_lshlrev_b32_e32 v148, 16, v2
	v_and_b32_e32 v149, 0xffff0000, v2
	v_lshlrev_b32_e32 v150, 16, v3
	v_and_b32_e32 v151, 0xffff0000, v3
	v_lshlrev_b32_e32 v152, 16, v4
	v_and_b32_e32 v153, 0xffff0000, v4
	v_lshlrev_b32_e32 v154, 16, v5
	v_and_b32_e32 v155, 0xffff0000, v5
	v_lshlrev_b32_e32 v156, 16, v6
	v_and_b32_e32 v157, 0xffff0000, v6
	v_lshlrev_b32_e32 v158, 16, v7
	v_and_b32_e32 v159, 0xffff0000, v7
	v_add_u32_e32 v181, 0xc00000, v183
	global_load_dwordx4 v[8:11], v181, s[78:79]
	global_load_dwordx4 v[12:15], v181, s[78:79] offset:16
	global_load_dwordx4 v[16:19], v181, s[78:79] offset:2048
	global_load_dwordx4 v[20:23], v181, s[78:79] offset:2064
	v_add_u32_e32 v181, 0xe00000, v183
	global_load_dwordx4 v[24:27], v181, s[78:79]
	global_load_dwordx4 v[28:31], v181, s[78:79] offset:16
	global_load_dwordx4 v[32:35], v181, s[78:79] offset:2048
	global_load_dwordx4 v[36:39], v181, s[78:79] offset:2064
	v_add_u32_e32 v181, 0x1000000, v183
	global_load_dwordx4 v[40:43], v181, s[78:79]
	global_load_dwordx4 v[44:47], v181, s[78:79] offset:16
	global_load_dwordx4 v[48:51], v181, s[78:79] offset:2048
	global_load_dwordx4 v[52:55], v181, s[78:79] offset:2064
	v_add_u32_e32 v181, 0x1200000, v183
	global_load_dwordx4 v[56:59], v181, s[78:79]
	global_load_dwordx4 v[60:63], v181, s[78:79] offset:16
	global_load_dwordx4 v[64:67], v181, s[78:79] offset:2048
	global_load_dwordx4 v[68:71], v181, s[78:79] offset:2064
	v_add_u32_e32 v181, 0x1400000, v183
	global_load_dwordx4 v[72:75], v181, s[78:79]
	global_load_dwordx4 v[76:79], v181, s[78:79] offset:16
	global_load_dwordx4 v[80:83], v181, s[78:79] offset:2048
	global_load_dwordx4 v[84:87], v181, s[78:79] offset:2064
	s_waitcnt vmcnt(16)
	v_pk_add_f32 v[160:161], v[160:161], v[8:9]
	v_pk_add_f32 v[162:163], v[162:163], v[10:11]
	v_pk_add_f32 v[164:165], v[164:165], v[12:13]
	v_pk_add_f32 v[166:167], v[166:167], v[14:15]
	v_pk_add_f32 v[168:169], v[168:169], v[16:17]
	v_pk_add_f32 v[170:171], v[170:171], v[18:19]
	v_pk_add_f32 v[172:173], v[172:173], v[20:21]
	v_pk_add_f32 v[174:175], v[174:175], v[22:23]
	s_waitcnt vmcnt(12)
	v_pk_add_f32 v[160:161], v[160:161], v[24:25]
	v_pk_add_f32 v[162:163], v[162:163], v[26:27]
	v_pk_add_f32 v[164:165], v[164:165], v[28:29]
	v_pk_add_f32 v[166:167], v[166:167], v[30:31]
	v_pk_add_f32 v[168:169], v[168:169], v[32:33]
	v_pk_add_f32 v[170:171], v[170:171], v[34:35]
	v_pk_add_f32 v[172:173], v[172:173], v[36:37]
	v_pk_add_f32 v[174:175], v[174:175], v[38:39]
	s_waitcnt vmcnt(8)
	v_pk_add_f32 v[160:161], v[160:161], v[40:41]
	v_pk_add_f32 v[162:163], v[162:163], v[42:43]
	v_pk_add_f32 v[164:165], v[164:165], v[44:45]
	v_pk_add_f32 v[166:167], v[166:167], v[46:47]
	v_pk_add_f32 v[168:169], v[168:169], v[48:49]
	v_pk_add_f32 v[170:171], v[170:171], v[50:51]
	v_pk_add_f32 v[172:173], v[172:173], v[52:53]
	v_pk_add_f32 v[174:175], v[174:175], v[54:55]
	s_waitcnt vmcnt(4)
	v_pk_add_f32 v[160:161], v[160:161], v[56:57]
	v_pk_add_f32 v[162:163], v[162:163], v[58:59]
	v_pk_add_f32 v[164:165], v[164:165], v[60:61]
	v_pk_add_f32 v[166:167], v[166:167], v[62:63]
	v_pk_add_f32 v[168:169], v[168:169], v[64:65]
	v_pk_add_f32 v[170:171], v[170:171], v[66:67]
	v_pk_add_f32 v[172:173], v[172:173], v[68:69]
	v_pk_add_f32 v[174:175], v[174:175], v[70:71]
	s_waitcnt vmcnt(0)
	v_pk_add_f32 v[160:161], v[160:161], v[72:73]
	v_pk_add_f32 v[162:163], v[162:163], v[74:75]
	v_pk_add_f32 v[164:165], v[164:165], v[76:77]
	v_pk_add_f32 v[166:167], v[166:167], v[78:79]
	v_pk_add_f32 v[168:169], v[168:169], v[80:81]
	v_pk_add_f32 v[170:171], v[170:171], v[82:83]
	v_pk_add_f32 v[172:173], v[172:173], v[84:85]
	v_pk_add_f32 v[174:175], v[174:175], v[86:87]
	v_pk_mul_f32 v[252:253], v[160:161], v[160:161]
	v_pk_mul_f32 v[254:255], v[162:163], v[162:163]
	v_pk_fma_f32 v[252:253], v[164:165], v[164:165], v[252:253]
	v_pk_fma_f32 v[254:255], v[166:167], v[166:167], v[254:255]
	v_pk_fma_f32 v[252:253], v[168:169], v[168:169], v[252:253]
	v_pk_fma_f32 v[254:255], v[170:171], v[170:171], v[254:255]
	v_pk_fma_f32 v[252:253], v[172:173], v[172:173], v[252:253]
	v_pk_fma_f32 v[254:255], v[174:175], v[174:175], v[254:255]
	v_pk_add_f32 v[252:253], v[252:253], v[254:255]
	s_nop 0
	v_add_f32_e32 v183, v252, v253
	s_nop 1
	v_add_f32_dpp v183, v183, v183 quad_perm:[1,0,3,2] row_mask:0xf bank_mask:0xf bound_ctrl:1
	s_nop 1
	v_add_f32_dpp v183, v183, v183 quad_perm:[2,3,0,1] row_mask:0xf bank_mask:0xf bound_ctrl:1
	s_nop 1
	v_add_f32_dpp v183, v183, v183 row_half_mirror row_mask:0xf bank_mask:0xf bound_ctrl:1
	s_nop 1
	v_add_f32_dpp v183, v183, v183 row_mirror row_mask:0xf bank_mask:0xf bound_ctrl:1
	s_nop 1
	v_readlane_b32 s98, v183, 0
	v_readlane_b32 s99, v183, 16
	v_readlane_b32 s100, v183, 32
	v_readlane_b32 s101, v183, 48
	s_nop 1
	v_mov_b32_e32 v183, s98
	v_add_f32_e32 v183, s99, v183
	v_add_f32_e32 v183, s100, v183
	v_add_f32_e32 v183, s101, v183
	v_fmamk_f32 v183, v183, 0x3a800000, v182
	v_cmp_gt_f32_e32 vcc, 0x800000, v183
	v_mul_f32_e32 v181, 0x4b800000, v183
	s_nop 1
	v_cndmask_b32_e32 v183, v183, v181, vcc
	v_rsq_f32_e32 v183, v183
	s_nop 0
	v_mul_f32_e32 v181, 0x45800000, v183
	v_cndmask_b32_e32 v184, v183, v181, vcc
	v_mov_b32_e32 v185, v184
	v_pk_mul_f32 v[160:161], v[160:161], v[184:185]
	v_pk_mul_f32 v[162:163], v[162:163], v[184:185]
	v_pk_mul_f32 v[164:165], v[164:165], v[184:185]
	v_pk_mul_f32 v[166:167], v[166:167], v[184:185]
	v_pk_mul_f32 v[168:169], v[168:169], v[184:185]
	v_pk_mul_f32 v[170:171], v[170:171], v[184:185]
	v_pk_mul_f32 v[172:173], v[172:173], v[184:185]
	v_pk_mul_f32 v[174:175], v[174:175], v[184:185]
	v_pk_fma_f32 v[144:145], v[160:161], v[128:129], v[144:145]
	v_pk_fma_f32 v[146:147], v[162:163], v[130:131], v[146:147]
	v_pk_fma_f32 v[148:149], v[164:165], v[132:133], v[148:149]
	v_pk_fma_f32 v[150:151], v[166:167], v[134:135], v[150:151]
	v_pk_fma_f32 v[152:153], v[168:169], v[136:137], v[152:153]
	v_pk_fma_f32 v[154:155], v[170:171], v[138:139], v[154:155]
	v_pk_fma_f32 v[156:157], v[172:173], v[140:141], v[156:157]
	v_pk_fma_f32 v[158:159], v[174:175], v[142:143], v[158:159]
	v_pk_mul_f32 v[252:253], v[144:145], v[144:145]
	v_pk_mul_f32 v[254:255], v[146:147], v[146:147]
	v_pk_fma_f32 v[252:253], v[148:149], v[148:149], v[252:253]
	v_pk_fma_f32 v[254:255], v[150:151], v[150:151], v[254:255]
	v_pk_fma_f32 v[252:253], v[152:153], v[152:153], v[252:253]
	v_pk_fma_f32 v[254:255], v[154:155], v[154:155], v[254:255]
	v_pk_fma_f32 v[252:253], v[156:157], v[156:157], v[252:253]
	v_pk_fma_f32 v[254:255], v[158:159], v[158:159], v[254:255]
	v_pk_add_f32 v[252:253], v[252:253], v[254:255]
	s_nop 0
	v_add_f32_e32 v183, v252, v253
	s_nop 1
	v_add_f32_dpp v183, v183, v183 quad_perm:[1,0,3,2] row_mask:0xf bank_mask:0xf bound_ctrl:1
	s_nop 1
	v_add_f32_dpp v183, v183, v183 quad_perm:[2,3,0,1] row_mask:0xf bank_mask:0xf bound_ctrl:1
	s_nop 1
	v_add_f32_dpp v183, v183, v183 row_half_mirror row_mask:0xf bank_mask:0xf bound_ctrl:1
	s_nop 1
	v_add_f32_dpp v183, v183, v183 row_mirror row_mask:0xf bank_mask:0xf bound_ctrl:1
	s_nop 1
	v_readlane_b32 s98, v183, 0
	v_readlane_b32 s99, v183, 16
	v_readlane_b32 s100, v183, 32
	v_readlane_b32 s101, v183, 48
	s_nop 1
	v_mov_b32_e32 v183, s98
	v_add_f32_e32 v183, s99, v183
	v_add_f32_e32 v183, s100, v183
	v_add_f32_e32 v183, s101, v183
	v_fmamk_f32 v183, v183, 0x3a800000, v182
	v_cmp_gt_f32_e32 vcc, 0x800000, v183
	v_mul_f32_e32 v181, 0x4b800000, v183
	s_nop 1
	v_cndmask_b32_e32 v183, v183, v181, vcc
	v_rsq_f32_e32 v183, v183
	s_nop 0
	v_mul_f32_e32 v181, 0x45800000, v183
	v_cndmask_b32_e32 v184, v183, v181, vcc
	v_mov_b32_e32 v185, v184
	v_cvt_pk_bf16_f32 v0, v144, v145
	v_cvt_pk_bf16_f32 v1, v146, v147
	v_cvt_pk_bf16_f32 v2, v148, v149
	v_cvt_pk_bf16_f32 v3, v150, v151
	v_cvt_pk_bf16_f32 v4, v152, v153
	v_cvt_pk_bf16_f32 v5, v154, v155
	v_cvt_pk_bf16_f32 v6, v156, v157
	v_cvt_pk_bf16_f32 v7, v158, v159
	v_add_u32_e32 v181, 0x3800000, v177
	global_store_dwordx4 v181, v[0:3], s[78:79]
	global_store_dwordx4 v181, v[4:7], s[78:79] offset:1024
	v_add_u32_e32 v236, 0x10000, v237
	s_mov_b64 exec, 1
	global_store_dword v236, v184, s[78:79]
	s_mov_b64 exec, -1

.LBB0_1863:
	v_readlane_b32 s0, v235, 52
	v_readlane_b32 s1, v235, 53
	s_and_b64 vcc, exec, s[0:1]
	s_waitcnt lgkmcnt(0)
	s_barrier
	v_mbcnt_lo_u32_b32 v0, -1, 0
	v_mbcnt_hi_u32_b32 v0, -1, v0
	s_cbranch_vccnz .LBB0_1883
	v_lshlrev_b32_e32 v2, 3, v0
	v_ashrrev_i32_e32 v3, 31, v2
	v_readlane_b32 s4, v235, 4
	v_lshlrev_b64 v[4:5], 1, v[2:3]
	v_lshlrev_b64 v[2:3], 2, v[2:3]
	v_readlane_b32 s14, v235, 14
	v_readlane_b32 s15, v235, 15
	v_lshl_add_u64 v[62:63], s[90:91], 0, v[2:3]
	v_readlane_b32 s5, v235, 5
	v_readlane_b32 s6, v235, 6
	v_readlane_b32 s7, v235, 7
	v_readlane_b32 s8, v235, 8
	v_readlane_b32 s9, v235, 9
	v_readlane_b32 s10, v235, 10
	v_readlane_b32 s11, v235, 11
	v_readlane_b32 s12, v235, 12
	v_readlane_b32 s13, v235, 13
	v_readlane_b32 s16, v235, 16
	v_readlane_b32 s17, v235, 17
	v_readlane_b32 s18, v235, 18
	v_readlane_b32 s19, v235, 19
	v_lshl_add_u64 v[2:3], s[14:15], 0, v[2:3]
	s_mov_b64 s[0:1], 0x2000
	v_lshl_add_u64 v[60:61], s[86:87], 0, v[4:5]
	v_lshl_add_u64 v[64:65], s[54:55], 0, v[4:5]
	v_lshl_add_u64 v[66:67], v[2:3], 0, s[0:1]
	s_mov_b32 s1, 0
	v_cmp_eq_u32_e64 s[16:17], 0, v0
	s_mov_b64 s[4:5], 0x200000
	s_mov_b64 s[6:7], 0x200800
	s_mov_b64 s[8:9], 0x400000
	s_mov_b64 s[10:11], 0x400800
	s_mov_b64 s[12:13], 0x600000
	s_mov_b64 s[14:15], 0x600800
	s_mov_b64 s[18:19], 0x800000
	s_mov_b32 s48, 0x800000
	s_mov_b64 s[20:21], 0x800800
	s_mov_b64 s[22:23], 0xa00000
	s_mov_b64 s[24:25], 0xa00800
	s_mov_b64 s[26:27], 0xc00000
	s_mov_b64 s[28:29], 0xc00800
	s_mov_b64 s[36:37], 0xe00000
	s_mov_b64 s[38:39], 0xe00800
	v_mov_b32_e32 v104, 0
	v_mov_b32_e32 v105, 0x358637bd
	v_readlane_b32 s42, v235, 61
	v_readlane_b32 s43, v235, 62
	v_mbcnt_lo_u32_b32 v176, -1, 0
	v_mbcnt_hi_u32_b32 v176, -1, v176
	v_readlane_b32 s98, v235, 49
	v_readlane_b32 s99, v235, 20
	v_readlane_b32 s100, v235, 14
	v_readlane_b32 s101, v235, 15
	s_nop 3
	s_lshr_b32 vcc_lo, s98, 3
	s_and_b32 vcc_hi, vcc_lo, 7
	s_lshr_b32 vcc_lo, vcc_lo, 3
	s_lshl_b32 vcc_lo, vcc_lo, 3
	s_add_i32 vcc_lo, vcc_lo, s99
	s_lshl_b32 s98, vcc_hi, 8
	s_add_i32 s98, s98, vcc_lo
	s_mov_b32 s99, s98
	v_mov_b32_e32 v183, s99
	v_lshlrev_b32_e32 v177, 4, v176
	s_lshl_b32 s99, s99, 11
	v_add_u32_e32 v177, s99, v177
	v_add_u32_e32 v178, 0x1800000, v177
	v_add_u32_e32 v179, 0x9e00000, v177
	v_lshlrev_b32_e32 v180, 5, v176
	v_add_u32_e32 v181, 0x2000, v180
	global_load_dwordx4 v[128:131], v181, s[100:101]
	global_load_dwordx4 v[132:135], v181, s[100:101] offset:16
	global_load_dwordx4 v[136:139], v181, s[100:101] offset:2048
	global_load_dwordx4 v[140:143], v181, s[100:101] offset:2064
	v_mov_b32_e32 v182, 0x358637bd
	global_load_dwordx4 v[0:3], v178, s[78:79]
	global_load_dwordx4 v[4:7], v178, s[78:79] offset:1024
	global_load_dwordx4 v[8:11], v179, s[78:79]
	global_load_dwordx4 v[12:15], v179, s[78:79] offset:1024
	v_add_u32_e32 v178, 0x400000, v178
	v_add_u32_e32 v179, 0x400000, v179
	global_load_dwordx4 v[16:19], v178, s[78:79]
	global_load_dwordx4 v[20:23], v178, s[78:79] offset:1024
	global_load_dwordx4 v[24:27], v179, s[78:79]
	global_load_dwordx4 v[28:31], v179, s[78:79] offset:1024
	v_add_u32_e32 v178, 0x400000, v178
	v_add_u32_e32 v179, 0x400000, v179
	global_load_dwordx4 v[32:35], v178, s[78:79]
	global_load_dwordx4 v[36:39], v178, s[78:79] offset:1024
	global_load_dwordx4 v[40:43], v179, s[78:79]
	global_load_dwordx4 v[44:47], v179, s[78:79] offset:1024
	v_add_u32_e32 v178, 0x400000, v178
	v_add_u32_e32 v179, 0x400000, v179
	global_load_dwordx4 v[48:51], v178, s[78:79]
	global_load_dwordx4 v[52:55], v178, s[78:79] offset:1024
	global_load_dwordx4 v[56:59], v179, s[78:79]
	global_load_dwordx4 v[60:63], v179, s[78:79] offset:1024
	v_add_u32_e32 v178, 0x400000, v178
	v_add_u32_e32 v179, 0x400000, v179
	global_load_dwordx4 v[64:67], v178, s[78:79]
	global_load_dwordx4 v[68:71], v178, s[78:79] offset:1024
	global_load_dwordx4 v[72:75], v179, s[78:79]
	global_load_dwordx4 v[76:79], v179, s[78:79] offset:1024
	v_add_u32_e32 v178, 0x400000, v178
	v_add_u32_e32 v179, 0x400000, v179
	global_load_dwordx4 v[80:83], v178, s[78:79]
	global_load_dwordx4 v[84:87], v178, s[78:79] offset:1024
	global_load_dwordx4 v[88:91], v179, s[78:79]
	global_load_dwordx4 v[92:95], v179, s[78:79] offset:1024
	v_add_u32_e32 v178, 0x400000, v178
	v_add_u32_e32 v179, 0x400000, v179
	global_load_dwordx4 v[96:99], v178, s[78:79]
	global_load_dwordx4 v[100:103], v178, s[78:79] offset:1024
	global_load_dwordx4 v[104:107], v179, s[78:79]
	global_load_dwordx4 v[108:111], v179, s[78:79] offset:1024
	v_add_u32_e32 v178, 0x400000, v178
	v_add_u32_e32 v179, 0x400000, v179
	global_load_dwordx4 v[112:115], v178, s[78:79]
	global_load_dwordx4 v[116:119], v178, s[78:79] offset:1024
	global_load_dwordx4 v[120:123], v179, s[78:79]
	global_load_dwordx4 v[124:127], v179, s[78:79] offset:1024
	v_lshlrev_b32_e32 v237, 2, v183
	v_add_u32_e32 v237, 0x10000, v237
	v_mov_b32_e32 v179, s98
	s_waitcnt vmcnt(28)
	v_lshlrev_b32_e32 v144, 16, v0
	v_and_b32_e32 v145, 0xffff0000, v0
	v_lshlrev_b32_e32 v146, 16, v1
	v_and_b32_e32 v147, 0xffff0000, v1
	v_lshlrev_b32_e32 v148, 16, v2
	v_and_b32_e32 v149, 0xffff0000, v2
	v_lshlrev_b32_e32 v150, 16, v3
	v_and_b32_e32 v151, 0xffff0000, v3
	v_lshlrev_b32_e32 v152, 16, v4
	v_and_b32_e32 v153, 0xffff0000, v4
	v_lshlrev_b32_e32 v154, 16, v5
	v_and_b32_e32 v155, 0xffff0000, v5
	v_lshlrev_b32_e32 v156, 16, v6
	v_and_b32_e32 v157, 0xffff0000, v6
	v_lshlrev_b32_e32 v158, 16, v7
	v_and_b32_e32 v159, 0xffff0000, v7
	v_lshlrev_b32_e32 v160, 16, v8
	v_and_b32_e32 v161, 0xffff0000, v8
	v_lshlrev_b32_e32 v162, 16, v9
	v_and_b32_e32 v163, 0xffff0000, v9
	v_lshlrev_b32_e32 v164, 16, v10
	v_and_b32_e32 v165, 0xffff0000, v10
	v_lshlrev_b32_e32 v166, 16, v11
	v_and_b32_e32 v167, 0xffff0000, v11
	v_lshlrev_b32_e32 v168, 16, v12
	v_and_b32_e32 v169, 0xffff0000, v12
	v_lshlrev_b32_e32 v170, 16, v13
	v_and_b32_e32 v171, 0xffff0000, v13
	v_lshlrev_b32_e32 v172, 16, v14
	v_and_b32_e32 v173, 0xffff0000, v14
	v_lshlrev_b32_e32 v174, 16, v15
	v_and_b32_e32 v175, 0xffff0000, v15
	v_pk_mul_f32 v[252:253], v[160:161], v[160:161]
	v_pk_mul_f32 v[254:255], v[162:163], v[162:163]
	v_pk_fma_f32 v[252:253], v[164:165], v[164:165], v[252:253]
	v_pk_fma_f32 v[254:255], v[166:167], v[166:167], v[254:255]
	v_pk_fma_f32 v[252:253], v[168:169], v[168:169], v[252:253]
	v_pk_fma_f32 v[254:255], v[170:171], v[170:171], v[254:255]
	v_pk_fma_f32 v[252:253], v[172:173], v[172:173], v[252:253]
	v_pk_fma_f32 v[254:255], v[174:175], v[174:175], v[254:255]
	v_pk_add_f32 v[252:253], v[252:253], v[254:255]
	s_nop 0
	v_add_f32_e32 v183, v252, v253
	s_nop 1
	v_add_f32_dpp v183, v183, v183 quad_perm:[1,0,3,2] row_mask:0xf bank_mask:0xf bound_ctrl:1
	s_nop 1
	v_add_f32_dpp v183, v183, v183 quad_perm:[2,3,0,1] row_mask:0xf bank_mask:0xf bound_ctrl:1
	s_nop 1
	v_add_f32_dpp v183, v183, v183 row_half_mirror row_mask:0xf bank_mask:0xf bound_ctrl:1
	s_nop 1
	v_add_f32_dpp v183, v183, v183 row_mirror row_mask:0xf bank_mask:0xf bound_ctrl:1
	s_nop 1
	v_readlane_b32 s98, v183, 0
	v_readlane_b32 s99, v183, 16
	v_readlane_b32 s100, v183, 32
	v_readlane_b32 s101, v183, 48
	s_nop 1
	v_mov_b32_e32 v183, s98
	v_add_f32_e32 v183, s99, v183
	v_add_f32_e32 v183, s100, v183
	v_add_f32_e32 v183, s101, v183
	v_fmamk_f32 v183, v183, 0x3a800000, v182
	v_cmp_gt_f32_e32 vcc, 0x800000, v183
	v_mul_f32_e32 v181, 0x4b800000, v183
	s_nop 1
	v_cndmask_b32_e32 v183, v183, v181, vcc
	v_rsq_f32_e32 v183, v183
	s_nop 0
	v_mul_f32_e32 v181, 0x45800000, v183
	v_cndmask_b32_e32 v184, v183, v181, vcc
	v_mov_b32_e32 v185, v184
	v_pk_mul_f32 v[160:161], v[160:161], v[184:185]
	v_pk_mul_f32 v[162:163], v[162:163], v[184:185]
	v_pk_mul_f32 v[164:165], v[164:165], v[184:185]
	v_pk_mul_f32 v[166:167], v[166:167], v[184:185]
	v_pk_mul_f32 v[168:169], v[168:169], v[184:185]
	v_pk_mul_f32 v[170:171], v[170:171], v[184:185]
	v_pk_mul_f32 v[172:173], v[172:173], v[184:185]
	v_pk_mul_f32 v[174:175], v[174:175], v[184:185]
	v_pk_fma_f32 v[144:145], v[160:161], v[128:129], v[144:145]
	v_pk_fma_f32 v[146:147], v[162:163], v[130:131], v[146:147]
	v_pk_fma_f32 v[148:149], v[164:165], v[132:133], v[148:149]
	v_pk_fma_f32 v[150:151], v[166:167], v[134:135], v[150:151]
	v_pk_fma_f32 v[152:153], v[168:169], v[136:137], v[152:153]
	v_pk_fma_f32 v[154:155], v[170:171], v[138:139], v[154:155]
	v_pk_fma_f32 v[156:157], v[172:173], v[140:141], v[156:157]
	v_pk_fma_f32 v[158:159], v[174:175], v[142:143], v[158:159]
	v_pk_mul_f32 v[252:253], v[144:145], v[144:145]
	v_pk_mul_f32 v[254:255], v[146:147], v[146:147]
	v_pk_fma_f32 v[252:253], v[148:149], v[148:149], v[252:253]
	v_pk_fma_f32 v[254:255], v[150:151], v[150:151], v[254:255]
	v_pk_fma_f32 v[252:253], v[152:153], v[152:153], v[252:253]
	v_pk_fma_f32 v[254:255], v[154:155], v[154:155], v[254:255]
	v_pk_fma_f32 v[252:253], v[156:157], v[156:157], v[252:253]
	v_pk_fma_f32 v[254:255], v[158:159], v[158:159], v[254:255]
	v_pk_add_f32 v[252:253], v[252:253], v[254:255]
	s_nop 0
	v_add_f32_e32 v183, v252, v253
	s_nop 1
	v_add_f32_dpp v183, v183, v183 quad_perm:[1,0,3,2] row_mask:0xf bank_mask:0xf bound_ctrl:1
	s_nop 1
	v_add_f32_dpp v183, v183, v183 quad_perm:[2,3,0,1] row_mask:0xf bank_mask:0xf bound_ctrl:1
	s_nop 1
	v_add_f32_dpp v183, v183, v183 row_half_mirror row_mask:0xf bank_mask:0xf bound_ctrl:1
	s_nop 1
	v_add_f32_dpp v183, v183, v183 row_mirror row_mask:0xf bank_mask:0xf bound_ctrl:1
	s_nop 1
	v_readlane_b32 s98, v183, 0
	v_readlane_b32 s99, v183, 16
	v_readlane_b32 s100, v183, 32
	v_readlane_b32 s101, v183, 48
	s_nop 1
	v_mov_b32_e32 v183, s98
	v_add_f32_e32 v183, s99, v183
	v_add_f32_e32 v183, s100, v183
	v_add_f32_e32 v183, s101, v183
	v_fmamk_f32 v183, v183, 0x3a800000, v182
	v_cmp_gt_f32_e32 vcc, 0x800000, v183
	v_mul_f32_e32 v181, 0x4b800000, v183
	s_nop 1
	v_cndmask_b32_e32 v183, v183, v181, vcc
	v_rsq_f32_e32 v183, v183
	s_nop 0
	v_mul_f32_e32 v181, 0x45800000, v183
	v_cndmask_b32_e32 v184, v183, v181, vcc
	v_mov_b32_e32 v185, v184
	v_cvt_pk_bf16_f32 v0, v144, v145
	v_cvt_pk_bf16_f32 v1, v146, v147
	v_cvt_pk_bf16_f32 v2, v148, v149
	v_cvt_pk_bf16_f32 v3, v150, v151
	v_cvt_pk_bf16_f32 v4, v152, v153
	v_cvt_pk_bf16_f32 v5, v154, v155
	v_cvt_pk_bf16_f32 v6, v156, v157
	v_cvt_pk_bf16_f32 v7, v158, v159
	v_add_u32_e32 v181, 0x1800000, v177
	global_store_dwordx4 v181, v[0:3], s[78:79]
	global_store_dwordx4 v181, v[4:7], s[78:79] offset:1024
	v_add_u32_e32 v236, 0x0, v237
	s_mov_b64 exec, 1
	global_store_dword v236, v184, s[78:79]
	s_mov_b64 exec, -1
	s_waitcnt vmcnt(24)
	v_lshlrev_b32_e32 v144, 16, v16
	v_and_b32_e32 v145, 0xffff0000, v16
	v_lshlrev_b32_e32 v146, 16, v17
	v_and_b32_e32 v147, 0xffff0000, v17
	v_lshlrev_b32_e32 v148, 16, v18
	v_and_b32_e32 v149, 0xffff0000, v18
	v_lshlrev_b32_e32 v150, 16, v19
	v_and_b32_e32 v151, 0xffff0000, v19
	v_lshlrev_b32_e32 v152, 16, v20
	v_and_b32_e32 v153, 0xffff0000, v20
	v_lshlrev_b32_e32 v154, 16, v21
	v_and_b32_e32 v155, 0xffff0000, v21
	v_lshlrev_b32_e32 v156, 16, v22
	v_and_b32_e32 v157, 0xffff0000, v22
	v_lshlrev_b32_e32 v158, 16, v23
	v_and_b32_e32 v159, 0xffff0000, v23
	v_lshlrev_b32_e32 v160, 16, v24
	v_and_b32_e32 v161, 0xffff0000, v24
	v_lshlrev_b32_e32 v162, 16, v25
	v_and_b32_e32 v163, 0xffff0000, v25
	v_lshlrev_b32_e32 v164, 16, v26
	v_and_b32_e32 v165, 0xffff0000, v26
	v_lshlrev_b32_e32 v166, 16, v27
	v_and_b32_e32 v167, 0xffff0000, v27
	v_lshlrev_b32_e32 v168, 16, v28
	v_and_b32_e32 v169, 0xffff0000, v28
	v_lshlrev_b32_e32 v170, 16, v29
	v_and_b32_e32 v171, 0xffff0000, v29
	v_lshlrev_b32_e32 v172, 16, v30
	v_and_b32_e32 v173, 0xffff0000, v30
	v_lshlrev_b32_e32 v174, 16, v31
	v_and_b32_e32 v175, 0xffff0000, v31
	v_pk_mul_f32 v[252:253], v[160:161], v[160:161]
	v_pk_mul_f32 v[254:255], v[162:163], v[162:163]
	v_pk_fma_f32 v[252:253], v[164:165], v[164:165], v[252:253]
	v_pk_fma_f32 v[254:255], v[166:167], v[166:167], v[254:255]
	v_pk_fma_f32 v[252:253], v[168:169], v[168:169], v[252:253]
	v_pk_fma_f32 v[254:255], v[170:171], v[170:171], v[254:255]
	v_pk_fma_f32 v[252:253], v[172:173], v[172:173], v[252:253]
	v_pk_fma_f32 v[254:255], v[174:175], v[174:175], v[254:255]
	v_pk_add_f32 v[252:253], v[252:253], v[254:255]
	s_nop 0
	v_add_f32_e32 v183, v252, v253
	s_nop 1
	v_add_f32_dpp v183, v183, v183 quad_perm:[1,0,3,2] row_mask:0xf bank_mask:0xf bound_ctrl:1
	s_nop 1
	v_add_f32_dpp v183, v183, v183 quad_perm:[2,3,0,1] row_mask:0xf bank_mask:0xf bound_ctrl:1
	s_nop 1
	v_add_f32_dpp v183, v183, v183 row_half_mirror row_mask:0xf bank_mask:0xf bound_ctrl:1
	s_nop 1
	v_add_f32_dpp v183, v183, v183 row_mirror row_mask:0xf bank_mask:0xf bound_ctrl:1
	s_nop 1
	v_readlane_b32 s98, v183, 0
	v_readlane_b32 s99, v183, 16
	v_readlane_b32 s100, v183, 32
	v_readlane_b32 s101, v183, 48
	s_nop 1
	v_mov_b32_e32 v183, s98
	v_add_f32_e32 v183, s99, v183
	v_add_f32_e32 v183, s100, v183
	v_add_f32_e32 v183, s101, v183
	v_fmamk_f32 v183, v183, 0x3a800000, v182
	v_cmp_gt_f32_e32 vcc, 0x800000, v183
	v_mul_f32_e32 v181, 0x4b800000, v183
	s_nop 1
	v_cndmask_b32_e32 v183, v183, v181, vcc
	v_rsq_f32_e32 v183, v183
	s_nop 0
	v_mul_f32_e32 v181, 0x45800000, v183
	v_cndmask_b32_e32 v184, v183, v181, vcc
	v_mov_b32_e32 v185, v184
	v_pk_mul_f32 v[160:161], v[160:161], v[184:185]
	v_pk_mul_f32 v[162:163], v[162:163], v[184:185]
	v_pk_mul_f32 v[164:165], v[164:165], v[184:185]
	v_pk_mul_f32 v[166:167], v[166:167], v[184:185]
	v_pk_mul_f32 v[168:169], v[168:169], v[184:185]
	v_pk_mul_f32 v[170:171], v[170:171], v[184:185]
	v_pk_mul_f32 v[172:173], v[172:173], v[184:185]
	v_pk_mul_f32 v[174:175], v[174:175], v[184:185]
	v_pk_fma_f32 v[144:145], v[160:161], v[128:129], v[144:145]
	v_pk_fma_f32 v[146:147], v[162:163], v[130:131], v[146:147]
	v_pk_fma_f32 v[148:149], v[164:165], v[132:133], v[148:149]
	v_pk_fma_f32 v[150:151], v[166:167], v[134:135], v[150:151]
	v_pk_fma_f32 v[152:153], v[168:169], v[136:137], v[152:153]
	v_pk_fma_f32 v[154:155], v[170:171], v[138:139], v[154:155]
	v_pk_fma_f32 v[156:157], v[172:173], v[140:141], v[156:157]
	v_pk_fma_f32 v[158:159], v[174:175], v[142:143], v[158:159]
	v_pk_mul_f32 v[252:253], v[144:145], v[144:145]
	v_pk_mul_f32 v[254:255], v[146:147], v[146:147]
	v_pk_fma_f32 v[252:253], v[148:149], v[148:149], v[252:253]
	v_pk_fma_f32 v[254:255], v[150:151], v[150:151], v[254:255]
	v_pk_fma_f32 v[252:253], v[152:153], v[152:153], v[252:253]
	v_pk_fma_f32 v[254:255], v[154:155], v[154:155], v[254:255]
	v_pk_fma_f32 v[252:253], v[156:157], v[156:157], v[252:253]
	v_pk_fma_f32 v[254:255], v[158:159], v[158:159], v[254:255]
	v_pk_add_f32 v[252:253], v[252:253], v[254:255]
	s_nop 0
	v_add_f32_e32 v183, v252, v253
	s_nop 1
	v_add_f32_dpp v183, v183, v183 quad_perm:[1,0,3,2] row_mask:0xf bank_mask:0xf bound_ctrl:1
	s_nop 1
	v_add_f32_dpp v183, v183, v183 quad_perm:[2,3,0,1] row_mask:0xf bank_mask:0xf bound_ctrl:1
	s_nop 1
	v_add_f32_dpp v183, v183, v183 row_half_mirror row_mask:0xf bank_mask:0xf bound_ctrl:1
	s_nop 1
	v_add_f32_dpp v183, v183, v183 row_mirror row_mask:0xf bank_mask:0xf bound_ctrl:1
	s_nop 1
	v_readlane_b32 s98, v183, 0
	v_readlane_b32 s99, v183, 16
	v_readlane_b32 s100, v183, 32
	v_readlane_b32 s101, v183, 48
	s_nop 1
	v_mov_b32_e32 v183, s98
	v_add_f32_e32 v183, s99, v183
	v_add_f32_e32 v183, s100, v183
	v_add_f32_e32 v183, s101, v183
	v_fmamk_f32 v183, v183, 0x3a800000, v182
	v_cmp_gt_f32_e32 vcc, 0x800000, v183
	v_mul_f32_e32 v181, 0x4b800000, v183
	s_nop 1
	v_cndmask_b32_e32 v183, v183, v181, vcc
	v_rsq_f32_e32 v183, v183
	s_nop 0
	v_mul_f32_e32 v181, 0x45800000, v183
	v_cndmask_b32_e32 v184, v183, v181, vcc
	v_mov_b32_e32 v185, v184
	v_cvt_pk_bf16_f32 v16, v144, v145
	v_cvt_pk_bf16_f32 v17, v146, v147
	v_cvt_pk_bf16_f32 v18, v148, v149
	v_cvt_pk_bf16_f32 v19, v150, v151
	v_cvt_pk_bf16_f32 v20, v152, v153
	v_cvt_pk_bf16_f32 v21, v154, v155
	v_cvt_pk_bf16_f32 v22, v156, v157
	v_cvt_pk_bf16_f32 v23, v158, v159
	v_add_u32_e32 v181, 0x1c00000, v177
	global_store_dwordx4 v181, v[16:19], s[78:79]
	global_store_dwordx4 v181, v[20:23], s[78:79] offset:1024
	v_add_u32_e32 v236, 0x2000, v237
	s_mov_b64 exec, 1
	global_store_dword v236, v184, s[78:79]
	s_mov_b64 exec, -1
	s_waitcnt vmcnt(20)
	v_lshlrev_b32_e32 v144, 16, v32
	v_and_b32_e32 v145, 0xffff0000, v32
	v_lshlrev_b32_e32 v146, 16, v33
	v_and_b32_e32 v147, 0xffff0000, v33
	v_lshlrev_b32_e32 v148, 16, v34
	v_and_b32_e32 v149, 0xffff0000, v34
	v_lshlrev_b32_e32 v150, 16, v35
	v_and_b32_e32 v151, 0xffff0000, v35
	v_lshlrev_b32_e32 v152, 16, v36
	v_and_b32_e32 v153, 0xffff0000, v36
	v_lshlrev_b32_e32 v154, 16, v37
	v_and_b32_e32 v155, 0xffff0000, v37
	v_lshlrev_b32_e32 v156, 16, v38
	v_and_b32_e32 v157, 0xffff0000, v38
	v_lshlrev_b32_e32 v158, 16, v39
	v_and_b32_e32 v159, 0xffff0000, v39
	v_lshlrev_b32_e32 v160, 16, v40
	v_and_b32_e32 v161, 0xffff0000, v40
	v_lshlrev_b32_e32 v162, 16, v41
	v_and_b32_e32 v163, 0xffff0000, v41
	v_lshlrev_b32_e32 v164, 16, v42
	v_and_b32_e32 v165, 0xffff0000, v42
	v_lshlrev_b32_e32 v166, 16, v43
	v_and_b32_e32 v167, 0xffff0000, v43
	v_lshlrev_b32_e32 v168, 16, v44
	v_and_b32_e32 v169, 0xffff0000, v44
	v_lshlrev_b32_e32 v170, 16, v45
	v_and_b32_e32 v171, 0xffff0000, v45
	v_lshlrev_b32_e32 v172, 16, v46
	v_and_b32_e32 v173, 0xffff0000, v46
	v_lshlrev_b32_e32 v174, 16, v47
	v_and_b32_e32 v175, 0xffff0000, v47
	v_pk_mul_f32 v[252:253], v[160:161], v[160:161]
	v_pk_mul_f32 v[254:255], v[162:163], v[162:163]
	v_pk_fma_f32 v[252:253], v[164:165], v[164:165], v[252:253]
	v_pk_fma_f32 v[254:255], v[166:167], v[166:167], v[254:255]
	v_pk_fma_f32 v[252:253], v[168:169], v[168:169], v[252:253]
	v_pk_fma_f32 v[254:255], v[170:171], v[170:171], v[254:255]
	v_pk_fma_f32 v[252:253], v[172:173], v[172:173], v[252:253]
	v_pk_fma_f32 v[254:255], v[174:175], v[174:175], v[254:255]
	v_pk_add_f32 v[252:253], v[252:253], v[254:255]
	s_nop 0
	v_add_f32_e32 v183, v252, v253
	s_nop 1
	v_add_f32_dpp v183, v183, v183 quad_perm:[1,0,3,2] row_mask:0xf bank_mask:0xf bound_ctrl:1
	s_nop 1
	v_add_f32_dpp v183, v183, v183 quad_perm:[2,3,0,1] row_mask:0xf bank_mask:0xf bound_ctrl:1
	s_nop 1
	v_add_f32_dpp v183, v183, v183 row_half_mirror row_mask:0xf bank_mask:0xf bound_ctrl:1
	s_nop 1
	v_add_f32_dpp v183, v183, v183 row_mirror row_mask:0xf bank_mask:0xf bound_ctrl:1
	s_nop 1
	v_readlane_b32 s98, v183, 0
	v_readlane_b32 s99, v183, 16
	v_readlane_b32 s100, v183, 32
	v_readlane_b32 s101, v183, 48
	s_nop 1
	v_mov_b32_e32 v183, s98
	v_add_f32_e32 v183, s99, v183
	v_add_f32_e32 v183, s100, v183
	v_add_f32_e32 v183, s101, v183
	v_fmamk_f32 v183, v183, 0x3a800000, v182
	v_cmp_gt_f32_e32 vcc, 0x800000, v183
	v_mul_f32_e32 v181, 0x4b800000, v183
	s_nop 1
	v_cndmask_b32_e32 v183, v183, v181, vcc
	v_rsq_f32_e32 v183, v183
	s_nop 0
	v_mul_f32_e32 v181, 0x45800000, v183
	v_cndmask_b32_e32 v184, v183, v181, vcc
	v_mov_b32_e32 v185, v184
	v_pk_mul_f32 v[160:161], v[160:161], v[184:185]
	v_pk_mul_f32 v[162:163], v[162:163], v[184:185]
	v_pk_mul_f32 v[164:165], v[164:165], v[184:185]
	v_pk_mul_f32 v[166:167], v[166:167], v[184:185]
	v_pk_mul_f32 v[168:169], v[168:169], v[184:185]
	v_pk_mul_f32 v[170:171], v[170:171], v[184:185]
	v_pk_mul_f32 v[172:173], v[172:173], v[184:185]
	v_pk_mul_f32 v[174:175], v[174:175], v[184:185]
	v_pk_fma_f32 v[144:145], v[160:161], v[128:129], v[144:145]
	v_pk_fma_f32 v[146:147], v[162:163], v[130:131], v[146:147]
	v_pk_fma_f32 v[148:149], v[164:165], v[132:133], v[148:149]
	v_pk_fma_f32 v[150:151], v[166:167], v[134:135], v[150:151]
	v_pk_fma_f32 v[152:153], v[168:169], v[136:137], v[152:153]
	v_pk_fma_f32 v[154:155], v[170:171], v[138:139], v[154:155]
	v_pk_fma_f32 v[156:157], v[172:173], v[140:141], v[156:157]
	v_pk_fma_f32 v[158:159], v[174:175], v[142:143], v[158:159]
	v_pk_mul_f32 v[252:253], v[144:145], v[144:145]
	v_pk_mul_f32 v[254:255], v[146:147], v[146:147]
	v_pk_fma_f32 v[252:253], v[148:149], v[148:149], v[252:253]
	v_pk_fma_f32 v[254:255], v[150:151], v[150:151], v[254:255]
	v_pk_fma_f32 v[252:253], v[152:153], v[152:153], v[252:253]
	v_pk_fma_f32 v[254:255], v[154:155], v[154:155], v[254:255]
	v_pk_fma_f32 v[252:253], v[156:157], v[156:157], v[252:253]
	v_pk_fma_f32 v[254:255], v[158:159], v[158:159], v[254:255]
	v_pk_add_f32 v[252:253], v[252:253], v[254:255]
	s_nop 0
	v_add_f32_e32 v183, v252, v253
	s_nop 1
	v_add_f32_dpp v183, v183, v183 quad_perm:[1,0,3,2] row_mask:0xf bank_mask:0xf bound_ctrl:1
	s_nop 1
	v_add_f32_dpp v183, v183, v183 quad_perm:[2,3,0,1] row_mask:0xf bank_mask:0xf bound_ctrl:1
	s_nop 1
	v_add_f32_dpp v183, v183, v183 row_half_mirror row_mask:0xf bank_mask:0xf bound_ctrl:1
	s_nop 1
	v_add_f32_dpp v183, v183, v183 row_mirror row_mask:0xf bank_mask:0xf bound_ctrl:1
	s_nop 1
	v_readlane_b32 s98, v183, 0
	v_readlane_b32 s99, v183, 16
	v_readlane_b32 s100, v183, 32
	v_readlane_b32 s101, v183, 48
	s_nop 1
	v_mov_b32_e32 v183, s98
	v_add_f32_e32 v183, s99, v183
	v_add_f32_e32 v183, s100, v183
	v_add_f32_e32 v183, s101, v183
	v_fmamk_f32 v183, v183, 0x3a800000, v182
	v_cmp_gt_f32_e32 vcc, 0x800000, v183
	v_mul_f32_e32 v181, 0x4b800000, v183
	s_nop 1
	v_cndmask_b32_e32 v183, v183, v181, vcc
	v_rsq_f32_e32 v183, v183
	s_nop 0
	v_mul_f32_e32 v181, 0x45800000, v183
	v_cndmask_b32_e32 v184, v183, v181, vcc
	v_mov_b32_e32 v185, v184
	v_cvt_pk_bf16_f32 v32, v144, v145
	v_cvt_pk_bf16_f32 v33, v146, v147
	v_cvt_pk_bf16_f32 v34, v148, v149
	v_cvt_pk_bf16_f32 v35, v150, v151
	v_cvt_pk_bf16_f32 v36, v152, v153
	v_cvt_pk_bf16_f32 v37, v154, v155
	v_cvt_pk_bf16_f32 v38, v156, v157
	v_cvt_pk_bf16_f32 v39, v158, v159
	v_add_u32_e32 v181, 0x2000000, v177
	global_store_dwordx4 v181, v[32:35], s[78:79]
	global_store_dwordx4 v181, v[36:39], s[78:79] offset:1024
	v_add_u32_e32 v236, 0x4000, v237
	s_mov_b64 exec, 1
	global_store_dword v236, v184, s[78:79]
	s_mov_b64 exec, -1
	s_waitcnt vmcnt(16)
	v_lshlrev_b32_e32 v144, 16, v48
	v_and_b32_e32 v145, 0xffff0000, v48
	v_lshlrev_b32_e32 v146, 16, v49
	v_and_b32_e32 v147, 0xffff0000, v49
	v_lshlrev_b32_e32 v148, 16, v50
	v_and_b32_e32 v149, 0xffff0000, v50
	v_lshlrev_b32_e32 v150, 16, v51
	v_and_b32_e32 v151, 0xffff0000, v51
	v_lshlrev_b32_e32 v152, 16, v52
	v_and_b32_e32 v153, 0xffff0000, v52
	v_lshlrev_b32_e32 v154, 16, v53
	v_and_b32_e32 v155, 0xffff0000, v53
	v_lshlrev_b32_e32 v156, 16, v54
	v_and_b32_e32 v157, 0xffff0000, v54
	v_lshlrev_b32_e32 v158, 16, v55
	v_and_b32_e32 v159, 0xffff0000, v55
	v_lshlrev_b32_e32 v160, 16, v56
	v_and_b32_e32 v161, 0xffff0000, v56
	v_lshlrev_b32_e32 v162, 16, v57
	v_and_b32_e32 v163, 0xffff0000, v57
	v_lshlrev_b32_e32 v164, 16, v58
	v_and_b32_e32 v165, 0xffff0000, v58
	v_lshlrev_b32_e32 v166, 16, v59
	v_and_b32_e32 v167, 0xffff0000, v59
	v_lshlrev_b32_e32 v168, 16, v60
	v_and_b32_e32 v169, 0xffff0000, v60
	v_lshlrev_b32_e32 v170, 16, v61
	v_and_b32_e32 v171, 0xffff0000, v61
	v_lshlrev_b32_e32 v172, 16, v62
	v_and_b32_e32 v173, 0xffff0000, v62
	v_lshlrev_b32_e32 v174, 16, v63
	v_and_b32_e32 v175, 0xffff0000, v63
	v_pk_mul_f32 v[252:253], v[160:161], v[160:161]
	v_pk_mul_f32 v[254:255], v[162:163], v[162:163]
	v_pk_fma_f32 v[252:253], v[164:165], v[164:165], v[252:253]
	v_pk_fma_f32 v[254:255], v[166:167], v[166:167], v[254:255]
	v_pk_fma_f32 v[252:253], v[168:169], v[168:169], v[252:253]
	v_pk_fma_f32 v[254:255], v[170:171], v[170:171], v[254:255]
	v_pk_fma_f32 v[252:253], v[172:173], v[172:173], v[252:253]
	v_pk_fma_f32 v[254:255], v[174:175], v[174:175], v[254:255]
	v_pk_add_f32 v[252:253], v[252:253], v[254:255]
	s_nop 0
	v_add_f32_e32 v183, v252, v253
	s_nop 1
	v_add_f32_dpp v183, v183, v183 quad_perm:[1,0,3,2] row_mask:0xf bank_mask:0xf bound_ctrl:1
	s_nop 1
	v_add_f32_dpp v183, v183, v183 quad_perm:[2,3,0,1] row_mask:0xf bank_mask:0xf bound_ctrl:1
	s_nop 1
	v_add_f32_dpp v183, v183, v183 row_half_mirror row_mask:0xf bank_mask:0xf bound_ctrl:1
	s_nop 1
	v_add_f32_dpp v183, v183, v183 row_mirror row_mask:0xf bank_mask:0xf bound_ctrl:1
	s_nop 1
	v_readlane_b32 s98, v183, 0
	v_readlane_b32 s99, v183, 16
	v_readlane_b32 s100, v183, 32
	v_readlane_b32 s101, v183, 48
	s_nop 1
	v_mov_b32_e32 v183, s98
	v_add_f32_e32 v183, s99, v183
	v_add_f32_e32 v183, s100, v183
	v_add_f32_e32 v183, s101, v183
	v_fmamk_f32 v183, v183, 0x3a800000, v182
	v_cmp_gt_f32_e32 vcc, 0x800000, v183
	v_mul_f32_e32 v181, 0x4b800000, v183
	s_nop 1
	v_cndmask_b32_e32 v183, v183, v181, vcc
	v_rsq_f32_e32 v183, v183
	s_nop 0
	v_mul_f32_e32 v181, 0x45800000, v183
	v_cndmask_b32_e32 v184, v183, v181, vcc
	v_mov_b32_e32 v185, v184
	v_pk_mul_f32 v[160:161], v[160:161], v[184:185]
	v_pk_mul_f32 v[162:163], v[162:163], v[184:185]
	v_pk_mul_f32 v[164:165], v[164:165], v[184:185]
	v_pk_mul_f32 v[166:167], v[166:167], v[184:185]
	v_pk_mul_f32 v[168:169], v[168:169], v[184:185]
	v_pk_mul_f32 v[170:171], v[170:171], v[184:185]
	v_pk_mul_f32 v[172:173], v[172:173], v[184:185]
	v_pk_mul_f32 v[174:175], v[174:175], v[184:185]
	v_pk_fma_f32 v[144:145], v[160:161], v[128:129], v[144:145]
	v_pk_fma_f32 v[146:147], v[162:163], v[130:131], v[146:147]
	v_pk_fma_f32 v[148:149], v[164:165], v[132:133], v[148:149]
	v_pk_fma_f32 v[150:151], v[166:167], v[134:135], v[150:151]
	v_pk_fma_f32 v[152:153], v[168:169], v[136:137], v[152:153]
	v_pk_fma_f32 v[154:155], v[170:171], v[138:139], v[154:155]
	v_pk_fma_f32 v[156:157], v[172:173], v[140:141], v[156:157]
	v_pk_fma_f32 v[158:159], v[174:175], v[142:143], v[158:159]
	v_pk_mul_f32 v[252:253], v[144:145], v[144:145]
	v_pk_mul_f32 v[254:255], v[146:147], v[146:147]
	v_pk_fma_f32 v[252:253], v[148:149], v[148:149], v[252:253]
	v_pk_fma_f32 v[254:255], v[150:151], v[150:151], v[254:255]
	v_pk_fma_f32 v[252:253], v[152:153], v[152:153], v[252:253]
	v_pk_fma_f32 v[254:255], v[154:155], v[154:155], v[254:255]
	v_pk_fma_f32 v[252:253], v[156:157], v[156:157], v[252:253]
	v_pk_fma_f32 v[254:255], v[158:159], v[158:159], v[254:255]
	v_pk_add_f32 v[252:253], v[252:253], v[254:255]
	s_nop 0
	v_add_f32_e32 v183, v252, v253
	s_nop 1
	v_add_f32_dpp v183, v183, v183 quad_perm:[1,0,3,2] row_mask:0xf bank_mask:0xf bound_ctrl:1
	s_nop 1
	v_add_f32_dpp v183, v183, v183 quad_perm:[2,3,0,1] row_mask:0xf bank_mask:0xf bound_ctrl:1
	s_nop 1
	v_add_f32_dpp v183, v183, v183 row_half_mirror row_mask:0xf bank_mask:0xf bound_ctrl:1
	s_nop 1
	v_add_f32_dpp v183, v183, v183 row_mirror row_mask:0xf bank_mask:0xf bound_ctrl:1
	s_nop 1
	v_readlane_b32 s98, v183, 0
	v_readlane_b32 s99, v183, 16
	v_readlane_b32 s100, v183, 32
	v_readlane_b32 s101, v183, 48
	s_nop 1
	v_mov_b32_e32 v183, s98
	v_add_f32_e32 v183, s99, v183
	v_add_f32_e32 v183, s100, v183
	v_add_f32_e32 v183, s101, v183
	v_fmamk_f32 v183, v183, 0x3a800000, v182
	v_cmp_gt_f32_e32 vcc, 0x800000, v183
	v_mul_f32_e32 v181, 0x4b800000, v183
	s_nop 1
	v_cndmask_b32_e32 v183, v183, v181, vcc
	v_rsq_f32_e32 v183, v183
	s_nop 0
	v_mul_f32_e32 v181, 0x45800000, v183
	v_cndmask_b32_e32 v184, v183, v181, vcc
	v_mov_b32_e32 v185, v184
	v_cvt_pk_bf16_f32 v48, v144, v145
	v_cvt_pk_bf16_f32 v49, v146, v147
	v_cvt_pk_bf16_f32 v50, v148, v149
	v_cvt_pk_bf16_f32 v51, v150, v151
	v_cvt_pk_bf16_f32 v52, v152, v153
	v_cvt_pk_bf16_f32 v53, v154, v155
	v_cvt_pk_bf16_f32 v54, v156, v157
	v_cvt_pk_bf16_f32 v55, v158, v159
	v_add_u32_e32 v181, 0x2400000, v177
	global_store_dwordx4 v181, v[48:51], s[78:79]
	global_store_dwordx4 v181, v[52:55], s[78:79] offset:1024
	v_add_u32_e32 v236, 0x6000, v237
	s_mov_b64 exec, 1
	global_store_dword v236, v184, s[78:79]
	s_mov_b64 exec, -1
	s_waitcnt vmcnt(12)
	v_lshlrev_b32_e32 v144, 16, v64
	v_and_b32_e32 v145, 0xffff0000, v64
	v_lshlrev_b32_e32 v146, 16, v65
	v_and_b32_e32 v147, 0xffff0000, v65
	v_lshlrev_b32_e32 v148, 16, v66
	v_and_b32_e32 v149, 0xffff0000, v66
	v_lshlrev_b32_e32 v150, 16, v67
	v_and_b32_e32 v151, 0xffff0000, v67
	v_lshlrev_b32_e32 v152, 16, v68
	v_and_b32_e32 v153, 0xffff0000, v68
	v_lshlrev_b32_e32 v154, 16, v69
	v_and_b32_e32 v155, 0xffff0000, v69
	v_lshlrev_b32_e32 v156, 16, v70
	v_and_b32_e32 v157, 0xffff0000, v70
	v_lshlrev_b32_e32 v158, 16, v71
	v_and_b32_e32 v159, 0xffff0000, v71
	v_lshlrev_b32_e32 v160, 16, v72
	v_and_b32_e32 v161, 0xffff0000, v72
	v_lshlrev_b32_e32 v162, 16, v73
	v_and_b32_e32 v163, 0xffff0000, v73
	v_lshlrev_b32_e32 v164, 16, v74
	v_and_b32_e32 v165, 0xffff0000, v74
	v_lshlrev_b32_e32 v166, 16, v75
	v_and_b32_e32 v167, 0xffff0000, v75
	v_lshlrev_b32_e32 v168, 16, v76
	v_and_b32_e32 v169, 0xffff0000, v76
	v_lshlrev_b32_e32 v170, 16, v77
	v_and_b32_e32 v171, 0xffff0000, v77
	v_lshlrev_b32_e32 v172, 16, v78
	v_and_b32_e32 v173, 0xffff0000, v78
	v_lshlrev_b32_e32 v174, 16, v79
	v_and_b32_e32 v175, 0xffff0000, v79
	v_pk_mul_f32 v[252:253], v[160:161], v[160:161]
	v_pk_mul_f32 v[254:255], v[162:163], v[162:163]
	v_pk_fma_f32 v[252:253], v[164:165], v[164:165], v[252:253]
	v_pk_fma_f32 v[254:255], v[166:167], v[166:167], v[254:255]
	v_pk_fma_f32 v[252:253], v[168:169], v[168:169], v[252:253]
	v_pk_fma_f32 v[254:255], v[170:171], v[170:171], v[254:255]
	v_pk_fma_f32 v[252:253], v[172:173], v[172:173], v[252:253]
	v_pk_fma_f32 v[254:255], v[174:175], v[174:175], v[254:255]
	v_pk_add_f32 v[252:253], v[252:253], v[254:255]
	s_nop 0
	v_add_f32_e32 v183, v252, v253
	s_nop 1
	v_add_f32_dpp v183, v183, v183 quad_perm:[1,0,3,2] row_mask:0xf bank_mask:0xf bound_ctrl:1
	s_nop 1
	v_add_f32_dpp v183, v183, v183 quad_perm:[2,3,0,1] row_mask:0xf bank_mask:0xf bound_ctrl:1
	s_nop 1
	v_add_f32_dpp v183, v183, v183 row_half_mirror row_mask:0xf bank_mask:0xf bound_ctrl:1
	s_nop 1
	v_add_f32_dpp v183, v183, v183 row_mirror row_mask:0xf bank_mask:0xf bound_ctrl:1
	s_nop 1
	v_readlane_b32 s98, v183, 0
	v_readlane_b32 s99, v183, 16
	v_readlane_b32 s100, v183, 32
	v_readlane_b32 s101, v183, 48
	s_nop 1
	v_mov_b32_e32 v183, s98
	v_add_f32_e32 v183, s99, v183
	v_add_f32_e32 v183, s100, v183
	v_add_f32_e32 v183, s101, v183
	v_fmamk_f32 v183, v183, 0x3a800000, v182
	v_cmp_gt_f32_e32 vcc, 0x800000, v183
	v_mul_f32_e32 v181, 0x4b800000, v183
	s_nop 1
	v_cndmask_b32_e32 v183, v183, v181, vcc
	v_rsq_f32_e32 v183, v183
	s_nop 0
	v_mul_f32_e32 v181, 0x45800000, v183
	v_cndmask_b32_e32 v184, v183, v181, vcc
	v_mov_b32_e32 v185, v184
	v_pk_mul_f32 v[160:161], v[160:161], v[184:185]
	v_pk_mul_f32 v[162:163], v[162:163], v[184:185]
	v_pk_mul_f32 v[164:165], v[164:165], v[184:185]
	v_pk_mul_f32 v[166:167], v[166:167], v[184:185]
	v_pk_mul_f32 v[168:169], v[168:169], v[184:185]
	v_pk_mul_f32 v[170:171], v[170:171], v[184:185]
	v_pk_mul_f32 v[172:173], v[172:173], v[184:185]
	v_pk_mul_f32 v[174:175], v[174:175], v[184:185]
	v_pk_fma_f32 v[144:145], v[160:161], v[128:129], v[144:145]
	v_pk_fma_f32 v[146:147], v[162:163], v[130:131], v[146:147]
	v_pk_fma_f32 v[148:149], v[164:165], v[132:133], v[148:149]
	v_pk_fma_f32 v[150:151], v[166:167], v[134:135], v[150:151]
	v_pk_fma_f32 v[152:153], v[168:169], v[136:137], v[152:153]
	v_pk_fma_f32 v[154:155], v[170:171], v[138:139], v[154:155]
	v_pk_fma_f32 v[156:157], v[172:173], v[140:141], v[156:157]
	v_pk_fma_f32 v[158:159], v[174:175], v[142:143], v[158:159]
	v_pk_mul_f32 v[252:253], v[144:145], v[144:145]
	v_pk_mul_f32 v[254:255], v[146:147], v[146:147]
	v_pk_fma_f32 v[252:253], v[148:149], v[148:149], v[252:253]
	v_pk_fma_f32 v[254:255], v[150:151], v[150:151], v[254:255]
	v_pk_fma_f32 v[252:253], v[152:153], v[152:153], v[252:253]
	v_pk_fma_f32 v[254:255], v[154:155], v[154:155], v[254:255]
	v_pk_fma_f32 v[252:253], v[156:157], v[156:157], v[252:253]
	v_pk_fma_f32 v[254:255], v[158:159], v[158:159], v[254:255]
	v_pk_add_f32 v[252:253], v[252:253], v[254:255]
	s_nop 0
	v_add_f32_e32 v183, v252, v253
	s_nop 1
	v_add_f32_dpp v183, v183, v183 quad_perm:[1,0,3,2] row_mask:0xf bank_mask:0xf bound_ctrl:1
	s_nop 1
	v_add_f32_dpp v183, v183, v183 quad_perm:[2,3,0,1] row_mask:0xf bank_mask:0xf bound_ctrl:1
	s_nop 1
	v_add_f32_dpp v183, v183, v183 row_half_mirror row_mask:0xf bank_mask:0xf bound_ctrl:1
	s_nop 1
	v_add_f32_dpp v183, v183, v183 row_mirror row_mask:0xf bank_mask:0xf bound_ctrl:1
	s_nop 1
	v_readlane_b32 s98, v183, 0
	v_readlane_b32 s99, v183, 16
	v_readlane_b32 s100, v183, 32
	v_readlane_b32 s101, v183, 48
	s_nop 1
	v_mov_b32_e32 v183, s98
	v_add_f32_e32 v183, s99, v183
	v_add_f32_e32 v183, s100, v183
	v_add_f32_e32 v183, s101, v183
	v_fmamk_f32 v183, v183, 0x3a800000, v182
	v_cmp_gt_f32_e32 vcc, 0x800000, v183
	v_mul_f32_e32 v181, 0x4b800000, v183
	s_nop 1
	v_cndmask_b32_e32 v183, v183, v181, vcc
	v_rsq_f32_e32 v183, v183
	s_nop 0
	v_mul_f32_e32 v181, 0x45800000, v183
	v_cndmask_b32_e32 v184, v183, v181, vcc
	v_mov_b32_e32 v185, v184
	v_cvt_pk_bf16_f32 v64, v144, v145
	v_cvt_pk_bf16_f32 v65, v146, v147
	v_cvt_pk_bf16_f32 v66, v148, v149
	v_cvt_pk_bf16_f32 v67, v150, v151
	v_cvt_pk_bf16_f32 v68, v152, v153
	v_cvt_pk_bf16_f32 v69, v154, v155
	v_cvt_pk_bf16_f32 v70, v156, v157
	v_cvt_pk_bf16_f32 v71, v158, v159
	v_add_u32_e32 v181, 0x2800000, v177
	global_store_dwordx4 v181, v[64:67], s[78:79]
	global_store_dwordx4 v181, v[68:71], s[78:79] offset:1024
	v_add_u32_e32 v236, 0x8000, v237
	s_mov_b64 exec, 1
	global_store_dword v236, v184, s[78:79]
	s_mov_b64 exec, -1
	s_waitcnt vmcnt(8)
	v_lshlrev_b32_e32 v144, 16, v80
	v_and_b32_e32 v145, 0xffff0000, v80
	v_lshlrev_b32_e32 v146, 16, v81
	v_and_b32_e32 v147, 0xffff0000, v81
	v_lshlrev_b32_e32 v148, 16, v82
	v_and_b32_e32 v149, 0xffff0000, v82
	v_lshlrev_b32_e32 v150, 16, v83
	v_and_b32_e32 v151, 0xffff0000, v83
	v_lshlrev_b32_e32 v152, 16, v84
	v_and_b32_e32 v153, 0xffff0000, v84
	v_lshlrev_b32_e32 v154, 16, v85
	v_and_b32_e32 v155, 0xffff0000, v85
	v_lshlrev_b32_e32 v156, 16, v86
	v_and_b32_e32 v157, 0xffff0000, v86
	v_lshlrev_b32_e32 v158, 16, v87
	v_and_b32_e32 v159, 0xffff0000, v87
	v_lshlrev_b32_e32 v160, 16, v88
	v_and_b32_e32 v161, 0xffff0000, v88
	v_lshlrev_b32_e32 v162, 16, v89
	v_and_b32_e32 v163, 0xffff0000, v89
	v_lshlrev_b32_e32 v164, 16, v90
	v_and_b32_e32 v165, 0xffff0000, v90
	v_lshlrev_b32_e32 v166, 16, v91
	v_and_b32_e32 v167, 0xffff0000, v91
	v_lshlrev_b32_e32 v168, 16, v92
	v_and_b32_e32 v169, 0xffff0000, v92
	v_lshlrev_b32_e32 v170, 16, v93
	v_and_b32_e32 v171, 0xffff0000, v93
	v_lshlrev_b32_e32 v172, 16, v94
	v_and_b32_e32 v173, 0xffff0000, v94
	v_lshlrev_b32_e32 v174, 16, v95
	v_and_b32_e32 v175, 0xffff0000, v95
	v_pk_mul_f32 v[252:253], v[160:161], v[160:161]
	v_pk_mul_f32 v[254:255], v[162:163], v[162:163]
	v_pk_fma_f32 v[252:253], v[164:165], v[164:165], v[252:253]
	v_pk_fma_f32 v[254:255], v[166:167], v[166:167], v[254:255]
	v_pk_fma_f32 v[252:253], v[168:169], v[168:169], v[252:253]
	v_pk_fma_f32 v[254:255], v[170:171], v[170:171], v[254:255]
	v_pk_fma_f32 v[252:253], v[172:173], v[172:173], v[252:253]
	v_pk_fma_f32 v[254:255], v[174:175], v[174:175], v[254:255]
	v_pk_add_f32 v[252:253], v[252:253], v[254:255]
	s_nop 0
	v_add_f32_e32 v183, v252, v253
	s_nop 1
	v_add_f32_dpp v183, v183, v183 quad_perm:[1,0,3,2] row_mask:0xf bank_mask:0xf bound_ctrl:1
	s_nop 1
	v_add_f32_dpp v183, v183, v183 quad_perm:[2,3,0,1] row_mask:0xf bank_mask:0xf bound_ctrl:1
	s_nop 1
	v_add_f32_dpp v183, v183, v183 row_half_mirror row_mask:0xf bank_mask:0xf bound_ctrl:1
	s_nop 1
	v_add_f32_dpp v183, v183, v183 row_mirror row_mask:0xf bank_mask:0xf bound_ctrl:1
	s_nop 1
	v_readlane_b32 s98, v183, 0
	v_readlane_b32 s99, v183, 16
	v_readlane_b32 s100, v183, 32
	v_readlane_b32 s101, v183, 48
	s_nop 1
	v_mov_b32_e32 v183, s98
	v_add_f32_e32 v183, s99, v183
	v_add_f32_e32 v183, s100, v183
	v_add_f32_e32 v183, s101, v183
	v_fmamk_f32 v183, v183, 0x3a800000, v182
	v_cmp_gt_f32_e32 vcc, 0x800000, v183
	v_mul_f32_e32 v181, 0x4b800000, v183
	s_nop 1
	v_cndmask_b32_e32 v183, v183, v181, vcc
	v_rsq_f32_e32 v183, v183
	s_nop 0
	v_mul_f32_e32 v181, 0x45800000, v183
	v_cndmask_b32_e32 v184, v183, v181, vcc
	v_mov_b32_e32 v185, v184
	v_pk_mul_f32 v[160:161], v[160:161], v[184:185]
	v_pk_mul_f32 v[162:163], v[162:163], v[184:185]
	v_pk_mul_f32 v[164:165], v[164:165], v[184:185]
	v_pk_mul_f32 v[166:167], v[166:167], v[184:185]
	v_pk_mul_f32 v[168:169], v[168:169], v[184:185]
	v_pk_mul_f32 v[170:171], v[170:171], v[184:185]
	v_pk_mul_f32 v[172:173], v[172:173], v[184:185]
	v_pk_mul_f32 v[174:175], v[174:175], v[184:185]
	v_pk_fma_f32 v[144:145], v[160:161], v[128:129], v[144:145]
	v_pk_fma_f32 v[146:147], v[162:163], v[130:131], v[146:147]
	v_pk_fma_f32 v[148:149], v[164:165], v[132:133], v[148:149]
	v_pk_fma_f32 v[150:151], v[166:167], v[134:135], v[150:151]
	v_pk_fma_f32 v[152:153], v[168:169], v[136:137], v[152:153]
	v_pk_fma_f32 v[154:155], v[170:171], v[138:139], v[154:155]
	v_pk_fma_f32 v[156:157], v[172:173], v[140:141], v[156:157]
	v_pk_fma_f32 v[158:159], v[174:175], v[142:143], v[158:159]
	v_pk_mul_f32 v[252:253], v[144:145], v[144:145]
	v_pk_mul_f32 v[254:255], v[146:147], v[146:147]
	v_pk_fma_f32 v[252:253], v[148:149], v[148:149], v[252:253]
	v_pk_fma_f32 v[254:255], v[150:151], v[150:151], v[254:255]
	v_pk_fma_f32 v[252:253], v[152:153], v[152:153], v[252:253]
	v_pk_fma_f32 v[254:255], v[154:155], v[154:155], v[254:255]
	v_pk_fma_f32 v[252:253], v[156:157], v[156:157], v[252:253]
	v_pk_fma_f32 v[254:255], v[158:159], v[158:159], v[254:255]
	v_pk_add_f32 v[252:253], v[252:253], v[254:255]
	s_nop 0
	v_add_f32_e32 v183, v252, v253
	s_nop 1
	v_add_f32_dpp v183, v183, v183 quad_perm:[1,0,3,2] row_mask:0xf bank_mask:0xf bound_ctrl:1
	s_nop 1
	v_add_f32_dpp v183, v183, v183 quad_perm:[2,3,0,1] row_mask:0xf bank_mask:0xf bound_ctrl:1
	s_nop 1
	v_add_f32_dpp v183, v183, v183 row_half_mirror row_mask:0xf bank_mask:0xf bound_ctrl:1
	s_nop 1
	v_add_f32_dpp v183, v183, v183 row_mirror row_mask:0xf bank_mask:0xf bound_ctrl:1
	s_nop 1
	v_readlane_b32 s98, v183, 0
	v_readlane_b32 s99, v183, 16
	v_readlane_b32 s100, v183, 32
	v_readlane_b32 s101, v183, 48
	s_nop 1
	v_mov_b32_e32 v183, s98
	v_add_f32_e32 v183, s99, v183
	v_add_f32_e32 v183, s100, v183
	v_add_f32_e32 v183, s101, v183
	v_fmamk_f32 v183, v183, 0x3a800000, v182
	v_cmp_gt_f32_e32 vcc, 0x800000, v183
	v_mul_f32_e32 v181, 0x4b800000, v183
	s_nop 1
	v_cndmask_b32_e32 v183, v183, v181, vcc
	v_rsq_f32_e32 v183, v183
	s_nop 0
	v_mul_f32_e32 v181, 0x45800000, v183
	v_cndmask_b32_e32 v184, v183, v181, vcc
	v_mov_b32_e32 v185, v184
	v_cvt_pk_bf16_f32 v80, v144, v145
	v_cvt_pk_bf16_f32 v81, v146, v147
	v_cvt_pk_bf16_f32 v82, v148, v149
	v_cvt_pk_bf16_f32 v83, v150, v151
	v_cvt_pk_bf16_f32 v84, v152, v153
	v_cvt_pk_bf16_f32 v85, v154, v155
	v_cvt_pk_bf16_f32 v86, v156, v157
	v_cvt_pk_bf16_f32 v87, v158, v159
	v_add_u32_e32 v181, 0x2c00000, v177
	global_store_dwordx4 v181, v[80:83], s[78:79]
	global_store_dwordx4 v181, v[84:87], s[78:79] offset:1024
	v_add_u32_e32 v236, 0xa000, v237
	s_mov_b64 exec, 1
	global_store_dword v236, v184, s[78:79]
	s_mov_b64 exec, -1
	s_waitcnt vmcnt(4)
	v_lshlrev_b32_e32 v144, 16, v96
	v_and_b32_e32 v145, 0xffff0000, v96
	v_lshlrev_b32_e32 v146, 16, v97
	v_and_b32_e32 v147, 0xffff0000, v97
	v_lshlrev_b32_e32 v148, 16, v98
	v_and_b32_e32 v149, 0xffff0000, v98
	v_lshlrev_b32_e32 v150, 16, v99
	v_and_b32_e32 v151, 0xffff0000, v99
	v_lshlrev_b32_e32 v152, 16, v100
	v_and_b32_e32 v153, 0xffff0000, v100
	v_lshlrev_b32_e32 v154, 16, v101
	v_and_b32_e32 v155, 0xffff0000, v101
	v_lshlrev_b32_e32 v156, 16, v102
	v_and_b32_e32 v157, 0xffff0000, v102
	v_lshlrev_b32_e32 v158, 16, v103
	v_and_b32_e32 v159, 0xffff0000, v103
	v_lshlrev_b32_e32 v160, 16, v104
	v_and_b32_e32 v161, 0xffff0000, v104
	v_lshlrev_b32_e32 v162, 16, v105
	v_and_b32_e32 v163, 0xffff0000, v105
	v_lshlrev_b32_e32 v164, 16, v106
	v_and_b32_e32 v165, 0xffff0000, v106
	v_lshlrev_b32_e32 v166, 16, v107
	v_and_b32_e32 v167, 0xffff0000, v107
	v_lshlrev_b32_e32 v168, 16, v108
	v_and_b32_e32 v169, 0xffff0000, v108
	v_lshlrev_b32_e32 v170, 16, v109
	v_and_b32_e32 v171, 0xffff0000, v109
	v_lshlrev_b32_e32 v172, 16, v110
	v_and_b32_e32 v173, 0xffff0000, v110
	v_lshlrev_b32_e32 v174, 16, v111
	v_and_b32_e32 v175, 0xffff0000, v111
	v_pk_mul_f32 v[252:253], v[160:161], v[160:161]
	v_pk_mul_f32 v[254:255], v[162:163], v[162:163]
	v_pk_fma_f32 v[252:253], v[164:165], v[164:165], v[252:253]
	v_pk_fma_f32 v[254:255], v[166:167], v[166:167], v[254:255]
	v_pk_fma_f32 v[252:253], v[168:169], v[168:169], v[252:253]
	v_pk_fma_f32 v[254:255], v[170:171], v[170:171], v[254:255]
	v_pk_fma_f32 v[252:253], v[172:173], v[172:173], v[252:253]
	v_pk_fma_f32 v[254:255], v[174:175], v[174:175], v[254:255]
	v_pk_add_f32 v[252:253], v[252:253], v[254:255]
	s_nop 0
	v_add_f32_e32 v183, v252, v253
	s_nop 1
	v_add_f32_dpp v183, v183, v183 quad_perm:[1,0,3,2] row_mask:0xf bank_mask:0xf bound_ctrl:1
	s_nop 1
	v_add_f32_dpp v183, v183, v183 quad_perm:[2,3,0,1] row_mask:0xf bank_mask:0xf bound_ctrl:1
	s_nop 1
	v_add_f32_dpp v183, v183, v183 row_half_mirror row_mask:0xf bank_mask:0xf bound_ctrl:1
	s_nop 1
	v_add_f32_dpp v183, v183, v183 row_mirror row_mask:0xf bank_mask:0xf bound_ctrl:1
	s_nop 1
	v_readlane_b32 s98, v183, 0
	v_readlane_b32 s99, v183, 16
	v_readlane_b32 s100, v183, 32
	v_readlane_b32 s101, v183, 48
	s_nop 1
	v_mov_b32_e32 v183, s98
	v_add_f32_e32 v183, s99, v183
	v_add_f32_e32 v183, s100, v183
	v_add_f32_e32 v183, s101, v183
	v_fmamk_f32 v183, v183, 0x3a800000, v182
	v_cmp_gt_f32_e32 vcc, 0x800000, v183
	v_mul_f32_e32 v181, 0x4b800000, v183
	s_nop 1
	v_cndmask_b32_e32 v183, v183, v181, vcc
	v_rsq_f32_e32 v183, v183
	s_nop 0
	v_mul_f32_e32 v181, 0x45800000, v183
	v_cndmask_b32_e32 v184, v183, v181, vcc
	v_mov_b32_e32 v185, v184
	v_pk_mul_f32 v[160:161], v[160:161], v[184:185]
	v_pk_mul_f32 v[162:163], v[162:163], v[184:185]
	v_pk_mul_f32 v[164:165], v[164:165], v[184:185]
	v_pk_mul_f32 v[166:167], v[166:167], v[184:185]
	v_pk_mul_f32 v[168:169], v[168:169], v[184:185]
	v_pk_mul_f32 v[170:171], v[170:171], v[184:185]
	v_pk_mul_f32 v[172:173], v[172:173], v[184:185]
	v_pk_mul_f32 v[174:175], v[174:175], v[184:185]
	v_pk_fma_f32 v[144:145], v[160:161], v[128:129], v[144:145]
	v_pk_fma_f32 v[146:147], v[162:163], v[130:131], v[146:147]
	v_pk_fma_f32 v[148:149], v[164:165], v[132:133], v[148:149]
	v_pk_fma_f32 v[150:151], v[166:167], v[134:135], v[150:151]
	v_pk_fma_f32 v[152:153], v[168:169], v[136:137], v[152:153]
	v_pk_fma_f32 v[154:155], v[170:171], v[138:139], v[154:155]
	v_pk_fma_f32 v[156:157], v[172:173], v[140:141], v[156:157]
	v_pk_fma_f32 v[158:159], v[174:175], v[142:143], v[158:159]
	v_pk_mul_f32 v[252:253], v[144:145], v[144:145]
	v_pk_mul_f32 v[254:255], v[146:147], v[146:147]
	v_pk_fma_f32 v[252:253], v[148:149], v[148:149], v[252:253]
	v_pk_fma_f32 v[254:255], v[150:151], v[150:151], v[254:255]
	v_pk_fma_f32 v[252:253], v[152:153], v[152:153], v[252:253]
	v_pk_fma_f32 v[254:255], v[154:155], v[154:155], v[254:255]
	v_pk_fma_f32 v[252:253], v[156:157], v[156:157], v[252:253]
	v_pk_fma_f32 v[254:255], v[158:159], v[158:159], v[254:255]
	v_pk_add_f32 v[252:253], v[252:253], v[254:255]
	s_nop 0
	v_add_f32_e32 v183, v252, v253
	s_nop 1
	v_add_f32_dpp v183, v183, v183 quad_perm:[1,0,3,2] row_mask:0xf bank_mask:0xf bound_ctrl:1
	s_nop 1
	v_add_f32_dpp v183, v183, v183 quad_perm:[2,3,0,1] row_mask:0xf bank_mask:0xf bound_ctrl:1
	s_nop 1
	v_add_f32_dpp v183, v183, v183 row_half_mirror row_mask:0xf bank_mask:0xf bound_ctrl:1
	s_nop 1
	v_add_f32_dpp v183, v183, v183 row_mirror row_mask:0xf bank_mask:0xf bound_ctrl:1
	s_nop 1
	v_readlane_b32 s98, v183, 0
	v_readlane_b32 s99, v183, 16
	v_readlane_b32 s100, v183, 32
	v_readlane_b32 s101, v183, 48
	s_nop 1
	v_mov_b32_e32 v183, s98
	v_add_f32_e32 v183, s99, v183
	v_add_f32_e32 v183, s100, v183
	v_add_f32_e32 v183, s101, v183
	v_fmamk_f32 v183, v183, 0x3a800000, v182
	v_cmp_gt_f32_e32 vcc, 0x800000, v183
	v_mul_f32_e32 v181, 0x4b800000, v183
	s_nop 1
	v_cndmask_b32_e32 v183, v183, v181, vcc
	v_rsq_f32_e32 v183, v183
	s_nop 0
	v_mul_f32_e32 v181, 0x45800000, v183
	v_cndmask_b32_e32 v184, v183, v181, vcc
	v_mov_b32_e32 v185, v184
	v_cvt_pk_bf16_f32 v96, v144, v145
	v_cvt_pk_bf16_f32 v97, v146, v147
	v_cvt_pk_bf16_f32 v98, v148, v149
	v_cvt_pk_bf16_f32 v99, v150, v151
	v_cvt_pk_bf16_f32 v100, v152, v153
	v_cvt_pk_bf16_f32 v101, v154, v155
	v_cvt_pk_bf16_f32 v102, v156, v157
	v_cvt_pk_bf16_f32 v103, v158, v159
	v_add_u32_e32 v181, 0x3000000, v177
	global_store_dwordx4 v181, v[96:99], s[78:79]
	global_store_dwordx4 v181, v[100:103], s[78:79] offset:1024
	v_add_u32_e32 v236, 0xc000, v237
	s_mov_b64 exec, 1
	global_store_dword v236, v184, s[78:79]
	s_mov_b64 exec, -1
	s_waitcnt vmcnt(0)
	v_lshlrev_b32_e32 v144, 16, v112
	v_and_b32_e32 v145, 0xffff0000, v112
	v_lshlrev_b32_e32 v146, 16, v113
	v_and_b32_e32 v147, 0xffff0000, v113
	v_lshlrev_b32_e32 v148, 16, v114
	v_and_b32_e32 v149, 0xffff0000, v114
	v_lshlrev_b32_e32 v150, 16, v115
	v_and_b32_e32 v151, 0xffff0000, v115
	v_lshlrev_b32_e32 v152, 16, v116
	v_and_b32_e32 v153, 0xffff0000, v116
	v_lshlrev_b32_e32 v154, 16, v117
	v_and_b32_e32 v155, 0xffff0000, v117
	v_lshlrev_b32_e32 v156, 16, v118
	v_and_b32_e32 v157, 0xffff0000, v118
	v_lshlrev_b32_e32 v158, 16, v119
	v_and_b32_e32 v159, 0xffff0000, v119
	v_lshlrev_b32_e32 v160, 16, v120
	v_and_b32_e32 v161, 0xffff0000, v120
	v_lshlrev_b32_e32 v162, 16, v121
	v_and_b32_e32 v163, 0xffff0000, v121
	v_lshlrev_b32_e32 v164, 16, v122
	v_and_b32_e32 v165, 0xffff0000, v122
	v_lshlrev_b32_e32 v166, 16, v123
	v_and_b32_e32 v167, 0xffff0000, v123
	v_lshlrev_b32_e32 v168, 16, v124
	v_and_b32_e32 v169, 0xffff0000, v124
	v_lshlrev_b32_e32 v170, 16, v125
	v_and_b32_e32 v171, 0xffff0000, v125
	v_lshlrev_b32_e32 v172, 16, v126
	v_and_b32_e32 v173, 0xffff0000, v126
	v_lshlrev_b32_e32 v174, 16, v127
	v_and_b32_e32 v175, 0xffff0000, v127
	v_pk_mul_f32 v[252:253], v[160:161], v[160:161]
	v_pk_mul_f32 v[254:255], v[162:163], v[162:163]
	v_pk_fma_f32 v[252:253], v[164:165], v[164:165], v[252:253]
	v_pk_fma_f32 v[254:255], v[166:167], v[166:167], v[254:255]
	v_pk_fma_f32 v[252:253], v[168:169], v[168:169], v[252:253]
	v_pk_fma_f32 v[254:255], v[170:171], v[170:171], v[254:255]
	v_pk_fma_f32 v[252:253], v[172:173], v[172:173], v[252:253]
	v_pk_fma_f32 v[254:255], v[174:175], v[174:175], v[254:255]
	v_pk_add_f32 v[252:253], v[252:253], v[254:255]
	s_nop 0
	v_add_f32_e32 v183, v252, v253
	s_nop 1
	v_add_f32_dpp v183, v183, v183 quad_perm:[1,0,3,2] row_mask:0xf bank_mask:0xf bound_ctrl:1
	s_nop 1
	v_add_f32_dpp v183, v183, v183 quad_perm:[2,3,0,1] row_mask:0xf bank_mask:0xf bound_ctrl:1
	s_nop 1
	v_add_f32_dpp v183, v183, v183 row_half_mirror row_mask:0xf bank_mask:0xf bound_ctrl:1
	s_nop 1
	v_add_f32_dpp v183, v183, v183 row_mirror row_mask:0xf bank_mask:0xf bound_ctrl:1
	s_nop 1
	v_readlane_b32 s98, v183, 0
	v_readlane_b32 s99, v183, 16
	v_readlane_b32 s100, v183, 32
	v_readlane_b32 s101, v183, 48
	s_nop 1
	v_mov_b32_e32 v183, s98
	v_add_f32_e32 v183, s99, v183
	v_add_f32_e32 v183, s100, v183
	v_add_f32_e32 v183, s101, v183
	v_fmamk_f32 v183, v183, 0x3a800000, v182
	v_cmp_gt_f32_e32 vcc, 0x800000, v183
	v_mul_f32_e32 v181, 0x4b800000, v183
	s_nop 1
	v_cndmask_b32_e32 v183, v183, v181, vcc
	v_rsq_f32_e32 v183, v183
	s_nop 0
	v_mul_f32_e32 v181, 0x45800000, v183
	v_cndmask_b32_e32 v184, v183, v181, vcc
	v_mov_b32_e32 v185, v184
	v_pk_mul_f32 v[160:161], v[160:161], v[184:185]
	v_pk_mul_f32 v[162:163], v[162:163], v[184:185]
	v_pk_mul_f32 v[164:165], v[164:165], v[184:185]
	v_pk_mul_f32 v[166:167], v[166:167], v[184:185]
	v_pk_mul_f32 v[168:169], v[168:169], v[184:185]
	v_pk_mul_f32 v[170:171], v[170:171], v[184:185]
	v_pk_mul_f32 v[172:173], v[172:173], v[184:185]
	v_pk_mul_f32 v[174:175], v[174:175], v[184:185]
	v_pk_fma_f32 v[144:145], v[160:161], v[128:129], v[144:145]
	v_pk_fma_f32 v[146:147], v[162:163], v[130:131], v[146:147]
	v_pk_fma_f32 v[148:149], v[164:165], v[132:133], v[148:149]
	v_pk_fma_f32 v[150:151], v[166:167], v[134:135], v[150:151]
	v_pk_fma_f32 v[152:153], v[168:169], v[136:137], v[152:153]
	v_pk_fma_f32 v[154:155], v[170:171], v[138:139], v[154:155]
	v_pk_fma_f32 v[156:157], v[172:173], v[140:141], v[156:157]
	v_pk_fma_f32 v[158:159], v[174:175], v[142:143], v[158:159]
	v_pk_mul_f32 v[252:253], v[144:145], v[144:145]
	v_pk_mul_f32 v[254:255], v[146:147], v[146:147]
	v_pk_fma_f32 v[252:253], v[148:149], v[148:149], v[252:253]
	v_pk_fma_f32 v[254:255], v[150:151], v[150:151], v[254:255]
	v_pk_fma_f32 v[252:253], v[152:153], v[152:153], v[252:253]
	v_pk_fma_f32 v[254:255], v[154:155], v[154:155], v[254:255]
	v_pk_fma_f32 v[252:253], v[156:157], v[156:157], v[252:253]
	v_pk_fma_f32 v[254:255], v[158:159], v[158:159], v[254:255]
	v_pk_add_f32 v[252:253], v[252:253], v[254:255]
	s_nop 0
	v_add_f32_e32 v183, v252, v253
	s_nop 1
	v_add_f32_dpp v183, v183, v183 quad_perm:[1,0,3,2] row_mask:0xf bank_mask:0xf bound_ctrl:1
	s_nop 1
	v_add_f32_dpp v183, v183, v183 quad_perm:[2,3,0,1] row_mask:0xf bank_mask:0xf bound_ctrl:1
	s_nop 1
	v_add_f32_dpp v183, v183, v183 row_half_mirror row_mask:0xf bank_mask:0xf bound_ctrl:1
	s_nop 1
	v_add_f32_dpp v183, v183, v183 row_mirror row_mask:0xf bank_mask:0xf bound_ctrl:1
	s_nop 1
	v_readlane_b32 s98, v183, 0
	v_readlane_b32 s99, v183, 16
	v_readlane_b32 s100, v183, 32
	v_readlane_b32 s101, v183, 48
	s_nop 1
	v_mov_b32_e32 v183, s98
	v_add_f32_e32 v183, s99, v183
	v_add_f32_e32 v183, s100, v183
	v_add_f32_e32 v183, s101, v183
	v_fmamk_f32 v183, v183, 0x3a800000, v182
	v_cmp_gt_f32_e32 vcc, 0x800000, v183
	v_mul_f32_e32 v181, 0x4b800000, v183
	s_nop 1
	v_cndmask_b32_e32 v183, v183, v181, vcc
	v_rsq_f32_e32 v183, v183
	s_nop 0
	v_mul_f32_e32 v181, 0x45800000, v183
	v_cndmask_b32_e32 v184, v183, v181, vcc
	v_mov_b32_e32 v185, v184
	v_cvt_pk_bf16_f32 v112, v144, v145
	v_cvt_pk_bf16_f32 v113, v146, v147
	v_cvt_pk_bf16_f32 v114, v148, v149
	v_cvt_pk_bf16_f32 v115, v150, v151
	v_cvt_pk_bf16_f32 v116, v152, v153
	v_cvt_pk_bf16_f32 v117, v154, v155
	v_cvt_pk_bf16_f32 v118, v156, v157
	v_cvt_pk_bf16_f32 v119, v158, v159
	v_add_u32_e32 v181, 0x3400000, v177
	global_store_dwordx4 v181, v[112:115], s[78:79]
	global_store_dwordx4 v181, v[116:119], s[78:79] offset:1024
	v_add_u32_e32 v236, 0xe000, v237
	s_mov_b64 exec, 1
	global_store_dword v236, v184, s[78:79]
	s_mov_b64 exec, -1
	v_readfirstlane_b32 s98, v179
	s_nop 3
	s_cmp_ge_u32 s98, 512
	s_cbranch_scc1 .Lmyxupd_done_4
	v_lshlrev_b32_e32 v177, 4, v176
	v_lshl_add_u32 v177, v179, 11, v177
	v_lshlrev_b32_e32 v237, 2, v179
	v_add_u32_e32 v237, 0x10000, v237
	v_add_u32_e32 v181, 0x3800000, v177
	global_load_dwordx4 v[0:3], v181, s[78:79]
	global_load_dwordx4 v[4:7], v181, s[78:79] offset:1024
	v_lshl_add_u32 v183, v179, 12, v180
	v_add_u32_e32 v183, 0xbf00000, v183
	v_add_u32_e32 v181, 0x0, v183
	global_load_dwordx4 v[8:11], v181, s[78:79]
	global_load_dwordx4 v[12:15], v181, s[78:79] offset:16
	global_load_dwordx4 v[16:19], v181, s[78:79] offset:2048
	global_load_dwordx4 v[20:23], v181, s[78:79] offset:2064
	v_add_u32_e32 v181, 0x200000, v183
	global_load_dwordx4 v[24:27], v181, s[78:79]
	global_load_dwordx4 v[28:31], v181, s[78:79] offset:16
	global_load_dwordx4 v[32:35], v181, s[78:79] offset:2048
	global_load_dwordx4 v[36:39], v181, s[78:79] offset:2064
	v_add_u32_e32 v181, 0x400000, v183
	global_load_dwordx4 v[40:43], v181, s[78:79]
	global_load_dwordx4 v[44:47], v181, s[78:79] offset:16
	global_load_dwordx4 v[48:51], v181, s[78:79] offset:2048
	global_load_dwordx4 v[52:55], v181, s[78:79] offset:2064
	v_add_u32_e32 v181, 0x600000, v183
	global_load_dwordx4 v[56:59], v181, s[78:79]
	global_load_dwordx4 v[60:63], v181, s[78:79] offset:16
	global_load_dwordx4 v[64:67], v181, s[78:79] offset:2048
	global_load_dwordx4 v[68:71], v181, s[78:79] offset:2064
	v_add_u32_e32 v181, 0x800000, v183
	global_load_dwordx4 v[72:75], v181, s[78:79]
	global_load_dwordx4 v[76:79], v181, s[78:79] offset:16
	global_load_dwordx4 v[80:83], v181, s[78:79] offset:2048
	global_load_dwordx4 v[84:87], v181, s[78:79] offset:2064
	v_add_u32_e32 v181, 0xa00000, v183
	global_load_dwordx4 v[88:91], v181, s[78:79]
	global_load_dwordx4 v[92:95], v181, s[78:79] offset:16
	global_load_dwordx4 v[96:99], v181, s[78:79] offset:2048
	global_load_dwordx4 v[100:103], v181, s[78:79] offset:2064
	s_waitcnt vmcnt(20)
	v_pk_add_f32 v[160:161], v[8:9], 0 op_sel_hi:[1,0]
	v_pk_add_f32 v[162:163], v[10:11], 0 op_sel_hi:[1,0]
	v_pk_add_f32 v[164:165], v[12:13], 0 op_sel_hi:[1,0]
	v_pk_add_f32 v[166:167], v[14:15], 0 op_sel_hi:[1,0]
	v_pk_add_f32 v[168:169], v[16:17], 0 op_sel_hi:[1,0]
	v_pk_add_f32 v[170:171], v[18:19], 0 op_sel_hi:[1,0]
	v_pk_add_f32 v[172:173], v[20:21], 0 op_sel_hi:[1,0]
	v_pk_add_f32 v[174:175], v[22:23], 0 op_sel_hi:[1,0]
	s_waitcnt vmcnt(16)
	v_pk_add_f32 v[160:161], v[160:161], v[24:25]
	v_pk_add_f32 v[162:163], v[162:163], v[26:27]
	v_pk_add_f32 v[164:165], v[164:165], v[28:29]
	v_pk_add_f32 v[166:167], v[166:167], v[30:31]
	v_pk_add_f32 v[168:169], v[168:169], v[32:33]
	v_pk_add_f32 v[170:171], v[170:171], v[34:35]
	v_pk_add_f32 v[172:173], v[172:173], v[36:37]
	v_pk_add_f32 v[174:175], v[174:175], v[38:39]
	s_waitcnt vmcnt(12)
	v_pk_add_f32 v[160:161], v[160:161], v[40:41]
	v_pk_add_f32 v[162:163], v[162:163], v[42:43]
	v_pk_add_f32 v[164:165], v[164:165], v[44:45]
	v_pk_add_f32 v[166:167], v[166:167], v[46:47]
	v_pk_add_f32 v[168:169], v[168:169], v[48:49]
	v_pk_add_f32 v[170:171], v[170:171], v[50:51]
	v_pk_add_f32 v[172:173], v[172:173], v[52:53]
	v_pk_add_f32 v[174:175], v[174:175], v[54:55]
	s_waitcnt vmcnt(8)
	v_pk_add_f32 v[160:161], v[160:161], v[56:57]
	v_pk_add_f32 v[162:163], v[162:163], v[58:59]
	v_pk_add_f32 v[164:165], v[164:165], v[60:61]
	v_pk_add_f32 v[166:167], v[166:167], v[62:63]
	v_pk_add_f32 v[168:169], v[168:169], v[64:65]
	v_pk_add_f32 v[170:171], v[170:171], v[66:67]
	v_pk_add_f32 v[172:173], v[172:173], v[68:69]
	v_pk_add_f32 v[174:175], v[174:175], v[70:71]
	s_waitcnt vmcnt(4)
	v_pk_add_f32 v[160:161], v[160:161], v[72:73]
	v_pk_add_f32 v[162:163], v[162:163], v[74:75]
	v_pk_add_f32 v[164:165], v[164:165], v[76:77]
	v_pk_add_f32 v[166:167], v[166:167], v[78:79]
	v_pk_add_f32 v[168:169], v[168:169], v[80:81]
	v_pk_add_f32 v[170:171], v[170:171], v[82:83]
	v_pk_add_f32 v[172:173], v[172:173], v[84:85]
	v_pk_add_f32 v[174:175], v[174:175], v[86:87]
	s_waitcnt vmcnt(0)
	v_pk_add_f32 v[160:161], v[160:161], v[88:89]
	v_pk_add_f32 v[162:163], v[162:163], v[90:91]
	v_pk_add_f32 v[164:165], v[164:165], v[92:93]
	v_pk_add_f32 v[166:167], v[166:167], v[94:95]
	v_pk_add_f32 v[168:169], v[168:169], v[96:97]
	v_pk_add_f32 v[170:171], v[170:171], v[98:99]
	v_pk_add_f32 v[172:173], v[172:173], v[100:101]
	v_pk_add_f32 v[174:175], v[174:175], v[102:103]
	v_lshlrev_b32_e32 v144, 16, v0
	v_and_b32_e32 v145, 0xffff0000, v0
	v_lshlrev_b32_e32 v146, 16, v1
	v_and_b32_e32 v147, 0xffff0000, v1
	v_lshlrev_b32_e32 v148, 16, v2
	v_and_b32_e32 v149, 0xffff0000, v2
	v_lshlrev_b32_e32 v150, 16, v3
	v_and_b32_e32 v151, 0xffff0000, v3
	v_lshlrev_b32_e32 v152, 16, v4
	v_and_b32_e32 v153, 0xffff0000, v4
	v_lshlrev_b32_e32 v154, 16, v5
	v_and_b32_e32 v155, 0xffff0000, v5
	v_lshlrev_b32_e32 v156, 16, v6
	v_and_b32_e32 v157, 0xffff0000, v6
	v_lshlrev_b32_e32 v158, 16, v7
	v_and_b32_e32 v159, 0xffff0000, v7
	v_add_u32_e32 v181, 0xc00000, v183
	global_load_dwordx4 v[8:11], v181, s[78:79]
	global_load_dwordx4 v[12:15], v181, s[78:79] offset:16
	global_load_dwordx4 v[16:19], v181, s[78:79] offset:2048
	global_load_dwordx4 v[20:23], v181, s[78:79] offset:2064
	v_add_u32_e32 v181, 0xe00000, v183
	global_load_dwordx4 v[24:27], v181, s[78:79]
	global_load_dwordx4 v[28:31], v181, s[78:79] offset:16
	global_load_dwordx4 v[32:35], v181, s[78:79] offset:2048
	global_load_dwordx4 v[36:39], v181, s[78:79] offset:2064
	s_waitcnt vmcnt(4)
	v_pk_add_f32 v[160:161], v[160:161], v[8:9]
	v_pk_add_f32 v[162:163], v[162:163], v[10:11]
	v_pk_add_f32 v[164:165], v[164:165], v[12:13]
	v_pk_add_f32 v[166:167], v[166:167], v[14:15]
	v_pk_add_f32 v[168:169], v[168:169], v[16:17]
	v_pk_add_f32 v[170:171], v[170:171], v[18:19]
	v_pk_add_f32 v[172:173], v[172:173], v[20:21]
	v_pk_add_f32 v[174:175], v[174:175], v[22:23]
	s_waitcnt vmcnt(0)
	v_pk_add_f32 v[160:161], v[160:161], v[24:25]
	v_pk_add_f32 v[162:163], v[162:163], v[26:27]
	v_pk_add_f32 v[164:165], v[164:165], v[28:29]
	v_pk_add_f32 v[166:167], v[166:167], v[30:31]
	v_pk_add_f32 v[168:169], v[168:169], v[32:33]
	v_pk_add_f32 v[170:171], v[170:171], v[34:35]
	v_pk_add_f32 v[172:173], v[172:173], v[36:37]
	v_pk_add_f32 v[174:175], v[174:175], v[38:39]
	v_pk_mul_f32 v[252:253], v[160:161], v[160:161]
	v_pk_mul_f32 v[254:255], v[162:163], v[162:163]
	v_pk_fma_f32 v[252:253], v[164:165], v[164:165], v[252:253]
	v_pk_fma_f32 v[254:255], v[166:167], v[166:167], v[254:255]
	v_pk_fma_f32 v[252:253], v[168:169], v[168:169], v[252:253]
	v_pk_fma_f32 v[254:255], v[170:171], v[170:171], v[254:255]
	v_pk_fma_f32 v[252:253], v[172:173], v[172:173], v[252:253]
	v_pk_fma_f32 v[254:255], v[174:175], v[174:175], v[254:255]
	v_pk_add_f32 v[252:253], v[252:253], v[254:255]
	s_nop 0
	v_add_f32_e32 v183, v252, v253
	s_nop 1
	v_add_f32_dpp v183, v183, v183 quad_perm:[1,0,3,2] row_mask:0xf bank_mask:0xf bound_ctrl:1
	s_nop 1
	v_add_f32_dpp v183, v183, v183 quad_perm:[2,3,0,1] row_mask:0xf bank_mask:0xf bound_ctrl:1
	s_nop 1
	v_add_f32_dpp v183, v183, v183 row_half_mirror row_mask:0xf bank_mask:0xf bound_ctrl:1
	s_nop 1
	v_add_f32_dpp v183, v183, v183 row_mirror row_mask:0xf bank_mask:0xf bound_ctrl:1
	s_nop 1
	v_readlane_b32 s98, v183, 0
	v_readlane_b32 s99, v183, 16
	v_readlane_b32 s100, v183, 32
	v_readlane_b32 s101, v183, 48
	s_nop 1
	v_mov_b32_e32 v183, s98
	v_add_f32_e32 v183, s99, v183
	v_add_f32_e32 v183, s100, v183
	v_add_f32_e32 v183, s101, v183
	v_fmamk_f32 v183, v183, 0x3a800000, v182
	v_cmp_gt_f32_e32 vcc, 0x800000, v183
	v_mul_f32_e32 v181, 0x4b800000, v183
	s_nop 1
	v_cndmask_b32_e32 v183, v183, v181, vcc
	v_rsq_f32_e32 v183, v183
	s_nop 0
	v_mul_f32_e32 v181, 0x45800000, v183
	v_cndmask_b32_e32 v184, v183, v181, vcc
	v_mov_b32_e32 v185, v184
	v_pk_mul_f32 v[160:161], v[160:161], v[184:185]
	v_pk_mul_f32 v[162:163], v[162:163], v[184:185]
	v_pk_mul_f32 v[164:165], v[164:165], v[184:185]
	v_pk_mul_f32 v[166:167], v[166:167], v[184:185]
	v_pk_mul_f32 v[168:169], v[168:169], v[184:185]
	v_pk_mul_f32 v[170:171], v[170:171], v[184:185]
	v_pk_mul_f32 v[172:173], v[172:173], v[184:185]
	v_pk_mul_f32 v[174:175], v[174:175], v[184:185]
	v_pk_fma_f32 v[144:145], v[160:161], v[128:129], v[144:145]
	v_pk_fma_f32 v[146:147], v[162:163], v[130:131], v[146:147]
	v_pk_fma_f32 v[148:149], v[164:165], v[132:133], v[148:149]
	v_pk_fma_f32 v[150:151], v[166:167], v[134:135], v[150:151]
	v_pk_fma_f32 v[152:153], v[168:169], v[136:137], v[152:153]
	v_pk_fma_f32 v[154:155], v[170:171], v[138:139], v[154:155]
	v_pk_fma_f32 v[156:157], v[172:173], v[140:141], v[156:157]
	v_pk_fma_f32 v[158:159], v[174:175], v[142:143], v[158:159]
	v_pk_mul_f32 v[252:253], v[144:145], v[144:145]
	v_pk_mul_f32 v[254:255], v[146:147], v[146:147]
	v_pk_fma_f32 v[252:253], v[148:149], v[148:149], v[252:253]
	v_pk_fma_f32 v[254:255], v[150:151], v[150:151], v[254:255]
	v_pk_fma_f32 v[252:253], v[152:153], v[152:153], v[252:253]
	v_pk_fma_f32 v[254:255], v[154:155], v[154:155], v[254:255]
	v_pk_fma_f32 v[252:253], v[156:157], v[156:157], v[252:253]
	v_pk_fma_f32 v[254:255], v[158:159], v[158:159], v[254:255]
	v_pk_add_f32 v[252:253], v[252:253], v[254:255]
	s_nop 0
	v_add_f32_e32 v183, v252, v253
	s_nop 1
	v_add_f32_dpp v183, v183, v183 quad_perm:[1,0,3,2] row_mask:0xf bank_mask:0xf bound_ctrl:1
	s_nop 1
	v_add_f32_dpp v183, v183, v183 quad_perm:[2,3,0,1] row_mask:0xf bank_mask:0xf bound_ctrl:1
	s_nop 1
	v_add_f32_dpp v183, v183, v183 row_half_mirror row_mask:0xf bank_mask:0xf bound_ctrl:1
	s_nop 1
	v_add_f32_dpp v183, v183, v183 row_mirror row_mask:0xf bank_mask:0xf bound_ctrl:1
	s_nop 1
	v_readlane_b32 s98, v183, 0
	v_readlane_b32 s99, v183, 16
	v_readlane_b32 s100, v183, 32
	v_readlane_b32 s101, v183, 48
	s_nop 1
	v_mov_b32_e32 v183, s98
	v_add_f32_e32 v183, s99, v183
	v_add_f32_e32 v183, s100, v183
	v_add_f32_e32 v183, s101, v183
	v_fmamk_f32 v183, v183, 0x3a800000, v182
	v_cmp_gt_f32_e32 vcc, 0x800000, v183
	v_mul_f32_e32 v181, 0x4b800000, v183
	s_nop 1
	v_cndmask_b32_e32 v183, v183, v181, vcc
	v_rsq_f32_e32 v183, v183
	s_nop 0
	v_mul_f32_e32 v181, 0x45800000, v183
	v_cndmask_b32_e32 v184, v183, v181, vcc
	v_mov_b32_e32 v185, v184
	v_cvt_pk_bf16_f32 v0, v144, v145
	v_cvt_pk_bf16_f32 v1, v146, v147
	v_cvt_pk_bf16_f32 v2, v148, v149
	v_cvt_pk_bf16_f32 v3, v150, v151
	v_cvt_pk_bf16_f32 v4, v152, v153
	v_cvt_pk_bf16_f32 v5, v154, v155
	v_cvt_pk_bf16_f32 v6, v156, v157
	v_cvt_pk_bf16_f32 v7, v158, v159
	v_add_u32_e32 v181, 0x3800000, v177
	global_store_dwordx4 v181, v[0:3], s[78:79]
	global_store_dwordx4 v181, v[4:7], s[78:79] offset:1024
	v_add_u32_e32 v236, 0x10000, v237
	s_mov_b64 exec, 1
	global_store_dword v236, v184, s[78:79]
	s_mov_b64 exec, -1

.LBB0_2139:
	v_readlane_b32 s0, v235, 52
	v_readlane_b32 s1, v235, 53
	s_and_b64 vcc, exec, s[0:1]
	s_waitcnt lgkmcnt(0)
	s_barrier
	v_mbcnt_lo_u32_b32 v0, -1, 0
	v_mbcnt_hi_u32_b32 v0, -1, v0
	s_cbranch_vccnz .LBB0_2159
	v_lshlrev_b32_e32 v2, 3, v0
	v_readlane_b32 s4, v235, 4
	v_ashrrev_i32_e32 v3, 31, v2
	v_readlane_b32 s6, v235, 6
	v_readlane_b32 s7, v235, 7
	v_lshlrev_b64 v[4:5], 1, v[2:3]
	v_lshlrev_b64 v[2:3], 2, v[2:3]
	v_readlane_b32 s5, v235, 5
	v_readlane_b32 s10, v235, 10
	v_readlane_b32 s11, v235, 11
	v_readlane_b32 s18, v235, 18
	v_readlane_b32 s19, v235, 19
	v_readlane_b32 s6, v235, 61
	v_lshl_add_u64 v[154:155], s[90:91], 0, v[2:3]
	v_readlane_b32 s8, v235, 8
	v_lshl_add_u64 v[2:3], s[18:19], 0, v[2:3]
	s_mov_b64 s[0:1], 0x2000
	v_readlane_b32 s4, v235, 0
	v_readlane_b32 s7, v235, 62
	s_mov_b32 s10, s6
	s_ashr_i32 s11, s6, 31
	v_readlane_b32 s9, v235, 9
	v_lshl_add_u64 v[158:159], v[2:3], 0, s[0:1]
	s_lshl_b32 s4, s4, 4
	s_add_i32 s0, s6, 0xffffc000
	s_lshl_b64 s[6:7], s[10:11], 2
	s_mov_b32 s8, s10
	v_readlane_b32 s12, v235, 12
	v_readlane_b32 s13, v235, 13
	v_readlane_b32 s14, v235, 14
	v_readlane_b32 s15, v235, 15
	v_readlane_b32 s16, v235, 16
	v_readlane_b32 s17, v235, 17
	v_readlane_b32 s5, v235, 1
	s_add_u32 s80, s6, 0x10000
	v_writelane_b32 v235, s8, 61
	s_addc_u32 s12, s7, 0
	s_ashr_i32 s5, s4, 31
	v_writelane_b32 v235, s9, 62
	s_lshl_b64 s[8:9], s[10:11], 11
	v_lshl_add_u64 v[152:153], s[86:87], 0, v[4:5]
	v_lshl_add_u64 v[156:157], s[54:55], 0, v[4:5]
	s_mov_b32 s1, 0
	v_cmp_eq_u32_e64 s[16:17], 0, v0
	s_lshl_b64 s[6:7], s[4:5], 2
	v_lshl_add_u64 v[160:161], s[8:9], 0, v[4:5]
	s_lshl_b64 s[8:9], s[4:5], 11
	s_mov_b64 s[20:21], 0x600000
	s_mov_b64 s[22:23], 0x600800
	s_mov_b64 s[24:25], 0x800000
	s_mov_b32 s5, 0x800000
	s_mov_b64 s[26:27], 0x800800
	s_mov_b64 s[28:29], 0xa00000
	s_mov_b64 s[36:37], 0xa00800
	s_mov_b64 s[38:39], 0xc00000
	s_mov_b64 s[40:41], 0xc00800
	s_mov_b64 s[42:43], 0xe00000
	s_mov_b64 s[44:45], 0xe00800
	s_mov_b64 s[46:47], 0x1000000
	s_mov_b32 s13, 0x1000000
	s_mov_b64 s[48:49], 0x1000800
	s_mov_b64 s[50:51], 0x1200000
	s_mov_b32 s14, 0x1200000
	s_mov_b64 s[10:11], 0x1200800
	s_mov_b64 s[82:83], 0x1400000
	s_mov_b32 s15, 0x1400000
	s_mov_b64 s[90:91], 0x1400800
	v_mov_b32_e32 v215, 0
	v_mov_b32_e32 v216, 0x358637bd
	v_mbcnt_lo_u32_b32 v176, -1, 0
	v_mbcnt_hi_u32_b32 v176, -1, v176
	v_readlane_b32 s98, v235, 49
	v_readlane_b32 s99, v235, 20
	v_readlane_b32 s100, v235, 18
	v_readlane_b32 s101, v235, 19
	s_nop 3
	s_lshr_b32 vcc_lo, s98, 3
	s_and_b32 vcc_hi, vcc_lo, 7
	s_lshr_b32 vcc_lo, vcc_lo, 3
	s_lshl_b32 vcc_lo, vcc_lo, 3
	s_add_i32 vcc_lo, vcc_lo, s99
	s_lshl_b32 s98, vcc_hi, 8
	s_add_i32 s98, s98, vcc_lo
	s_mov_b32 s99, s98
	v_mov_b32_e32 v183, s99
	v_lshlrev_b32_e32 v177, 4, v176
	s_lshl_b32 s99, s99, 11
	v_add_u32_e32 v177, s99, v177
	v_add_u32_e32 v178, 0x1800000, v177
	v_add_u32_e32 v179, 0x9e00000, v177
	v_lshlrev_b32_e32 v180, 5, v176
	v_add_u32_e32 v181, 0x2000, v180
	global_load_dwordx4 v[128:131], v181, s[100:101]
	global_load_dwordx4 v[132:135], v181, s[100:101] offset:16
	global_load_dwordx4 v[136:139], v181, s[100:101] offset:2048
	global_load_dwordx4 v[140:143], v181, s[100:101] offset:2064
	v_mov_b32_e32 v182, 0x358637bd
	global_load_dwordx4 v[0:3], v178, s[78:79]
	global_load_dwordx4 v[4:7], v178, s[78:79] offset:1024
	global_load_dwordx4 v[8:11], v179, s[78:79]
	global_load_dwordx4 v[12:15], v179, s[78:79] offset:1024
	v_add_u32_e32 v178, 0x400000, v178
	v_add_u32_e32 v179, 0x400000, v179
	global_load_dwordx4 v[16:19], v178, s[78:79]
	global_load_dwordx4 v[20:23], v178, s[78:79] offset:1024
	global_load_dwordx4 v[24:27], v179, s[78:79]
	global_load_dwordx4 v[28:31], v179, s[78:79] offset:1024
	v_add_u32_e32 v178, 0x400000, v178
	v_add_u32_e32 v179, 0x400000, v179
	global_load_dwordx4 v[32:35], v178, s[78:79]
	global_load_dwordx4 v[36:39], v178, s[78:79] offset:1024
	global_load_dwordx4 v[40:43], v179, s[78:79]
	global_load_dwordx4 v[44:47], v179, s[78:79] offset:1024
	v_add_u32_e32 v178, 0x400000, v178
	v_add_u32_e32 v179, 0x400000, v179
	global_load_dwordx4 v[48:51], v178, s[78:79]
	global_load_dwordx4 v[52:55], v178, s[78:79] offset:1024
	global_load_dwordx4 v[56:59], v179, s[78:79]
	global_load_dwordx4 v[60:63], v179, s[78:79] offset:1024
	v_add_u32_e32 v178, 0x400000, v178
	v_add_u32_e32 v179, 0x400000, v179
	global_load_dwordx4 v[64:67], v178, s[78:79]
	global_load_dwordx4 v[68:71], v178, s[78:79] offset:1024
	global_load_dwordx4 v[72:75], v179, s[78:79]
	global_load_dwordx4 v[76:79], v179, s[78:79] offset:1024
	v_add_u32_e32 v178, 0x400000, v178
	v_add_u32_e32 v179, 0x400000, v179
	global_load_dwordx4 v[80:83], v178, s[78:79]
	global_load_dwordx4 v[84:87], v178, s[78:79] offset:1024
	global_load_dwordx4 v[88:91], v179, s[78:79]
	global_load_dwordx4 v[92:95], v179, s[78:79] offset:1024
	v_add_u32_e32 v178, 0x400000, v178
	v_add_u32_e32 v179, 0x400000, v179
	global_load_dwordx4 v[96:99], v178, s[78:79]
	global_load_dwordx4 v[100:103], v178, s[78:79] offset:1024
	global_load_dwordx4 v[104:107], v179, s[78:79]
	global_load_dwordx4 v[108:111], v179, s[78:79] offset:1024
	v_add_u32_e32 v178, 0x400000, v178
	v_add_u32_e32 v179, 0x400000, v179
	global_load_dwordx4 v[112:115], v178, s[78:79]
	global_load_dwordx4 v[116:119], v178, s[78:79] offset:1024
	global_load_dwordx4 v[120:123], v179, s[78:79]
	global_load_dwordx4 v[124:127], v179, s[78:79] offset:1024
	v_lshlrev_b32_e32 v237, 2, v183
	v_add_u32_e32 v237, 0x10000, v237
	v_mov_b32_e32 v179, s98
	s_waitcnt vmcnt(28)
	v_lshlrev_b32_e32 v144, 16, v0
	v_and_b32_e32 v145, 0xffff0000, v0
	v_lshlrev_b32_e32 v146, 16, v1
	v_and_b32_e32 v147, 0xffff0000, v1
	v_lshlrev_b32_e32 v148, 16, v2
	v_and_b32_e32 v149, 0xffff0000, v2
	v_lshlrev_b32_e32 v150, 16, v3
	v_and_b32_e32 v151, 0xffff0000, v3
	v_lshlrev_b32_e32 v152, 16, v4
	v_and_b32_e32 v153, 0xffff0000, v4
	v_lshlrev_b32_e32 v154, 16, v5
	v_and_b32_e32 v155, 0xffff0000, v5
	v_lshlrev_b32_e32 v156, 16, v6
	v_and_b32_e32 v157, 0xffff0000, v6
	v_lshlrev_b32_e32 v158, 16, v7
	v_and_b32_e32 v159, 0xffff0000, v7
	v_lshlrev_b32_e32 v160, 16, v8
	v_and_b32_e32 v161, 0xffff0000, v8
	v_lshlrev_b32_e32 v162, 16, v9
	v_and_b32_e32 v163, 0xffff0000, v9
	v_lshlrev_b32_e32 v164, 16, v10
	v_and_b32_e32 v165, 0xffff0000, v10
	v_lshlrev_b32_e32 v166, 16, v11
	v_and_b32_e32 v167, 0xffff0000, v11
	v_lshlrev_b32_e32 v168, 16, v12
	v_and_b32_e32 v169, 0xffff0000, v12
	v_lshlrev_b32_e32 v170, 16, v13
	v_and_b32_e32 v171, 0xffff0000, v13
	v_lshlrev_b32_e32 v172, 16, v14
	v_and_b32_e32 v173, 0xffff0000, v14
	v_lshlrev_b32_e32 v174, 16, v15
	v_and_b32_e32 v175, 0xffff0000, v15
	v_pk_mul_f32 v[252:253], v[160:161], v[160:161]
	v_pk_mul_f32 v[254:255], v[162:163], v[162:163]
	v_pk_fma_f32 v[252:253], v[164:165], v[164:165], v[252:253]
	v_pk_fma_f32 v[254:255], v[166:167], v[166:167], v[254:255]
	v_pk_fma_f32 v[252:253], v[168:169], v[168:169], v[252:253]
	v_pk_fma_f32 v[254:255], v[170:171], v[170:171], v[254:255]
	v_pk_fma_f32 v[252:253], v[172:173], v[172:173], v[252:253]
	v_pk_fma_f32 v[254:255], v[174:175], v[174:175], v[254:255]
	v_pk_add_f32 v[252:253], v[252:253], v[254:255]
	s_nop 0
	v_add_f32_e32 v183, v252, v253
	s_nop 1
	v_add_f32_dpp v183, v183, v183 quad_perm:[1,0,3,2] row_mask:0xf bank_mask:0xf bound_ctrl:1
	s_nop 1
	v_add_f32_dpp v183, v183, v183 quad_perm:[2,3,0,1] row_mask:0xf bank_mask:0xf bound_ctrl:1
	s_nop 1
	v_add_f32_dpp v183, v183, v183 row_half_mirror row_mask:0xf bank_mask:0xf bound_ctrl:1
	s_nop 1
	v_add_f32_dpp v183, v183, v183 row_mirror row_mask:0xf bank_mask:0xf bound_ctrl:1
	s_nop 1
	v_readlane_b32 s98, v183, 0
	v_readlane_b32 s99, v183, 16
	v_readlane_b32 s100, v183, 32
	v_readlane_b32 s101, v183, 48
	s_nop 1
	v_mov_b32_e32 v183, s98
	v_add_f32_e32 v183, s99, v183
	v_add_f32_e32 v183, s100, v183
	v_add_f32_e32 v183, s101, v183
	v_fmamk_f32 v183, v183, 0x3a800000, v182
	v_cmp_gt_f32_e32 vcc, 0x800000, v183
	v_mul_f32_e32 v181, 0x4b800000, v183
	s_nop 1
	v_cndmask_b32_e32 v183, v183, v181, vcc
	v_rsq_f32_e32 v183, v183
	s_nop 0
	v_mul_f32_e32 v181, 0x45800000, v183
	v_cndmask_b32_e32 v184, v183, v181, vcc
	v_mov_b32_e32 v185, v184
	v_pk_mul_f32 v[160:161], v[160:161], v[184:185]
	v_pk_mul_f32 v[162:163], v[162:163], v[184:185]
	v_pk_mul_f32 v[164:165], v[164:165], v[184:185]
	v_pk_mul_f32 v[166:167], v[166:167], v[184:185]
	v_pk_mul_f32 v[168:169], v[168:169], v[184:185]
	v_pk_mul_f32 v[170:171], v[170:171], v[184:185]
	v_pk_mul_f32 v[172:173], v[172:173], v[184:185]
	v_pk_mul_f32 v[174:175], v[174:175], v[184:185]
	v_pk_fma_f32 v[144:145], v[160:161], v[128:129], v[144:145]
	v_pk_fma_f32 v[146:147], v[162:163], v[130:131], v[146:147]
	v_pk_fma_f32 v[148:149], v[164:165], v[132:133], v[148:149]
	v_pk_fma_f32 v[150:151], v[166:167], v[134:135], v[150:151]
	v_pk_fma_f32 v[152:153], v[168:169], v[136:137], v[152:153]
	v_pk_fma_f32 v[154:155], v[170:171], v[138:139], v[154:155]
	v_pk_fma_f32 v[156:157], v[172:173], v[140:141], v[156:157]
	v_pk_fma_f32 v[158:159], v[174:175], v[142:143], v[158:159]
	v_pk_mul_f32 v[252:253], v[144:145], v[144:145]
	v_pk_mul_f32 v[254:255], v[146:147], v[146:147]
	v_pk_fma_f32 v[252:253], v[148:149], v[148:149], v[252:253]
	v_pk_fma_f32 v[254:255], v[150:151], v[150:151], v[254:255]
	v_pk_fma_f32 v[252:253], v[152:153], v[152:153], v[252:253]
	v_pk_fma_f32 v[254:255], v[154:155], v[154:155], v[254:255]
	v_pk_fma_f32 v[252:253], v[156:157], v[156:157], v[252:253]
	v_pk_fma_f32 v[254:255], v[158:159], v[158:159], v[254:255]
	v_pk_add_f32 v[252:253], v[252:253], v[254:255]
	s_nop 0
	v_add_f32_e32 v183, v252, v253
	s_nop 1
	v_add_f32_dpp v183, v183, v183 quad_perm:[1,0,3,2] row_mask:0xf bank_mask:0xf bound_ctrl:1
	s_nop 1
	v_add_f32_dpp v183, v183, v183 quad_perm:[2,3,0,1] row_mask:0xf bank_mask:0xf bound_ctrl:1
	s_nop 1
	v_add_f32_dpp v183, v183, v183 row_half_mirror row_mask:0xf bank_mask:0xf bound_ctrl:1
	s_nop 1
	v_add_f32_dpp v183, v183, v183 row_mirror row_mask:0xf bank_mask:0xf bound_ctrl:1
	s_nop 1
	v_readlane_b32 s98, v183, 0
	v_readlane_b32 s99, v183, 16
	v_readlane_b32 s100, v183, 32
	v_readlane_b32 s101, v183, 48
	s_nop 1
	v_mov_b32_e32 v183, s98
	v_add_f32_e32 v183, s99, v183
	v_add_f32_e32 v183, s100, v183
	v_add_f32_e32 v183, s101, v183
	v_fmamk_f32 v183, v183, 0x3a800000, v182
	v_cmp_gt_f32_e32 vcc, 0x800000, v183
	v_mul_f32_e32 v181, 0x4b800000, v183
	s_nop 1
	v_cndmask_b32_e32 v183, v183, v181, vcc
	v_rsq_f32_e32 v183, v183
	s_nop 0
	v_mul_f32_e32 v181, 0x45800000, v183
	v_cndmask_b32_e32 v184, v183, v181, vcc
	v_mov_b32_e32 v185, v184
	v_cvt_pk_bf16_f32 v0, v144, v145
	v_cvt_pk_bf16_f32 v1, v146, v147
	v_cvt_pk_bf16_f32 v2, v148, v149
	v_cvt_pk_bf16_f32 v3, v150, v151
	v_cvt_pk_bf16_f32 v4, v152, v153
	v_cvt_pk_bf16_f32 v5, v154, v155
	v_cvt_pk_bf16_f32 v6, v156, v157
	v_cvt_pk_bf16_f32 v7, v158, v159
	v_add_u32_e32 v181, 0x1800000, v177
	global_store_dwordx4 v181, v[0:3], s[78:79]
	global_store_dwordx4 v181, v[4:7], s[78:79] offset:1024
	v_add_u32_e32 v236, 0x0, v237
	s_mov_b64 exec, 1
	global_store_dword v236, v184, s[78:79]
	s_mov_b64 exec, -1
	s_waitcnt vmcnt(24)
	v_lshlrev_b32_e32 v144, 16, v16
	v_and_b32_e32 v145, 0xffff0000, v16
	v_lshlrev_b32_e32 v146, 16, v17
	v_and_b32_e32 v147, 0xffff0000, v17
	v_lshlrev_b32_e32 v148, 16, v18
	v_and_b32_e32 v149, 0xffff0000, v18
	v_lshlrev_b32_e32 v150, 16, v19
	v_and_b32_e32 v151, 0xffff0000, v19
	v_lshlrev_b32_e32 v152, 16, v20
	v_and_b32_e32 v153, 0xffff0000, v20
	v_lshlrev_b32_e32 v154, 16, v21
	v_and_b32_e32 v155, 0xffff0000, v21
	v_lshlrev_b32_e32 v156, 16, v22
	v_and_b32_e32 v157, 0xffff0000, v22
	v_lshlrev_b32_e32 v158, 16, v23
	v_and_b32_e32 v159, 0xffff0000, v23
	v_lshlrev_b32_e32 v160, 16, v24
	v_and_b32_e32 v161, 0xffff0000, v24
	v_lshlrev_b32_e32 v162, 16, v25
	v_and_b32_e32 v163, 0xffff0000, v25
	v_lshlrev_b32_e32 v164, 16, v26
	v_and_b32_e32 v165, 0xffff0000, v26
	v_lshlrev_b32_e32 v166, 16, v27
	v_and_b32_e32 v167, 0xffff0000, v27
	v_lshlrev_b32_e32 v168, 16, v28
	v_and_b32_e32 v169, 0xffff0000, v28
	v_lshlrev_b32_e32 v170, 16, v29
	v_and_b32_e32 v171, 0xffff0000, v29
	v_lshlrev_b32_e32 v172, 16, v30
	v_and_b32_e32 v173, 0xffff0000, v30
	v_lshlrev_b32_e32 v174, 16, v31
	v_and_b32_e32 v175, 0xffff0000, v31
	v_pk_mul_f32 v[252:253], v[160:161], v[160:161]
	v_pk_mul_f32 v[254:255], v[162:163], v[162:163]
	v_pk_fma_f32 v[252:253], v[164:165], v[164:165], v[252:253]
	v_pk_fma_f32 v[254:255], v[166:167], v[166:167], v[254:255]
	v_pk_fma_f32 v[252:253], v[168:169], v[168:169], v[252:253]
	v_pk_fma_f32 v[254:255], v[170:171], v[170:171], v[254:255]
	v_pk_fma_f32 v[252:253], v[172:173], v[172:173], v[252:253]
	v_pk_fma_f32 v[254:255], v[174:175], v[174:175], v[254:255]
	v_pk_add_f32 v[252:253], v[252:253], v[254:255]
	s_nop 0
	v_add_f32_e32 v183, v252, v253
	s_nop 1
	v_add_f32_dpp v183, v183, v183 quad_perm:[1,0,3,2] row_mask:0xf bank_mask:0xf bound_ctrl:1
	s_nop 1
	v_add_f32_dpp v183, v183, v183 quad_perm:[2,3,0,1] row_mask:0xf bank_mask:0xf bound_ctrl:1
	s_nop 1
	v_add_f32_dpp v183, v183, v183 row_half_mirror row_mask:0xf bank_mask:0xf bound_ctrl:1
	s_nop 1
	v_add_f32_dpp v183, v183, v183 row_mirror row_mask:0xf bank_mask:0xf bound_ctrl:1
	s_nop 1
	v_readlane_b32 s98, v183, 0
	v_readlane_b32 s99, v183, 16
	v_readlane_b32 s100, v183, 32
	v_readlane_b32 s101, v183, 48
	s_nop 1
	v_mov_b32_e32 v183, s98
	v_add_f32_e32 v183, s99, v183
	v_add_f32_e32 v183, s100, v183
	v_add_f32_e32 v183, s101, v183
	v_fmamk_f32 v183, v183, 0x3a800000, v182
	v_cmp_gt_f32_e32 vcc, 0x800000, v183
	v_mul_f32_e32 v181, 0x4b800000, v183
	s_nop 1
	v_cndmask_b32_e32 v183, v183, v181, vcc
	v_rsq_f32_e32 v183, v183
	s_nop 0
	v_mul_f32_e32 v181, 0x45800000, v183
	v_cndmask_b32_e32 v184, v183, v181, vcc
	v_mov_b32_e32 v185, v184
	v_pk_mul_f32 v[160:161], v[160:161], v[184:185]
	v_pk_mul_f32 v[162:163], v[162:163], v[184:185]
	v_pk_mul_f32 v[164:165], v[164:165], v[184:185]
	v_pk_mul_f32 v[166:167], v[166:167], v[184:185]
	v_pk_mul_f32 v[168:169], v[168:169], v[184:185]
	v_pk_mul_f32 v[170:171], v[170:171], v[184:185]
	v_pk_mul_f32 v[172:173], v[172:173], v[184:185]
	v_pk_mul_f32 v[174:175], v[174:175], v[184:185]
	v_pk_fma_f32 v[144:145], v[160:161], v[128:129], v[144:145]
	v_pk_fma_f32 v[146:147], v[162:163], v[130:131], v[146:147]
	v_pk_fma_f32 v[148:149], v[164:165], v[132:133], v[148:149]
	v_pk_fma_f32 v[150:151], v[166:167], v[134:135], v[150:151]
	v_pk_fma_f32 v[152:153], v[168:169], v[136:137], v[152:153]
	v_pk_fma_f32 v[154:155], v[170:171], v[138:139], v[154:155]
	v_pk_fma_f32 v[156:157], v[172:173], v[140:141], v[156:157]
	v_pk_fma_f32 v[158:159], v[174:175], v[142:143], v[158:159]
	v_pk_mul_f32 v[252:253], v[144:145], v[144:145]
	v_pk_mul_f32 v[254:255], v[146:147], v[146:147]
	v_pk_fma_f32 v[252:253], v[148:149], v[148:149], v[252:253]
	v_pk_fma_f32 v[254:255], v[150:151], v[150:151], v[254:255]
	v_pk_fma_f32 v[252:253], v[152:153], v[152:153], v[252:253]
	v_pk_fma_f32 v[254:255], v[154:155], v[154:155], v[254:255]
	v_pk_fma_f32 v[252:253], v[156:157], v[156:157], v[252:253]
	v_pk_fma_f32 v[254:255], v[158:159], v[158:159], v[254:255]
	v_pk_add_f32 v[252:253], v[252:253], v[254:255]
	s_nop 0
	v_add_f32_e32 v183, v252, v253
	s_nop 1
	v_add_f32_dpp v183, v183, v183 quad_perm:[1,0,3,2] row_mask:0xf bank_mask:0xf bound_ctrl:1
	s_nop 1
	v_add_f32_dpp v183, v183, v183 quad_perm:[2,3,0,1] row_mask:0xf bank_mask:0xf bound_ctrl:1
	s_nop 1
	v_add_f32_dpp v183, v183, v183 row_half_mirror row_mask:0xf bank_mask:0xf bound_ctrl:1
	s_nop 1
	v_add_f32_dpp v183, v183, v183 row_mirror row_mask:0xf bank_mask:0xf bound_ctrl:1
	s_nop 1
	v_readlane_b32 s98, v183, 0
	v_readlane_b32 s99, v183, 16
	v_readlane_b32 s100, v183, 32
	v_readlane_b32 s101, v183, 48
	s_nop 1
	v_mov_b32_e32 v183, s98
	v_add_f32_e32 v183, s99, v183
	v_add_f32_e32 v183, s100, v183
	v_add_f32_e32 v183, s101, v183
	v_fmamk_f32 v183, v183, 0x3a800000, v182
	v_cmp_gt_f32_e32 vcc, 0x800000, v183
	v_mul_f32_e32 v181, 0x4b800000, v183
	s_nop 1
	v_cndmask_b32_e32 v183, v183, v181, vcc
	v_rsq_f32_e32 v183, v183
	s_nop 0
	v_mul_f32_e32 v181, 0x45800000, v183
	v_cndmask_b32_e32 v184, v183, v181, vcc
	v_mov_b32_e32 v185, v184
	v_cvt_pk_bf16_f32 v16, v144, v145
	v_cvt_pk_bf16_f32 v17, v146, v147
	v_cvt_pk_bf16_f32 v18, v148, v149
	v_cvt_pk_bf16_f32 v19, v150, v151
	v_cvt_pk_bf16_f32 v20, v152, v153
	v_cvt_pk_bf16_f32 v21, v154, v155
	v_cvt_pk_bf16_f32 v22, v156, v157
	v_cvt_pk_bf16_f32 v23, v158, v159
	v_add_u32_e32 v181, 0x1c00000, v177
	global_store_dwordx4 v181, v[16:19], s[78:79]
	global_store_dwordx4 v181, v[20:23], s[78:79] offset:1024
	v_add_u32_e32 v236, 0x2000, v237
	s_mov_b64 exec, 1
	global_store_dword v236, v184, s[78:79]
	s_mov_b64 exec, -1
	s_waitcnt vmcnt(20)
	v_lshlrev_b32_e32 v144, 16, v32
	v_and_b32_e32 v145, 0xffff0000, v32
	v_lshlrev_b32_e32 v146, 16, v33
	v_and_b32_e32 v147, 0xffff0000, v33
	v_lshlrev_b32_e32 v148, 16, v34
	v_and_b32_e32 v149, 0xffff0000, v34
	v_lshlrev_b32_e32 v150, 16, v35
	v_and_b32_e32 v151, 0xffff0000, v35
	v_lshlrev_b32_e32 v152, 16, v36
	v_and_b32_e32 v153, 0xffff0000, v36
	v_lshlrev_b32_e32 v154, 16, v37
	v_and_b32_e32 v155, 0xffff0000, v37
	v_lshlrev_b32_e32 v156, 16, v38
	v_and_b32_e32 v157, 0xffff0000, v38
	v_lshlrev_b32_e32 v158, 16, v39
	v_and_b32_e32 v159, 0xffff0000, v39
	v_lshlrev_b32_e32 v160, 16, v40
	v_and_b32_e32 v161, 0xffff0000, v40
	v_lshlrev_b32_e32 v162, 16, v41
	v_and_b32_e32 v163, 0xffff0000, v41
	v_lshlrev_b32_e32 v164, 16, v42
	v_and_b32_e32 v165, 0xffff0000, v42
	v_lshlrev_b32_e32 v166, 16, v43
	v_and_b32_e32 v167, 0xffff0000, v43
	v_lshlrev_b32_e32 v168, 16, v44
	v_and_b32_e32 v169, 0xffff0000, v44
	v_lshlrev_b32_e32 v170, 16, v45
	v_and_b32_e32 v171, 0xffff0000, v45
	v_lshlrev_b32_e32 v172, 16, v46
	v_and_b32_e32 v173, 0xffff0000, v46
	v_lshlrev_b32_e32 v174, 16, v47
	v_and_b32_e32 v175, 0xffff0000, v47
	v_pk_mul_f32 v[252:253], v[160:161], v[160:161]
	v_pk_mul_f32 v[254:255], v[162:163], v[162:163]
	v_pk_fma_f32 v[252:253], v[164:165], v[164:165], v[252:253]
	v_pk_fma_f32 v[254:255], v[166:167], v[166:167], v[254:255]
	v_pk_fma_f32 v[252:253], v[168:169], v[168:169], v[252:253]
	v_pk_fma_f32 v[254:255], v[170:171], v[170:171], v[254:255]
	v_pk_fma_f32 v[252:253], v[172:173], v[172:173], v[252:253]
	v_pk_fma_f32 v[254:255], v[174:175], v[174:175], v[254:255]
	v_pk_add_f32 v[252:253], v[252:253], v[254:255]
	s_nop 0
	v_add_f32_e32 v183, v252, v253
	s_nop 1
	v_add_f32_dpp v183, v183, v183 quad_perm:[1,0,3,2] row_mask:0xf bank_mask:0xf bound_ctrl:1
	s_nop 1
	v_add_f32_dpp v183, v183, v183 quad_perm:[2,3,0,1] row_mask:0xf bank_mask:0xf bound_ctrl:1
	s_nop 1
	v_add_f32_dpp v183, v183, v183 row_half_mirror row_mask:0xf bank_mask:0xf bound_ctrl:1
	s_nop 1
	v_add_f32_dpp v183, v183, v183 row_mirror row_mask:0xf bank_mask:0xf bound_ctrl:1
	s_nop 1
	v_readlane_b32 s98, v183, 0
	v_readlane_b32 s99, v183, 16
	v_readlane_b32 s100, v183, 32
	v_readlane_b32 s101, v183, 48
	s_nop 1
	v_mov_b32_e32 v183, s98
	v_add_f32_e32 v183, s99, v183
	v_add_f32_e32 v183, s100, v183
	v_add_f32_e32 v183, s101, v183
	v_fmamk_f32 v183, v183, 0x3a800000, v182
	v_cmp_gt_f32_e32 vcc, 0x800000, v183
	v_mul_f32_e32 v181, 0x4b800000, v183
	s_nop 1
	v_cndmask_b32_e32 v183, v183, v181, vcc
	v_rsq_f32_e32 v183, v183
	s_nop 0
	v_mul_f32_e32 v181, 0x45800000, v183
	v_cndmask_b32_e32 v184, v183, v181, vcc
	v_mov_b32_e32 v185, v184
	v_pk_mul_f32 v[160:161], v[160:161], v[184:185]
	v_pk_mul_f32 v[162:163], v[162:163], v[184:185]
	v_pk_mul_f32 v[164:165], v[164:165], v[184:185]
	v_pk_mul_f32 v[166:167], v[166:167], v[184:185]
	v_pk_mul_f32 v[168:169], v[168:169], v[184:185]
	v_pk_mul_f32 v[170:171], v[170:171], v[184:185]
	v_pk_mul_f32 v[172:173], v[172:173], v[184:185]
	v_pk_mul_f32 v[174:175], v[174:175], v[184:185]
	v_pk_fma_f32 v[144:145], v[160:161], v[128:129], v[144:145]
	v_pk_fma_f32 v[146:147], v[162:163], v[130:131], v[146:147]
	v_pk_fma_f32 v[148:149], v[164:165], v[132:133], v[148:149]
	v_pk_fma_f32 v[150:151], v[166:167], v[134:135], v[150:151]
	v_pk_fma_f32 v[152:153], v[168:169], v[136:137], v[152:153]
	v_pk_fma_f32 v[154:155], v[170:171], v[138:139], v[154:155]
	v_pk_fma_f32 v[156:157], v[172:173], v[140:141], v[156:157]
	v_pk_fma_f32 v[158:159], v[174:175], v[142:143], v[158:159]
	v_pk_mul_f32 v[252:253], v[144:145], v[144:145]
	v_pk_mul_f32 v[254:255], v[146:147], v[146:147]
	v_pk_fma_f32 v[252:253], v[148:149], v[148:149], v[252:253]
	v_pk_fma_f32 v[254:255], v[150:151], v[150:151], v[254:255]
	v_pk_fma_f32 v[252:253], v[152:153], v[152:153], v[252:253]
	v_pk_fma_f32 v[254:255], v[154:155], v[154:155], v[254:255]
	v_pk_fma_f32 v[252:253], v[156:157], v[156:157], v[252:253]
	v_pk_fma_f32 v[254:255], v[158:159], v[158:159], v[254:255]
	v_pk_add_f32 v[252:253], v[252:253], v[254:255]
	s_nop 0
	v_add_f32_e32 v183, v252, v253
	s_nop 1
	v_add_f32_dpp v183, v183, v183 quad_perm:[1,0,3,2] row_mask:0xf bank_mask:0xf bound_ctrl:1
	s_nop 1
	v_add_f32_dpp v183, v183, v183 quad_perm:[2,3,0,1] row_mask:0xf bank_mask:0xf bound_ctrl:1
	s_nop 1
	v_add_f32_dpp v183, v183, v183 row_half_mirror row_mask:0xf bank_mask:0xf bound_ctrl:1
	s_nop 1
	v_add_f32_dpp v183, v183, v183 row_mirror row_mask:0xf bank_mask:0xf bound_ctrl:1
	s_nop 1
	v_readlane_b32 s98, v183, 0
	v_readlane_b32 s99, v183, 16
	v_readlane_b32 s100, v183, 32
	v_readlane_b32 s101, v183, 48
	s_nop 1
	v_mov_b32_e32 v183, s98
	v_add_f32_e32 v183, s99, v183
	v_add_f32_e32 v183, s100, v183
	v_add_f32_e32 v183, s101, v183
	v_fmamk_f32 v183, v183, 0x3a800000, v182
	v_cmp_gt_f32_e32 vcc, 0x800000, v183
	v_mul_f32_e32 v181, 0x4b800000, v183
	s_nop 1
	v_cndmask_b32_e32 v183, v183, v181, vcc
	v_rsq_f32_e32 v183, v183
	s_nop 0
	v_mul_f32_e32 v181, 0x45800000, v183
	v_cndmask_b32_e32 v184, v183, v181, vcc
	v_mov_b32_e32 v185, v184
	v_cvt_pk_bf16_f32 v32, v144, v145
	v_cvt_pk_bf16_f32 v33, v146, v147
	v_cvt_pk_bf16_f32 v34, v148, v149
	v_cvt_pk_bf16_f32 v35, v150, v151
	v_cvt_pk_bf16_f32 v36, v152, v153
	v_cvt_pk_bf16_f32 v37, v154, v155
	v_cvt_pk_bf16_f32 v38, v156, v157
	v_cvt_pk_bf16_f32 v39, v158, v159
	v_add_u32_e32 v181, 0x2000000, v177
	global_store_dwordx4 v181, v[32:35], s[78:79]
	global_store_dwordx4 v181, v[36:39], s[78:79] offset:1024
	v_add_u32_e32 v236, 0x4000, v237
	s_mov_b64 exec, 1
	global_store_dword v236, v184, s[78:79]
	s_mov_b64 exec, -1
	s_waitcnt vmcnt(16)
	v_lshlrev_b32_e32 v144, 16, v48
	v_and_b32_e32 v145, 0xffff0000, v48
	v_lshlrev_b32_e32 v146, 16, v49
	v_and_b32_e32 v147, 0xffff0000, v49
	v_lshlrev_b32_e32 v148, 16, v50
	v_and_b32_e32 v149, 0xffff0000, v50
	v_lshlrev_b32_e32 v150, 16, v51
	v_and_b32_e32 v151, 0xffff0000, v51
	v_lshlrev_b32_e32 v152, 16, v52
	v_and_b32_e32 v153, 0xffff0000, v52
	v_lshlrev_b32_e32 v154, 16, v53
	v_and_b32_e32 v155, 0xffff0000, v53
	v_lshlrev_b32_e32 v156, 16, v54
	v_and_b32_e32 v157, 0xffff0000, v54
	v_lshlrev_b32_e32 v158, 16, v55
	v_and_b32_e32 v159, 0xffff0000, v55
	v_lshlrev_b32_e32 v160, 16, v56
	v_and_b32_e32 v161, 0xffff0000, v56
	v_lshlrev_b32_e32 v162, 16, v57
	v_and_b32_e32 v163, 0xffff0000, v57
	v_lshlrev_b32_e32 v164, 16, v58
	v_and_b32_e32 v165, 0xffff0000, v58
	v_lshlrev_b32_e32 v166, 16, v59
	v_and_b32_e32 v167, 0xffff0000, v59
	v_lshlrev_b32_e32 v168, 16, v60
	v_and_b32_e32 v169, 0xffff0000, v60
	v_lshlrev_b32_e32 v170, 16, v61
	v_and_b32_e32 v171, 0xffff0000, v61
	v_lshlrev_b32_e32 v172, 16, v62
	v_and_b32_e32 v173, 0xffff0000, v62
	v_lshlrev_b32_e32 v174, 16, v63
	v_and_b32_e32 v175, 0xffff0000, v63
	v_pk_mul_f32 v[252:253], v[160:161], v[160:161]
	v_pk_mul_f32 v[254:255], v[162:163], v[162:163]
	v_pk_fma_f32 v[252:253], v[164:165], v[164:165], v[252:253]
	v_pk_fma_f32 v[254:255], v[166:167], v[166:167], v[254:255]
	v_pk_fma_f32 v[252:253], v[168:169], v[168:169], v[252:253]
	v_pk_fma_f32 v[254:255], v[170:171], v[170:171], v[254:255]
	v_pk_fma_f32 v[252:253], v[172:173], v[172:173], v[252:253]
	v_pk_fma_f32 v[254:255], v[174:175], v[174:175], v[254:255]
	v_pk_add_f32 v[252:253], v[252:253], v[254:255]
	s_nop 0
	v_add_f32_e32 v183, v252, v253
	s_nop 1
	v_add_f32_dpp v183, v183, v183 quad_perm:[1,0,3,2] row_mask:0xf bank_mask:0xf bound_ctrl:1
	s_nop 1
	v_add_f32_dpp v183, v183, v183 quad_perm:[2,3,0,1] row_mask:0xf bank_mask:0xf bound_ctrl:1
	s_nop 1
	v_add_f32_dpp v183, v183, v183 row_half_mirror row_mask:0xf bank_mask:0xf bound_ctrl:1
	s_nop 1
	v_add_f32_dpp v183, v183, v183 row_mirror row_mask:0xf bank_mask:0xf bound_ctrl:1
	s_nop 1
	v_readlane_b32 s98, v183, 0
	v_readlane_b32 s99, v183, 16
	v_readlane_b32 s100, v183, 32
	v_readlane_b32 s101, v183, 48
	s_nop 1
	v_mov_b32_e32 v183, s98
	v_add_f32_e32 v183, s99, v183
	v_add_f32_e32 v183, s100, v183
	v_add_f32_e32 v183, s101, v183
	v_fmamk_f32 v183, v183, 0x3a800000, v182
	v_cmp_gt_f32_e32 vcc, 0x800000, v183
	v_mul_f32_e32 v181, 0x4b800000, v183
	s_nop 1
	v_cndmask_b32_e32 v183, v183, v181, vcc
	v_rsq_f32_e32 v183, v183
	s_nop 0
	v_mul_f32_e32 v181, 0x45800000, v183
	v_cndmask_b32_e32 v184, v183, v181, vcc
	v_mov_b32_e32 v185, v184
	v_pk_mul_f32 v[160:161], v[160:161], v[184:185]
	v_pk_mul_f32 v[162:163], v[162:163], v[184:185]
	v_pk_mul_f32 v[164:165], v[164:165], v[184:185]
	v_pk_mul_f32 v[166:167], v[166:167], v[184:185]
	v_pk_mul_f32 v[168:169], v[168:169], v[184:185]
	v_pk_mul_f32 v[170:171], v[170:171], v[184:185]
	v_pk_mul_f32 v[172:173], v[172:173], v[184:185]
	v_pk_mul_f32 v[174:175], v[174:175], v[184:185]
	v_pk_fma_f32 v[144:145], v[160:161], v[128:129], v[144:145]
	v_pk_fma_f32 v[146:147], v[162:163], v[130:131], v[146:147]
	v_pk_fma_f32 v[148:149], v[164:165], v[132:133], v[148:149]
	v_pk_fma_f32 v[150:151], v[166:167], v[134:135], v[150:151]
	v_pk_fma_f32 v[152:153], v[168:169], v[136:137], v[152:153]
	v_pk_fma_f32 v[154:155], v[170:171], v[138:139], v[154:155]
	v_pk_fma_f32 v[156:157], v[172:173], v[140:141], v[156:157]
	v_pk_fma_f32 v[158:159], v[174:175], v[142:143], v[158:159]
	v_pk_mul_f32 v[252:253], v[144:145], v[144:145]
	v_pk_mul_f32 v[254:255], v[146:147], v[146:147]
	v_pk_fma_f32 v[252:253], v[148:149], v[148:149], v[252:253]
	v_pk_fma_f32 v[254:255], v[150:151], v[150:151], v[254:255]
	v_pk_fma_f32 v[252:253], v[152:153], v[152:153], v[252:253]
	v_pk_fma_f32 v[254:255], v[154:155], v[154:155], v[254:255]
	v_pk_fma_f32 v[252:253], v[156:157], v[156:157], v[252:253]
	v_pk_fma_f32 v[254:255], v[158:159], v[158:159], v[254:255]
	v_pk_add_f32 v[252:253], v[252:253], v[254:255]
	s_nop 0
	v_add_f32_e32 v183, v252, v253
	s_nop 1
	v_add_f32_dpp v183, v183, v183 quad_perm:[1,0,3,2] row_mask:0xf bank_mask:0xf bound_ctrl:1
	s_nop 1
	v_add_f32_dpp v183, v183, v183 quad_perm:[2,3,0,1] row_mask:0xf bank_mask:0xf bound_ctrl:1
	s_nop 1
	v_add_f32_dpp v183, v183, v183 row_half_mirror row_mask:0xf bank_mask:0xf bound_ctrl:1
	s_nop 1
	v_add_f32_dpp v183, v183, v183 row_mirror row_mask:0xf bank_mask:0xf bound_ctrl:1
	s_nop 1
	v_readlane_b32 s98, v183, 0
	v_readlane_b32 s99, v183, 16
	v_readlane_b32 s100, v183, 32
	v_readlane_b32 s101, v183, 48
	s_nop 1
	v_mov_b32_e32 v183, s98
	v_add_f32_e32 v183, s99, v183
	v_add_f32_e32 v183, s100, v183
	v_add_f32_e32 v183, s101, v183
	v_fmamk_f32 v183, v183, 0x3a800000, v182
	v_cmp_gt_f32_e32 vcc, 0x800000, v183
	v_mul_f32_e32 v181, 0x4b800000, v183
	s_nop 1
	v_cndmask_b32_e32 v183, v183, v181, vcc
	v_rsq_f32_e32 v183, v183
	s_nop 0
	v_mul_f32_e32 v181, 0x45800000, v183
	v_cndmask_b32_e32 v184, v183, v181, vcc
	v_mov_b32_e32 v185, v184
	v_cvt_pk_bf16_f32 v48, v144, v145
	v_cvt_pk_bf16_f32 v49, v146, v147
	v_cvt_pk_bf16_f32 v50, v148, v149
	v_cvt_pk_bf16_f32 v51, v150, v151
	v_cvt_pk_bf16_f32 v52, v152, v153
	v_cvt_pk_bf16_f32 v53, v154, v155
	v_cvt_pk_bf16_f32 v54, v156, v157
	v_cvt_pk_bf16_f32 v55, v158, v159
	v_add_u32_e32 v181, 0x2400000, v177
	global_store_dwordx4 v181, v[48:51], s[78:79]
	global_store_dwordx4 v181, v[52:55], s[78:79] offset:1024
	v_add_u32_e32 v236, 0x6000, v237
	s_mov_b64 exec, 1
	global_store_dword v236, v184, s[78:79]
	s_mov_b64 exec, -1
	s_waitcnt vmcnt(12)
	v_lshlrev_b32_e32 v144, 16, v64
	v_and_b32_e32 v145, 0xffff0000, v64
	v_lshlrev_b32_e32 v146, 16, v65
	v_and_b32_e32 v147, 0xffff0000, v65
	v_lshlrev_b32_e32 v148, 16, v66
	v_and_b32_e32 v149, 0xffff0000, v66
	v_lshlrev_b32_e32 v150, 16, v67
	v_and_b32_e32 v151, 0xffff0000, v67
	v_lshlrev_b32_e32 v152, 16, v68
	v_and_b32_e32 v153, 0xffff0000, v68
	v_lshlrev_b32_e32 v154, 16, v69
	v_and_b32_e32 v155, 0xffff0000, v69
	v_lshlrev_b32_e32 v156, 16, v70
	v_and_b32_e32 v157, 0xffff0000, v70
	v_lshlrev_b32_e32 v158, 16, v71
	v_and_b32_e32 v159, 0xffff0000, v71
	v_lshlrev_b32_e32 v160, 16, v72
	v_and_b32_e32 v161, 0xffff0000, v72
	v_lshlrev_b32_e32 v162, 16, v73
	v_and_b32_e32 v163, 0xffff0000, v73
	v_lshlrev_b32_e32 v164, 16, v74
	v_and_b32_e32 v165, 0xffff0000, v74
	v_lshlrev_b32_e32 v166, 16, v75
	v_and_b32_e32 v167, 0xffff0000, v75
	v_lshlrev_b32_e32 v168, 16, v76
	v_and_b32_e32 v169, 0xffff0000, v76
	v_lshlrev_b32_e32 v170, 16, v77
	v_and_b32_e32 v171, 0xffff0000, v77
	v_lshlrev_b32_e32 v172, 16, v78
	v_and_b32_e32 v173, 0xffff0000, v78
	v_lshlrev_b32_e32 v174, 16, v79
	v_and_b32_e32 v175, 0xffff0000, v79
	v_pk_mul_f32 v[252:253], v[160:161], v[160:161]
	v_pk_mul_f32 v[254:255], v[162:163], v[162:163]
	v_pk_fma_f32 v[252:253], v[164:165], v[164:165], v[252:253]
	v_pk_fma_f32 v[254:255], v[166:167], v[166:167], v[254:255]
	v_pk_fma_f32 v[252:253], v[168:169], v[168:169], v[252:253]
	v_pk_fma_f32 v[254:255], v[170:171], v[170:171], v[254:255]
	v_pk_fma_f32 v[252:253], v[172:173], v[172:173], v[252:253]
	v_pk_fma_f32 v[254:255], v[174:175], v[174:175], v[254:255]
	v_pk_add_f32 v[252:253], v[252:253], v[254:255]
	s_nop 0
	v_add_f32_e32 v183, v252, v253
	s_nop 1
	v_add_f32_dpp v183, v183, v183 quad_perm:[1,0,3,2] row_mask:0xf bank_mask:0xf bound_ctrl:1
	s_nop 1
	v_add_f32_dpp v183, v183, v183 quad_perm:[2,3,0,1] row_mask:0xf bank_mask:0xf bound_ctrl:1
	s_nop 1
	v_add_f32_dpp v183, v183, v183 row_half_mirror row_mask:0xf bank_mask:0xf bound_ctrl:1
	s_nop 1
	v_add_f32_dpp v183, v183, v183 row_mirror row_mask:0xf bank_mask:0xf bound_ctrl:1
	s_nop 1
	v_readlane_b32 s98, v183, 0
	v_readlane_b32 s99, v183, 16
	v_readlane_b32 s100, v183, 32
	v_readlane_b32 s101, v183, 48
	s_nop 1
	v_mov_b32_e32 v183, s98
	v_add_f32_e32 v183, s99, v183
	v_add_f32_e32 v183, s100, v183
	v_add_f32_e32 v183, s101, v183
	v_fmamk_f32 v183, v183, 0x3a800000, v182
	v_cmp_gt_f32_e32 vcc, 0x800000, v183
	v_mul_f32_e32 v181, 0x4b800000, v183
	s_nop 1
	v_cndmask_b32_e32 v183, v183, v181, vcc
	v_rsq_f32_e32 v183, v183
	s_nop 0
	v_mul_f32_e32 v181, 0x45800000, v183
	v_cndmask_b32_e32 v184, v183, v181, vcc
	v_mov_b32_e32 v185, v184
	v_pk_mul_f32 v[160:161], v[160:161], v[184:185]
	v_pk_mul_f32 v[162:163], v[162:163], v[184:185]
	v_pk_mul_f32 v[164:165], v[164:165], v[184:185]
	v_pk_mul_f32 v[166:167], v[166:167], v[184:185]
	v_pk_mul_f32 v[168:169], v[168:169], v[184:185]
	v_pk_mul_f32 v[170:171], v[170:171], v[184:185]
	v_pk_mul_f32 v[172:173], v[172:173], v[184:185]
	v_pk_mul_f32 v[174:175], v[174:175], v[184:185]
	v_pk_fma_f32 v[144:145], v[160:161], v[128:129], v[144:145]
	v_pk_fma_f32 v[146:147], v[162:163], v[130:131], v[146:147]
	v_pk_fma_f32 v[148:149], v[164:165], v[132:133], v[148:149]
	v_pk_fma_f32 v[150:151], v[166:167], v[134:135], v[150:151]
	v_pk_fma_f32 v[152:153], v[168:169], v[136:137], v[152:153]
	v_pk_fma_f32 v[154:155], v[170:171], v[138:139], v[154:155]
	v_pk_fma_f32 v[156:157], v[172:173], v[140:141], v[156:157]
	v_pk_fma_f32 v[158:159], v[174:175], v[142:143], v[158:159]
	v_pk_mul_f32 v[252:253], v[144:145], v[144:145]
	v_pk_mul_f32 v[254:255], v[146:147], v[146:147]
	v_pk_fma_f32 v[252:253], v[148:149], v[148:149], v[252:253]
	v_pk_fma_f32 v[254:255], v[150:151], v[150:151], v[254:255]
	v_pk_fma_f32 v[252:253], v[152:153], v[152:153], v[252:253]
	v_pk_fma_f32 v[254:255], v[154:155], v[154:155], v[254:255]
	v_pk_fma_f32 v[252:253], v[156:157], v[156:157], v[252:253]
	v_pk_fma_f32 v[254:255], v[158:159], v[158:159], v[254:255]
	v_pk_add_f32 v[252:253], v[252:253], v[254:255]
	s_nop 0
	v_add_f32_e32 v183, v252, v253
	s_nop 1
	v_add_f32_dpp v183, v183, v183 quad_perm:[1,0,3,2] row_mask:0xf bank_mask:0xf bound_ctrl:1
	s_nop 1
	v_add_f32_dpp v183, v183, v183 quad_perm:[2,3,0,1] row_mask:0xf bank_mask:0xf bound_ctrl:1
	s_nop 1
	v_add_f32_dpp v183, v183, v183 row_half_mirror row_mask:0xf bank_mask:0xf bound_ctrl:1
	s_nop 1
	v_add_f32_dpp v183, v183, v183 row_mirror row_mask:0xf bank_mask:0xf bound_ctrl:1
	s_nop 1
	v_readlane_b32 s98, v183, 0
	v_readlane_b32 s99, v183, 16
	v_readlane_b32 s100, v183, 32
	v_readlane_b32 s101, v183, 48
	s_nop 1
	v_mov_b32_e32 v183, s98
	v_add_f32_e32 v183, s99, v183
	v_add_f32_e32 v183, s100, v183
	v_add_f32_e32 v183, s101, v183
	v_fmamk_f32 v183, v183, 0x3a800000, v182
	v_cmp_gt_f32_e32 vcc, 0x800000, v183
	v_mul_f32_e32 v181, 0x4b800000, v183
	s_nop 1
	v_cndmask_b32_e32 v183, v183, v181, vcc
	v_rsq_f32_e32 v183, v183
	s_nop 0
	v_mul_f32_e32 v181, 0x45800000, v183
	v_cndmask_b32_e32 v184, v183, v181, vcc
	v_mov_b32_e32 v185, v184
	v_cvt_pk_bf16_f32 v64, v144, v145
	v_cvt_pk_bf16_f32 v65, v146, v147
	v_cvt_pk_bf16_f32 v66, v148, v149
	v_cvt_pk_bf16_f32 v67, v150, v151
	v_cvt_pk_bf16_f32 v68, v152, v153
	v_cvt_pk_bf16_f32 v69, v154, v155
	v_cvt_pk_bf16_f32 v70, v156, v157
	v_cvt_pk_bf16_f32 v71, v158, v159
	v_add_u32_e32 v181, 0x2800000, v177
	global_store_dwordx4 v181, v[64:67], s[78:79]
	global_store_dwordx4 v181, v[68:71], s[78:79] offset:1024
	v_add_u32_e32 v236, 0x8000, v237
	s_mov_b64 exec, 1
	global_store_dword v236, v184, s[78:79]
	s_mov_b64 exec, -1
	s_waitcnt vmcnt(8)
	v_lshlrev_b32_e32 v144, 16, v80
	v_and_b32_e32 v145, 0xffff0000, v80
	v_lshlrev_b32_e32 v146, 16, v81
	v_and_b32_e32 v147, 0xffff0000, v81
	v_lshlrev_b32_e32 v148, 16, v82
	v_and_b32_e32 v149, 0xffff0000, v82
	v_lshlrev_b32_e32 v150, 16, v83
	v_and_b32_e32 v151, 0xffff0000, v83
	v_lshlrev_b32_e32 v152, 16, v84
	v_and_b32_e32 v153, 0xffff0000, v84
	v_lshlrev_b32_e32 v154, 16, v85
	v_and_b32_e32 v155, 0xffff0000, v85
	v_lshlrev_b32_e32 v156, 16, v86
	v_and_b32_e32 v157, 0xffff0000, v86
	v_lshlrev_b32_e32 v158, 16, v87
	v_and_b32_e32 v159, 0xffff0000, v87
	v_lshlrev_b32_e32 v160, 16, v88
	v_and_b32_e32 v161, 0xffff0000, v88
	v_lshlrev_b32_e32 v162, 16, v89
	v_and_b32_e32 v163, 0xffff0000, v89
	v_lshlrev_b32_e32 v164, 16, v90
	v_and_b32_e32 v165, 0xffff0000, v90
	v_lshlrev_b32_e32 v166, 16, v91
	v_and_b32_e32 v167, 0xffff0000, v91
	v_lshlrev_b32_e32 v168, 16, v92
	v_and_b32_e32 v169, 0xffff0000, v92
	v_lshlrev_b32_e32 v170, 16, v93
	v_and_b32_e32 v171, 0xffff0000, v93
	v_lshlrev_b32_e32 v172, 16, v94
	v_and_b32_e32 v173, 0xffff0000, v94
	v_lshlrev_b32_e32 v174, 16, v95
	v_and_b32_e32 v175, 0xffff0000, v95
	v_pk_mul_f32 v[252:253], v[160:161], v[160:161]
	v_pk_mul_f32 v[254:255], v[162:163], v[162:163]
	v_pk_fma_f32 v[252:253], v[164:165], v[164:165], v[252:253]
	v_pk_fma_f32 v[254:255], v[166:167], v[166:167], v[254:255]
	v_pk_fma_f32 v[252:253], v[168:169], v[168:169], v[252:253]
	v_pk_fma_f32 v[254:255], v[170:171], v[170:171], v[254:255]
	v_pk_fma_f32 v[252:253], v[172:173], v[172:173], v[252:253]
	v_pk_fma_f32 v[254:255], v[174:175], v[174:175], v[254:255]
	v_pk_add_f32 v[252:253], v[252:253], v[254:255]
	s_nop 0
	v_add_f32_e32 v183, v252, v253
	s_nop 1
	v_add_f32_dpp v183, v183, v183 quad_perm:[1,0,3,2] row_mask:0xf bank_mask:0xf bound_ctrl:1
	s_nop 1
	v_add_f32_dpp v183, v183, v183 quad_perm:[2,3,0,1] row_mask:0xf bank_mask:0xf bound_ctrl:1
	s_nop 1
	v_add_f32_dpp v183, v183, v183 row_half_mirror row_mask:0xf bank_mask:0xf bound_ctrl:1
	s_nop 1
	v_add_f32_dpp v183, v183, v183 row_mirror row_mask:0xf bank_mask:0xf bound_ctrl:1
	s_nop 1
	v_readlane_b32 s98, v183, 0
	v_readlane_b32 s99, v183, 16
	v_readlane_b32 s100, v183, 32
	v_readlane_b32 s101, v183, 48
	s_nop 1
	v_mov_b32_e32 v183, s98
	v_add_f32_e32 v183, s99, v183
	v_add_f32_e32 v183, s100, v183
	v_add_f32_e32 v183, s101, v183
	v_fmamk_f32 v183, v183, 0x3a800000, v182
	v_cmp_gt_f32_e32 vcc, 0x800000, v183
	v_mul_f32_e32 v181, 0x4b800000, v183
	s_nop 1
	v_cndmask_b32_e32 v183, v183, v181, vcc
	v_rsq_f32_e32 v183, v183
	s_nop 0
	v_mul_f32_e32 v181, 0x45800000, v183
	v_cndmask_b32_e32 v184, v183, v181, vcc
	v_mov_b32_e32 v185, v184
	v_pk_mul_f32 v[160:161], v[160:161], v[184:185]
	v_pk_mul_f32 v[162:163], v[162:163], v[184:185]
	v_pk_mul_f32 v[164:165], v[164:165], v[184:185]
	v_pk_mul_f32 v[166:167], v[166:167], v[184:185]
	v_pk_mul_f32 v[168:169], v[168:169], v[184:185]
	v_pk_mul_f32 v[170:171], v[170:171], v[184:185]
	v_pk_mul_f32 v[172:173], v[172:173], v[184:185]
	v_pk_mul_f32 v[174:175], v[174:175], v[184:185]
	v_pk_fma_f32 v[144:145], v[160:161], v[128:129], v[144:145]
	v_pk_fma_f32 v[146:147], v[162:163], v[130:131], v[146:147]
	v_pk_fma_f32 v[148:149], v[164:165], v[132:133], v[148:149]
	v_pk_fma_f32 v[150:151], v[166:167], v[134:135], v[150:151]
	v_pk_fma_f32 v[152:153], v[168:169], v[136:137], v[152:153]
	v_pk_fma_f32 v[154:155], v[170:171], v[138:139], v[154:155]
	v_pk_fma_f32 v[156:157], v[172:173], v[140:141], v[156:157]
	v_pk_fma_f32 v[158:159], v[174:175], v[142:143], v[158:159]
	v_pk_mul_f32 v[252:253], v[144:145], v[144:145]
	v_pk_mul_f32 v[254:255], v[146:147], v[146:147]
	v_pk_fma_f32 v[252:253], v[148:149], v[148:149], v[252:253]
	v_pk_fma_f32 v[254:255], v[150:151], v[150:151], v[254:255]
	v_pk_fma_f32 v[252:253], v[152:153], v[152:153], v[252:253]
	v_pk_fma_f32 v[254:255], v[154:155], v[154:155], v[254:255]
	v_pk_fma_f32 v[252:253], v[156:157], v[156:157], v[252:253]
	v_pk_fma_f32 v[254:255], v[158:159], v[158:159], v[254:255]
	v_pk_add_f32 v[252:253], v[252:253], v[254:255]
	s_nop 0
	v_add_f32_e32 v183, v252, v253
	s_nop 1
	v_add_f32_dpp v183, v183, v183 quad_perm:[1,0,3,2] row_mask:0xf bank_mask:0xf bound_ctrl:1
	s_nop 1
	v_add_f32_dpp v183, v183, v183 quad_perm:[2,3,0,1] row_mask:0xf bank_mask:0xf bound_ctrl:1
	s_nop 1
	v_add_f32_dpp v183, v183, v183 row_half_mirror row_mask:0xf bank_mask:0xf bound_ctrl:1
	s_nop 1
	v_add_f32_dpp v183, v183, v183 row_mirror row_mask:0xf bank_mask:0xf bound_ctrl:1
	s_nop 1
	v_readlane_b32 s98, v183, 0
	v_readlane_b32 s99, v183, 16
	v_readlane_b32 s100, v183, 32
	v_readlane_b32 s101, v183, 48
	s_nop 1
	v_mov_b32_e32 v183, s98
	v_add_f32_e32 v183, s99, v183
	v_add_f32_e32 v183, s100, v183
	v_add_f32_e32 v183, s101, v183
	v_fmamk_f32 v183, v183, 0x3a800000, v182
	v_cmp_gt_f32_e32 vcc, 0x800000, v183
	v_mul_f32_e32 v181, 0x4b800000, v183
	s_nop 1
	v_cndmask_b32_e32 v183, v183, v181, vcc
	v_rsq_f32_e32 v183, v183
	s_nop 0
	v_mul_f32_e32 v181, 0x45800000, v183
	v_cndmask_b32_e32 v184, v183, v181, vcc
	v_mov_b32_e32 v185, v184
	v_cvt_pk_bf16_f32 v80, v144, v145
	v_cvt_pk_bf16_f32 v81, v146, v147
	v_cvt_pk_bf16_f32 v82, v148, v149
	v_cvt_pk_bf16_f32 v83, v150, v151
	v_cvt_pk_bf16_f32 v84, v152, v153
	v_cvt_pk_bf16_f32 v85, v154, v155
	v_cvt_pk_bf16_f32 v86, v156, v157
	v_cvt_pk_bf16_f32 v87, v158, v159
	v_add_u32_e32 v181, 0x2c00000, v177
	global_store_dwordx4 v181, v[80:83], s[78:79]
	global_store_dwordx4 v181, v[84:87], s[78:79] offset:1024
	v_add_u32_e32 v236, 0xa000, v237
	s_mov_b64 exec, 1
	global_store_dword v236, v184, s[78:79]
	s_mov_b64 exec, -1
	s_waitcnt vmcnt(4)
	v_lshlrev_b32_e32 v144, 16, v96
	v_and_b32_e32 v145, 0xffff0000, v96
	v_lshlrev_b32_e32 v146, 16, v97
	v_and_b32_e32 v147, 0xffff0000, v97
	v_lshlrev_b32_e32 v148, 16, v98
	v_and_b32_e32 v149, 0xffff0000, v98
	v_lshlrev_b32_e32 v150, 16, v99
	v_and_b32_e32 v151, 0xffff0000, v99
	v_lshlrev_b32_e32 v152, 16, v100
	v_and_b32_e32 v153, 0xffff0000, v100
	v_lshlrev_b32_e32 v154, 16, v101
	v_and_b32_e32 v155, 0xffff0000, v101
	v_lshlrev_b32_e32 v156, 16, v102
	v_and_b32_e32 v157, 0xffff0000, v102
	v_lshlrev_b32_e32 v158, 16, v103
	v_and_b32_e32 v159, 0xffff0000, v103
	v_lshlrev_b32_e32 v160, 16, v104
	v_and_b32_e32 v161, 0xffff0000, v104
	v_lshlrev_b32_e32 v162, 16, v105
	v_and_b32_e32 v163, 0xffff0000, v105
	v_lshlrev_b32_e32 v164, 16, v106
	v_and_b32_e32 v165, 0xffff0000, v106
	v_lshlrev_b32_e32 v166, 16, v107
	v_and_b32_e32 v167, 0xffff0000, v107
	v_lshlrev_b32_e32 v168, 16, v108
	v_and_b32_e32 v169, 0xffff0000, v108
	v_lshlrev_b32_e32 v170, 16, v109
	v_and_b32_e32 v171, 0xffff0000, v109
	v_lshlrev_b32_e32 v172, 16, v110
	v_and_b32_e32 v173, 0xffff0000, v110
	v_lshlrev_b32_e32 v174, 16, v111
	v_and_b32_e32 v175, 0xffff0000, v111
	v_pk_mul_f32 v[252:253], v[160:161], v[160:161]
	v_pk_mul_f32 v[254:255], v[162:163], v[162:163]
	v_pk_fma_f32 v[252:253], v[164:165], v[164:165], v[252:253]
	v_pk_fma_f32 v[254:255], v[166:167], v[166:167], v[254:255]
	v_pk_fma_f32 v[252:253], v[168:169], v[168:169], v[252:253]
	v_pk_fma_f32 v[254:255], v[170:171], v[170:171], v[254:255]
	v_pk_fma_f32 v[252:253], v[172:173], v[172:173], v[252:253]
	v_pk_fma_f32 v[254:255], v[174:175], v[174:175], v[254:255]
	v_pk_add_f32 v[252:253], v[252:253], v[254:255]
	s_nop 0
	v_add_f32_e32 v183, v252, v253
	s_nop 1
	v_add_f32_dpp v183, v183, v183 quad_perm:[1,0,3,2] row_mask:0xf bank_mask:0xf bound_ctrl:1
	s_nop 1
	v_add_f32_dpp v183, v183, v183 quad_perm:[2,3,0,1] row_mask:0xf bank_mask:0xf bound_ctrl:1
	s_nop 1
	v_add_f32_dpp v183, v183, v183 row_half_mirror row_mask:0xf bank_mask:0xf bound_ctrl:1
	s_nop 1
	v_add_f32_dpp v183, v183, v183 row_mirror row_mask:0xf bank_mask:0xf bound_ctrl:1
	s_nop 1
	v_readlane_b32 s98, v183, 0
	v_readlane_b32 s99, v183, 16
	v_readlane_b32 s100, v183, 32
	v_readlane_b32 s101, v183, 48
	s_nop 1
	v_mov_b32_e32 v183, s98
	v_add_f32_e32 v183, s99, v183
	v_add_f32_e32 v183, s100, v183
	v_add_f32_e32 v183, s101, v183
	v_fmamk_f32 v183, v183, 0x3a800000, v182
	v_cmp_gt_f32_e32 vcc, 0x800000, v183
	v_mul_f32_e32 v181, 0x4b800000, v183
	s_nop 1
	v_cndmask_b32_e32 v183, v183, v181, vcc
	v_rsq_f32_e32 v183, v183
	s_nop 0
	v_mul_f32_e32 v181, 0x45800000, v183
	v_cndmask_b32_e32 v184, v183, v181, vcc
	v_mov_b32_e32 v185, v184
	v_pk_mul_f32 v[160:161], v[160:161], v[184:185]
	v_pk_mul_f32 v[162:163], v[162:163], v[184:185]
	v_pk_mul_f32 v[164:165], v[164:165], v[184:185]
	v_pk_mul_f32 v[166:167], v[166:167], v[184:185]
	v_pk_mul_f32 v[168:169], v[168:169], v[184:185]
	v_pk_mul_f32 v[170:171], v[170:171], v[184:185]
	v_pk_mul_f32 v[172:173], v[172:173], v[184:185]
	v_pk_mul_f32 v[174:175], v[174:175], v[184:185]
	v_pk_fma_f32 v[144:145], v[160:161], v[128:129], v[144:145]
	v_pk_fma_f32 v[146:147], v[162:163], v[130:131], v[146:147]
	v_pk_fma_f32 v[148:149], v[164:165], v[132:133], v[148:149]
	v_pk_fma_f32 v[150:151], v[166:167], v[134:135], v[150:151]
	v_pk_fma_f32 v[152:153], v[168:169], v[136:137], v[152:153]
	v_pk_fma_f32 v[154:155], v[170:171], v[138:139], v[154:155]
	v_pk_fma_f32 v[156:157], v[172:173], v[140:141], v[156:157]
	v_pk_fma_f32 v[158:159], v[174:175], v[142:143], v[158:159]
	v_pk_mul_f32 v[252:253], v[144:145], v[144:145]
	v_pk_mul_f32 v[254:255], v[146:147], v[146:147]
	v_pk_fma_f32 v[252:253], v[148:149], v[148:149], v[252:253]
	v_pk_fma_f32 v[254:255], v[150:151], v[150:151], v[254:255]
	v_pk_fma_f32 v[252:253], v[152:153], v[152:153], v[252:253]
	v_pk_fma_f32 v[254:255], v[154:155], v[154:155], v[254:255]
	v_pk_fma_f32 v[252:253], v[156:157], v[156:157], v[252:253]
	v_pk_fma_f32 v[254:255], v[158:159], v[158:159], v[254:255]
	v_pk_add_f32 v[252:253], v[252:253], v[254:255]
	s_nop 0
	v_add_f32_e32 v183, v252, v253
	s_nop 1
	v_add_f32_dpp v183, v183, v183 quad_perm:[1,0,3,2] row_mask:0xf bank_mask:0xf bound_ctrl:1
	s_nop 1
	v_add_f32_dpp v183, v183, v183 quad_perm:[2,3,0,1] row_mask:0xf bank_mask:0xf bound_ctrl:1
	s_nop 1
	v_add_f32_dpp v183, v183, v183 row_half_mirror row_mask:0xf bank_mask:0xf bound_ctrl:1
	s_nop 1
	v_add_f32_dpp v183, v183, v183 row_mirror row_mask:0xf bank_mask:0xf bound_ctrl:1
	s_nop 1
	v_readlane_b32 s98, v183, 0
	v_readlane_b32 s99, v183, 16
	v_readlane_b32 s100, v183, 32
	v_readlane_b32 s101, v183, 48
	s_nop 1
	v_mov_b32_e32 v183, s98
	v_add_f32_e32 v183, s99, v183
	v_add_f32_e32 v183, s100, v183
	v_add_f32_e32 v183, s101, v183
	v_fmamk_f32 v183, v183, 0x3a800000, v182
	v_cmp_gt_f32_e32 vcc, 0x800000, v183
	v_mul_f32_e32 v181, 0x4b800000, v183
	s_nop 1
	v_cndmask_b32_e32 v183, v183, v181, vcc
	v_rsq_f32_e32 v183, v183
	s_nop 0
	v_mul_f32_e32 v181, 0x45800000, v183
	v_cndmask_b32_e32 v184, v183, v181, vcc
	v_mov_b32_e32 v185, v184
	v_cvt_pk_bf16_f32 v96, v144, v145
	v_cvt_pk_bf16_f32 v97, v146, v147
	v_cvt_pk_bf16_f32 v98, v148, v149
	v_cvt_pk_bf16_f32 v99, v150, v151
	v_cvt_pk_bf16_f32 v100, v152, v153
	v_cvt_pk_bf16_f32 v101, v154, v155
	v_cvt_pk_bf16_f32 v102, v156, v157
	v_cvt_pk_bf16_f32 v103, v158, v159
	v_add_u32_e32 v181, 0x3000000, v177
	global_store_dwordx4 v181, v[96:99], s[78:79]
	global_store_dwordx4 v181, v[100:103], s[78:79] offset:1024
	v_add_u32_e32 v236, 0xc000, v237
	s_mov_b64 exec, 1
	global_store_dword v236, v184, s[78:79]
	s_mov_b64 exec, -1
	s_waitcnt vmcnt(0)
	v_lshlrev_b32_e32 v144, 16, v112
	v_and_b32_e32 v145, 0xffff0000, v112
	v_lshlrev_b32_e32 v146, 16, v113
	v_and_b32_e32 v147, 0xffff0000, v113
	v_lshlrev_b32_e32 v148, 16, v114
	v_and_b32_e32 v149, 0xffff0000, v114
	v_lshlrev_b32_e32 v150, 16, v115
	v_and_b32_e32 v151, 0xffff0000, v115
	v_lshlrev_b32_e32 v152, 16, v116
	v_and_b32_e32 v153, 0xffff0000, v116
	v_lshlrev_b32_e32 v154, 16, v117
	v_and_b32_e32 v155, 0xffff0000, v117
	v_lshlrev_b32_e32 v156, 16, v118
	v_and_b32_e32 v157, 0xffff0000, v118
	v_lshlrev_b32_e32 v158, 16, v119
	v_and_b32_e32 v159, 0xffff0000, v119
	v_lshlrev_b32_e32 v160, 16, v120
	v_and_b32_e32 v161, 0xffff0000, v120
	v_lshlrev_b32_e32 v162, 16, v121
	v_and_b32_e32 v163, 0xffff0000, v121
	v_lshlrev_b32_e32 v164, 16, v122
	v_and_b32_e32 v165, 0xffff0000, v122
	v_lshlrev_b32_e32 v166, 16, v123
	v_and_b32_e32 v167, 0xffff0000, v123
	v_lshlrev_b32_e32 v168, 16, v124
	v_and_b32_e32 v169, 0xffff0000, v124
	v_lshlrev_b32_e32 v170, 16, v125
	v_and_b32_e32 v171, 0xffff0000, v125
	v_lshlrev_b32_e32 v172, 16, v126
	v_and_b32_e32 v173, 0xffff0000, v126
	v_lshlrev_b32_e32 v174, 16, v127
	v_and_b32_e32 v175, 0xffff0000, v127
	v_pk_mul_f32 v[252:253], v[160:161], v[160:161]
	v_pk_mul_f32 v[254:255], v[162:163], v[162:163]
	v_pk_fma_f32 v[252:253], v[164:165], v[164:165], v[252:253]
	v_pk_fma_f32 v[254:255], v[166:167], v[166:167], v[254:255]
	v_pk_fma_f32 v[252:253], v[168:169], v[168:169], v[252:253]
	v_pk_fma_f32 v[254:255], v[170:171], v[170:171], v[254:255]
	v_pk_fma_f32 v[252:253], v[172:173], v[172:173], v[252:253]
	v_pk_fma_f32 v[254:255], v[174:175], v[174:175], v[254:255]
	v_pk_add_f32 v[252:253], v[252:253], v[254:255]
	s_nop 0
	v_add_f32_e32 v183, v252, v253
	s_nop 1
	v_add_f32_dpp v183, v183, v183 quad_perm:[1,0,3,2] row_mask:0xf bank_mask:0xf bound_ctrl:1
	s_nop 1
	v_add_f32_dpp v183, v183, v183 quad_perm:[2,3,0,1] row_mask:0xf bank_mask:0xf bound_ctrl:1
	s_nop 1
	v_add_f32_dpp v183, v183, v183 row_half_mirror row_mask:0xf bank_mask:0xf bound_ctrl:1
	s_nop 1
	v_add_f32_dpp v183, v183, v183 row_mirror row_mask:0xf bank_mask:0xf bound_ctrl:1
	s_nop 1
	v_readlane_b32 s98, v183, 0
	v_readlane_b32 s99, v183, 16
	v_readlane_b32 s100, v183, 32
	v_readlane_b32 s101, v183, 48
	s_nop 1
	v_mov_b32_e32 v183, s98
	v_add_f32_e32 v183, s99, v183
	v_add_f32_e32 v183, s100, v183
	v_add_f32_e32 v183, s101, v183
	v_fmamk_f32 v183, v183, 0x3a800000, v182
	v_cmp_gt_f32_e32 vcc, 0x800000, v183
	v_mul_f32_e32 v181, 0x4b800000, v183
	s_nop 1
	v_cndmask_b32_e32 v183, v183, v181, vcc
	v_rsq_f32_e32 v183, v183
	s_nop 0
	v_mul_f32_e32 v181, 0x45800000, v183
	v_cndmask_b32_e32 v184, v183, v181, vcc
	v_mov_b32_e32 v185, v184
	v_pk_mul_f32 v[160:161], v[160:161], v[184:185]
	v_pk_mul_f32 v[162:163], v[162:163], v[184:185]
	v_pk_mul_f32 v[164:165], v[164:165], v[184:185]
	v_pk_mul_f32 v[166:167], v[166:167], v[184:185]
	v_pk_mul_f32 v[168:169], v[168:169], v[184:185]
	v_pk_mul_f32 v[170:171], v[170:171], v[184:185]
	v_pk_mul_f32 v[172:173], v[172:173], v[184:185]
	v_pk_mul_f32 v[174:175], v[174:175], v[184:185]
	v_pk_fma_f32 v[144:145], v[160:161], v[128:129], v[144:145]
	v_pk_fma_f32 v[146:147], v[162:163], v[130:131], v[146:147]
	v_pk_fma_f32 v[148:149], v[164:165], v[132:133], v[148:149]
	v_pk_fma_f32 v[150:151], v[166:167], v[134:135], v[150:151]
	v_pk_fma_f32 v[152:153], v[168:169], v[136:137], v[152:153]
	v_pk_fma_f32 v[154:155], v[170:171], v[138:139], v[154:155]
	v_pk_fma_f32 v[156:157], v[172:173], v[140:141], v[156:157]
	v_pk_fma_f32 v[158:159], v[174:175], v[142:143], v[158:159]
	v_pk_mul_f32 v[252:253], v[144:145], v[144:145]
	v_pk_mul_f32 v[254:255], v[146:147], v[146:147]
	v_pk_fma_f32 v[252:253], v[148:149], v[148:149], v[252:253]
	v_pk_fma_f32 v[254:255], v[150:151], v[150:151], v[254:255]
	v_pk_fma_f32 v[252:253], v[152:153], v[152:153], v[252:253]
	v_pk_fma_f32 v[254:255], v[154:155], v[154:155], v[254:255]
	v_pk_fma_f32 v[252:253], v[156:157], v[156:157], v[252:253]
	v_pk_fma_f32 v[254:255], v[158:159], v[158:159], v[254:255]
	v_pk_add_f32 v[252:253], v[252:253], v[254:255]
	s_nop 0
	v_add_f32_e32 v183, v252, v253
	s_nop 1
	v_add_f32_dpp v183, v183, v183 quad_perm:[1,0,3,2] row_mask:0xf bank_mask:0xf bound_ctrl:1
	s_nop 1
	v_add_f32_dpp v183, v183, v183 quad_perm:[2,3,0,1] row_mask:0xf bank_mask:0xf bound_ctrl:1
	s_nop 1
	v_add_f32_dpp v183, v183, v183 row_half_mirror row_mask:0xf bank_mask:0xf bound_ctrl:1
	s_nop 1
	v_add_f32_dpp v183, v183, v183 row_mirror row_mask:0xf bank_mask:0xf bound_ctrl:1
	s_nop 1
	v_readlane_b32 s98, v183, 0
	v_readlane_b32 s99, v183, 16
	v_readlane_b32 s100, v183, 32
	v_readlane_b32 s101, v183, 48
	s_nop 1
	v_mov_b32_e32 v183, s98
	v_add_f32_e32 v183, s99, v183
	v_add_f32_e32 v183, s100, v183
	v_add_f32_e32 v183, s101, v183
	v_fmamk_f32 v183, v183, 0x3a800000, v182
	v_cmp_gt_f32_e32 vcc, 0x800000, v183
	v_mul_f32_e32 v181, 0x4b800000, v183
	s_nop 1
	v_cndmask_b32_e32 v183, v183, v181, vcc
	v_rsq_f32_e32 v183, v183
	s_nop 0
	v_mul_f32_e32 v181, 0x45800000, v183
	v_cndmask_b32_e32 v184, v183, v181, vcc
	v_mov_b32_e32 v185, v184
	v_cvt_pk_bf16_f32 v112, v144, v145
	v_cvt_pk_bf16_f32 v113, v146, v147
	v_cvt_pk_bf16_f32 v114, v148, v149
	v_cvt_pk_bf16_f32 v115, v150, v151
	v_cvt_pk_bf16_f32 v116, v152, v153
	v_cvt_pk_bf16_f32 v117, v154, v155
	v_cvt_pk_bf16_f32 v118, v156, v157
	v_cvt_pk_bf16_f32 v119, v158, v159
	v_add_u32_e32 v181, 0x3400000, v177
	global_store_dwordx4 v181, v[112:115], s[78:79]
	global_store_dwordx4 v181, v[116:119], s[78:79] offset:1024
	v_add_u32_e32 v236, 0xe000, v237
	s_mov_b64 exec, 1
	global_store_dword v236, v184, s[78:79]
	s_mov_b64 exec, -1
	v_readfirstlane_b32 s98, v179
	s_nop 3
	s_cmp_ge_u32 s98, 512
	s_cbranch_scc1 .Lmyxupd_done_5
	v_lshlrev_b32_e32 v177, 4, v176
	v_lshl_add_u32 v177, v179, 11, v177
	v_lshlrev_b32_e32 v237, 2, v179
	v_add_u32_e32 v237, 0x10000, v237
	v_add_u32_e32 v181, 0x3800000, v177
	global_load_dwordx4 v[0:3], v181, s[78:79]
	global_load_dwordx4 v[4:7], v181, s[78:79] offset:1024
	v_lshl_add_u32 v183, v179, 12, v180
	v_add_u32_e32 v183, 0xbf00000, v183
	v_add_u32_e32 v181, 0x0, v183
	global_load_dwordx4 v[8:11], v181, s[78:79]
	global_load_dwordx4 v[12:15], v181, s[78:79] offset:16
	global_load_dwordx4 v[16:19], v181, s[78:79] offset:2048
	global_load_dwordx4 v[20:23], v181, s[78:79] offset:2064
	v_add_u32_e32 v181, 0x200000, v183
	global_load_dwordx4 v[24:27], v181, s[78:79]
	global_load_dwordx4 v[28:31], v181, s[78:79] offset:16
	global_load_dwordx4 v[32:35], v181, s[78:79] offset:2048
	global_load_dwordx4 v[36:39], v181, s[78:79] offset:2064
	v_add_u32_e32 v181, 0x400000, v183
	global_load_dwordx4 v[40:43], v181, s[78:79]
	global_load_dwordx4 v[44:47], v181, s[78:79] offset:16
	global_load_dwordx4 v[48:51], v181, s[78:79] offset:2048
	global_load_dwordx4 v[52:55], v181, s[78:79] offset:2064
	v_add_u32_e32 v181, 0x600000, v183
	global_load_dwordx4 v[56:59], v181, s[78:79]
	global_load_dwordx4 v[60:63], v181, s[78:79] offset:16
	global_load_dwordx4 v[64:67], v181, s[78:79] offset:2048
	global_load_dwordx4 v[68:71], v181, s[78:79] offset:2064
	v_add_u32_e32 v181, 0x800000, v183
	global_load_dwordx4 v[72:75], v181, s[78:79]
	global_load_dwordx4 v[76:79], v181, s[78:79] offset:16
	global_load_dwordx4 v[80:83], v181, s[78:79] offset:2048
	global_load_dwordx4 v[84:87], v181, s[78:79] offset:2064
	v_add_u32_e32 v181, 0xa00000, v183
	global_load_dwordx4 v[88:91], v181, s[78:79]
	global_load_dwordx4 v[92:95], v181, s[78:79] offset:16
	global_load_dwordx4 v[96:99], v181, s[78:79] offset:2048
	global_load_dwordx4 v[100:103], v181, s[78:79] offset:2064
	s_waitcnt vmcnt(20)
	v_pk_add_f32 v[160:161], v[8:9], 0 op_sel_hi:[1,0]
	v_pk_add_f32 v[162:163], v[10:11], 0 op_sel_hi:[1,0]
	v_pk_add_f32 v[164:165], v[12:13], 0 op_sel_hi:[1,0]
	v_pk_add_f32 v[166:167], v[14:15], 0 op_sel_hi:[1,0]
	v_pk_add_f32 v[168:169], v[16:17], 0 op_sel_hi:[1,0]
	v_pk_add_f32 v[170:171], v[18:19], 0 op_sel_hi:[1,0]
	v_pk_add_f32 v[172:173], v[20:21], 0 op_sel_hi:[1,0]
	v_pk_add_f32 v[174:175], v[22:23], 0 op_sel_hi:[1,0]
	s_waitcnt vmcnt(16)
	v_pk_add_f32 v[160:161], v[160:161], v[24:25]
	v_pk_add_f32 v[162:163], v[162:163], v[26:27]
	v_pk_add_f32 v[164:165], v[164:165], v[28:29]
	v_pk_add_f32 v[166:167], v[166:167], v[30:31]
	v_pk_add_f32 v[168:169], v[168:169], v[32:33]
	v_pk_add_f32 v[170:171], v[170:171], v[34:35]
	v_pk_add_f32 v[172:173], v[172:173], v[36:37]
	v_pk_add_f32 v[174:175], v[174:175], v[38:39]
	s_waitcnt vmcnt(12)
	v_pk_add_f32 v[160:161], v[160:161], v[40:41]
	v_pk_add_f32 v[162:163], v[162:163], v[42:43]
	v_pk_add_f32 v[164:165], v[164:165], v[44:45]
	v_pk_add_f32 v[166:167], v[166:167], v[46:47]
	v_pk_add_f32 v[168:169], v[168:169], v[48:49]
	v_pk_add_f32 v[170:171], v[170:171], v[50:51]
	v_pk_add_f32 v[172:173], v[172:173], v[52:53]
	v_pk_add_f32 v[174:175], v[174:175], v[54:55]
	s_waitcnt vmcnt(8)
	v_pk_add_f32 v[160:161], v[160:161], v[56:57]
	v_pk_add_f32 v[162:163], v[162:163], v[58:59]
	v_pk_add_f32 v[164:165], v[164:165], v[60:61]
	v_pk_add_f32 v[166:167], v[166:167], v[62:63]
	v_pk_add_f32 v[168:169], v[168:169], v[64:65]
	v_pk_add_f32 v[170:171], v[170:171], v[66:67]
	v_pk_add_f32 v[172:173], v[172:173], v[68:69]
	v_pk_add_f32 v[174:175], v[174:175], v[70:71]
	s_waitcnt vmcnt(4)
	v_pk_add_f32 v[160:161], v[160:161], v[72:73]
	v_pk_add_f32 v[162:163], v[162:163], v[74:75]
	v_pk_add_f32 v[164:165], v[164:165], v[76:77]
	v_pk_add_f32 v[166:167], v[166:167], v[78:79]
	v_pk_add_f32 v[168:169], v[168:169], v[80:81]
	v_pk_add_f32 v[170:171], v[170:171], v[82:83]
	v_pk_add_f32 v[172:173], v[172:173], v[84:85]
	v_pk_add_f32 v[174:175], v[174:175], v[86:87]
	s_waitcnt vmcnt(0)
	v_pk_add_f32 v[160:161], v[160:161], v[88:89]
	v_pk_add_f32 v[162:163], v[162:163], v[90:91]
	v_pk_add_f32 v[164:165], v[164:165], v[92:93]
	v_pk_add_f32 v[166:167], v[166:167], v[94:95]
	v_pk_add_f32 v[168:169], v[168:169], v[96:97]
	v_pk_add_f32 v[170:171], v[170:171], v[98:99]
	v_pk_add_f32 v[172:173], v[172:173], v[100:101]
	v_pk_add_f32 v[174:175], v[174:175], v[102:103]
	v_lshlrev_b32_e32 v144, 16, v0
	v_and_b32_e32 v145, 0xffff0000, v0
	v_lshlrev_b32_e32 v146, 16, v1
	v_and_b32_e32 v147, 0xffff0000, v1
	v_lshlrev_b32_e32 v148, 16, v2
	v_and_b32_e32 v149, 0xffff0000, v2
	v_lshlrev_b32_e32 v150, 16, v3
	v_and_b32_e32 v151, 0xffff0000, v3
	v_lshlrev_b32_e32 v152, 16, v4
	v_and_b32_e32 v153, 0xffff0000, v4
	v_lshlrev_b32_e32 v154, 16, v5
	v_and_b32_e32 v155, 0xffff0000, v5
	v_lshlrev_b32_e32 v156, 16, v6
	v_and_b32_e32 v157, 0xffff0000, v6
	v_lshlrev_b32_e32 v158, 16, v7
	v_and_b32_e32 v159, 0xffff0000, v7
	v_add_u32_e32 v181, 0xc00000, v183
	global_load_dwordx4 v[8:11], v181, s[78:79]
	global_load_dwordx4 v[12:15], v181, s[78:79] offset:16
	global_load_dwordx4 v[16:19], v181, s[78:79] offset:2048
	global_load_dwordx4 v[20:23], v181, s[78:79] offset:2064
	v_add_u32_e32 v181, 0xe00000, v183
	global_load_dwordx4 v[24:27], v181, s[78:79]
	global_load_dwordx4 v[28:31], v181, s[78:79] offset:16
	global_load_dwordx4 v[32:35], v181, s[78:79] offset:2048
	global_load_dwordx4 v[36:39], v181, s[78:79] offset:2064
	v_add_u32_e32 v181, 0x1000000, v183
	global_load_dwordx4 v[40:43], v181, s[78:79]
	global_load_dwordx4 v[44:47], v181, s[78:79] offset:16
	global_load_dwordx4 v[48:51], v181, s[78:79] offset:2048
	global_load_dwordx4 v[52:55], v181, s[78:79] offset:2064
	v_add_u32_e32 v181, 0x1200000, v183
	global_load_dwordx4 v[56:59], v181, s[78:79]
	global_load_dwordx4 v[60:63], v181, s[78:79] offset:16
	global_load_dwordx4 v[64:67], v181, s[78:79] offset:2048
	global_load_dwordx4 v[68:71], v181, s[78:79] offset:2064
	v_add_u32_e32 v181, 0x1400000, v183
	global_load_dwordx4 v[72:75], v181, s[78:79]
	global_load_dwordx4 v[76:79], v181, s[78:79] offset:16
	global_load_dwordx4 v[80:83], v181, s[78:79] offset:2048
	global_load_dwordx4 v[84:87], v181, s[78:79] offset:2064
	s_waitcnt vmcnt(16)
	v_pk_add_f32 v[160:161], v[160:161], v[8:9]
	v_pk_add_f32 v[162:163], v[162:163], v[10:11]
	v_pk_add_f32 v[164:165], v[164:165], v[12:13]
	v_pk_add_f32 v[166:167], v[166:167], v[14:15]
	v_pk_add_f32 v[168:169], v[168:169], v[16:17]
	v_pk_add_f32 v[170:171], v[170:171], v[18:19]
	v_pk_add_f32 v[172:173], v[172:173], v[20:21]
	v_pk_add_f32 v[174:175], v[174:175], v[22:23]
	s_waitcnt vmcnt(12)
	v_pk_add_f32 v[160:161], v[160:161], v[24:25]
	v_pk_add_f32 v[162:163], v[162:163], v[26:27]
	v_pk_add_f32 v[164:165], v[164:165], v[28:29]
	v_pk_add_f32 v[166:167], v[166:167], v[30:31]
	v_pk_add_f32 v[168:169], v[168:169], v[32:33]
	v_pk_add_f32 v[170:171], v[170:171], v[34:35]
	v_pk_add_f32 v[172:173], v[172:173], v[36:37]
	v_pk_add_f32 v[174:175], v[174:175], v[38:39]
	s_waitcnt vmcnt(8)
	v_pk_add_f32 v[160:161], v[160:161], v[40:41]
	v_pk_add_f32 v[162:163], v[162:163], v[42:43]
	v_pk_add_f32 v[164:165], v[164:165], v[44:45]
	v_pk_add_f32 v[166:167], v[166:167], v[46:47]
	v_pk_add_f32 v[168:169], v[168:169], v[48:49]
	v_pk_add_f32 v[170:171], v[170:171], v[50:51]
	v_pk_add_f32 v[172:173], v[172:173], v[52:53]
	v_pk_add_f32 v[174:175], v[174:175], v[54:55]
	s_waitcnt vmcnt(4)
	v_pk_add_f32 v[160:161], v[160:161], v[56:57]
	v_pk_add_f32 v[162:163], v[162:163], v[58:59]
	v_pk_add_f32 v[164:165], v[164:165], v[60:61]
	v_pk_add_f32 v[166:167], v[166:167], v[62:63]
	v_pk_add_f32 v[168:169], v[168:169], v[64:65]
	v_pk_add_f32 v[170:171], v[170:171], v[66:67]
	v_pk_add_f32 v[172:173], v[172:173], v[68:69]
	v_pk_add_f32 v[174:175], v[174:175], v[70:71]
	s_waitcnt vmcnt(0)
	v_pk_add_f32 v[160:161], v[160:161], v[72:73]
	v_pk_add_f32 v[162:163], v[162:163], v[74:75]
	v_pk_add_f32 v[164:165], v[164:165], v[76:77]
	v_pk_add_f32 v[166:167], v[166:167], v[78:79]
	v_pk_add_f32 v[168:169], v[168:169], v[80:81]
	v_pk_add_f32 v[170:171], v[170:171], v[82:83]
	v_pk_add_f32 v[172:173], v[172:173], v[84:85]
	v_pk_add_f32 v[174:175], v[174:175], v[86:87]
	v_pk_mul_f32 v[252:253], v[160:161], v[160:161]
	v_pk_mul_f32 v[254:255], v[162:163], v[162:163]
	v_pk_fma_f32 v[252:253], v[164:165], v[164:165], v[252:253]
	v_pk_fma_f32 v[254:255], v[166:167], v[166:167], v[254:255]
	v_pk_fma_f32 v[252:253], v[168:169], v[168:169], v[252:253]
	v_pk_fma_f32 v[254:255], v[170:171], v[170:171], v[254:255]
	v_pk_fma_f32 v[252:253], v[172:173], v[172:173], v[252:253]
	v_pk_fma_f32 v[254:255], v[174:175], v[174:175], v[254:255]
	v_pk_add_f32 v[252:253], v[252:253], v[254:255]
	s_nop 0
	v_add_f32_e32 v183, v252, v253
	s_nop 1
	v_add_f32_dpp v183, v183, v183 quad_perm:[1,0,3,2] row_mask:0xf bank_mask:0xf bound_ctrl:1
	s_nop 1
	v_add_f32_dpp v183, v183, v183 quad_perm:[2,3,0,1] row_mask:0xf bank_mask:0xf bound_ctrl:1
	s_nop 1
	v_add_f32_dpp v183, v183, v183 row_half_mirror row_mask:0xf bank_mask:0xf bound_ctrl:1
	s_nop 1
	v_add_f32_dpp v183, v183, v183 row_mirror row_mask:0xf bank_mask:0xf bound_ctrl:1
	s_nop 1
	v_readlane_b32 s98, v183, 0
	v_readlane_b32 s99, v183, 16
	v_readlane_b32 s100, v183, 32
	v_readlane_b32 s101, v183, 48
	s_nop 1
	v_mov_b32_e32 v183, s98
	v_add_f32_e32 v183, s99, v183
	v_add_f32_e32 v183, s100, v183
	v_add_f32_e32 v183, s101, v183
	v_fmamk_f32 v183, v183, 0x3a800000, v182
	v_cmp_gt_f32_e32 vcc, 0x800000, v183
	v_mul_f32_e32 v181, 0x4b800000, v183
	s_nop 1
	v_cndmask_b32_e32 v183, v183, v181, vcc
	v_rsq_f32_e32 v183, v183
	s_nop 0
	v_mul_f32_e32 v181, 0x45800000, v183
	v_cndmask_b32_e32 v184, v183, v181, vcc
	v_mov_b32_e32 v185, v184
	v_pk_mul_f32 v[160:161], v[160:161], v[184:185]
	v_pk_mul_f32 v[162:163], v[162:163], v[184:185]
	v_pk_mul_f32 v[164:165], v[164:165], v[184:185]
	v_pk_mul_f32 v[166:167], v[166:167], v[184:185]
	v_pk_mul_f32 v[168:169], v[168:169], v[184:185]
	v_pk_mul_f32 v[170:171], v[170:171], v[184:185]
	v_pk_mul_f32 v[172:173], v[172:173], v[184:185]
	v_pk_mul_f32 v[174:175], v[174:175], v[184:185]
	v_pk_fma_f32 v[144:145], v[160:161], v[128:129], v[144:145]
	v_pk_fma_f32 v[146:147], v[162:163], v[130:131], v[146:147]
	v_pk_fma_f32 v[148:149], v[164:165], v[132:133], v[148:149]
	v_pk_fma_f32 v[150:151], v[166:167], v[134:135], v[150:151]
	v_pk_fma_f32 v[152:153], v[168:169], v[136:137], v[152:153]
	v_pk_fma_f32 v[154:155], v[170:171], v[138:139], v[154:155]
	v_pk_fma_f32 v[156:157], v[172:173], v[140:141], v[156:157]
	v_pk_fma_f32 v[158:159], v[174:175], v[142:143], v[158:159]
	v_pk_mul_f32 v[252:253], v[144:145], v[144:145]
	v_pk_mul_f32 v[254:255], v[146:147], v[146:147]
	v_pk_fma_f32 v[252:253], v[148:149], v[148:149], v[252:253]
	v_pk_fma_f32 v[254:255], v[150:151], v[150:151], v[254:255]
	v_pk_fma_f32 v[252:253], v[152:153], v[152:153], v[252:253]
	v_pk_fma_f32 v[254:255], v[154:155], v[154:155], v[254:255]
	v_pk_fma_f32 v[252:253], v[156:157], v[156:157], v[252:253]
	v_pk_fma_f32 v[254:255], v[158:159], v[158:159], v[254:255]
	v_pk_add_f32 v[252:253], v[252:253], v[254:255]
	s_nop 0
	v_add_f32_e32 v183, v252, v253
	s_nop 1
	v_add_f32_dpp v183, v183, v183 quad_perm:[1,0,3,2] row_mask:0xf bank_mask:0xf bound_ctrl:1
	s_nop 1
	v_add_f32_dpp v183, v183, v183 quad_perm:[2,3,0,1] row_mask:0xf bank_mask:0xf bound_ctrl:1
	s_nop 1
	v_add_f32_dpp v183, v183, v183 row_half_mirror row_mask:0xf bank_mask:0xf bound_ctrl:1
	s_nop 1
	v_add_f32_dpp v183, v183, v183 row_mirror row_mask:0xf bank_mask:0xf bound_ctrl:1
	s_nop 1
	v_readlane_b32 s98, v183, 0
	v_readlane_b32 s99, v183, 16
	v_readlane_b32 s100, v183, 32
	v_readlane_b32 s101, v183, 48
	s_nop 1
	v_mov_b32_e32 v183, s98
	v_add_f32_e32 v183, s99, v183
	v_add_f32_e32 v183, s100, v183
	v_add_f32_e32 v183, s101, v183
	v_fmamk_f32 v183, v183, 0x3a800000, v182
	v_cmp_gt_f32_e32 vcc, 0x800000, v183
	v_mul_f32_e32 v181, 0x4b800000, v183
	s_nop 1
	v_cndmask_b32_e32 v183, v183, v181, vcc
	v_rsq_f32_e32 v183, v183
	s_nop 0
	v_mul_f32_e32 v181, 0x45800000, v183
	v_cndmask_b32_e32 v184, v183, v181, vcc
	v_mov_b32_e32 v185, v184
	v_cvt_pk_bf16_f32 v0, v144, v145
	v_cvt_pk_bf16_f32 v1, v146, v147
	v_cvt_pk_bf16_f32 v2, v148, v149
	v_cvt_pk_bf16_f32 v3, v150, v151
	v_cvt_pk_bf16_f32 v4, v152, v153
	v_cvt_pk_bf16_f32 v5, v154, v155
	v_cvt_pk_bf16_f32 v6, v156, v157
	v_cvt_pk_bf16_f32 v7, v158, v159
	v_add_u32_e32 v181, 0x3800000, v177
	global_store_dwordx4 v181, v[0:3], s[78:79]
	global_store_dwordx4 v181, v[4:7], s[78:79] offset:1024
	v_add_u32_e32 v236, 0x10000, v237
	s_mov_b64 exec, 1
	global_store_dword v236, v184, s[78:79]
	s_mov_b64 exec, -1

.LBB0_2573:
	v_readlane_b32 s0, v235, 52
	v_readlane_b32 s1, v235, 53
	s_and_b64 vcc, exec, s[0:1]
	s_waitcnt lgkmcnt(0)
	s_barrier
	v_mbcnt_lo_u32_b32 v0, -1, 0
	v_mbcnt_hi_u32_b32 v0, -1, v0
	s_cbranch_vccnz .LBB0_2593
	v_lshlrev_b32_e32 v2, 3, v0
	v_ashrrev_i32_e32 v3, 31, v2
	v_readlane_b32 s4, v235, 4
	v_lshlrev_b64 v[4:5], 1, v[2:3]
	v_lshlrev_b64 v[2:3], 2, v[2:3]
	v_readlane_b32 s14, v235, 14
	v_readlane_b32 s15, v235, 15
	v_lshl_add_u64 v[62:63], s[90:91], 0, v[2:3]
	v_readlane_b32 s5, v235, 5
	v_readlane_b32 s6, v235, 6
	v_readlane_b32 s7, v235, 7
	v_readlane_b32 s8, v235, 8
	v_readlane_b32 s9, v235, 9
	v_readlane_b32 s10, v235, 10
	v_readlane_b32 s11, v235, 11
	v_readlane_b32 s12, v235, 12
	v_readlane_b32 s13, v235, 13
	v_readlane_b32 s16, v235, 16
	v_readlane_b32 s17, v235, 17
	v_readlane_b32 s18, v235, 18
	v_readlane_b32 s19, v235, 19
	v_lshl_add_u64 v[2:3], s[14:15], 0, v[2:3]
	s_mov_b64 s[0:1], 0x3000
	v_lshl_add_u64 v[60:61], s[86:87], 0, v[4:5]
	v_lshl_add_u64 v[64:65], s[54:55], 0, v[4:5]
	v_lshl_add_u64 v[66:67], v[2:3], 0, s[0:1]
	s_mov_b32 s1, 0
	v_cmp_eq_u32_e64 s[4:5], 0, v0
	s_mov_b64 s[6:7], 0x200000
	s_mov_b64 s[8:9], 0x200800
	s_mov_b64 s[10:11], 0x400000
	s_mov_b64 s[12:13], 0x400800
	s_mov_b64 s[14:15], 0x600000
	s_mov_b64 s[16:17], 0x600800
	s_mov_b64 s[18:19], 0x800000
	s_mov_b32 s48, 0x800000
	s_mov_b64 s[20:21], 0x800800
	s_mov_b64 s[22:23], 0xa00000
	s_mov_b64 s[24:25], 0xa00800
	s_mov_b64 s[26:27], 0xc00000
	s_mov_b64 s[28:29], 0xc00800
	s_mov_b64 s[30:31], 0xe00000
	s_mov_b64 s[36:37], 0xe00800
	v_mov_b32_e32 v104, 0
	v_mov_b32_e32 v105, 0x358637bd
	v_readlane_b32 s38, v235, 61
	v_readlane_b32 s39, v235, 62
	v_mbcnt_lo_u32_b32 v176, -1, 0
	v_mbcnt_hi_u32_b32 v176, -1, v176
	v_readlane_b32 s98, v235, 49
	v_readlane_b32 s99, v235, 20
	v_readlane_b32 s100, v235, 14
	v_readlane_b32 s101, v235, 15
	s_nop 3
	s_lshr_b32 vcc_lo, s98, 3
	s_and_b32 vcc_hi, vcc_lo, 7
	s_lshr_b32 vcc_lo, vcc_lo, 3
	s_lshl_b32 vcc_lo, vcc_lo, 3
	s_add_i32 vcc_lo, vcc_lo, s99
	s_lshl_b32 s98, vcc_hi, 8
	s_add_i32 s98, s98, vcc_lo
	s_mov_b32 s99, s98
	v_mov_b32_e32 v183, s99
	v_lshlrev_b32_e32 v177, 4, v176
	s_lshl_b32 s99, s99, 11
	v_add_u32_e32 v177, s99, v177
	v_add_u32_e32 v178, 0x1800000, v177
	v_add_u32_e32 v179, 0x9e00000, v177
	v_lshlrev_b32_e32 v180, 5, v176
	v_add_u32_e32 v181, 0x3000, v180
	global_load_dwordx4 v[128:131], v181, s[100:101]
	global_load_dwordx4 v[132:135], v181, s[100:101] offset:16
	global_load_dwordx4 v[136:139], v181, s[100:101] offset:2048
	global_load_dwordx4 v[140:143], v181, s[100:101] offset:2064
	v_mov_b32_e32 v182, 0x358637bd
	global_load_dwordx4 v[0:3], v178, s[78:79]
	global_load_dwordx4 v[4:7], v178, s[78:79] offset:1024
	global_load_dwordx4 v[8:11], v179, s[78:79]
	global_load_dwordx4 v[12:15], v179, s[78:79] offset:1024
	v_add_u32_e32 v178, 0x400000, v178
	v_add_u32_e32 v179, 0x400000, v179
	global_load_dwordx4 v[16:19], v178, s[78:79]
	global_load_dwordx4 v[20:23], v178, s[78:79] offset:1024
	global_load_dwordx4 v[24:27], v179, s[78:79]
	global_load_dwordx4 v[28:31], v179, s[78:79] offset:1024
	v_add_u32_e32 v178, 0x400000, v178
	v_add_u32_e32 v179, 0x400000, v179
	global_load_dwordx4 v[32:35], v178, s[78:79]
	global_load_dwordx4 v[36:39], v178, s[78:79] offset:1024
	global_load_dwordx4 v[40:43], v179, s[78:79]
	global_load_dwordx4 v[44:47], v179, s[78:79] offset:1024
	v_add_u32_e32 v178, 0x400000, v178
	v_add_u32_e32 v179, 0x400000, v179
	global_load_dwordx4 v[48:51], v178, s[78:79]
	global_load_dwordx4 v[52:55], v178, s[78:79] offset:1024
	global_load_dwordx4 v[56:59], v179, s[78:79]
	global_load_dwordx4 v[60:63], v179, s[78:79] offset:1024
	v_add_u32_e32 v178, 0x400000, v178
	v_add_u32_e32 v179, 0x400000, v179
	global_load_dwordx4 v[64:67], v178, s[78:79]
	global_load_dwordx4 v[68:71], v178, s[78:79] offset:1024
	global_load_dwordx4 v[72:75], v179, s[78:79]
	global_load_dwordx4 v[76:79], v179, s[78:79] offset:1024
	v_add_u32_e32 v178, 0x400000, v178
	v_add_u32_e32 v179, 0x400000, v179
	global_load_dwordx4 v[80:83], v178, s[78:79]
	global_load_dwordx4 v[84:87], v178, s[78:79] offset:1024
	global_load_dwordx4 v[88:91], v179, s[78:79]
	global_load_dwordx4 v[92:95], v179, s[78:79] offset:1024
	v_add_u32_e32 v178, 0x400000, v178
	v_add_u32_e32 v179, 0x400000, v179
	global_load_dwordx4 v[96:99], v178, s[78:79]
	global_load_dwordx4 v[100:103], v178, s[78:79] offset:1024
	global_load_dwordx4 v[104:107], v179, s[78:79]
	global_load_dwordx4 v[108:111], v179, s[78:79] offset:1024
	v_add_u32_e32 v178, 0x400000, v178
	v_add_u32_e32 v179, 0x400000, v179
	global_load_dwordx4 v[112:115], v178, s[78:79]
	global_load_dwordx4 v[116:119], v178, s[78:79] offset:1024
	global_load_dwordx4 v[120:123], v179, s[78:79]
	global_load_dwordx4 v[124:127], v179, s[78:79] offset:1024
	v_lshlrev_b32_e32 v237, 2, v183
	v_add_u32_e32 v237, 0x10000, v237
	v_mov_b32_e32 v179, s98
	s_waitcnt vmcnt(28)
	v_lshlrev_b32_e32 v144, 16, v0
	v_and_b32_e32 v145, 0xffff0000, v0
	v_lshlrev_b32_e32 v146, 16, v1
	v_and_b32_e32 v147, 0xffff0000, v1
	v_lshlrev_b32_e32 v148, 16, v2
	v_and_b32_e32 v149, 0xffff0000, v2
	v_lshlrev_b32_e32 v150, 16, v3
	v_and_b32_e32 v151, 0xffff0000, v3
	v_lshlrev_b32_e32 v152, 16, v4
	v_and_b32_e32 v153, 0xffff0000, v4
	v_lshlrev_b32_e32 v154, 16, v5
	v_and_b32_e32 v155, 0xffff0000, v5
	v_lshlrev_b32_e32 v156, 16, v6
	v_and_b32_e32 v157, 0xffff0000, v6
	v_lshlrev_b32_e32 v158, 16, v7
	v_and_b32_e32 v159, 0xffff0000, v7
	v_lshlrev_b32_e32 v160, 16, v8
	v_and_b32_e32 v161, 0xffff0000, v8
	v_lshlrev_b32_e32 v162, 16, v9
	v_and_b32_e32 v163, 0xffff0000, v9
	v_lshlrev_b32_e32 v164, 16, v10
	v_and_b32_e32 v165, 0xffff0000, v10
	v_lshlrev_b32_e32 v166, 16, v11
	v_and_b32_e32 v167, 0xffff0000, v11
	v_lshlrev_b32_e32 v168, 16, v12
	v_and_b32_e32 v169, 0xffff0000, v12
	v_lshlrev_b32_e32 v170, 16, v13
	v_and_b32_e32 v171, 0xffff0000, v13
	v_lshlrev_b32_e32 v172, 16, v14
	v_and_b32_e32 v173, 0xffff0000, v14
	v_lshlrev_b32_e32 v174, 16, v15
	v_and_b32_e32 v175, 0xffff0000, v15
	v_pk_mul_f32 v[252:253], v[160:161], v[160:161]
	v_pk_mul_f32 v[254:255], v[162:163], v[162:163]
	v_pk_fma_f32 v[252:253], v[164:165], v[164:165], v[252:253]
	v_pk_fma_f32 v[254:255], v[166:167], v[166:167], v[254:255]
	v_pk_fma_f32 v[252:253], v[168:169], v[168:169], v[252:253]
	v_pk_fma_f32 v[254:255], v[170:171], v[170:171], v[254:255]
	v_pk_fma_f32 v[252:253], v[172:173], v[172:173], v[252:253]
	v_pk_fma_f32 v[254:255], v[174:175], v[174:175], v[254:255]
	v_pk_add_f32 v[252:253], v[252:253], v[254:255]
	s_nop 0
	v_add_f32_e32 v183, v252, v253
	s_nop 1
	v_add_f32_dpp v183, v183, v183 quad_perm:[1,0,3,2] row_mask:0xf bank_mask:0xf bound_ctrl:1
	s_nop 1
	v_add_f32_dpp v183, v183, v183 quad_perm:[2,3,0,1] row_mask:0xf bank_mask:0xf bound_ctrl:1
	s_nop 1
	v_add_f32_dpp v183, v183, v183 row_half_mirror row_mask:0xf bank_mask:0xf bound_ctrl:1
	s_nop 1
	v_add_f32_dpp v183, v183, v183 row_mirror row_mask:0xf bank_mask:0xf bound_ctrl:1
	s_nop 1
	v_readlane_b32 s98, v183, 0
	v_readlane_b32 s99, v183, 16
	v_readlane_b32 s100, v183, 32
	v_readlane_b32 s101, v183, 48
	s_nop 1
	v_mov_b32_e32 v183, s98
	v_add_f32_e32 v183, s99, v183
	v_add_f32_e32 v183, s100, v183
	v_add_f32_e32 v183, s101, v183
	v_fmamk_f32 v183, v183, 0x3a800000, v182
	v_cmp_gt_f32_e32 vcc, 0x800000, v183
	v_mul_f32_e32 v181, 0x4b800000, v183
	s_nop 1
	v_cndmask_b32_e32 v183, v183, v181, vcc
	v_rsq_f32_e32 v183, v183
	s_nop 0
	v_mul_f32_e32 v181, 0x45800000, v183
	v_cndmask_b32_e32 v184, v183, v181, vcc
	v_mov_b32_e32 v185, v184
	v_pk_mul_f32 v[160:161], v[160:161], v[184:185]
	v_pk_mul_f32 v[162:163], v[162:163], v[184:185]
	v_pk_mul_f32 v[164:165], v[164:165], v[184:185]
	v_pk_mul_f32 v[166:167], v[166:167], v[184:185]
	v_pk_mul_f32 v[168:169], v[168:169], v[184:185]
	v_pk_mul_f32 v[170:171], v[170:171], v[184:185]
	v_pk_mul_f32 v[172:173], v[172:173], v[184:185]
	v_pk_mul_f32 v[174:175], v[174:175], v[184:185]
	v_pk_fma_f32 v[144:145], v[160:161], v[128:129], v[144:145]
	v_pk_fma_f32 v[146:147], v[162:163], v[130:131], v[146:147]
	v_pk_fma_f32 v[148:149], v[164:165], v[132:133], v[148:149]
	v_pk_fma_f32 v[150:151], v[166:167], v[134:135], v[150:151]
	v_pk_fma_f32 v[152:153], v[168:169], v[136:137], v[152:153]
	v_pk_fma_f32 v[154:155], v[170:171], v[138:139], v[154:155]
	v_pk_fma_f32 v[156:157], v[172:173], v[140:141], v[156:157]
	v_pk_fma_f32 v[158:159], v[174:175], v[142:143], v[158:159]
	v_pk_mul_f32 v[252:253], v[144:145], v[144:145]
	v_pk_mul_f32 v[254:255], v[146:147], v[146:147]
	v_pk_fma_f32 v[252:253], v[148:149], v[148:149], v[252:253]
	v_pk_fma_f32 v[254:255], v[150:151], v[150:151], v[254:255]
	v_pk_fma_f32 v[252:253], v[152:153], v[152:153], v[252:253]
	v_pk_fma_f32 v[254:255], v[154:155], v[154:155], v[254:255]
	v_pk_fma_f32 v[252:253], v[156:157], v[156:157], v[252:253]
	v_pk_fma_f32 v[254:255], v[158:159], v[158:159], v[254:255]
	v_pk_add_f32 v[252:253], v[252:253], v[254:255]
	s_nop 0
	v_add_f32_e32 v183, v252, v253
	s_nop 1
	v_add_f32_dpp v183, v183, v183 quad_perm:[1,0,3,2] row_mask:0xf bank_mask:0xf bound_ctrl:1
	s_nop 1
	v_add_f32_dpp v183, v183, v183 quad_perm:[2,3,0,1] row_mask:0xf bank_mask:0xf bound_ctrl:1
	s_nop 1
	v_add_f32_dpp v183, v183, v183 row_half_mirror row_mask:0xf bank_mask:0xf bound_ctrl:1
	s_nop 1
	v_add_f32_dpp v183, v183, v183 row_mirror row_mask:0xf bank_mask:0xf bound_ctrl:1
	s_nop 1
	v_readlane_b32 s98, v183, 0
	v_readlane_b32 s99, v183, 16
	v_readlane_b32 s100, v183, 32
	v_readlane_b32 s101, v183, 48
	s_nop 1
	v_mov_b32_e32 v183, s98
	v_add_f32_e32 v183, s99, v183
	v_add_f32_e32 v183, s100, v183
	v_add_f32_e32 v183, s101, v183
	v_fmamk_f32 v183, v183, 0x3a800000, v182
	v_cmp_gt_f32_e32 vcc, 0x800000, v183
	v_mul_f32_e32 v181, 0x4b800000, v183
	s_nop 1
	v_cndmask_b32_e32 v183, v183, v181, vcc
	v_rsq_f32_e32 v183, v183
	s_nop 0
	v_mul_f32_e32 v181, 0x45800000, v183
	v_cndmask_b32_e32 v184, v183, v181, vcc
	v_mov_b32_e32 v185, v184
	v_cvt_pk_bf16_f32 v0, v144, v145
	v_cvt_pk_bf16_f32 v1, v146, v147
	v_cvt_pk_bf16_f32 v2, v148, v149
	v_cvt_pk_bf16_f32 v3, v150, v151
	v_cvt_pk_bf16_f32 v4, v152, v153
	v_cvt_pk_bf16_f32 v5, v154, v155
	v_cvt_pk_bf16_f32 v6, v156, v157
	v_cvt_pk_bf16_f32 v7, v158, v159
	v_add_u32_e32 v181, 0x1800000, v177
	global_store_dwordx4 v181, v[0:3], s[78:79]
	global_store_dwordx4 v181, v[4:7], s[78:79] offset:1024
	v_add_u32_e32 v236, 0x0, v237
	s_mov_b64 exec, 1
	global_store_dword v236, v184, s[78:79]
	s_mov_b64 exec, -1
	s_waitcnt vmcnt(24)
	v_lshlrev_b32_e32 v144, 16, v16
	v_and_b32_e32 v145, 0xffff0000, v16
	v_lshlrev_b32_e32 v146, 16, v17
	v_and_b32_e32 v147, 0xffff0000, v17
	v_lshlrev_b32_e32 v148, 16, v18
	v_and_b32_e32 v149, 0xffff0000, v18
	v_lshlrev_b32_e32 v150, 16, v19
	v_and_b32_e32 v151, 0xffff0000, v19
	v_lshlrev_b32_e32 v152, 16, v20
	v_and_b32_e32 v153, 0xffff0000, v20
	v_lshlrev_b32_e32 v154, 16, v21
	v_and_b32_e32 v155, 0xffff0000, v21
	v_lshlrev_b32_e32 v156, 16, v22
	v_and_b32_e32 v157, 0xffff0000, v22
	v_lshlrev_b32_e32 v158, 16, v23
	v_and_b32_e32 v159, 0xffff0000, v23
	v_lshlrev_b32_e32 v160, 16, v24
	v_and_b32_e32 v161, 0xffff0000, v24
	v_lshlrev_b32_e32 v162, 16, v25
	v_and_b32_e32 v163, 0xffff0000, v25
	v_lshlrev_b32_e32 v164, 16, v26
	v_and_b32_e32 v165, 0xffff0000, v26
	v_lshlrev_b32_e32 v166, 16, v27
	v_and_b32_e32 v167, 0xffff0000, v27
	v_lshlrev_b32_e32 v168, 16, v28
	v_and_b32_e32 v169, 0xffff0000, v28
	v_lshlrev_b32_e32 v170, 16, v29
	v_and_b32_e32 v171, 0xffff0000, v29
	v_lshlrev_b32_e32 v172, 16, v30
	v_and_b32_e32 v173, 0xffff0000, v30
	v_lshlrev_b32_e32 v174, 16, v31
	v_and_b32_e32 v175, 0xffff0000, v31
	v_pk_mul_f32 v[252:253], v[160:161], v[160:161]
	v_pk_mul_f32 v[254:255], v[162:163], v[162:163]
	v_pk_fma_f32 v[252:253], v[164:165], v[164:165], v[252:253]
	v_pk_fma_f32 v[254:255], v[166:167], v[166:167], v[254:255]
	v_pk_fma_f32 v[252:253], v[168:169], v[168:169], v[252:253]
	v_pk_fma_f32 v[254:255], v[170:171], v[170:171], v[254:255]
	v_pk_fma_f32 v[252:253], v[172:173], v[172:173], v[252:253]
	v_pk_fma_f32 v[254:255], v[174:175], v[174:175], v[254:255]
	v_pk_add_f32 v[252:253], v[252:253], v[254:255]
	s_nop 0
	v_add_f32_e32 v183, v252, v253
	s_nop 1
	v_add_f32_dpp v183, v183, v183 quad_perm:[1,0,3,2] row_mask:0xf bank_mask:0xf bound_ctrl:1
	s_nop 1
	v_add_f32_dpp v183, v183, v183 quad_perm:[2,3,0,1] row_mask:0xf bank_mask:0xf bound_ctrl:1
	s_nop 1
	v_add_f32_dpp v183, v183, v183 row_half_mirror row_mask:0xf bank_mask:0xf bound_ctrl:1
	s_nop 1
	v_add_f32_dpp v183, v183, v183 row_mirror row_mask:0xf bank_mask:0xf bound_ctrl:1
	s_nop 1
	v_readlane_b32 s98, v183, 0
	v_readlane_b32 s99, v183, 16
	v_readlane_b32 s100, v183, 32
	v_readlane_b32 s101, v183, 48
	s_nop 1
	v_mov_b32_e32 v183, s98
	v_add_f32_e32 v183, s99, v183
	v_add_f32_e32 v183, s100, v183
	v_add_f32_e32 v183, s101, v183
	v_fmamk_f32 v183, v183, 0x3a800000, v182
	v_cmp_gt_f32_e32 vcc, 0x800000, v183
	v_mul_f32_e32 v181, 0x4b800000, v183
	s_nop 1
	v_cndmask_b32_e32 v183, v183, v181, vcc
	v_rsq_f32_e32 v183, v183
	s_nop 0
	v_mul_f32_e32 v181, 0x45800000, v183
	v_cndmask_b32_e32 v184, v183, v181, vcc
	v_mov_b32_e32 v185, v184
	v_pk_mul_f32 v[160:161], v[160:161], v[184:185]
	v_pk_mul_f32 v[162:163], v[162:163], v[184:185]
	v_pk_mul_f32 v[164:165], v[164:165], v[184:185]
	v_pk_mul_f32 v[166:167], v[166:167], v[184:185]
	v_pk_mul_f32 v[168:169], v[168:169], v[184:185]
	v_pk_mul_f32 v[170:171], v[170:171], v[184:185]
	v_pk_mul_f32 v[172:173], v[172:173], v[184:185]
	v_pk_mul_f32 v[174:175], v[174:175], v[184:185]
	v_pk_fma_f32 v[144:145], v[160:161], v[128:129], v[144:145]
	v_pk_fma_f32 v[146:147], v[162:163], v[130:131], v[146:147]
	v_pk_fma_f32 v[148:149], v[164:165], v[132:133], v[148:149]
	v_pk_fma_f32 v[150:151], v[166:167], v[134:135], v[150:151]
	v_pk_fma_f32 v[152:153], v[168:169], v[136:137], v[152:153]
	v_pk_fma_f32 v[154:155], v[170:171], v[138:139], v[154:155]
	v_pk_fma_f32 v[156:157], v[172:173], v[140:141], v[156:157]
	v_pk_fma_f32 v[158:159], v[174:175], v[142:143], v[158:159]
	v_pk_mul_f32 v[252:253], v[144:145], v[144:145]
	v_pk_mul_f32 v[254:255], v[146:147], v[146:147]
	v_pk_fma_f32 v[252:253], v[148:149], v[148:149], v[252:253]
	v_pk_fma_f32 v[254:255], v[150:151], v[150:151], v[254:255]
	v_pk_fma_f32 v[252:253], v[152:153], v[152:153], v[252:253]
	v_pk_fma_f32 v[254:255], v[154:155], v[154:155], v[254:255]
	v_pk_fma_f32 v[252:253], v[156:157], v[156:157], v[252:253]
	v_pk_fma_f32 v[254:255], v[158:159], v[158:159], v[254:255]
	v_pk_add_f32 v[252:253], v[252:253], v[254:255]
	s_nop 0
	v_add_f32_e32 v183, v252, v253
	s_nop 1
	v_add_f32_dpp v183, v183, v183 quad_perm:[1,0,3,2] row_mask:0xf bank_mask:0xf bound_ctrl:1
	s_nop 1
	v_add_f32_dpp v183, v183, v183 quad_perm:[2,3,0,1] row_mask:0xf bank_mask:0xf bound_ctrl:1
	s_nop 1
	v_add_f32_dpp v183, v183, v183 row_half_mirror row_mask:0xf bank_mask:0xf bound_ctrl:1
	s_nop 1
	v_add_f32_dpp v183, v183, v183 row_mirror row_mask:0xf bank_mask:0xf bound_ctrl:1
	s_nop 1
	v_readlane_b32 s98, v183, 0
	v_readlane_b32 s99, v183, 16
	v_readlane_b32 s100, v183, 32
	v_readlane_b32 s101, v183, 48
	s_nop 1
	v_mov_b32_e32 v183, s98
	v_add_f32_e32 v183, s99, v183
	v_add_f32_e32 v183, s100, v183
	v_add_f32_e32 v183, s101, v183
	v_fmamk_f32 v183, v183, 0x3a800000, v182
	v_cmp_gt_f32_e32 vcc, 0x800000, v183
	v_mul_f32_e32 v181, 0x4b800000, v183
	s_nop 1
	v_cndmask_b32_e32 v183, v183, v181, vcc
	v_rsq_f32_e32 v183, v183
	s_nop 0
	v_mul_f32_e32 v181, 0x45800000, v183
	v_cndmask_b32_e32 v184, v183, v181, vcc
	v_mov_b32_e32 v185, v184
	v_cvt_pk_bf16_f32 v16, v144, v145
	v_cvt_pk_bf16_f32 v17, v146, v147
	v_cvt_pk_bf16_f32 v18, v148, v149
	v_cvt_pk_bf16_f32 v19, v150, v151
	v_cvt_pk_bf16_f32 v20, v152, v153
	v_cvt_pk_bf16_f32 v21, v154, v155
	v_cvt_pk_bf16_f32 v22, v156, v157
	v_cvt_pk_bf16_f32 v23, v158, v159
	v_add_u32_e32 v181, 0x1c00000, v177
	global_store_dwordx4 v181, v[16:19], s[78:79]
	global_store_dwordx4 v181, v[20:23], s[78:79] offset:1024
	v_add_u32_e32 v236, 0x2000, v237
	s_mov_b64 exec, 1
	global_store_dword v236, v184, s[78:79]
	s_mov_b64 exec, -1
	s_waitcnt vmcnt(20)
	v_lshlrev_b32_e32 v144, 16, v32
	v_and_b32_e32 v145, 0xffff0000, v32
	v_lshlrev_b32_e32 v146, 16, v33
	v_and_b32_e32 v147, 0xffff0000, v33
	v_lshlrev_b32_e32 v148, 16, v34
	v_and_b32_e32 v149, 0xffff0000, v34
	v_lshlrev_b32_e32 v150, 16, v35
	v_and_b32_e32 v151, 0xffff0000, v35
	v_lshlrev_b32_e32 v152, 16, v36
	v_and_b32_e32 v153, 0xffff0000, v36
	v_lshlrev_b32_e32 v154, 16, v37
	v_and_b32_e32 v155, 0xffff0000, v37
	v_lshlrev_b32_e32 v156, 16, v38
	v_and_b32_e32 v157, 0xffff0000, v38
	v_lshlrev_b32_e32 v158, 16, v39
	v_and_b32_e32 v159, 0xffff0000, v39
	v_lshlrev_b32_e32 v160, 16, v40
	v_and_b32_e32 v161, 0xffff0000, v40
	v_lshlrev_b32_e32 v162, 16, v41
	v_and_b32_e32 v163, 0xffff0000, v41
	v_lshlrev_b32_e32 v164, 16, v42
	v_and_b32_e32 v165, 0xffff0000, v42
	v_lshlrev_b32_e32 v166, 16, v43
	v_and_b32_e32 v167, 0xffff0000, v43
	v_lshlrev_b32_e32 v168, 16, v44
	v_and_b32_e32 v169, 0xffff0000, v44
	v_lshlrev_b32_e32 v170, 16, v45
	v_and_b32_e32 v171, 0xffff0000, v45
	v_lshlrev_b32_e32 v172, 16, v46
	v_and_b32_e32 v173, 0xffff0000, v46
	v_lshlrev_b32_e32 v174, 16, v47
	v_and_b32_e32 v175, 0xffff0000, v47
	v_pk_mul_f32 v[252:253], v[160:161], v[160:161]
	v_pk_mul_f32 v[254:255], v[162:163], v[162:163]
	v_pk_fma_f32 v[252:253], v[164:165], v[164:165], v[252:253]
	v_pk_fma_f32 v[254:255], v[166:167], v[166:167], v[254:255]
	v_pk_fma_f32 v[252:253], v[168:169], v[168:169], v[252:253]
	v_pk_fma_f32 v[254:255], v[170:171], v[170:171], v[254:255]
	v_pk_fma_f32 v[252:253], v[172:173], v[172:173], v[252:253]
	v_pk_fma_f32 v[254:255], v[174:175], v[174:175], v[254:255]
	v_pk_add_f32 v[252:253], v[252:253], v[254:255]
	s_nop 0
	v_add_f32_e32 v183, v252, v253
	s_nop 1
	v_add_f32_dpp v183, v183, v183 quad_perm:[1,0,3,2] row_mask:0xf bank_mask:0xf bound_ctrl:1
	s_nop 1
	v_add_f32_dpp v183, v183, v183 quad_perm:[2,3,0,1] row_mask:0xf bank_mask:0xf bound_ctrl:1
	s_nop 1
	v_add_f32_dpp v183, v183, v183 row_half_mirror row_mask:0xf bank_mask:0xf bound_ctrl:1
	s_nop 1
	v_add_f32_dpp v183, v183, v183 row_mirror row_mask:0xf bank_mask:0xf bound_ctrl:1
	s_nop 1
	v_readlane_b32 s98, v183, 0
	v_readlane_b32 s99, v183, 16
	v_readlane_b32 s100, v183, 32
	v_readlane_b32 s101, v183, 48
	s_nop 1
	v_mov_b32_e32 v183, s98
	v_add_f32_e32 v183, s99, v183
	v_add_f32_e32 v183, s100, v183
	v_add_f32_e32 v183, s101, v183
	v_fmamk_f32 v183, v183, 0x3a800000, v182
	v_cmp_gt_f32_e32 vcc, 0x800000, v183
	v_mul_f32_e32 v181, 0x4b800000, v183
	s_nop 1
	v_cndmask_b32_e32 v183, v183, v181, vcc
	v_rsq_f32_e32 v183, v183
	s_nop 0
	v_mul_f32_e32 v181, 0x45800000, v183
	v_cndmask_b32_e32 v184, v183, v181, vcc
	v_mov_b32_e32 v185, v184
	v_pk_mul_f32 v[160:161], v[160:161], v[184:185]
	v_pk_mul_f32 v[162:163], v[162:163], v[184:185]
	v_pk_mul_f32 v[164:165], v[164:165], v[184:185]
	v_pk_mul_f32 v[166:167], v[166:167], v[184:185]
	v_pk_mul_f32 v[168:169], v[168:169], v[184:185]
	v_pk_mul_f32 v[170:171], v[170:171], v[184:185]
	v_pk_mul_f32 v[172:173], v[172:173], v[184:185]
	v_pk_mul_f32 v[174:175], v[174:175], v[184:185]
	v_pk_fma_f32 v[144:145], v[160:161], v[128:129], v[144:145]
	v_pk_fma_f32 v[146:147], v[162:163], v[130:131], v[146:147]
	v_pk_fma_f32 v[148:149], v[164:165], v[132:133], v[148:149]
	v_pk_fma_f32 v[150:151], v[166:167], v[134:135], v[150:151]
	v_pk_fma_f32 v[152:153], v[168:169], v[136:137], v[152:153]
	v_pk_fma_f32 v[154:155], v[170:171], v[138:139], v[154:155]
	v_pk_fma_f32 v[156:157], v[172:173], v[140:141], v[156:157]
	v_pk_fma_f32 v[158:159], v[174:175], v[142:143], v[158:159]
	v_pk_mul_f32 v[252:253], v[144:145], v[144:145]
	v_pk_mul_f32 v[254:255], v[146:147], v[146:147]
	v_pk_fma_f32 v[252:253], v[148:149], v[148:149], v[252:253]
	v_pk_fma_f32 v[254:255], v[150:151], v[150:151], v[254:255]
	v_pk_fma_f32 v[252:253], v[152:153], v[152:153], v[252:253]
	v_pk_fma_f32 v[254:255], v[154:155], v[154:155], v[254:255]
	v_pk_fma_f32 v[252:253], v[156:157], v[156:157], v[252:253]
	v_pk_fma_f32 v[254:255], v[158:159], v[158:159], v[254:255]
	v_pk_add_f32 v[252:253], v[252:253], v[254:255]
	s_nop 0
	v_add_f32_e32 v183, v252, v253
	s_nop 1
	v_add_f32_dpp v183, v183, v183 quad_perm:[1,0,3,2] row_mask:0xf bank_mask:0xf bound_ctrl:1
	s_nop 1
	v_add_f32_dpp v183, v183, v183 quad_perm:[2,3,0,1] row_mask:0xf bank_mask:0xf bound_ctrl:1
	s_nop 1
	v_add_f32_dpp v183, v183, v183 row_half_mirror row_mask:0xf bank_mask:0xf bound_ctrl:1
	s_nop 1
	v_add_f32_dpp v183, v183, v183 row_mirror row_mask:0xf bank_mask:0xf bound_ctrl:1
	s_nop 1
	v_readlane_b32 s98, v183, 0
	v_readlane_b32 s99, v183, 16
	v_readlane_b32 s100, v183, 32
	v_readlane_b32 s101, v183, 48
	s_nop 1
	v_mov_b32_e32 v183, s98
	v_add_f32_e32 v183, s99, v183
	v_add_f32_e32 v183, s100, v183
	v_add_f32_e32 v183, s101, v183
	v_fmamk_f32 v183, v183, 0x3a800000, v182
	v_cmp_gt_f32_e32 vcc, 0x800000, v183
	v_mul_f32_e32 v181, 0x4b800000, v183
	s_nop 1
	v_cndmask_b32_e32 v183, v183, v181, vcc
	v_rsq_f32_e32 v183, v183
	s_nop 0
	v_mul_f32_e32 v181, 0x45800000, v183
	v_cndmask_b32_e32 v184, v183, v181, vcc
	v_mov_b32_e32 v185, v184
	v_cvt_pk_bf16_f32 v32, v144, v145
	v_cvt_pk_bf16_f32 v33, v146, v147
	v_cvt_pk_bf16_f32 v34, v148, v149
	v_cvt_pk_bf16_f32 v35, v150, v151
	v_cvt_pk_bf16_f32 v36, v152, v153
	v_cvt_pk_bf16_f32 v37, v154, v155
	v_cvt_pk_bf16_f32 v38, v156, v157
	v_cvt_pk_bf16_f32 v39, v158, v159
	v_add_u32_e32 v181, 0x2000000, v177
	global_store_dwordx4 v181, v[32:35], s[78:79]
	global_store_dwordx4 v181, v[36:39], s[78:79] offset:1024
	v_add_u32_e32 v236, 0x4000, v237
	s_mov_b64 exec, 1
	global_store_dword v236, v184, s[78:79]
	s_mov_b64 exec, -1
	s_waitcnt vmcnt(16)
	v_lshlrev_b32_e32 v144, 16, v48
	v_and_b32_e32 v145, 0xffff0000, v48
	v_lshlrev_b32_e32 v146, 16, v49
	v_and_b32_e32 v147, 0xffff0000, v49
	v_lshlrev_b32_e32 v148, 16, v50
	v_and_b32_e32 v149, 0xffff0000, v50
	v_lshlrev_b32_e32 v150, 16, v51
	v_and_b32_e32 v151, 0xffff0000, v51
	v_lshlrev_b32_e32 v152, 16, v52
	v_and_b32_e32 v153, 0xffff0000, v52
	v_lshlrev_b32_e32 v154, 16, v53
	v_and_b32_e32 v155, 0xffff0000, v53
	v_lshlrev_b32_e32 v156, 16, v54
	v_and_b32_e32 v157, 0xffff0000, v54
	v_lshlrev_b32_e32 v158, 16, v55
	v_and_b32_e32 v159, 0xffff0000, v55
	v_lshlrev_b32_e32 v160, 16, v56
	v_and_b32_e32 v161, 0xffff0000, v56
	v_lshlrev_b32_e32 v162, 16, v57
	v_and_b32_e32 v163, 0xffff0000, v57
	v_lshlrev_b32_e32 v164, 16, v58
	v_and_b32_e32 v165, 0xffff0000, v58
	v_lshlrev_b32_e32 v166, 16, v59
	v_and_b32_e32 v167, 0xffff0000, v59
	v_lshlrev_b32_e32 v168, 16, v60
	v_and_b32_e32 v169, 0xffff0000, v60
	v_lshlrev_b32_e32 v170, 16, v61
	v_and_b32_e32 v171, 0xffff0000, v61
	v_lshlrev_b32_e32 v172, 16, v62
	v_and_b32_e32 v173, 0xffff0000, v62
	v_lshlrev_b32_e32 v174, 16, v63
	v_and_b32_e32 v175, 0xffff0000, v63
	v_pk_mul_f32 v[252:253], v[160:161], v[160:161]
	v_pk_mul_f32 v[254:255], v[162:163], v[162:163]
	v_pk_fma_f32 v[252:253], v[164:165], v[164:165], v[252:253]
	v_pk_fma_f32 v[254:255], v[166:167], v[166:167], v[254:255]
	v_pk_fma_f32 v[252:253], v[168:169], v[168:169], v[252:253]
	v_pk_fma_f32 v[254:255], v[170:171], v[170:171], v[254:255]
	v_pk_fma_f32 v[252:253], v[172:173], v[172:173], v[252:253]
	v_pk_fma_f32 v[254:255], v[174:175], v[174:175], v[254:255]
	v_pk_add_f32 v[252:253], v[252:253], v[254:255]
	s_nop 0
	v_add_f32_e32 v183, v252, v253
	s_nop 1
	v_add_f32_dpp v183, v183, v183 quad_perm:[1,0,3,2] row_mask:0xf bank_mask:0xf bound_ctrl:1
	s_nop 1
	v_add_f32_dpp v183, v183, v183 quad_perm:[2,3,0,1] row_mask:0xf bank_mask:0xf bound_ctrl:1
	s_nop 1
	v_add_f32_dpp v183, v183, v183 row_half_mirror row_mask:0xf bank_mask:0xf bound_ctrl:1
	s_nop 1
	v_add_f32_dpp v183, v183, v183 row_mirror row_mask:0xf bank_mask:0xf bound_ctrl:1
	s_nop 1
	v_readlane_b32 s98, v183, 0
	v_readlane_b32 s99, v183, 16
	v_readlane_b32 s100, v183, 32
	v_readlane_b32 s101, v183, 48
	s_nop 1
	v_mov_b32_e32 v183, s98
	v_add_f32_e32 v183, s99, v183
	v_add_f32_e32 v183, s100, v183
	v_add_f32_e32 v183, s101, v183
	v_fmamk_f32 v183, v183, 0x3a800000, v182
	v_cmp_gt_f32_e32 vcc, 0x800000, v183
	v_mul_f32_e32 v181, 0x4b800000, v183
	s_nop 1
	v_cndmask_b32_e32 v183, v183, v181, vcc
	v_rsq_f32_e32 v183, v183
	s_nop 0
	v_mul_f32_e32 v181, 0x45800000, v183
	v_cndmask_b32_e32 v184, v183, v181, vcc
	v_mov_b32_e32 v185, v184
	v_pk_mul_f32 v[160:161], v[160:161], v[184:185]
	v_pk_mul_f32 v[162:163], v[162:163], v[184:185]
	v_pk_mul_f32 v[164:165], v[164:165], v[184:185]
	v_pk_mul_f32 v[166:167], v[166:167], v[184:185]
	v_pk_mul_f32 v[168:169], v[168:169], v[184:185]
	v_pk_mul_f32 v[170:171], v[170:171], v[184:185]
	v_pk_mul_f32 v[172:173], v[172:173], v[184:185]
	v_pk_mul_f32 v[174:175], v[174:175], v[184:185]
	v_pk_fma_f32 v[144:145], v[160:161], v[128:129], v[144:145]
	v_pk_fma_f32 v[146:147], v[162:163], v[130:131], v[146:147]
	v_pk_fma_f32 v[148:149], v[164:165], v[132:133], v[148:149]
	v_pk_fma_f32 v[150:151], v[166:167], v[134:135], v[150:151]
	v_pk_fma_f32 v[152:153], v[168:169], v[136:137], v[152:153]
	v_pk_fma_f32 v[154:155], v[170:171], v[138:139], v[154:155]
	v_pk_fma_f32 v[156:157], v[172:173], v[140:141], v[156:157]
	v_pk_fma_f32 v[158:159], v[174:175], v[142:143], v[158:159]
	v_pk_mul_f32 v[252:253], v[144:145], v[144:145]
	v_pk_mul_f32 v[254:255], v[146:147], v[146:147]
	v_pk_fma_f32 v[252:253], v[148:149], v[148:149], v[252:253]
	v_pk_fma_f32 v[254:255], v[150:151], v[150:151], v[254:255]
	v_pk_fma_f32 v[252:253], v[152:153], v[152:153], v[252:253]
	v_pk_fma_f32 v[254:255], v[154:155], v[154:155], v[254:255]
	v_pk_fma_f32 v[252:253], v[156:157], v[156:157], v[252:253]
	v_pk_fma_f32 v[254:255], v[158:159], v[158:159], v[254:255]
	v_pk_add_f32 v[252:253], v[252:253], v[254:255]
	s_nop 0
	v_add_f32_e32 v183, v252, v253
	s_nop 1
	v_add_f32_dpp v183, v183, v183 quad_perm:[1,0,3,2] row_mask:0xf bank_mask:0xf bound_ctrl:1
	s_nop 1
	v_add_f32_dpp v183, v183, v183 quad_perm:[2,3,0,1] row_mask:0xf bank_mask:0xf bound_ctrl:1
	s_nop 1
	v_add_f32_dpp v183, v183, v183 row_half_mirror row_mask:0xf bank_mask:0xf bound_ctrl:1
	s_nop 1
	v_add_f32_dpp v183, v183, v183 row_mirror row_mask:0xf bank_mask:0xf bound_ctrl:1
	s_nop 1
	v_readlane_b32 s98, v183, 0
	v_readlane_b32 s99, v183, 16
	v_readlane_b32 s100, v183, 32
	v_readlane_b32 s101, v183, 48
	s_nop 1
	v_mov_b32_e32 v183, s98
	v_add_f32_e32 v183, s99, v183
	v_add_f32_e32 v183, s100, v183
	v_add_f32_e32 v183, s101, v183
	v_fmamk_f32 v183, v183, 0x3a800000, v182
	v_cmp_gt_f32_e32 vcc, 0x800000, v183
	v_mul_f32_e32 v181, 0x4b800000, v183
	s_nop 1
	v_cndmask_b32_e32 v183, v183, v181, vcc
	v_rsq_f32_e32 v183, v183
	s_nop 0
	v_mul_f32_e32 v181, 0x45800000, v183
	v_cndmask_b32_e32 v184, v183, v181, vcc
	v_mov_b32_e32 v185, v184
	v_cvt_pk_bf16_f32 v48, v144, v145
	v_cvt_pk_bf16_f32 v49, v146, v147
	v_cvt_pk_bf16_f32 v50, v148, v149
	v_cvt_pk_bf16_f32 v51, v150, v151
	v_cvt_pk_bf16_f32 v52, v152, v153
	v_cvt_pk_bf16_f32 v53, v154, v155
	v_cvt_pk_bf16_f32 v54, v156, v157
	v_cvt_pk_bf16_f32 v55, v158, v159
	v_add_u32_e32 v181, 0x2400000, v177
	global_store_dwordx4 v181, v[48:51], s[78:79]
	global_store_dwordx4 v181, v[52:55], s[78:79] offset:1024
	v_add_u32_e32 v236, 0x6000, v237
	s_mov_b64 exec, 1
	global_store_dword v236, v184, s[78:79]
	s_mov_b64 exec, -1
	s_waitcnt vmcnt(12)
	v_lshlrev_b32_e32 v144, 16, v64
	v_and_b32_e32 v145, 0xffff0000, v64
	v_lshlrev_b32_e32 v146, 16, v65
	v_and_b32_e32 v147, 0xffff0000, v65
	v_lshlrev_b32_e32 v148, 16, v66
	v_and_b32_e32 v149, 0xffff0000, v66
	v_lshlrev_b32_e32 v150, 16, v67
	v_and_b32_e32 v151, 0xffff0000, v67
	v_lshlrev_b32_e32 v152, 16, v68
	v_and_b32_e32 v153, 0xffff0000, v68
	v_lshlrev_b32_e32 v154, 16, v69
	v_and_b32_e32 v155, 0xffff0000, v69
	v_lshlrev_b32_e32 v156, 16, v70
	v_and_b32_e32 v157, 0xffff0000, v70
	v_lshlrev_b32_e32 v158, 16, v71
	v_and_b32_e32 v159, 0xffff0000, v71
	v_lshlrev_b32_e32 v160, 16, v72
	v_and_b32_e32 v161, 0xffff0000, v72
	v_lshlrev_b32_e32 v162, 16, v73
	v_and_b32_e32 v163, 0xffff0000, v73
	v_lshlrev_b32_e32 v164, 16, v74
	v_and_b32_e32 v165, 0xffff0000, v74
	v_lshlrev_b32_e32 v166, 16, v75
	v_and_b32_e32 v167, 0xffff0000, v75
	v_lshlrev_b32_e32 v168, 16, v76
	v_and_b32_e32 v169, 0xffff0000, v76
	v_lshlrev_b32_e32 v170, 16, v77
	v_and_b32_e32 v171, 0xffff0000, v77
	v_lshlrev_b32_e32 v172, 16, v78
	v_and_b32_e32 v173, 0xffff0000, v78
	v_lshlrev_b32_e32 v174, 16, v79
	v_and_b32_e32 v175, 0xffff0000, v79
	v_pk_mul_f32 v[252:253], v[160:161], v[160:161]
	v_pk_mul_f32 v[254:255], v[162:163], v[162:163]
	v_pk_fma_f32 v[252:253], v[164:165], v[164:165], v[252:253]
	v_pk_fma_f32 v[254:255], v[166:167], v[166:167], v[254:255]
	v_pk_fma_f32 v[252:253], v[168:169], v[168:169], v[252:253]
	v_pk_fma_f32 v[254:255], v[170:171], v[170:171], v[254:255]
	v_pk_fma_f32 v[252:253], v[172:173], v[172:173], v[252:253]
	v_pk_fma_f32 v[254:255], v[174:175], v[174:175], v[254:255]
	v_pk_add_f32 v[252:253], v[252:253], v[254:255]
	s_nop 0
	v_add_f32_e32 v183, v252, v253
	s_nop 1
	v_add_f32_dpp v183, v183, v183 quad_perm:[1,0,3,2] row_mask:0xf bank_mask:0xf bound_ctrl:1
	s_nop 1
	v_add_f32_dpp v183, v183, v183 quad_perm:[2,3,0,1] row_mask:0xf bank_mask:0xf bound_ctrl:1
	s_nop 1
	v_add_f32_dpp v183, v183, v183 row_half_mirror row_mask:0xf bank_mask:0xf bound_ctrl:1
	s_nop 1
	v_add_f32_dpp v183, v183, v183 row_mirror row_mask:0xf bank_mask:0xf bound_ctrl:1
	s_nop 1
	v_readlane_b32 s98, v183, 0
	v_readlane_b32 s99, v183, 16
	v_readlane_b32 s100, v183, 32
	v_readlane_b32 s101, v183, 48
	s_nop 1
	v_mov_b32_e32 v183, s98
	v_add_f32_e32 v183, s99, v183
	v_add_f32_e32 v183, s100, v183
	v_add_f32_e32 v183, s101, v183
	v_fmamk_f32 v183, v183, 0x3a800000, v182
	v_cmp_gt_f32_e32 vcc, 0x800000, v183
	v_mul_f32_e32 v181, 0x4b800000, v183
	s_nop 1
	v_cndmask_b32_e32 v183, v183, v181, vcc
	v_rsq_f32_e32 v183, v183
	s_nop 0
	v_mul_f32_e32 v181, 0x45800000, v183
	v_cndmask_b32_e32 v184, v183, v181, vcc
	v_mov_b32_e32 v185, v184
	v_pk_mul_f32 v[160:161], v[160:161], v[184:185]
	v_pk_mul_f32 v[162:163], v[162:163], v[184:185]
	v_pk_mul_f32 v[164:165], v[164:165], v[184:185]
	v_pk_mul_f32 v[166:167], v[166:167], v[184:185]
	v_pk_mul_f32 v[168:169], v[168:169], v[184:185]
	v_pk_mul_f32 v[170:171], v[170:171], v[184:185]
	v_pk_mul_f32 v[172:173], v[172:173], v[184:185]
	v_pk_mul_f32 v[174:175], v[174:175], v[184:185]
	v_pk_fma_f32 v[144:145], v[160:161], v[128:129], v[144:145]
	v_pk_fma_f32 v[146:147], v[162:163], v[130:131], v[146:147]
	v_pk_fma_f32 v[148:149], v[164:165], v[132:133], v[148:149]
	v_pk_fma_f32 v[150:151], v[166:167], v[134:135], v[150:151]
	v_pk_fma_f32 v[152:153], v[168:169], v[136:137], v[152:153]
	v_pk_fma_f32 v[154:155], v[170:171], v[138:139], v[154:155]
	v_pk_fma_f32 v[156:157], v[172:173], v[140:141], v[156:157]
	v_pk_fma_f32 v[158:159], v[174:175], v[142:143], v[158:159]
	v_pk_mul_f32 v[252:253], v[144:145], v[144:145]
	v_pk_mul_f32 v[254:255], v[146:147], v[146:147]
	v_pk_fma_f32 v[252:253], v[148:149], v[148:149], v[252:253]
	v_pk_fma_f32 v[254:255], v[150:151], v[150:151], v[254:255]
	v_pk_fma_f32 v[252:253], v[152:153], v[152:153], v[252:253]
	v_pk_fma_f32 v[254:255], v[154:155], v[154:155], v[254:255]
	v_pk_fma_f32 v[252:253], v[156:157], v[156:157], v[252:253]
	v_pk_fma_f32 v[254:255], v[158:159], v[158:159], v[254:255]
	v_pk_add_f32 v[252:253], v[252:253], v[254:255]
	s_nop 0
	v_add_f32_e32 v183, v252, v253
	s_nop 1
	v_add_f32_dpp v183, v183, v183 quad_perm:[1,0,3,2] row_mask:0xf bank_mask:0xf bound_ctrl:1
	s_nop 1
	v_add_f32_dpp v183, v183, v183 quad_perm:[2,3,0,1] row_mask:0xf bank_mask:0xf bound_ctrl:1
	s_nop 1
	v_add_f32_dpp v183, v183, v183 row_half_mirror row_mask:0xf bank_mask:0xf bound_ctrl:1
	s_nop 1
	v_add_f32_dpp v183, v183, v183 row_mirror row_mask:0xf bank_mask:0xf bound_ctrl:1
	s_nop 1
	v_readlane_b32 s98, v183, 0
	v_readlane_b32 s99, v183, 16
	v_readlane_b32 s100, v183, 32
	v_readlane_b32 s101, v183, 48
	s_nop 1
	v_mov_b32_e32 v183, s98
	v_add_f32_e32 v183, s99, v183
	v_add_f32_e32 v183, s100, v183
	v_add_f32_e32 v183, s101, v183
	v_fmamk_f32 v183, v183, 0x3a800000, v182
	v_cmp_gt_f32_e32 vcc, 0x800000, v183
	v_mul_f32_e32 v181, 0x4b800000, v183
	s_nop 1
	v_cndmask_b32_e32 v183, v183, v181, vcc
	v_rsq_f32_e32 v183, v183
	s_nop 0
	v_mul_f32_e32 v181, 0x45800000, v183
	v_cndmask_b32_e32 v184, v183, v181, vcc
	v_mov_b32_e32 v185, v184
	v_cvt_pk_bf16_f32 v64, v144, v145
	v_cvt_pk_bf16_f32 v65, v146, v147
	v_cvt_pk_bf16_f32 v66, v148, v149
	v_cvt_pk_bf16_f32 v67, v150, v151
	v_cvt_pk_bf16_f32 v68, v152, v153
	v_cvt_pk_bf16_f32 v69, v154, v155
	v_cvt_pk_bf16_f32 v70, v156, v157
	v_cvt_pk_bf16_f32 v71, v158, v159
	v_add_u32_e32 v181, 0x2800000, v177
	global_store_dwordx4 v181, v[64:67], s[78:79]
	global_store_dwordx4 v181, v[68:71], s[78:79] offset:1024
	v_add_u32_e32 v236, 0x8000, v237
	s_mov_b64 exec, 1
	global_store_dword v236, v184, s[78:79]
	s_mov_b64 exec, -1
	s_waitcnt vmcnt(8)
	v_lshlrev_b32_e32 v144, 16, v80
	v_and_b32_e32 v145, 0xffff0000, v80
	v_lshlrev_b32_e32 v146, 16, v81
	v_and_b32_e32 v147, 0xffff0000, v81
	v_lshlrev_b32_e32 v148, 16, v82
	v_and_b32_e32 v149, 0xffff0000, v82
	v_lshlrev_b32_e32 v150, 16, v83
	v_and_b32_e32 v151, 0xffff0000, v83
	v_lshlrev_b32_e32 v152, 16, v84
	v_and_b32_e32 v153, 0xffff0000, v84
	v_lshlrev_b32_e32 v154, 16, v85
	v_and_b32_e32 v155, 0xffff0000, v85
	v_lshlrev_b32_e32 v156, 16, v86
	v_and_b32_e32 v157, 0xffff0000, v86
	v_lshlrev_b32_e32 v158, 16, v87
	v_and_b32_e32 v159, 0xffff0000, v87
	v_lshlrev_b32_e32 v160, 16, v88
	v_and_b32_e32 v161, 0xffff0000, v88
	v_lshlrev_b32_e32 v162, 16, v89
	v_and_b32_e32 v163, 0xffff0000, v89
	v_lshlrev_b32_e32 v164, 16, v90
	v_and_b32_e32 v165, 0xffff0000, v90
	v_lshlrev_b32_e32 v166, 16, v91
	v_and_b32_e32 v167, 0xffff0000, v91
	v_lshlrev_b32_e32 v168, 16, v92
	v_and_b32_e32 v169, 0xffff0000, v92
	v_lshlrev_b32_e32 v170, 16, v93
	v_and_b32_e32 v171, 0xffff0000, v93
	v_lshlrev_b32_e32 v172, 16, v94
	v_and_b32_e32 v173, 0xffff0000, v94
	v_lshlrev_b32_e32 v174, 16, v95
	v_and_b32_e32 v175, 0xffff0000, v95
	v_pk_mul_f32 v[252:253], v[160:161], v[160:161]
	v_pk_mul_f32 v[254:255], v[162:163], v[162:163]
	v_pk_fma_f32 v[252:253], v[164:165], v[164:165], v[252:253]
	v_pk_fma_f32 v[254:255], v[166:167], v[166:167], v[254:255]
	v_pk_fma_f32 v[252:253], v[168:169], v[168:169], v[252:253]
	v_pk_fma_f32 v[254:255], v[170:171], v[170:171], v[254:255]
	v_pk_fma_f32 v[252:253], v[172:173], v[172:173], v[252:253]
	v_pk_fma_f32 v[254:255], v[174:175], v[174:175], v[254:255]
	v_pk_add_f32 v[252:253], v[252:253], v[254:255]
	s_nop 0
	v_add_f32_e32 v183, v252, v253
	s_nop 1
	v_add_f32_dpp v183, v183, v183 quad_perm:[1,0,3,2] row_mask:0xf bank_mask:0xf bound_ctrl:1
	s_nop 1
	v_add_f32_dpp v183, v183, v183 quad_perm:[2,3,0,1] row_mask:0xf bank_mask:0xf bound_ctrl:1
	s_nop 1
	v_add_f32_dpp v183, v183, v183 row_half_mirror row_mask:0xf bank_mask:0xf bound_ctrl:1
	s_nop 1
	v_add_f32_dpp v183, v183, v183 row_mirror row_mask:0xf bank_mask:0xf bound_ctrl:1
	s_nop 1
	v_readlane_b32 s98, v183, 0
	v_readlane_b32 s99, v183, 16
	v_readlane_b32 s100, v183, 32
	v_readlane_b32 s101, v183, 48
	s_nop 1
	v_mov_b32_e32 v183, s98
	v_add_f32_e32 v183, s99, v183
	v_add_f32_e32 v183, s100, v183
	v_add_f32_e32 v183, s101, v183
	v_fmamk_f32 v183, v183, 0x3a800000, v182
	v_cmp_gt_f32_e32 vcc, 0x800000, v183
	v_mul_f32_e32 v181, 0x4b800000, v183
	s_nop 1
	v_cndmask_b32_e32 v183, v183, v181, vcc
	v_rsq_f32_e32 v183, v183
	s_nop 0
	v_mul_f32_e32 v181, 0x45800000, v183
	v_cndmask_b32_e32 v184, v183, v181, vcc
	v_mov_b32_e32 v185, v184
	v_pk_mul_f32 v[160:161], v[160:161], v[184:185]
	v_pk_mul_f32 v[162:163], v[162:163], v[184:185]
	v_pk_mul_f32 v[164:165], v[164:165], v[184:185]
	v_pk_mul_f32 v[166:167], v[166:167], v[184:185]
	v_pk_mul_f32 v[168:169], v[168:169], v[184:185]
	v_pk_mul_f32 v[170:171], v[170:171], v[184:185]
	v_pk_mul_f32 v[172:173], v[172:173], v[184:185]
	v_pk_mul_f32 v[174:175], v[174:175], v[184:185]
	v_pk_fma_f32 v[144:145], v[160:161], v[128:129], v[144:145]
	v_pk_fma_f32 v[146:147], v[162:163], v[130:131], v[146:147]
	v_pk_fma_f32 v[148:149], v[164:165], v[132:133], v[148:149]
	v_pk_fma_f32 v[150:151], v[166:167], v[134:135], v[150:151]
	v_pk_fma_f32 v[152:153], v[168:169], v[136:137], v[152:153]
	v_pk_fma_f32 v[154:155], v[170:171], v[138:139], v[154:155]
	v_pk_fma_f32 v[156:157], v[172:173], v[140:141], v[156:157]
	v_pk_fma_f32 v[158:159], v[174:175], v[142:143], v[158:159]
	v_pk_mul_f32 v[252:253], v[144:145], v[144:145]
	v_pk_mul_f32 v[254:255], v[146:147], v[146:147]
	v_pk_fma_f32 v[252:253], v[148:149], v[148:149], v[252:253]
	v_pk_fma_f32 v[254:255], v[150:151], v[150:151], v[254:255]
	v_pk_fma_f32 v[252:253], v[152:153], v[152:153], v[252:253]
	v_pk_fma_f32 v[254:255], v[154:155], v[154:155], v[254:255]
	v_pk_fma_f32 v[252:253], v[156:157], v[156:157], v[252:253]
	v_pk_fma_f32 v[254:255], v[158:159], v[158:159], v[254:255]
	v_pk_add_f32 v[252:253], v[252:253], v[254:255]
	s_nop 0
	v_add_f32_e32 v183, v252, v253
	s_nop 1
	v_add_f32_dpp v183, v183, v183 quad_perm:[1,0,3,2] row_mask:0xf bank_mask:0xf bound_ctrl:1
	s_nop 1
	v_add_f32_dpp v183, v183, v183 quad_perm:[2,3,0,1] row_mask:0xf bank_mask:0xf bound_ctrl:1
	s_nop 1
	v_add_f32_dpp v183, v183, v183 row_half_mirror row_mask:0xf bank_mask:0xf bound_ctrl:1
	s_nop 1
	v_add_f32_dpp v183, v183, v183 row_mirror row_mask:0xf bank_mask:0xf bound_ctrl:1
	s_nop 1
	v_readlane_b32 s98, v183, 0
	v_readlane_b32 s99, v183, 16
	v_readlane_b32 s100, v183, 32
	v_readlane_b32 s101, v183, 48
	s_nop 1
	v_mov_b32_e32 v183, s98
	v_add_f32_e32 v183, s99, v183
	v_add_f32_e32 v183, s100, v183
	v_add_f32_e32 v183, s101, v183
	v_fmamk_f32 v183, v183, 0x3a800000, v182
	v_cmp_gt_f32_e32 vcc, 0x800000, v183
	v_mul_f32_e32 v181, 0x4b800000, v183
	s_nop 1
	v_cndmask_b32_e32 v183, v183, v181, vcc
	v_rsq_f32_e32 v183, v183
	s_nop 0
	v_mul_f32_e32 v181, 0x45800000, v183
	v_cndmask_b32_e32 v184, v183, v181, vcc
	v_mov_b32_e32 v185, v184
	v_cvt_pk_bf16_f32 v80, v144, v145
	v_cvt_pk_bf16_f32 v81, v146, v147
	v_cvt_pk_bf16_f32 v82, v148, v149
	v_cvt_pk_bf16_f32 v83, v150, v151
	v_cvt_pk_bf16_f32 v84, v152, v153
	v_cvt_pk_bf16_f32 v85, v154, v155
	v_cvt_pk_bf16_f32 v86, v156, v157
	v_cvt_pk_bf16_f32 v87, v158, v159
	v_add_u32_e32 v181, 0x2c00000, v177
	global_store_dwordx4 v181, v[80:83], s[78:79]
	global_store_dwordx4 v181, v[84:87], s[78:79] offset:1024
	v_add_u32_e32 v236, 0xa000, v237
	s_mov_b64 exec, 1
	global_store_dword v236, v184, s[78:79]
	s_mov_b64 exec, -1
	s_waitcnt vmcnt(4)
	v_lshlrev_b32_e32 v144, 16, v96
	v_and_b32_e32 v145, 0xffff0000, v96
	v_lshlrev_b32_e32 v146, 16, v97
	v_and_b32_e32 v147, 0xffff0000, v97
	v_lshlrev_b32_e32 v148, 16, v98
	v_and_b32_e32 v149, 0xffff0000, v98
	v_lshlrev_b32_e32 v150, 16, v99
	v_and_b32_e32 v151, 0xffff0000, v99
	v_lshlrev_b32_e32 v152, 16, v100
	v_and_b32_e32 v153, 0xffff0000, v100
	v_lshlrev_b32_e32 v154, 16, v101
	v_and_b32_e32 v155, 0xffff0000, v101
	v_lshlrev_b32_e32 v156, 16, v102
	v_and_b32_e32 v157, 0xffff0000, v102
	v_lshlrev_b32_e32 v158, 16, v103
	v_and_b32_e32 v159, 0xffff0000, v103
	v_lshlrev_b32_e32 v160, 16, v104
	v_and_b32_e32 v161, 0xffff0000, v104
	v_lshlrev_b32_e32 v162, 16, v105
	v_and_b32_e32 v163, 0xffff0000, v105
	v_lshlrev_b32_e32 v164, 16, v106
	v_and_b32_e32 v165, 0xffff0000, v106
	v_lshlrev_b32_e32 v166, 16, v107
	v_and_b32_e32 v167, 0xffff0000, v107
	v_lshlrev_b32_e32 v168, 16, v108
	v_and_b32_e32 v169, 0xffff0000, v108
	v_lshlrev_b32_e32 v170, 16, v109
	v_and_b32_e32 v171, 0xffff0000, v109
	v_lshlrev_b32_e32 v172, 16, v110
	v_and_b32_e32 v173, 0xffff0000, v110
	v_lshlrev_b32_e32 v174, 16, v111
	v_and_b32_e32 v175, 0xffff0000, v111
	v_pk_mul_f32 v[252:253], v[160:161], v[160:161]
	v_pk_mul_f32 v[254:255], v[162:163], v[162:163]
	v_pk_fma_f32 v[252:253], v[164:165], v[164:165], v[252:253]
	v_pk_fma_f32 v[254:255], v[166:167], v[166:167], v[254:255]
	v_pk_fma_f32 v[252:253], v[168:169], v[168:169], v[252:253]
	v_pk_fma_f32 v[254:255], v[170:171], v[170:171], v[254:255]
	v_pk_fma_f32 v[252:253], v[172:173], v[172:173], v[252:253]
	v_pk_fma_f32 v[254:255], v[174:175], v[174:175], v[254:255]
	v_pk_add_f32 v[252:253], v[252:253], v[254:255]
	s_nop 0
	v_add_f32_e32 v183, v252, v253
	s_nop 1
	v_add_f32_dpp v183, v183, v183 quad_perm:[1,0,3,2] row_mask:0xf bank_mask:0xf bound_ctrl:1
	s_nop 1
	v_add_f32_dpp v183, v183, v183 quad_perm:[2,3,0,1] row_mask:0xf bank_mask:0xf bound_ctrl:1
	s_nop 1
	v_add_f32_dpp v183, v183, v183 row_half_mirror row_mask:0xf bank_mask:0xf bound_ctrl:1
	s_nop 1
	v_add_f32_dpp v183, v183, v183 row_mirror row_mask:0xf bank_mask:0xf bound_ctrl:1
	s_nop 1
	v_readlane_b32 s98, v183, 0
	v_readlane_b32 s99, v183, 16
	v_readlane_b32 s100, v183, 32
	v_readlane_b32 s101, v183, 48
	s_nop 1
	v_mov_b32_e32 v183, s98
	v_add_f32_e32 v183, s99, v183
	v_add_f32_e32 v183, s100, v183
	v_add_f32_e32 v183, s101, v183
	v_fmamk_f32 v183, v183, 0x3a800000, v182
	v_cmp_gt_f32_e32 vcc, 0x800000, v183
	v_mul_f32_e32 v181, 0x4b800000, v183
	s_nop 1
	v_cndmask_b32_e32 v183, v183, v181, vcc
	v_rsq_f32_e32 v183, v183
	s_nop 0
	v_mul_f32_e32 v181, 0x45800000, v183
	v_cndmask_b32_e32 v184, v183, v181, vcc
	v_mov_b32_e32 v185, v184
	v_pk_mul_f32 v[160:161], v[160:161], v[184:185]
	v_pk_mul_f32 v[162:163], v[162:163], v[184:185]
	v_pk_mul_f32 v[164:165], v[164:165], v[184:185]
	v_pk_mul_f32 v[166:167], v[166:167], v[184:185]
	v_pk_mul_f32 v[168:169], v[168:169], v[184:185]
	v_pk_mul_f32 v[170:171], v[170:171], v[184:185]
	v_pk_mul_f32 v[172:173], v[172:173], v[184:185]
	v_pk_mul_f32 v[174:175], v[174:175], v[184:185]
	v_pk_fma_f32 v[144:145], v[160:161], v[128:129], v[144:145]
	v_pk_fma_f32 v[146:147], v[162:163], v[130:131], v[146:147]
	v_pk_fma_f32 v[148:149], v[164:165], v[132:133], v[148:149]
	v_pk_fma_f32 v[150:151], v[166:167], v[134:135], v[150:151]
	v_pk_fma_f32 v[152:153], v[168:169], v[136:137], v[152:153]
	v_pk_fma_f32 v[154:155], v[170:171], v[138:139], v[154:155]
	v_pk_fma_f32 v[156:157], v[172:173], v[140:141], v[156:157]
	v_pk_fma_f32 v[158:159], v[174:175], v[142:143], v[158:159]
	v_pk_mul_f32 v[252:253], v[144:145], v[144:145]
	v_pk_mul_f32 v[254:255], v[146:147], v[146:147]
	v_pk_fma_f32 v[252:253], v[148:149], v[148:149], v[252:253]
	v_pk_fma_f32 v[254:255], v[150:151], v[150:151], v[254:255]
	v_pk_fma_f32 v[252:253], v[152:153], v[152:153], v[252:253]
	v_pk_fma_f32 v[254:255], v[154:155], v[154:155], v[254:255]
	v_pk_fma_f32 v[252:253], v[156:157], v[156:157], v[252:253]
	v_pk_fma_f32 v[254:255], v[158:159], v[158:159], v[254:255]
	v_pk_add_f32 v[252:253], v[252:253], v[254:255]
	s_nop 0
	v_add_f32_e32 v183, v252, v253
	s_nop 1
	v_add_f32_dpp v183, v183, v183 quad_perm:[1,0,3,2] row_mask:0xf bank_mask:0xf bound_ctrl:1
	s_nop 1
	v_add_f32_dpp v183, v183, v183 quad_perm:[2,3,0,1] row_mask:0xf bank_mask:0xf bound_ctrl:1
	s_nop 1
	v_add_f32_dpp v183, v183, v183 row_half_mirror row_mask:0xf bank_mask:0xf bound_ctrl:1
	s_nop 1
	v_add_f32_dpp v183, v183, v183 row_mirror row_mask:0xf bank_mask:0xf bound_ctrl:1
	s_nop 1
	v_readlane_b32 s98, v183, 0
	v_readlane_b32 s99, v183, 16
	v_readlane_b32 s100, v183, 32
	v_readlane_b32 s101, v183, 48
	s_nop 1
	v_mov_b32_e32 v183, s98
	v_add_f32_e32 v183, s99, v183
	v_add_f32_e32 v183, s100, v183
	v_add_f32_e32 v183, s101, v183
	v_fmamk_f32 v183, v183, 0x3a800000, v182
	v_cmp_gt_f32_e32 vcc, 0x800000, v183
	v_mul_f32_e32 v181, 0x4b800000, v183
	s_nop 1
	v_cndmask_b32_e32 v183, v183, v181, vcc
	v_rsq_f32_e32 v183, v183
	s_nop 0
	v_mul_f32_e32 v181, 0x45800000, v183
	v_cndmask_b32_e32 v184, v183, v181, vcc
	v_mov_b32_e32 v185, v184
	v_cvt_pk_bf16_f32 v96, v144, v145
	v_cvt_pk_bf16_f32 v97, v146, v147
	v_cvt_pk_bf16_f32 v98, v148, v149
	v_cvt_pk_bf16_f32 v99, v150, v151
	v_cvt_pk_bf16_f32 v100, v152, v153
	v_cvt_pk_bf16_f32 v101, v154, v155
	v_cvt_pk_bf16_f32 v102, v156, v157
	v_cvt_pk_bf16_f32 v103, v158, v159
	v_add_u32_e32 v181, 0x3000000, v177
	global_store_dwordx4 v181, v[96:99], s[78:79]
	global_store_dwordx4 v181, v[100:103], s[78:79] offset:1024
	v_add_u32_e32 v236, 0xc000, v237
	s_mov_b64 exec, 1
	global_store_dword v236, v184, s[78:79]
	s_mov_b64 exec, -1
	s_waitcnt vmcnt(0)
	v_lshlrev_b32_e32 v144, 16, v112
	v_and_b32_e32 v145, 0xffff0000, v112
	v_lshlrev_b32_e32 v146, 16, v113
	v_and_b32_e32 v147, 0xffff0000, v113
	v_lshlrev_b32_e32 v148, 16, v114
	v_and_b32_e32 v149, 0xffff0000, v114
	v_lshlrev_b32_e32 v150, 16, v115
	v_and_b32_e32 v151, 0xffff0000, v115
	v_lshlrev_b32_e32 v152, 16, v116
	v_and_b32_e32 v153, 0xffff0000, v116
	v_lshlrev_b32_e32 v154, 16, v117
	v_and_b32_e32 v155, 0xffff0000, v117
	v_lshlrev_b32_e32 v156, 16, v118
	v_and_b32_e32 v157, 0xffff0000, v118
	v_lshlrev_b32_e32 v158, 16, v119
	v_and_b32_e32 v159, 0xffff0000, v119
	v_lshlrev_b32_e32 v160, 16, v120
	v_and_b32_e32 v161, 0xffff0000, v120
	v_lshlrev_b32_e32 v162, 16, v121
	v_and_b32_e32 v163, 0xffff0000, v121
	v_lshlrev_b32_e32 v164, 16, v122
	v_and_b32_e32 v165, 0xffff0000, v122
	v_lshlrev_b32_e32 v166, 16, v123
	v_and_b32_e32 v167, 0xffff0000, v123
	v_lshlrev_b32_e32 v168, 16, v124
	v_and_b32_e32 v169, 0xffff0000, v124
	v_lshlrev_b32_e32 v170, 16, v125
	v_and_b32_e32 v171, 0xffff0000, v125
	v_lshlrev_b32_e32 v172, 16, v126
	v_and_b32_e32 v173, 0xffff0000, v126
	v_lshlrev_b32_e32 v174, 16, v127
	v_and_b32_e32 v175, 0xffff0000, v127
	v_pk_mul_f32 v[252:253], v[160:161], v[160:161]
	v_pk_mul_f32 v[254:255], v[162:163], v[162:163]
	v_pk_fma_f32 v[252:253], v[164:165], v[164:165], v[252:253]
	v_pk_fma_f32 v[254:255], v[166:167], v[166:167], v[254:255]
	v_pk_fma_f32 v[252:253], v[168:169], v[168:169], v[252:253]
	v_pk_fma_f32 v[254:255], v[170:171], v[170:171], v[254:255]
	v_pk_fma_f32 v[252:253], v[172:173], v[172:173], v[252:253]
	v_pk_fma_f32 v[254:255], v[174:175], v[174:175], v[254:255]
	v_pk_add_f32 v[252:253], v[252:253], v[254:255]
	s_nop 0
	v_add_f32_e32 v183, v252, v253
	s_nop 1
	v_add_f32_dpp v183, v183, v183 quad_perm:[1,0,3,2] row_mask:0xf bank_mask:0xf bound_ctrl:1
	s_nop 1
	v_add_f32_dpp v183, v183, v183 quad_perm:[2,3,0,1] row_mask:0xf bank_mask:0xf bound_ctrl:1
	s_nop 1
	v_add_f32_dpp v183, v183, v183 row_half_mirror row_mask:0xf bank_mask:0xf bound_ctrl:1
	s_nop 1
	v_add_f32_dpp v183, v183, v183 row_mirror row_mask:0xf bank_mask:0xf bound_ctrl:1
	s_nop 1
	v_readlane_b32 s98, v183, 0
	v_readlane_b32 s99, v183, 16
	v_readlane_b32 s100, v183, 32
	v_readlane_b32 s101, v183, 48
	s_nop 1
	v_mov_b32_e32 v183, s98
	v_add_f32_e32 v183, s99, v183
	v_add_f32_e32 v183, s100, v183
	v_add_f32_e32 v183, s101, v183
	v_fmamk_f32 v183, v183, 0x3a800000, v182
	v_cmp_gt_f32_e32 vcc, 0x800000, v183
	v_mul_f32_e32 v181, 0x4b800000, v183
	s_nop 1
	v_cndmask_b32_e32 v183, v183, v181, vcc
	v_rsq_f32_e32 v183, v183
	s_nop 0
	v_mul_f32_e32 v181, 0x45800000, v183
	v_cndmask_b32_e32 v184, v183, v181, vcc
	v_mov_b32_e32 v185, v184
	v_pk_mul_f32 v[160:161], v[160:161], v[184:185]
	v_pk_mul_f32 v[162:163], v[162:163], v[184:185]
	v_pk_mul_f32 v[164:165], v[164:165], v[184:185]
	v_pk_mul_f32 v[166:167], v[166:167], v[184:185]
	v_pk_mul_f32 v[168:169], v[168:169], v[184:185]
	v_pk_mul_f32 v[170:171], v[170:171], v[184:185]
	v_pk_mul_f32 v[172:173], v[172:173], v[184:185]
	v_pk_mul_f32 v[174:175], v[174:175], v[184:185]
	v_pk_fma_f32 v[144:145], v[160:161], v[128:129], v[144:145]
	v_pk_fma_f32 v[146:147], v[162:163], v[130:131], v[146:147]
	v_pk_fma_f32 v[148:149], v[164:165], v[132:133], v[148:149]
	v_pk_fma_f32 v[150:151], v[166:167], v[134:135], v[150:151]
	v_pk_fma_f32 v[152:153], v[168:169], v[136:137], v[152:153]
	v_pk_fma_f32 v[154:155], v[170:171], v[138:139], v[154:155]
	v_pk_fma_f32 v[156:157], v[172:173], v[140:141], v[156:157]
	v_pk_fma_f32 v[158:159], v[174:175], v[142:143], v[158:159]
	v_pk_mul_f32 v[252:253], v[144:145], v[144:145]
	v_pk_mul_f32 v[254:255], v[146:147], v[146:147]
	v_pk_fma_f32 v[252:253], v[148:149], v[148:149], v[252:253]
	v_pk_fma_f32 v[254:255], v[150:151], v[150:151], v[254:255]
	v_pk_fma_f32 v[252:253], v[152:153], v[152:153], v[252:253]
	v_pk_fma_f32 v[254:255], v[154:155], v[154:155], v[254:255]
	v_pk_fma_f32 v[252:253], v[156:157], v[156:157], v[252:253]
	v_pk_fma_f32 v[254:255], v[158:159], v[158:159], v[254:255]
	v_pk_add_f32 v[252:253], v[252:253], v[254:255]
	s_nop 0
	v_add_f32_e32 v183, v252, v253
	s_nop 1
	v_add_f32_dpp v183, v183, v183 quad_perm:[1,0,3,2] row_mask:0xf bank_mask:0xf bound_ctrl:1
	s_nop 1
	v_add_f32_dpp v183, v183, v183 quad_perm:[2,3,0,1] row_mask:0xf bank_mask:0xf bound_ctrl:1
	s_nop 1
	v_add_f32_dpp v183, v183, v183 row_half_mirror row_mask:0xf bank_mask:0xf bound_ctrl:1
	s_nop 1
	v_add_f32_dpp v183, v183, v183 row_mirror row_mask:0xf bank_mask:0xf bound_ctrl:1
	s_nop 1
	v_readlane_b32 s98, v183, 0
	v_readlane_b32 s99, v183, 16
	v_readlane_b32 s100, v183, 32
	v_readlane_b32 s101, v183, 48
	s_nop 1
	v_mov_b32_e32 v183, s98
	v_add_f32_e32 v183, s99, v183
	v_add_f32_e32 v183, s100, v183
	v_add_f32_e32 v183, s101, v183
	v_fmamk_f32 v183, v183, 0x3a800000, v182
	v_cmp_gt_f32_e32 vcc, 0x800000, v183
	v_mul_f32_e32 v181, 0x4b800000, v183
	s_nop 1
	v_cndmask_b32_e32 v183, v183, v181, vcc
	v_rsq_f32_e32 v183, v183
	s_nop 0
	v_mul_f32_e32 v181, 0x45800000, v183
	v_cndmask_b32_e32 v184, v183, v181, vcc
	v_mov_b32_e32 v185, v184
	v_cvt_pk_bf16_f32 v112, v144, v145
	v_cvt_pk_bf16_f32 v113, v146, v147
	v_cvt_pk_bf16_f32 v114, v148, v149
	v_cvt_pk_bf16_f32 v115, v150, v151
	v_cvt_pk_bf16_f32 v116, v152, v153
	v_cvt_pk_bf16_f32 v117, v154, v155
	v_cvt_pk_bf16_f32 v118, v156, v157
	v_cvt_pk_bf16_f32 v119, v158, v159
	v_add_u32_e32 v181, 0x3400000, v177
	global_store_dwordx4 v181, v[112:115], s[78:79]
	global_store_dwordx4 v181, v[116:119], s[78:79] offset:1024
	v_add_u32_e32 v236, 0xe000, v237
	s_mov_b64 exec, 1
	global_store_dword v236, v184, s[78:79]
	s_mov_b64 exec, -1
	v_readfirstlane_b32 s98, v179
	s_nop 3
	s_cmp_ge_u32 s98, 512
	s_cbranch_scc1 .Lmyxupd_done_6
	v_lshlrev_b32_e32 v177, 4, v176
	v_lshl_add_u32 v177, v179, 11, v177
	v_lshlrev_b32_e32 v237, 2, v179
	v_add_u32_e32 v237, 0x10000, v237
	v_add_u32_e32 v181, 0x3800000, v177
	global_load_dwordx4 v[0:3], v181, s[78:79]
	global_load_dwordx4 v[4:7], v181, s[78:79] offset:1024
	v_lshl_add_u32 v183, v179, 12, v180
	v_add_u32_e32 v183, 0xbf00000, v183
	v_add_u32_e32 v181, 0x0, v183
	global_load_dwordx4 v[8:11], v181, s[78:79]
	global_load_dwordx4 v[12:15], v181, s[78:79] offset:16
	global_load_dwordx4 v[16:19], v181, s[78:79] offset:2048
	global_load_dwordx4 v[20:23], v181, s[78:79] offset:2064
	v_add_u32_e32 v181, 0x200000, v183
	global_load_dwordx4 v[24:27], v181, s[78:79]
	global_load_dwordx4 v[28:31], v181, s[78:79] offset:16
	global_load_dwordx4 v[32:35], v181, s[78:79] offset:2048
	global_load_dwordx4 v[36:39], v181, s[78:79] offset:2064
	v_add_u32_e32 v181, 0x400000, v183
	global_load_dwordx4 v[40:43], v181, s[78:79]
	global_load_dwordx4 v[44:47], v181, s[78:79] offset:16
	global_load_dwordx4 v[48:51], v181, s[78:79] offset:2048
	global_load_dwordx4 v[52:55], v181, s[78:79] offset:2064
	v_add_u32_e32 v181, 0x600000, v183
	global_load_dwordx4 v[56:59], v181, s[78:79]
	global_load_dwordx4 v[60:63], v181, s[78:79] offset:16
	global_load_dwordx4 v[64:67], v181, s[78:79] offset:2048
	global_load_dwordx4 v[68:71], v181, s[78:79] offset:2064
	v_add_u32_e32 v181, 0x800000, v183
	global_load_dwordx4 v[72:75], v181, s[78:79]
	global_load_dwordx4 v[76:79], v181, s[78:79] offset:16
	global_load_dwordx4 v[80:83], v181, s[78:79] offset:2048
	global_load_dwordx4 v[84:87], v181, s[78:79] offset:2064
	v_add_u32_e32 v181, 0xa00000, v183
	global_load_dwordx4 v[88:91], v181, s[78:79]
	global_load_dwordx4 v[92:95], v181, s[78:79] offset:16
	global_load_dwordx4 v[96:99], v181, s[78:79] offset:2048
	global_load_dwordx4 v[100:103], v181, s[78:79] offset:2064
	s_waitcnt vmcnt(20)
	v_pk_add_f32 v[160:161], v[8:9], 0 op_sel_hi:[1,0]
	v_pk_add_f32 v[162:163], v[10:11], 0 op_sel_hi:[1,0]
	v_pk_add_f32 v[164:165], v[12:13], 0 op_sel_hi:[1,0]
	v_pk_add_f32 v[166:167], v[14:15], 0 op_sel_hi:[1,0]
	v_pk_add_f32 v[168:169], v[16:17], 0 op_sel_hi:[1,0]
	v_pk_add_f32 v[170:171], v[18:19], 0 op_sel_hi:[1,0]
	v_pk_add_f32 v[172:173], v[20:21], 0 op_sel_hi:[1,0]
	v_pk_add_f32 v[174:175], v[22:23], 0 op_sel_hi:[1,0]
	s_waitcnt vmcnt(16)
	v_pk_add_f32 v[160:161], v[160:161], v[24:25]
	v_pk_add_f32 v[162:163], v[162:163], v[26:27]
	v_pk_add_f32 v[164:165], v[164:165], v[28:29]
	v_pk_add_f32 v[166:167], v[166:167], v[30:31]
	v_pk_add_f32 v[168:169], v[168:169], v[32:33]
	v_pk_add_f32 v[170:171], v[170:171], v[34:35]
	v_pk_add_f32 v[172:173], v[172:173], v[36:37]
	v_pk_add_f32 v[174:175], v[174:175], v[38:39]
	s_waitcnt vmcnt(12)
	v_pk_add_f32 v[160:161], v[160:161], v[40:41]
	v_pk_add_f32 v[162:163], v[162:163], v[42:43]
	v_pk_add_f32 v[164:165], v[164:165], v[44:45]
	v_pk_add_f32 v[166:167], v[166:167], v[46:47]
	v_pk_add_f32 v[168:169], v[168:169], v[48:49]
	v_pk_add_f32 v[170:171], v[170:171], v[50:51]
	v_pk_add_f32 v[172:173], v[172:173], v[52:53]
	v_pk_add_f32 v[174:175], v[174:175], v[54:55]
	s_waitcnt vmcnt(8)
	v_pk_add_f32 v[160:161], v[160:161], v[56:57]
	v_pk_add_f32 v[162:163], v[162:163], v[58:59]
	v_pk_add_f32 v[164:165], v[164:165], v[60:61]
	v_pk_add_f32 v[166:167], v[166:167], v[62:63]
	v_pk_add_f32 v[168:169], v[168:169], v[64:65]
	v_pk_add_f32 v[170:171], v[170:171], v[66:67]
	v_pk_add_f32 v[172:173], v[172:173], v[68:69]
	v_pk_add_f32 v[174:175], v[174:175], v[70:71]
	s_waitcnt vmcnt(4)
	v_pk_add_f32 v[160:161], v[160:161], v[72:73]
	v_pk_add_f32 v[162:163], v[162:163], v[74:75]
	v_pk_add_f32 v[164:165], v[164:165], v[76:77]
	v_pk_add_f32 v[166:167], v[166:167], v[78:79]
	v_pk_add_f32 v[168:169], v[168:169], v[80:81]
	v_pk_add_f32 v[170:171], v[170:171], v[82:83]
	v_pk_add_f32 v[172:173], v[172:173], v[84:85]
	v_pk_add_f32 v[174:175], v[174:175], v[86:87]
	s_waitcnt vmcnt(0)
	v_pk_add_f32 v[160:161], v[160:161], v[88:89]
	v_pk_add_f32 v[162:163], v[162:163], v[90:91]
	v_pk_add_f32 v[164:165], v[164:165], v[92:93]
	v_pk_add_f32 v[166:167], v[166:167], v[94:95]
	v_pk_add_f32 v[168:169], v[168:169], v[96:97]
	v_pk_add_f32 v[170:171], v[170:171], v[98:99]
	v_pk_add_f32 v[172:173], v[172:173], v[100:101]
	v_pk_add_f32 v[174:175], v[174:175], v[102:103]
	v_lshlrev_b32_e32 v144, 16, v0
	v_and_b32_e32 v145, 0xffff0000, v0
	v_lshlrev_b32_e32 v146, 16, v1
	v_and_b32_e32 v147, 0xffff0000, v1
	v_lshlrev_b32_e32 v148, 16, v2
	v_and_b32_e32 v149, 0xffff0000, v2
	v_lshlrev_b32_e32 v150, 16, v3
	v_and_b32_e32 v151, 0xffff0000, v3
	v_lshlrev_b32_e32 v152, 16, v4
	v_and_b32_e32 v153, 0xffff0000, v4
	v_lshlrev_b32_e32 v154, 16, v5
	v_and_b32_e32 v155, 0xffff0000, v5
	v_lshlrev_b32_e32 v156, 16, v6
	v_and_b32_e32 v157, 0xffff0000, v6
	v_lshlrev_b32_e32 v158, 16, v7
	v_and_b32_e32 v159, 0xffff0000, v7
	v_add_u32_e32 v181, 0xc00000, v183
	global_load_dwordx4 v[8:11], v181, s[78:79]
	global_load_dwordx4 v[12:15], v181, s[78:79] offset:16
	global_load_dwordx4 v[16:19], v181, s[78:79] offset:2048
	global_load_dwordx4 v[20:23], v181, s[78:79] offset:2064
	v_add_u32_e32 v181, 0xe00000, v183
	global_load_dwordx4 v[24:27], v181, s[78:79]
	global_load_dwordx4 v[28:31], v181, s[78:79] offset:16
	global_load_dwordx4 v[32:35], v181, s[78:79] offset:2048
	global_load_dwordx4 v[36:39], v181, s[78:79] offset:2064
	s_waitcnt vmcnt(4)
	v_pk_add_f32 v[160:161], v[160:161], v[8:9]
	v_pk_add_f32 v[162:163], v[162:163], v[10:11]
	v_pk_add_f32 v[164:165], v[164:165], v[12:13]
	v_pk_add_f32 v[166:167], v[166:167], v[14:15]
	v_pk_add_f32 v[168:169], v[168:169], v[16:17]
	v_pk_add_f32 v[170:171], v[170:171], v[18:19]
	v_pk_add_f32 v[172:173], v[172:173], v[20:21]
	v_pk_add_f32 v[174:175], v[174:175], v[22:23]
	s_waitcnt vmcnt(0)
	v_pk_add_f32 v[160:161], v[160:161], v[24:25]
	v_pk_add_f32 v[162:163], v[162:163], v[26:27]
	v_pk_add_f32 v[164:165], v[164:165], v[28:29]
	v_pk_add_f32 v[166:167], v[166:167], v[30:31]
	v_pk_add_f32 v[168:169], v[168:169], v[32:33]
	v_pk_add_f32 v[170:171], v[170:171], v[34:35]
	v_pk_add_f32 v[172:173], v[172:173], v[36:37]
	v_pk_add_f32 v[174:175], v[174:175], v[38:39]
	v_pk_mul_f32 v[252:253], v[160:161], v[160:161]
	v_pk_mul_f32 v[254:255], v[162:163], v[162:163]
	v_pk_fma_f32 v[252:253], v[164:165], v[164:165], v[252:253]
	v_pk_fma_f32 v[254:255], v[166:167], v[166:167], v[254:255]
	v_pk_fma_f32 v[252:253], v[168:169], v[168:169], v[252:253]
	v_pk_fma_f32 v[254:255], v[170:171], v[170:171], v[254:255]
	v_pk_fma_f32 v[252:253], v[172:173], v[172:173], v[252:253]
	v_pk_fma_f32 v[254:255], v[174:175], v[174:175], v[254:255]
	v_pk_add_f32 v[252:253], v[252:253], v[254:255]
	s_nop 0
	v_add_f32_e32 v183, v252, v253
	s_nop 1
	v_add_f32_dpp v183, v183, v183 quad_perm:[1,0,3,2] row_mask:0xf bank_mask:0xf bound_ctrl:1
	s_nop 1
	v_add_f32_dpp v183, v183, v183 quad_perm:[2,3,0,1] row_mask:0xf bank_mask:0xf bound_ctrl:1
	s_nop 1
	v_add_f32_dpp v183, v183, v183 row_half_mirror row_mask:0xf bank_mask:0xf bound_ctrl:1
	s_nop 1
	v_add_f32_dpp v183, v183, v183 row_mirror row_mask:0xf bank_mask:0xf bound_ctrl:1
	s_nop 1
	v_readlane_b32 s98, v183, 0
	v_readlane_b32 s99, v183, 16
	v_readlane_b32 s100, v183, 32
	v_readlane_b32 s101, v183, 48
	s_nop 1
	v_mov_b32_e32 v183, s98
	v_add_f32_e32 v183, s99, v183
	v_add_f32_e32 v183, s100, v183
	v_add_f32_e32 v183, s101, v183
	v_fmamk_f32 v183, v183, 0x3a800000, v182
	v_cmp_gt_f32_e32 vcc, 0x800000, v183
	v_mul_f32_e32 v181, 0x4b800000, v183
	s_nop 1
	v_cndmask_b32_e32 v183, v183, v181, vcc
	v_rsq_f32_e32 v183, v183
	s_nop 0
	v_mul_f32_e32 v181, 0x45800000, v183
	v_cndmask_b32_e32 v184, v183, v181, vcc
	v_mov_b32_e32 v185, v184
	v_pk_mul_f32 v[160:161], v[160:161], v[184:185]
	v_pk_mul_f32 v[162:163], v[162:163], v[184:185]
	v_pk_mul_f32 v[164:165], v[164:165], v[184:185]
	v_pk_mul_f32 v[166:167], v[166:167], v[184:185]
	v_pk_mul_f32 v[168:169], v[168:169], v[184:185]
	v_pk_mul_f32 v[170:171], v[170:171], v[184:185]
	v_pk_mul_f32 v[172:173], v[172:173], v[184:185]
	v_pk_mul_f32 v[174:175], v[174:175], v[184:185]
	v_pk_fma_f32 v[144:145], v[160:161], v[128:129], v[144:145]
	v_pk_fma_f32 v[146:147], v[162:163], v[130:131], v[146:147]
	v_pk_fma_f32 v[148:149], v[164:165], v[132:133], v[148:149]
	v_pk_fma_f32 v[150:151], v[166:167], v[134:135], v[150:151]
	v_pk_fma_f32 v[152:153], v[168:169], v[136:137], v[152:153]
	v_pk_fma_f32 v[154:155], v[170:171], v[138:139], v[154:155]
	v_pk_fma_f32 v[156:157], v[172:173], v[140:141], v[156:157]
	v_pk_fma_f32 v[158:159], v[174:175], v[142:143], v[158:159]
	v_pk_mul_f32 v[252:253], v[144:145], v[144:145]
	v_pk_mul_f32 v[254:255], v[146:147], v[146:147]
	v_pk_fma_f32 v[252:253], v[148:149], v[148:149], v[252:253]
	v_pk_fma_f32 v[254:255], v[150:151], v[150:151], v[254:255]
	v_pk_fma_f32 v[252:253], v[152:153], v[152:153], v[252:253]
	v_pk_fma_f32 v[254:255], v[154:155], v[154:155], v[254:255]
	v_pk_fma_f32 v[252:253], v[156:157], v[156:157], v[252:253]
	v_pk_fma_f32 v[254:255], v[158:159], v[158:159], v[254:255]
	v_pk_add_f32 v[252:253], v[252:253], v[254:255]
	s_nop 0
	v_add_f32_e32 v183, v252, v253
	s_nop 1
	v_add_f32_dpp v183, v183, v183 quad_perm:[1,0,3,2] row_mask:0xf bank_mask:0xf bound_ctrl:1
	s_nop 1
	v_add_f32_dpp v183, v183, v183 quad_perm:[2,3,0,1] row_mask:0xf bank_mask:0xf bound_ctrl:1
	s_nop 1
	v_add_f32_dpp v183, v183, v183 row_half_mirror row_mask:0xf bank_mask:0xf bound_ctrl:1
	s_nop 1
	v_add_f32_dpp v183, v183, v183 row_mirror row_mask:0xf bank_mask:0xf bound_ctrl:1
	s_nop 1
	v_readlane_b32 s98, v183, 0
	v_readlane_b32 s99, v183, 16
	v_readlane_b32 s100, v183, 32
	v_readlane_b32 s101, v183, 48
	s_nop 1
	v_mov_b32_e32 v183, s98
	v_add_f32_e32 v183, s99, v183
	v_add_f32_e32 v183, s100, v183
	v_add_f32_e32 v183, s101, v183
	v_fmamk_f32 v183, v183, 0x3a800000, v182
	v_cmp_gt_f32_e32 vcc, 0x800000, v183
	v_mul_f32_e32 v181, 0x4b800000, v183
	s_nop 1
	v_cndmask_b32_e32 v183, v183, v181, vcc
	v_rsq_f32_e32 v183, v183
	s_nop 0
	v_mul_f32_e32 v181, 0x45800000, v183
	v_cndmask_b32_e32 v184, v183, v181, vcc
	v_mov_b32_e32 v185, v184
	v_cvt_pk_bf16_f32 v0, v144, v145
	v_cvt_pk_bf16_f32 v1, v146, v147
	v_cvt_pk_bf16_f32 v2, v148, v149
	v_cvt_pk_bf16_f32 v3, v150, v151
	v_cvt_pk_bf16_f32 v4, v152, v153
	v_cvt_pk_bf16_f32 v5, v154, v155
	v_cvt_pk_bf16_f32 v6, v156, v157
	v_cvt_pk_bf16_f32 v7, v158, v159
	v_add_u32_e32 v181, 0x3800000, v177
	global_store_dwordx4 v181, v[0:3], s[78:79]
	global_store_dwordx4 v181, v[4:7], s[78:79] offset:1024
	v_add_u32_e32 v236, 0x10000, v237
	s_mov_b64 exec, 1
	global_store_dword v236, v184, s[78:79]
	s_mov_b64 exec, -1

.LBB0_2849:
	v_readlane_b32 s0, v235, 52
	v_readlane_b32 s1, v235, 53
	s_and_b64 vcc, exec, s[0:1]
	s_waitcnt lgkmcnt(0)
	s_barrier
	v_mbcnt_lo_u32_b32 v0, -1, 0
	v_mbcnt_hi_u32_b32 v0, -1, v0
	s_cbranch_vccnz .LBB0_2864
	v_lshlrev_b32_e32 v0, 3, v0
	v_ashrrev_i32_e32 v1, 31, v0
	v_readlane_b32 s0, v235, 4
	v_lshlrev_b64 v[2:3], 1, v[0:1]
	v_lshlrev_b64 v[0:1], 2, v[0:1]
	v_readlane_b32 s1, v235, 5
	v_readlane_b32 s14, v235, 18
	v_readlane_b32 s15, v235, 19
	s_mov_b64 s[0:1], 0x3000
	v_readlane_b32 s2, v235, 6
	v_lshl_add_u64 v[4:5], s[14:15], 0, v[0:1]
	v_readlane_b32 s4, v235, 8
	v_readlane_b32 s5, v235, 9
	v_lshl_add_u64 v[50:51], v[4:5], 0, s[0:1]
	v_readlane_b32 s0, v235, 0
	s_ashr_i32 s25, s24, 31
	s_lshl_b32 s0, s0, 4
	s_add_i32 s2, s24, 0xffffc000
	s_lshl_b64 s[4:5], s[24:25], 11
	s_add_u32 s4, s78, s4
	v_readlane_b32 s1, v235, 1
	s_addc_u32 s5, s79, s5
	v_lshl_add_u64 v[44:45], s[86:87], 0, v[2:3]
	v_lshl_add_u64 v[48:49], s[54:55], 0, v[2:3]
	v_readlane_b32 s6, v235, 10
	v_readlane_b32 s7, v235, 11
	v_lshl_add_u64 v[2:3], s[4:5], 0, v[2:3]
	s_mov_b64 s[4:5], 0x9e00000
	s_ashr_i32 s1, s0, 31
	v_lshl_add_u64 v[56:57], v[2:3], 0, s[4:5]
	s_lshl_b64 s[4:5], s[0:1], 11
	s_lshl_b64 s[6:7], s[24:25], 12
	s_add_u32 s6, s76, s6
	s_addc_u32 s7, s77, s7
	v_lshl_add_u64 v[46:47], s[90:91], 0, v[0:1]
	v_readlane_b32 s3, v235, 7
	v_readlane_b32 s8, v235, 12
	v_readlane_b32 s9, v235, 13
	v_readlane_b32 s10, v235, 14
	v_readlane_b32 s11, v235, 15
	v_readlane_b32 s12, v235, 16
	v_readlane_b32 s13, v235, 17
	v_lshl_add_u64 v[52:53], s[74:75], 0, v[0:1]
	v_lshl_add_u64 v[54:55], s[76:77], 0, v[0:1]
	v_lshl_add_u64 v[0:1], s[6:7], 0, v[0:1]
	s_mov_b64 s[6:7], 0x810
	v_lshl_add_u64 v[58:59], v[0:1], 0, s[6:7]
	s_lshl_b64 s[6:7], s[0:1], 12
	s_mov_b32 s3, 0
	s_mov_b64 s[8:9], 0x200000
	s_mov_b64 s[10:11], 0x200800
	s_mov_b64 s[12:13], 0x400000
	s_mov_b64 s[14:15], 0x400800
	s_mov_b64 s[16:17], 0x600000
	s_mov_b64 s[18:19], 0x600800
	s_mov_b64 s[20:21], 0x800000
	s_mov_b32 s1, 0x800000
	s_mov_b64 s[22:23], 0x800800
	s_mov_b64 s[24:25], 0xa00000
	s_mov_b64 s[26:27], 0xa00800
	s_mov_b64 s[28:29], 0xc00000
	s_mov_b64 s[30:31], 0xc00800
	s_mov_b64 s[34:35], 0xe00000
	s_mov_b64 s[36:37], 0xe00800
	s_mov_b64 s[38:39], 0x1000000
	s_mov_b32 s60, 0x1000000
	s_mov_b64 s[40:41], 0x1000800
	s_mov_b64 s[42:43], 0x1200000
	s_mov_b32 s61, 0x1200000
	s_mov_b64 s[44:45], 0x1200800
	s_mov_b64 s[46:47], 0x1400000
	s_mov_b32 s62, 0x1400000
	s_mov_b64 s[48:49], 0x1400800
	v_mov_b32_e32 v100, 0x358637bd
	v_mbcnt_lo_u32_b32 v176, -1, 0
	v_mbcnt_hi_u32_b32 v176, -1, v176
	v_readlane_b32 s98, v235, 49
	v_readlane_b32 s99, v235, 20
	v_readlane_b32 s100, v235, 18
	v_readlane_b32 s101, v235, 19
	s_nop 3
	s_lshr_b32 vcc_lo, s98, 3
	s_and_b32 vcc_hi, vcc_lo, 7
	s_lshr_b32 vcc_lo, vcc_lo, 3
	s_lshl_b32 vcc_lo, vcc_lo, 3
	s_add_i32 vcc_lo, vcc_lo, s99
	s_lshl_b32 s98, vcc_hi, 8
	s_add_i32 s98, s98, vcc_lo
	s_mov_b32 s99, s98
	v_mov_b32_e32 v183, s99
	v_lshlrev_b32_e32 v177, 4, v176
	s_lshl_b32 s99, s99, 11
	v_add_u32_e32 v177, s99, v177
	v_add_u32_e32 v178, 0x1800000, v177
	v_add_u32_e32 v179, 0x9e00000, v177
	v_lshlrev_b32_e32 v180, 5, v176
	v_add_u32_e32 v181, 0x3000, v180
	global_load_dwordx4 v[128:131], v181, s[100:101]
	global_load_dwordx4 v[132:135], v181, s[100:101] offset:16
	global_load_dwordx4 v[136:139], v181, s[100:101] offset:2048
	global_load_dwordx4 v[140:143], v181, s[100:101] offset:2064
	global_load_dwordx4 v[236:239], v180, s[74:75]
	global_load_dwordx4 v[240:243], v180, s[74:75] offset:16
	global_load_dwordx4 v[244:247], v180, s[74:75] offset:2048
	global_load_dwordx4 v[248:251], v180, s[74:75] offset:2064
	v_mov_b32_e32 v182, 0x358637bd
	global_load_dwordx4 v[0:3], v178, s[78:79]
	global_load_dwordx4 v[4:7], v178, s[78:79] offset:1024
	global_load_dwordx4 v[8:11], v179, s[78:79]
	global_load_dwordx4 v[12:15], v179, s[78:79] offset:1024
	v_add_u32_e32 v178, 0x400000, v178
	v_add_u32_e32 v179, 0x400000, v179
	global_load_dwordx4 v[16:19], v178, s[78:79]
	global_load_dwordx4 v[20:23], v178, s[78:79] offset:1024
	global_load_dwordx4 v[24:27], v179, s[78:79]
	global_load_dwordx4 v[28:31], v179, s[78:79] offset:1024
	v_add_u32_e32 v178, 0x400000, v178
	v_add_u32_e32 v179, 0x400000, v179
	global_load_dwordx4 v[32:35], v178, s[78:79]
	global_load_dwordx4 v[36:39], v178, s[78:79] offset:1024
	global_load_dwordx4 v[40:43], v179, s[78:79]
	global_load_dwordx4 v[44:47], v179, s[78:79] offset:1024
	v_add_u32_e32 v178, 0x400000, v178
	v_add_u32_e32 v179, 0x400000, v179
	global_load_dwordx4 v[48:51], v178, s[78:79]
	global_load_dwordx4 v[52:55], v178, s[78:79] offset:1024
	global_load_dwordx4 v[56:59], v179, s[78:79]
	global_load_dwordx4 v[60:63], v179, s[78:79] offset:1024
	v_add_u32_e32 v178, 0x400000, v178
	v_add_u32_e32 v179, 0x400000, v179
	global_load_dwordx4 v[64:67], v178, s[78:79]
	global_load_dwordx4 v[68:71], v178, s[78:79] offset:1024
	global_load_dwordx4 v[72:75], v179, s[78:79]
	global_load_dwordx4 v[76:79], v179, s[78:79] offset:1024
	v_add_u32_e32 v178, 0x400000, v178
	v_add_u32_e32 v179, 0x400000, v179
	global_load_dwordx4 v[80:83], v178, s[78:79]
	global_load_dwordx4 v[84:87], v178, s[78:79] offset:1024
	global_load_dwordx4 v[88:91], v179, s[78:79]
	global_load_dwordx4 v[92:95], v179, s[78:79] offset:1024
	v_add_u32_e32 v178, 0x400000, v178
	v_add_u32_e32 v179, 0x400000, v179
	global_load_dwordx4 v[96:99], v178, s[78:79]
	global_load_dwordx4 v[100:103], v178, s[78:79] offset:1024
	global_load_dwordx4 v[104:107], v179, s[78:79]
	global_load_dwordx4 v[108:111], v179, s[78:79] offset:1024
	v_add_u32_e32 v178, 0x400000, v178
	v_add_u32_e32 v179, 0x400000, v179
	global_load_dwordx4 v[112:115], v178, s[78:79]
	global_load_dwordx4 v[116:119], v178, s[78:79] offset:1024
	global_load_dwordx4 v[120:123], v179, s[78:79]
	global_load_dwordx4 v[124:127], v179, s[78:79] offset:1024
	v_lshl_add_u32 v178, v183, 12, v180
	v_mov_b32_e32 v179, s98
	s_waitcnt vmcnt(28)
	v_lshlrev_b32_e32 v144, 16, v0
	v_and_b32_e32 v145, 0xffff0000, v0
	v_lshlrev_b32_e32 v146, 16, v1
	v_and_b32_e32 v147, 0xffff0000, v1
	v_lshlrev_b32_e32 v148, 16, v2
	v_and_b32_e32 v149, 0xffff0000, v2
	v_lshlrev_b32_e32 v150, 16, v3
	v_and_b32_e32 v151, 0xffff0000, v3
	v_lshlrev_b32_e32 v152, 16, v4
	v_and_b32_e32 v153, 0xffff0000, v4
	v_lshlrev_b32_e32 v154, 16, v5
	v_and_b32_e32 v155, 0xffff0000, v5
	v_lshlrev_b32_e32 v156, 16, v6
	v_and_b32_e32 v157, 0xffff0000, v6
	v_lshlrev_b32_e32 v158, 16, v7
	v_and_b32_e32 v159, 0xffff0000, v7
	v_lshlrev_b32_e32 v160, 16, v8
	v_and_b32_e32 v161, 0xffff0000, v8
	v_lshlrev_b32_e32 v162, 16, v9
	v_and_b32_e32 v163, 0xffff0000, v9
	v_lshlrev_b32_e32 v164, 16, v10
	v_and_b32_e32 v165, 0xffff0000, v10
	v_lshlrev_b32_e32 v166, 16, v11
	v_and_b32_e32 v167, 0xffff0000, v11
	v_lshlrev_b32_e32 v168, 16, v12
	v_and_b32_e32 v169, 0xffff0000, v12
	v_lshlrev_b32_e32 v170, 16, v13
	v_and_b32_e32 v171, 0xffff0000, v13
	v_lshlrev_b32_e32 v172, 16, v14
	v_and_b32_e32 v173, 0xffff0000, v14
	v_lshlrev_b32_e32 v174, 16, v15
	v_and_b32_e32 v175, 0xffff0000, v15
	v_pk_mul_f32 v[252:253], v[160:161], v[160:161]
	v_pk_mul_f32 v[254:255], v[162:163], v[162:163]
	v_pk_fma_f32 v[252:253], v[164:165], v[164:165], v[252:253]
	v_pk_fma_f32 v[254:255], v[166:167], v[166:167], v[254:255]
	v_pk_fma_f32 v[252:253], v[168:169], v[168:169], v[252:253]
	v_pk_fma_f32 v[254:255], v[170:171], v[170:171], v[254:255]
	v_pk_fma_f32 v[252:253], v[172:173], v[172:173], v[252:253]
	v_pk_fma_f32 v[254:255], v[174:175], v[174:175], v[254:255]
	v_pk_add_f32 v[252:253], v[252:253], v[254:255]
	s_nop 0
	v_add_f32_e32 v183, v252, v253
	s_nop 1
	v_add_f32_dpp v183, v183, v183 quad_perm:[1,0,3,2] row_mask:0xf bank_mask:0xf bound_ctrl:1
	s_nop 1
	v_add_f32_dpp v183, v183, v183 quad_perm:[2,3,0,1] row_mask:0xf bank_mask:0xf bound_ctrl:1
	s_nop 1
	v_add_f32_dpp v183, v183, v183 row_half_mirror row_mask:0xf bank_mask:0xf bound_ctrl:1
	s_nop 1
	v_add_f32_dpp v183, v183, v183 row_mirror row_mask:0xf bank_mask:0xf bound_ctrl:1
	s_nop 1
	v_readlane_b32 s98, v183, 0
	v_readlane_b32 s99, v183, 16
	v_readlane_b32 s100, v183, 32
	v_readlane_b32 s101, v183, 48
	s_nop 1
	v_mov_b32_e32 v183, s98
	v_add_f32_e32 v183, s99, v183
	v_add_f32_e32 v183, s100, v183
	v_add_f32_e32 v183, s101, v183
	v_fmamk_f32 v183, v183, 0x3a800000, v182
	v_cmp_gt_f32_e32 vcc, 0x800000, v183
	v_mul_f32_e32 v181, 0x4b800000, v183
	s_nop 1
	v_cndmask_b32_e32 v183, v183, v181, vcc
	v_rsq_f32_e32 v183, v183
	s_nop 0
	v_mul_f32_e32 v181, 0x45800000, v183
	v_cndmask_b32_e32 v184, v183, v181, vcc
	v_mov_b32_e32 v185, v184
	v_pk_mul_f32 v[160:161], v[160:161], v[184:185]
	v_pk_mul_f32 v[162:163], v[162:163], v[184:185]
	v_pk_mul_f32 v[164:165], v[164:165], v[184:185]
	v_pk_mul_f32 v[166:167], v[166:167], v[184:185]
	v_pk_mul_f32 v[168:169], v[168:169], v[184:185]
	v_pk_mul_f32 v[170:171], v[170:171], v[184:185]
	v_pk_mul_f32 v[172:173], v[172:173], v[184:185]
	v_pk_mul_f32 v[174:175], v[174:175], v[184:185]
	v_pk_fma_f32 v[144:145], v[160:161], v[128:129], v[144:145]
	v_pk_fma_f32 v[146:147], v[162:163], v[130:131], v[146:147]
	v_pk_fma_f32 v[148:149], v[164:165], v[132:133], v[148:149]
	v_pk_fma_f32 v[150:151], v[166:167], v[134:135], v[150:151]
	v_pk_fma_f32 v[152:153], v[168:169], v[136:137], v[152:153]
	v_pk_fma_f32 v[154:155], v[170:171], v[138:139], v[154:155]
	v_pk_fma_f32 v[156:157], v[172:173], v[140:141], v[156:157]
	v_pk_fma_f32 v[158:159], v[174:175], v[142:143], v[158:159]
	v_pk_mul_f32 v[252:253], v[144:145], v[144:145]
	v_pk_mul_f32 v[254:255], v[146:147], v[146:147]
	v_pk_fma_f32 v[252:253], v[148:149], v[148:149], v[252:253]
	v_pk_fma_f32 v[254:255], v[150:151], v[150:151], v[254:255]
	v_pk_fma_f32 v[252:253], v[152:153], v[152:153], v[252:253]
	v_pk_fma_f32 v[254:255], v[154:155], v[154:155], v[254:255]
	v_pk_fma_f32 v[252:253], v[156:157], v[156:157], v[252:253]
	v_pk_fma_f32 v[254:255], v[158:159], v[158:159], v[254:255]
	v_pk_add_f32 v[252:253], v[252:253], v[254:255]
	s_nop 0
	v_add_f32_e32 v183, v252, v253
	s_nop 1
	v_add_f32_dpp v183, v183, v183 quad_perm:[1,0,3,2] row_mask:0xf bank_mask:0xf bound_ctrl:1
	s_nop 1
	v_add_f32_dpp v183, v183, v183 quad_perm:[2,3,0,1] row_mask:0xf bank_mask:0xf bound_ctrl:1
	s_nop 1
	v_add_f32_dpp v183, v183, v183 row_half_mirror row_mask:0xf bank_mask:0xf bound_ctrl:1
	s_nop 1
	v_add_f32_dpp v183, v183, v183 row_mirror row_mask:0xf bank_mask:0xf bound_ctrl:1
	s_nop 1
	v_readlane_b32 s98, v183, 0
	v_readlane_b32 s99, v183, 16
	v_readlane_b32 s100, v183, 32
	v_readlane_b32 s101, v183, 48
	s_nop 1
	v_mov_b32_e32 v183, s98
	v_add_f32_e32 v183, s99, v183
	v_add_f32_e32 v183, s100, v183
	v_add_f32_e32 v183, s101, v183
	v_fmamk_f32 v183, v183, 0x3a800000, v182
	v_cmp_gt_f32_e32 vcc, 0x800000, v183
	v_mul_f32_e32 v181, 0x4b800000, v183
	s_nop 1
	v_cndmask_b32_e32 v183, v183, v181, vcc
	v_rsq_f32_e32 v183, v183
	s_nop 0
	v_mul_f32_e32 v181, 0x45800000, v183
	v_cndmask_b32_e32 v184, v183, v181, vcc
	v_mov_b32_e32 v185, v184
	v_pk_mul_f32 v[144:145], v[144:145], v[184:185]
	v_pk_mul_f32 v[146:147], v[146:147], v[184:185]
	v_pk_mul_f32 v[148:149], v[148:149], v[184:185]
	v_pk_mul_f32 v[150:151], v[150:151], v[184:185]
	v_pk_mul_f32 v[152:153], v[152:153], v[184:185]
	v_pk_mul_f32 v[154:155], v[154:155], v[184:185]
	v_pk_mul_f32 v[156:157], v[156:157], v[184:185]
	v_pk_mul_f32 v[158:159], v[158:159], v[184:185]
	v_pk_mul_f32 v[144:145], v[144:145], v[236:237]
	v_pk_mul_f32 v[146:147], v[146:147], v[238:239]
	v_pk_mul_f32 v[148:149], v[148:149], v[240:241]
	v_pk_mul_f32 v[150:151], v[150:151], v[242:243]
	v_pk_mul_f32 v[152:153], v[152:153], v[244:245]
	v_pk_mul_f32 v[154:155], v[154:155], v[246:247]
	v_pk_mul_f32 v[156:157], v[156:157], v[248:249]
	v_pk_mul_f32 v[158:159], v[158:159], v[250:251]
	v_add_u32_e32 v181, 0x0, v178
	global_store_dwordx4 v181, v[144:147], s[76:77]
	global_store_dwordx4 v181, v[148:151], s[76:77] offset:16
	global_store_dwordx4 v181, v[152:155], s[76:77] offset:2048
	global_store_dwordx4 v181, v[156:159], s[76:77] offset:2064
	s_nop 1
	s_waitcnt vmcnt(24)
	v_lshlrev_b32_e32 v144, 16, v16
	v_and_b32_e32 v145, 0xffff0000, v16
	v_lshlrev_b32_e32 v146, 16, v17
	v_and_b32_e32 v147, 0xffff0000, v17
	v_lshlrev_b32_e32 v148, 16, v18
	v_and_b32_e32 v149, 0xffff0000, v18
	v_lshlrev_b32_e32 v150, 16, v19
	v_and_b32_e32 v151, 0xffff0000, v19
	v_lshlrev_b32_e32 v152, 16, v20
	v_and_b32_e32 v153, 0xffff0000, v20
	v_lshlrev_b32_e32 v154, 16, v21
	v_and_b32_e32 v155, 0xffff0000, v21
	v_lshlrev_b32_e32 v156, 16, v22
	v_and_b32_e32 v157, 0xffff0000, v22
	v_lshlrev_b32_e32 v158, 16, v23
	v_and_b32_e32 v159, 0xffff0000, v23
	v_lshlrev_b32_e32 v160, 16, v24
	v_and_b32_e32 v161, 0xffff0000, v24
	v_lshlrev_b32_e32 v162, 16, v25
	v_and_b32_e32 v163, 0xffff0000, v25
	v_lshlrev_b32_e32 v164, 16, v26
	v_and_b32_e32 v165, 0xffff0000, v26
	v_lshlrev_b32_e32 v166, 16, v27
	v_and_b32_e32 v167, 0xffff0000, v27
	v_lshlrev_b32_e32 v168, 16, v28
	v_and_b32_e32 v169, 0xffff0000, v28
	v_lshlrev_b32_e32 v170, 16, v29
	v_and_b32_e32 v171, 0xffff0000, v29
	v_lshlrev_b32_e32 v172, 16, v30
	v_and_b32_e32 v173, 0xffff0000, v30
	v_lshlrev_b32_e32 v174, 16, v31
	v_and_b32_e32 v175, 0xffff0000, v31
	v_pk_mul_f32 v[252:253], v[160:161], v[160:161]
	v_pk_mul_f32 v[254:255], v[162:163], v[162:163]
	v_pk_fma_f32 v[252:253], v[164:165], v[164:165], v[252:253]
	v_pk_fma_f32 v[254:255], v[166:167], v[166:167], v[254:255]
	v_pk_fma_f32 v[252:253], v[168:169], v[168:169], v[252:253]
	v_pk_fma_f32 v[254:255], v[170:171], v[170:171], v[254:255]
	v_pk_fma_f32 v[252:253], v[172:173], v[172:173], v[252:253]
	v_pk_fma_f32 v[254:255], v[174:175], v[174:175], v[254:255]
	v_pk_add_f32 v[252:253], v[252:253], v[254:255]
	s_nop 0
	v_add_f32_e32 v183, v252, v253
	s_nop 1
	v_add_f32_dpp v183, v183, v183 quad_perm:[1,0,3,2] row_mask:0xf bank_mask:0xf bound_ctrl:1
	s_nop 1
	v_add_f32_dpp v183, v183, v183 quad_perm:[2,3,0,1] row_mask:0xf bank_mask:0xf bound_ctrl:1
	s_nop 1
	v_add_f32_dpp v183, v183, v183 row_half_mirror row_mask:0xf bank_mask:0xf bound_ctrl:1
	s_nop 1
	v_add_f32_dpp v183, v183, v183 row_mirror row_mask:0xf bank_mask:0xf bound_ctrl:1
	s_nop 1
	v_readlane_b32 s98, v183, 0
	v_readlane_b32 s99, v183, 16
	v_readlane_b32 s100, v183, 32
	v_readlane_b32 s101, v183, 48
	s_nop 1
	v_mov_b32_e32 v183, s98
	v_add_f32_e32 v183, s99, v183
	v_add_f32_e32 v183, s100, v183
	v_add_f32_e32 v183, s101, v183
	v_fmamk_f32 v183, v183, 0x3a800000, v182
	v_cmp_gt_f32_e32 vcc, 0x800000, v183
	v_mul_f32_e32 v181, 0x4b800000, v183
	s_nop 1
	v_cndmask_b32_e32 v183, v183, v181, vcc
	v_rsq_f32_e32 v183, v183
	s_nop 0
	v_mul_f32_e32 v181, 0x45800000, v183
	v_cndmask_b32_e32 v184, v183, v181, vcc
	v_mov_b32_e32 v185, v184
	v_pk_mul_f32 v[160:161], v[160:161], v[184:185]
	v_pk_mul_f32 v[162:163], v[162:163], v[184:185]
	v_pk_mul_f32 v[164:165], v[164:165], v[184:185]
	v_pk_mul_f32 v[166:167], v[166:167], v[184:185]
	v_pk_mul_f32 v[168:169], v[168:169], v[184:185]
	v_pk_mul_f32 v[170:171], v[170:171], v[184:185]
	v_pk_mul_f32 v[172:173], v[172:173], v[184:185]
	v_pk_mul_f32 v[174:175], v[174:175], v[184:185]
	v_pk_fma_f32 v[144:145], v[160:161], v[128:129], v[144:145]
	v_pk_fma_f32 v[146:147], v[162:163], v[130:131], v[146:147]
	v_pk_fma_f32 v[148:149], v[164:165], v[132:133], v[148:149]
	v_pk_fma_f32 v[150:151], v[166:167], v[134:135], v[150:151]
	v_pk_fma_f32 v[152:153], v[168:169], v[136:137], v[152:153]
	v_pk_fma_f32 v[154:155], v[170:171], v[138:139], v[154:155]
	v_pk_fma_f32 v[156:157], v[172:173], v[140:141], v[156:157]
	v_pk_fma_f32 v[158:159], v[174:175], v[142:143], v[158:159]
	v_pk_mul_f32 v[252:253], v[144:145], v[144:145]
	v_pk_mul_f32 v[254:255], v[146:147], v[146:147]
	v_pk_fma_f32 v[252:253], v[148:149], v[148:149], v[252:253]
	v_pk_fma_f32 v[254:255], v[150:151], v[150:151], v[254:255]
	v_pk_fma_f32 v[252:253], v[152:153], v[152:153], v[252:253]
	v_pk_fma_f32 v[254:255], v[154:155], v[154:155], v[254:255]
	v_pk_fma_f32 v[252:253], v[156:157], v[156:157], v[252:253]
	v_pk_fma_f32 v[254:255], v[158:159], v[158:159], v[254:255]
	v_pk_add_f32 v[252:253], v[252:253], v[254:255]
	s_nop 0
	v_add_f32_e32 v183, v252, v253
	s_nop 1
	v_add_f32_dpp v183, v183, v183 quad_perm:[1,0,3,2] row_mask:0xf bank_mask:0xf bound_ctrl:1
	s_nop 1
	v_add_f32_dpp v183, v183, v183 quad_perm:[2,3,0,1] row_mask:0xf bank_mask:0xf bound_ctrl:1
	s_nop 1
	v_add_f32_dpp v183, v183, v183 row_half_mirror row_mask:0xf bank_mask:0xf bound_ctrl:1
	s_nop 1
	v_add_f32_dpp v183, v183, v183 row_mirror row_mask:0xf bank_mask:0xf bound_ctrl:1
	s_nop 1
	v_readlane_b32 s98, v183, 0
	v_readlane_b32 s99, v183, 16
	v_readlane_b32 s100, v183, 32
	v_readlane_b32 s101, v183, 48
	s_nop 1
	v_mov_b32_e32 v183, s98
	v_add_f32_e32 v183, s99, v183
	v_add_f32_e32 v183, s100, v183
	v_add_f32_e32 v183, s101, v183
	v_fmamk_f32 v183, v183, 0x3a800000, v182
	v_cmp_gt_f32_e32 vcc, 0x800000, v183
	v_mul_f32_e32 v181, 0x4b800000, v183
	s_nop 1
	v_cndmask_b32_e32 v183, v183, v181, vcc
	v_rsq_f32_e32 v183, v183
	s_nop 0
	v_mul_f32_e32 v181, 0x45800000, v183
	v_cndmask_b32_e32 v184, v183, v181, vcc
	v_mov_b32_e32 v185, v184
	v_pk_mul_f32 v[144:145], v[144:145], v[184:185]
	v_pk_mul_f32 v[146:147], v[146:147], v[184:185]
	v_pk_mul_f32 v[148:149], v[148:149], v[184:185]
	v_pk_mul_f32 v[150:151], v[150:151], v[184:185]
	v_pk_mul_f32 v[152:153], v[152:153], v[184:185]
	v_pk_mul_f32 v[154:155], v[154:155], v[184:185]
	v_pk_mul_f32 v[156:157], v[156:157], v[184:185]
	v_pk_mul_f32 v[158:159], v[158:159], v[184:185]
	v_pk_mul_f32 v[144:145], v[144:145], v[236:237]
	v_pk_mul_f32 v[146:147], v[146:147], v[238:239]
	v_pk_mul_f32 v[148:149], v[148:149], v[240:241]
	v_pk_mul_f32 v[150:151], v[150:151], v[242:243]
	v_pk_mul_f32 v[152:153], v[152:153], v[244:245]
	v_pk_mul_f32 v[154:155], v[154:155], v[246:247]
	v_pk_mul_f32 v[156:157], v[156:157], v[248:249]
	v_pk_mul_f32 v[158:159], v[158:159], v[250:251]
	v_add_u32_e32 v181, 0x800000, v178
	global_store_dwordx4 v181, v[144:147], s[76:77]
	global_store_dwordx4 v181, v[148:151], s[76:77] offset:16
	global_store_dwordx4 v181, v[152:155], s[76:77] offset:2048
	global_store_dwordx4 v181, v[156:159], s[76:77] offset:2064
	s_nop 1
	s_waitcnt vmcnt(20)
	v_lshlrev_b32_e32 v144, 16, v32
	v_and_b32_e32 v145, 0xffff0000, v32
	v_lshlrev_b32_e32 v146, 16, v33
	v_and_b32_e32 v147, 0xffff0000, v33
	v_lshlrev_b32_e32 v148, 16, v34
	v_and_b32_e32 v149, 0xffff0000, v34
	v_lshlrev_b32_e32 v150, 16, v35
	v_and_b32_e32 v151, 0xffff0000, v35
	v_lshlrev_b32_e32 v152, 16, v36
	v_and_b32_e32 v153, 0xffff0000, v36
	v_lshlrev_b32_e32 v154, 16, v37
	v_and_b32_e32 v155, 0xffff0000, v37
	v_lshlrev_b32_e32 v156, 16, v38
	v_and_b32_e32 v157, 0xffff0000, v38
	v_lshlrev_b32_e32 v158, 16, v39
	v_and_b32_e32 v159, 0xffff0000, v39
	v_lshlrev_b32_e32 v160, 16, v40
	v_and_b32_e32 v161, 0xffff0000, v40
	v_lshlrev_b32_e32 v162, 16, v41
	v_and_b32_e32 v163, 0xffff0000, v41
	v_lshlrev_b32_e32 v164, 16, v42
	v_and_b32_e32 v165, 0xffff0000, v42
	v_lshlrev_b32_e32 v166, 16, v43
	v_and_b32_e32 v167, 0xffff0000, v43
	v_lshlrev_b32_e32 v168, 16, v44
	v_and_b32_e32 v169, 0xffff0000, v44
	v_lshlrev_b32_e32 v170, 16, v45
	v_and_b32_e32 v171, 0xffff0000, v45
	v_lshlrev_b32_e32 v172, 16, v46
	v_and_b32_e32 v173, 0xffff0000, v46
	v_lshlrev_b32_e32 v174, 16, v47
	v_and_b32_e32 v175, 0xffff0000, v47
	v_pk_mul_f32 v[252:253], v[160:161], v[160:161]
	v_pk_mul_f32 v[254:255], v[162:163], v[162:163]
	v_pk_fma_f32 v[252:253], v[164:165], v[164:165], v[252:253]
	v_pk_fma_f32 v[254:255], v[166:167], v[166:167], v[254:255]
	v_pk_fma_f32 v[252:253], v[168:169], v[168:169], v[252:253]
	v_pk_fma_f32 v[254:255], v[170:171], v[170:171], v[254:255]
	v_pk_fma_f32 v[252:253], v[172:173], v[172:173], v[252:253]
	v_pk_fma_f32 v[254:255], v[174:175], v[174:175], v[254:255]
	v_pk_add_f32 v[252:253], v[252:253], v[254:255]
	s_nop 0
	v_add_f32_e32 v183, v252, v253
	s_nop 1
	v_add_f32_dpp v183, v183, v183 quad_perm:[1,0,3,2] row_mask:0xf bank_mask:0xf bound_ctrl:1
	s_nop 1
	v_add_f32_dpp v183, v183, v183 quad_perm:[2,3,0,1] row_mask:0xf bank_mask:0xf bound_ctrl:1
	s_nop 1
	v_add_f32_dpp v183, v183, v183 row_half_mirror row_mask:0xf bank_mask:0xf bound_ctrl:1
	s_nop 1
	v_add_f32_dpp v183, v183, v183 row_mirror row_mask:0xf bank_mask:0xf bound_ctrl:1
	s_nop 1
	v_readlane_b32 s98, v183, 0
	v_readlane_b32 s99, v183, 16
	v_readlane_b32 s100, v183, 32
	v_readlane_b32 s101, v183, 48
	s_nop 1
	v_mov_b32_e32 v183, s98
	v_add_f32_e32 v183, s99, v183
	v_add_f32_e32 v183, s100, v183
	v_add_f32_e32 v183, s101, v183
	v_fmamk_f32 v183, v183, 0x3a800000, v182
	v_cmp_gt_f32_e32 vcc, 0x800000, v183
	v_mul_f32_e32 v181, 0x4b800000, v183
	s_nop 1
	v_cndmask_b32_e32 v183, v183, v181, vcc
	v_rsq_f32_e32 v183, v183
	s_nop 0
	v_mul_f32_e32 v181, 0x45800000, v183
	v_cndmask_b32_e32 v184, v183, v181, vcc
	v_mov_b32_e32 v185, v184
	v_pk_mul_f32 v[160:161], v[160:161], v[184:185]
	v_pk_mul_f32 v[162:163], v[162:163], v[184:185]
	v_pk_mul_f32 v[164:165], v[164:165], v[184:185]
	v_pk_mul_f32 v[166:167], v[166:167], v[184:185]
	v_pk_mul_f32 v[168:169], v[168:169], v[184:185]
	v_pk_mul_f32 v[170:171], v[170:171], v[184:185]
	v_pk_mul_f32 v[172:173], v[172:173], v[184:185]
	v_pk_mul_f32 v[174:175], v[174:175], v[184:185]
	v_pk_fma_f32 v[144:145], v[160:161], v[128:129], v[144:145]
	v_pk_fma_f32 v[146:147], v[162:163], v[130:131], v[146:147]
	v_pk_fma_f32 v[148:149], v[164:165], v[132:133], v[148:149]
	v_pk_fma_f32 v[150:151], v[166:167], v[134:135], v[150:151]
	v_pk_fma_f32 v[152:153], v[168:169], v[136:137], v[152:153]
	v_pk_fma_f32 v[154:155], v[170:171], v[138:139], v[154:155]
	v_pk_fma_f32 v[156:157], v[172:173], v[140:141], v[156:157]
	v_pk_fma_f32 v[158:159], v[174:175], v[142:143], v[158:159]
	v_pk_mul_f32 v[252:253], v[144:145], v[144:145]
	v_pk_mul_f32 v[254:255], v[146:147], v[146:147]
	v_pk_fma_f32 v[252:253], v[148:149], v[148:149], v[252:253]
	v_pk_fma_f32 v[254:255], v[150:151], v[150:151], v[254:255]
	v_pk_fma_f32 v[252:253], v[152:153], v[152:153], v[252:253]
	v_pk_fma_f32 v[254:255], v[154:155], v[154:155], v[254:255]
	v_pk_fma_f32 v[252:253], v[156:157], v[156:157], v[252:253]
	v_pk_fma_f32 v[254:255], v[158:159], v[158:159], v[254:255]
	v_pk_add_f32 v[252:253], v[252:253], v[254:255]
	s_nop 0
	v_add_f32_e32 v183, v252, v253
	s_nop 1
	v_add_f32_dpp v183, v183, v183 quad_perm:[1,0,3,2] row_mask:0xf bank_mask:0xf bound_ctrl:1
	s_nop 1
	v_add_f32_dpp v183, v183, v183 quad_perm:[2,3,0,1] row_mask:0xf bank_mask:0xf bound_ctrl:1
	s_nop 1
	v_add_f32_dpp v183, v183, v183 row_half_mirror row_mask:0xf bank_mask:0xf bound_ctrl:1
	s_nop 1
	v_add_f32_dpp v183, v183, v183 row_mirror row_mask:0xf bank_mask:0xf bound_ctrl:1
	s_nop 1
	v_readlane_b32 s98, v183, 0
	v_readlane_b32 s99, v183, 16
	v_readlane_b32 s100, v183, 32
	v_readlane_b32 s101, v183, 48
	s_nop 1
	v_mov_b32_e32 v183, s98
	v_add_f32_e32 v183, s99, v183
	v_add_f32_e32 v183, s100, v183
	v_add_f32_e32 v183, s101, v183
	v_fmamk_f32 v183, v183, 0x3a800000, v182
	v_cmp_gt_f32_e32 vcc, 0x800000, v183
	v_mul_f32_e32 v181, 0x4b800000, v183
	s_nop 1
	v_cndmask_b32_e32 v183, v183, v181, vcc
	v_rsq_f32_e32 v183, v183
	s_nop 0
	v_mul_f32_e32 v181, 0x45800000, v183
	v_cndmask_b32_e32 v184, v183, v181, vcc
	v_mov_b32_e32 v185, v184
	v_pk_mul_f32 v[144:145], v[144:145], v[184:185]
	v_pk_mul_f32 v[146:147], v[146:147], v[184:185]
	v_pk_mul_f32 v[148:149], v[148:149], v[184:185]
	v_pk_mul_f32 v[150:151], v[150:151], v[184:185]
	v_pk_mul_f32 v[152:153], v[152:153], v[184:185]
	v_pk_mul_f32 v[154:155], v[154:155], v[184:185]
	v_pk_mul_f32 v[156:157], v[156:157], v[184:185]
	v_pk_mul_f32 v[158:159], v[158:159], v[184:185]
	v_pk_mul_f32 v[144:145], v[144:145], v[236:237]
	v_pk_mul_f32 v[146:147], v[146:147], v[238:239]
	v_pk_mul_f32 v[148:149], v[148:149], v[240:241]
	v_pk_mul_f32 v[150:151], v[150:151], v[242:243]
	v_pk_mul_f32 v[152:153], v[152:153], v[244:245]
	v_pk_mul_f32 v[154:155], v[154:155], v[246:247]
	v_pk_mul_f32 v[156:157], v[156:157], v[248:249]
	v_pk_mul_f32 v[158:159], v[158:159], v[250:251]
	v_add_u32_e32 v181, 0x1000000, v178
	global_store_dwordx4 v181, v[144:147], s[76:77]
	global_store_dwordx4 v181, v[148:151], s[76:77] offset:16
	global_store_dwordx4 v181, v[152:155], s[76:77] offset:2048
	global_store_dwordx4 v181, v[156:159], s[76:77] offset:2064
	s_nop 1
	s_waitcnt vmcnt(16)
	v_lshlrev_b32_e32 v144, 16, v48
	v_and_b32_e32 v145, 0xffff0000, v48
	v_lshlrev_b32_e32 v146, 16, v49
	v_and_b32_e32 v147, 0xffff0000, v49
	v_lshlrev_b32_e32 v148, 16, v50
	v_and_b32_e32 v149, 0xffff0000, v50
	v_lshlrev_b32_e32 v150, 16, v51
	v_and_b32_e32 v151, 0xffff0000, v51
	v_lshlrev_b32_e32 v152, 16, v52
	v_and_b32_e32 v153, 0xffff0000, v52
	v_lshlrev_b32_e32 v154, 16, v53
	v_and_b32_e32 v155, 0xffff0000, v53
	v_lshlrev_b32_e32 v156, 16, v54
	v_and_b32_e32 v157, 0xffff0000, v54
	v_lshlrev_b32_e32 v158, 16, v55
	v_and_b32_e32 v159, 0xffff0000, v55
	v_lshlrev_b32_e32 v160, 16, v56
	v_and_b32_e32 v161, 0xffff0000, v56
	v_lshlrev_b32_e32 v162, 16, v57
	v_and_b32_e32 v163, 0xffff0000, v57
	v_lshlrev_b32_e32 v164, 16, v58
	v_and_b32_e32 v165, 0xffff0000, v58
	v_lshlrev_b32_e32 v166, 16, v59
	v_and_b32_e32 v167, 0xffff0000, v59
	v_lshlrev_b32_e32 v168, 16, v60
	v_and_b32_e32 v169, 0xffff0000, v60
	v_lshlrev_b32_e32 v170, 16, v61
	v_and_b32_e32 v171, 0xffff0000, v61
	v_lshlrev_b32_e32 v172, 16, v62
	v_and_b32_e32 v173, 0xffff0000, v62
	v_lshlrev_b32_e32 v174, 16, v63
	v_and_b32_e32 v175, 0xffff0000, v63
	v_pk_mul_f32 v[252:253], v[160:161], v[160:161]
	v_pk_mul_f32 v[254:255], v[162:163], v[162:163]
	v_pk_fma_f32 v[252:253], v[164:165], v[164:165], v[252:253]
	v_pk_fma_f32 v[254:255], v[166:167], v[166:167], v[254:255]
	v_pk_fma_f32 v[252:253], v[168:169], v[168:169], v[252:253]
	v_pk_fma_f32 v[254:255], v[170:171], v[170:171], v[254:255]
	v_pk_fma_f32 v[252:253], v[172:173], v[172:173], v[252:253]
	v_pk_fma_f32 v[254:255], v[174:175], v[174:175], v[254:255]
	v_pk_add_f32 v[252:253], v[252:253], v[254:255]
	s_nop 0
	v_add_f32_e32 v183, v252, v253
	s_nop 1
	v_add_f32_dpp v183, v183, v183 quad_perm:[1,0,3,2] row_mask:0xf bank_mask:0xf bound_ctrl:1
	s_nop 1
	v_add_f32_dpp v183, v183, v183 quad_perm:[2,3,0,1] row_mask:0xf bank_mask:0xf bound_ctrl:1
	s_nop 1
	v_add_f32_dpp v183, v183, v183 row_half_mirror row_mask:0xf bank_mask:0xf bound_ctrl:1
	s_nop 1
	v_add_f32_dpp v183, v183, v183 row_mirror row_mask:0xf bank_mask:0xf bound_ctrl:1
	s_nop 1
	v_readlane_b32 s98, v183, 0
	v_readlane_b32 s99, v183, 16
	v_readlane_b32 s100, v183, 32
	v_readlane_b32 s101, v183, 48
	s_nop 1
	v_mov_b32_e32 v183, s98
	v_add_f32_e32 v183, s99, v183
	v_add_f32_e32 v183, s100, v183
	v_add_f32_e32 v183, s101, v183
	v_fmamk_f32 v183, v183, 0x3a800000, v182
	v_cmp_gt_f32_e32 vcc, 0x800000, v183
	v_mul_f32_e32 v181, 0x4b800000, v183
	s_nop 1
	v_cndmask_b32_e32 v183, v183, v181, vcc
	v_rsq_f32_e32 v183, v183
	s_nop 0
	v_mul_f32_e32 v181, 0x45800000, v183
	v_cndmask_b32_e32 v184, v183, v181, vcc
	v_mov_b32_e32 v185, v184
	v_pk_mul_f32 v[160:161], v[160:161], v[184:185]
	v_pk_mul_f32 v[162:163], v[162:163], v[184:185]
	v_pk_mul_f32 v[164:165], v[164:165], v[184:185]
	v_pk_mul_f32 v[166:167], v[166:167], v[184:185]
	v_pk_mul_f32 v[168:169], v[168:169], v[184:185]
	v_pk_mul_f32 v[170:171], v[170:171], v[184:185]
	v_pk_mul_f32 v[172:173], v[172:173], v[184:185]
	v_pk_mul_f32 v[174:175], v[174:175], v[184:185]
	v_pk_fma_f32 v[144:145], v[160:161], v[128:129], v[144:145]
	v_pk_fma_f32 v[146:147], v[162:163], v[130:131], v[146:147]
	v_pk_fma_f32 v[148:149], v[164:165], v[132:133], v[148:149]
	v_pk_fma_f32 v[150:151], v[166:167], v[134:135], v[150:151]
	v_pk_fma_f32 v[152:153], v[168:169], v[136:137], v[152:153]
	v_pk_fma_f32 v[154:155], v[170:171], v[138:139], v[154:155]
	v_pk_fma_f32 v[156:157], v[172:173], v[140:141], v[156:157]
	v_pk_fma_f32 v[158:159], v[174:175], v[142:143], v[158:159]
	v_pk_mul_f32 v[252:253], v[144:145], v[144:145]
	v_pk_mul_f32 v[254:255], v[146:147], v[146:147]
	v_pk_fma_f32 v[252:253], v[148:149], v[148:149], v[252:253]
	v_pk_fma_f32 v[254:255], v[150:151], v[150:151], v[254:255]
	v_pk_fma_f32 v[252:253], v[152:153], v[152:153], v[252:253]
	v_pk_fma_f32 v[254:255], v[154:155], v[154:155], v[254:255]
	v_pk_fma_f32 v[252:253], v[156:157], v[156:157], v[252:253]
	v_pk_fma_f32 v[254:255], v[158:159], v[158:159], v[254:255]
	v_pk_add_f32 v[252:253], v[252:253], v[254:255]
	s_nop 0
	v_add_f32_e32 v183, v252, v253
	s_nop 1
	v_add_f32_dpp v183, v183, v183 quad_perm:[1,0,3,2] row_mask:0xf bank_mask:0xf bound_ctrl:1
	s_nop 1
	v_add_f32_dpp v183, v183, v183 quad_perm:[2,3,0,1] row_mask:0xf bank_mask:0xf bound_ctrl:1
	s_nop 1
	v_add_f32_dpp v183, v183, v183 row_half_mirror row_mask:0xf bank_mask:0xf bound_ctrl:1
	s_nop 1
	v_add_f32_dpp v183, v183, v183 row_mirror row_mask:0xf bank_mask:0xf bound_ctrl:1
	s_nop 1
	v_readlane_b32 s98, v183, 0
	v_readlane_b32 s99, v183, 16
	v_readlane_b32 s100, v183, 32
	v_readlane_b32 s101, v183, 48
	s_nop 1
	v_mov_b32_e32 v183, s98
	v_add_f32_e32 v183, s99, v183
	v_add_f32_e32 v183, s100, v183
	v_add_f32_e32 v183, s101, v183
	v_fmamk_f32 v183, v183, 0x3a800000, v182
	v_cmp_gt_f32_e32 vcc, 0x800000, v183
	v_mul_f32_e32 v181, 0x4b800000, v183
	s_nop 1
	v_cndmask_b32_e32 v183, v183, v181, vcc
	v_rsq_f32_e32 v183, v183
	s_nop 0
	v_mul_f32_e32 v181, 0x45800000, v183
	v_cndmask_b32_e32 v184, v183, v181, vcc
	v_mov_b32_e32 v185, v184
	v_pk_mul_f32 v[144:145], v[144:145], v[184:185]
	v_pk_mul_f32 v[146:147], v[146:147], v[184:185]
	v_pk_mul_f32 v[148:149], v[148:149], v[184:185]
	v_pk_mul_f32 v[150:151], v[150:151], v[184:185]
	v_pk_mul_f32 v[152:153], v[152:153], v[184:185]
	v_pk_mul_f32 v[154:155], v[154:155], v[184:185]
	v_pk_mul_f32 v[156:157], v[156:157], v[184:185]
	v_pk_mul_f32 v[158:159], v[158:159], v[184:185]
	v_pk_mul_f32 v[144:145], v[144:145], v[236:237]
	v_pk_mul_f32 v[146:147], v[146:147], v[238:239]
	v_pk_mul_f32 v[148:149], v[148:149], v[240:241]
	v_pk_mul_f32 v[150:151], v[150:151], v[242:243]
	v_pk_mul_f32 v[152:153], v[152:153], v[244:245]
	v_pk_mul_f32 v[154:155], v[154:155], v[246:247]
	v_pk_mul_f32 v[156:157], v[156:157], v[248:249]
	v_pk_mul_f32 v[158:159], v[158:159], v[250:251]
	v_add_u32_e32 v181, 0x1800000, v178
	global_store_dwordx4 v181, v[144:147], s[76:77]
	global_store_dwordx4 v181, v[148:151], s[76:77] offset:16
	global_store_dwordx4 v181, v[152:155], s[76:77] offset:2048
	global_store_dwordx4 v181, v[156:159], s[76:77] offset:2064
	s_nop 1
	s_waitcnt vmcnt(12)
	v_lshlrev_b32_e32 v144, 16, v64
	v_and_b32_e32 v145, 0xffff0000, v64
	v_lshlrev_b32_e32 v146, 16, v65
	v_and_b32_e32 v147, 0xffff0000, v65
	v_lshlrev_b32_e32 v148, 16, v66
	v_and_b32_e32 v149, 0xffff0000, v66
	v_lshlrev_b32_e32 v150, 16, v67
	v_and_b32_e32 v151, 0xffff0000, v67
	v_lshlrev_b32_e32 v152, 16, v68
	v_and_b32_e32 v153, 0xffff0000, v68
	v_lshlrev_b32_e32 v154, 16, v69
	v_and_b32_e32 v155, 0xffff0000, v69
	v_lshlrev_b32_e32 v156, 16, v70
	v_and_b32_e32 v157, 0xffff0000, v70
	v_lshlrev_b32_e32 v158, 16, v71
	v_and_b32_e32 v159, 0xffff0000, v71
	v_lshlrev_b32_e32 v160, 16, v72
	v_and_b32_e32 v161, 0xffff0000, v72
	v_lshlrev_b32_e32 v162, 16, v73
	v_and_b32_e32 v163, 0xffff0000, v73
	v_lshlrev_b32_e32 v164, 16, v74
	v_and_b32_e32 v165, 0xffff0000, v74
	v_lshlrev_b32_e32 v166, 16, v75
	v_and_b32_e32 v167, 0xffff0000, v75
	v_lshlrev_b32_e32 v168, 16, v76
	v_and_b32_e32 v169, 0xffff0000, v76
	v_lshlrev_b32_e32 v170, 16, v77
	v_and_b32_e32 v171, 0xffff0000, v77
	v_lshlrev_b32_e32 v172, 16, v78
	v_and_b32_e32 v173, 0xffff0000, v78
	v_lshlrev_b32_e32 v174, 16, v79
	v_and_b32_e32 v175, 0xffff0000, v79
	v_pk_mul_f32 v[252:253], v[160:161], v[160:161]
	v_pk_mul_f32 v[254:255], v[162:163], v[162:163]
	v_pk_fma_f32 v[252:253], v[164:165], v[164:165], v[252:253]
	v_pk_fma_f32 v[254:255], v[166:167], v[166:167], v[254:255]
	v_pk_fma_f32 v[252:253], v[168:169], v[168:169], v[252:253]
	v_pk_fma_f32 v[254:255], v[170:171], v[170:171], v[254:255]
	v_pk_fma_f32 v[252:253], v[172:173], v[172:173], v[252:253]
	v_pk_fma_f32 v[254:255], v[174:175], v[174:175], v[254:255]
	v_pk_add_f32 v[252:253], v[252:253], v[254:255]
	s_nop 0
	v_add_f32_e32 v183, v252, v253
	s_nop 1
	v_add_f32_dpp v183, v183, v183 quad_perm:[1,0,3,2] row_mask:0xf bank_mask:0xf bound_ctrl:1
	s_nop 1
	v_add_f32_dpp v183, v183, v183 quad_perm:[2,3,0,1] row_mask:0xf bank_mask:0xf bound_ctrl:1
	s_nop 1
	v_add_f32_dpp v183, v183, v183 row_half_mirror row_mask:0xf bank_mask:0xf bound_ctrl:1
	s_nop 1
	v_add_f32_dpp v183, v183, v183 row_mirror row_mask:0xf bank_mask:0xf bound_ctrl:1
	s_nop 1
	v_readlane_b32 s98, v183, 0
	v_readlane_b32 s99, v183, 16
	v_readlane_b32 s100, v183, 32
	v_readlane_b32 s101, v183, 48
	s_nop 1
	v_mov_b32_e32 v183, s98
	v_add_f32_e32 v183, s99, v183
	v_add_f32_e32 v183, s100, v183
	v_add_f32_e32 v183, s101, v183
	v_fmamk_f32 v183, v183, 0x3a800000, v182
	v_cmp_gt_f32_e32 vcc, 0x800000, v183
	v_mul_f32_e32 v181, 0x4b800000, v183
	s_nop 1
	v_cndmask_b32_e32 v183, v183, v181, vcc
	v_rsq_f32_e32 v183, v183
	s_nop 0
	v_mul_f32_e32 v181, 0x45800000, v183
	v_cndmask_b32_e32 v184, v183, v181, vcc
	v_mov_b32_e32 v185, v184
	v_pk_mul_f32 v[160:161], v[160:161], v[184:185]
	v_pk_mul_f32 v[162:163], v[162:163], v[184:185]
	v_pk_mul_f32 v[164:165], v[164:165], v[184:185]
	v_pk_mul_f32 v[166:167], v[166:167], v[184:185]
	v_pk_mul_f32 v[168:169], v[168:169], v[184:185]
	v_pk_mul_f32 v[170:171], v[170:171], v[184:185]
	v_pk_mul_f32 v[172:173], v[172:173], v[184:185]
	v_pk_mul_f32 v[174:175], v[174:175], v[184:185]
	v_pk_fma_f32 v[144:145], v[160:161], v[128:129], v[144:145]
	v_pk_fma_f32 v[146:147], v[162:163], v[130:131], v[146:147]
	v_pk_fma_f32 v[148:149], v[164:165], v[132:133], v[148:149]
	v_pk_fma_f32 v[150:151], v[166:167], v[134:135], v[150:151]
	v_pk_fma_f32 v[152:153], v[168:169], v[136:137], v[152:153]
	v_pk_fma_f32 v[154:155], v[170:171], v[138:139], v[154:155]
	v_pk_fma_f32 v[156:157], v[172:173], v[140:141], v[156:157]
	v_pk_fma_f32 v[158:159], v[174:175], v[142:143], v[158:159]
	v_pk_mul_f32 v[252:253], v[144:145], v[144:145]
	v_pk_mul_f32 v[254:255], v[146:147], v[146:147]
	v_pk_fma_f32 v[252:253], v[148:149], v[148:149], v[252:253]
	v_pk_fma_f32 v[254:255], v[150:151], v[150:151], v[254:255]
	v_pk_fma_f32 v[252:253], v[152:153], v[152:153], v[252:253]
	v_pk_fma_f32 v[254:255], v[154:155], v[154:155], v[254:255]
	v_pk_fma_f32 v[252:253], v[156:157], v[156:157], v[252:253]
	v_pk_fma_f32 v[254:255], v[158:159], v[158:159], v[254:255]
	v_pk_add_f32 v[252:253], v[252:253], v[254:255]
	s_nop 0
	v_add_f32_e32 v183, v252, v253
	s_nop 1
	v_add_f32_dpp v183, v183, v183 quad_perm:[1,0,3,2] row_mask:0xf bank_mask:0xf bound_ctrl:1
	s_nop 1
	v_add_f32_dpp v183, v183, v183 quad_perm:[2,3,0,1] row_mask:0xf bank_mask:0xf bound_ctrl:1
	s_nop 1
	v_add_f32_dpp v183, v183, v183 row_half_mirror row_mask:0xf bank_mask:0xf bound_ctrl:1
	s_nop 1
	v_add_f32_dpp v183, v183, v183 row_mirror row_mask:0xf bank_mask:0xf bound_ctrl:1
	s_nop 1
	v_readlane_b32 s98, v183, 0
	v_readlane_b32 s99, v183, 16
	v_readlane_b32 s100, v183, 32
	v_readlane_b32 s101, v183, 48
	s_nop 1
	v_mov_b32_e32 v183, s98
	v_add_f32_e32 v183, s99, v183
	v_add_f32_e32 v183, s100, v183
	v_add_f32_e32 v183, s101, v183
	v_fmamk_f32 v183, v183, 0x3a800000, v182
	v_cmp_gt_f32_e32 vcc, 0x800000, v183
	v_mul_f32_e32 v181, 0x4b800000, v183
	s_nop 1
	v_cndmask_b32_e32 v183, v183, v181, vcc
	v_rsq_f32_e32 v183, v183
	s_nop 0
	v_mul_f32_e32 v181, 0x45800000, v183
	v_cndmask_b32_e32 v184, v183, v181, vcc
	v_mov_b32_e32 v185, v184
	v_pk_mul_f32 v[144:145], v[144:145], v[184:185]
	v_pk_mul_f32 v[146:147], v[146:147], v[184:185]
	v_pk_mul_f32 v[148:149], v[148:149], v[184:185]
	v_pk_mul_f32 v[150:151], v[150:151], v[184:185]
	v_pk_mul_f32 v[152:153], v[152:153], v[184:185]
	v_pk_mul_f32 v[154:155], v[154:155], v[184:185]
	v_pk_mul_f32 v[156:157], v[156:157], v[184:185]
	v_pk_mul_f32 v[158:159], v[158:159], v[184:185]
	v_pk_mul_f32 v[144:145], v[144:145], v[236:237]
	v_pk_mul_f32 v[146:147], v[146:147], v[238:239]
	v_pk_mul_f32 v[148:149], v[148:149], v[240:241]
	v_pk_mul_f32 v[150:151], v[150:151], v[242:243]
	v_pk_mul_f32 v[152:153], v[152:153], v[244:245]
	v_pk_mul_f32 v[154:155], v[154:155], v[246:247]
	v_pk_mul_f32 v[156:157], v[156:157], v[248:249]
	v_pk_mul_f32 v[158:159], v[158:159], v[250:251]
	v_add_u32_e32 v181, 0x2000000, v178
	global_store_dwordx4 v181, v[144:147], s[76:77]
	global_store_dwordx4 v181, v[148:151], s[76:77] offset:16
	global_store_dwordx4 v181, v[152:155], s[76:77] offset:2048
	global_store_dwordx4 v181, v[156:159], s[76:77] offset:2064
	s_nop 1
	s_waitcnt vmcnt(8)
	v_lshlrev_b32_e32 v144, 16, v80
	v_and_b32_e32 v145, 0xffff0000, v80
	v_lshlrev_b32_e32 v146, 16, v81
	v_and_b32_e32 v147, 0xffff0000, v81
	v_lshlrev_b32_e32 v148, 16, v82
	v_and_b32_e32 v149, 0xffff0000, v82
	v_lshlrev_b32_e32 v150, 16, v83
	v_and_b32_e32 v151, 0xffff0000, v83
	v_lshlrev_b32_e32 v152, 16, v84
	v_and_b32_e32 v153, 0xffff0000, v84
	v_lshlrev_b32_e32 v154, 16, v85
	v_and_b32_e32 v155, 0xffff0000, v85
	v_lshlrev_b32_e32 v156, 16, v86
	v_and_b32_e32 v157, 0xffff0000, v86
	v_lshlrev_b32_e32 v158, 16, v87
	v_and_b32_e32 v159, 0xffff0000, v87
	v_lshlrev_b32_e32 v160, 16, v88
	v_and_b32_e32 v161, 0xffff0000, v88
	v_lshlrev_b32_e32 v162, 16, v89
	v_and_b32_e32 v163, 0xffff0000, v89
	v_lshlrev_b32_e32 v164, 16, v90
	v_and_b32_e32 v165, 0xffff0000, v90
	v_lshlrev_b32_e32 v166, 16, v91
	v_and_b32_e32 v167, 0xffff0000, v91
	v_lshlrev_b32_e32 v168, 16, v92
	v_and_b32_e32 v169, 0xffff0000, v92
	v_lshlrev_b32_e32 v170, 16, v93
	v_and_b32_e32 v171, 0xffff0000, v93
	v_lshlrev_b32_e32 v172, 16, v94
	v_and_b32_e32 v173, 0xffff0000, v94
	v_lshlrev_b32_e32 v174, 16, v95
	v_and_b32_e32 v175, 0xffff0000, v95
	v_pk_mul_f32 v[252:253], v[160:161], v[160:161]
	v_pk_mul_f32 v[254:255], v[162:163], v[162:163]
	v_pk_fma_f32 v[252:253], v[164:165], v[164:165], v[252:253]
	v_pk_fma_f32 v[254:255], v[166:167], v[166:167], v[254:255]
	v_pk_fma_f32 v[252:253], v[168:169], v[168:169], v[252:253]
	v_pk_fma_f32 v[254:255], v[170:171], v[170:171], v[254:255]
	v_pk_fma_f32 v[252:253], v[172:173], v[172:173], v[252:253]
	v_pk_fma_f32 v[254:255], v[174:175], v[174:175], v[254:255]
	v_pk_add_f32 v[252:253], v[252:253], v[254:255]
	s_nop 0
	v_add_f32_e32 v183, v252, v253
	s_nop 1
	v_add_f32_dpp v183, v183, v183 quad_perm:[1,0,3,2] row_mask:0xf bank_mask:0xf bound_ctrl:1
	s_nop 1
	v_add_f32_dpp v183, v183, v183 quad_perm:[2,3,0,1] row_mask:0xf bank_mask:0xf bound_ctrl:1
	s_nop 1
	v_add_f32_dpp v183, v183, v183 row_half_mirror row_mask:0xf bank_mask:0xf bound_ctrl:1
	s_nop 1
	v_add_f32_dpp v183, v183, v183 row_mirror row_mask:0xf bank_mask:0xf bound_ctrl:1
	s_nop 1
	v_readlane_b32 s98, v183, 0
	v_readlane_b32 s99, v183, 16
	v_readlane_b32 s100, v183, 32
	v_readlane_b32 s101, v183, 48
	s_nop 1
	v_mov_b32_e32 v183, s98
	v_add_f32_e32 v183, s99, v183
	v_add_f32_e32 v183, s100, v183
	v_add_f32_e32 v183, s101, v183
	v_fmamk_f32 v183, v183, 0x3a800000, v182
	v_cmp_gt_f32_e32 vcc, 0x800000, v183
	v_mul_f32_e32 v181, 0x4b800000, v183
	s_nop 1
	v_cndmask_b32_e32 v183, v183, v181, vcc
	v_rsq_f32_e32 v183, v183
	s_nop 0
	v_mul_f32_e32 v181, 0x45800000, v183
	v_cndmask_b32_e32 v184, v183, v181, vcc
	v_mov_b32_e32 v185, v184
	v_pk_mul_f32 v[160:161], v[160:161], v[184:185]
	v_pk_mul_f32 v[162:163], v[162:163], v[184:185]
	v_pk_mul_f32 v[164:165], v[164:165], v[184:185]
	v_pk_mul_f32 v[166:167], v[166:167], v[184:185]
	v_pk_mul_f32 v[168:169], v[168:169], v[184:185]
	v_pk_mul_f32 v[170:171], v[170:171], v[184:185]
	v_pk_mul_f32 v[172:173], v[172:173], v[184:185]
	v_pk_mul_f32 v[174:175], v[174:175], v[184:185]
	v_pk_fma_f32 v[144:145], v[160:161], v[128:129], v[144:145]
	v_pk_fma_f32 v[146:147], v[162:163], v[130:131], v[146:147]
	v_pk_fma_f32 v[148:149], v[164:165], v[132:133], v[148:149]
	v_pk_fma_f32 v[150:151], v[166:167], v[134:135], v[150:151]
	v_pk_fma_f32 v[152:153], v[168:169], v[136:137], v[152:153]
	v_pk_fma_f32 v[154:155], v[170:171], v[138:139], v[154:155]
	v_pk_fma_f32 v[156:157], v[172:173], v[140:141], v[156:157]
	v_pk_fma_f32 v[158:159], v[174:175], v[142:143], v[158:159]
	v_pk_mul_f32 v[252:253], v[144:145], v[144:145]
	v_pk_mul_f32 v[254:255], v[146:147], v[146:147]
	v_pk_fma_f32 v[252:253], v[148:149], v[148:149], v[252:253]
	v_pk_fma_f32 v[254:255], v[150:151], v[150:151], v[254:255]
	v_pk_fma_f32 v[252:253], v[152:153], v[152:153], v[252:253]
	v_pk_fma_f32 v[254:255], v[154:155], v[154:155], v[254:255]
	v_pk_fma_f32 v[252:253], v[156:157], v[156:157], v[252:253]
	v_pk_fma_f32 v[254:255], v[158:159], v[158:159], v[254:255]
	v_pk_add_f32 v[252:253], v[252:253], v[254:255]
	s_nop 0
	v_add_f32_e32 v183, v252, v253
	s_nop 1
	v_add_f32_dpp v183, v183, v183 quad_perm:[1,0,3,2] row_mask:0xf bank_mask:0xf bound_ctrl:1
	s_nop 1
	v_add_f32_dpp v183, v183, v183 quad_perm:[2,3,0,1] row_mask:0xf bank_mask:0xf bound_ctrl:1
	s_nop 1
	v_add_f32_dpp v183, v183, v183 row_half_mirror row_mask:0xf bank_mask:0xf bound_ctrl:1
	s_nop 1
	v_add_f32_dpp v183, v183, v183 row_mirror row_mask:0xf bank_mask:0xf bound_ctrl:1
	s_nop 1
	v_readlane_b32 s98, v183, 0
	v_readlane_b32 s99, v183, 16
	v_readlane_b32 s100, v183, 32
	v_readlane_b32 s101, v183, 48
	s_nop 1
	v_mov_b32_e32 v183, s98
	v_add_f32_e32 v183, s99, v183
	v_add_f32_e32 v183, s100, v183
	v_add_f32_e32 v183, s101, v183
	v_fmamk_f32 v183, v183, 0x3a800000, v182
	v_cmp_gt_f32_e32 vcc, 0x800000, v183
	v_mul_f32_e32 v181, 0x4b800000, v183
	s_nop 1
	v_cndmask_b32_e32 v183, v183, v181, vcc
	v_rsq_f32_e32 v183, v183
	s_nop 0
	v_mul_f32_e32 v181, 0x45800000, v183
	v_cndmask_b32_e32 v184, v183, v181, vcc
	v_mov_b32_e32 v185, v184
	v_pk_mul_f32 v[144:145], v[144:145], v[184:185]
	v_pk_mul_f32 v[146:147], v[146:147], v[184:185]
	v_pk_mul_f32 v[148:149], v[148:149], v[184:185]
	v_pk_mul_f32 v[150:151], v[150:151], v[184:185]
	v_pk_mul_f32 v[152:153], v[152:153], v[184:185]
	v_pk_mul_f32 v[154:155], v[154:155], v[184:185]
	v_pk_mul_f32 v[156:157], v[156:157], v[184:185]
	v_pk_mul_f32 v[158:159], v[158:159], v[184:185]
	v_pk_mul_f32 v[144:145], v[144:145], v[236:237]
	v_pk_mul_f32 v[146:147], v[146:147], v[238:239]
	v_pk_mul_f32 v[148:149], v[148:149], v[240:241]
	v_pk_mul_f32 v[150:151], v[150:151], v[242:243]
	v_pk_mul_f32 v[152:153], v[152:153], v[244:245]
	v_pk_mul_f32 v[154:155], v[154:155], v[246:247]
	v_pk_mul_f32 v[156:157], v[156:157], v[248:249]
	v_pk_mul_f32 v[158:159], v[158:159], v[250:251]
	v_add_u32_e32 v181, 0x2800000, v178
	global_store_dwordx4 v181, v[144:147], s[76:77]
	global_store_dwordx4 v181, v[148:151], s[76:77] offset:16
	global_store_dwordx4 v181, v[152:155], s[76:77] offset:2048
	global_store_dwordx4 v181, v[156:159], s[76:77] offset:2064
	s_nop 1
	s_waitcnt vmcnt(4)
	v_lshlrev_b32_e32 v144, 16, v96
	v_and_b32_e32 v145, 0xffff0000, v96
	v_lshlrev_b32_e32 v146, 16, v97
	v_and_b32_e32 v147, 0xffff0000, v97
	v_lshlrev_b32_e32 v148, 16, v98
	v_and_b32_e32 v149, 0xffff0000, v98
	v_lshlrev_b32_e32 v150, 16, v99
	v_and_b32_e32 v151, 0xffff0000, v99
	v_lshlrev_b32_e32 v152, 16, v100
	v_and_b32_e32 v153, 0xffff0000, v100
	v_lshlrev_b32_e32 v154, 16, v101
	v_and_b32_e32 v155, 0xffff0000, v101
	v_lshlrev_b32_e32 v156, 16, v102
	v_and_b32_e32 v157, 0xffff0000, v102
	v_lshlrev_b32_e32 v158, 16, v103
	v_and_b32_e32 v159, 0xffff0000, v103
	v_lshlrev_b32_e32 v160, 16, v104
	v_and_b32_e32 v161, 0xffff0000, v104
	v_lshlrev_b32_e32 v162, 16, v105
	v_and_b32_e32 v163, 0xffff0000, v105
	v_lshlrev_b32_e32 v164, 16, v106
	v_and_b32_e32 v165, 0xffff0000, v106
	v_lshlrev_b32_e32 v166, 16, v107
	v_and_b32_e32 v167, 0xffff0000, v107
	v_lshlrev_b32_e32 v168, 16, v108
	v_and_b32_e32 v169, 0xffff0000, v108
	v_lshlrev_b32_e32 v170, 16, v109
	v_and_b32_e32 v171, 0xffff0000, v109
	v_lshlrev_b32_e32 v172, 16, v110
	v_and_b32_e32 v173, 0xffff0000, v110
	v_lshlrev_b32_e32 v174, 16, v111
	v_and_b32_e32 v175, 0xffff0000, v111
	v_pk_mul_f32 v[252:253], v[160:161], v[160:161]
	v_pk_mul_f32 v[254:255], v[162:163], v[162:163]
	v_pk_fma_f32 v[252:253], v[164:165], v[164:165], v[252:253]
	v_pk_fma_f32 v[254:255], v[166:167], v[166:167], v[254:255]
	v_pk_fma_f32 v[252:253], v[168:169], v[168:169], v[252:253]
	v_pk_fma_f32 v[254:255], v[170:171], v[170:171], v[254:255]
	v_pk_fma_f32 v[252:253], v[172:173], v[172:173], v[252:253]
	v_pk_fma_f32 v[254:255], v[174:175], v[174:175], v[254:255]
	v_pk_add_f32 v[252:253], v[252:253], v[254:255]
	s_nop 0
	v_add_f32_e32 v183, v252, v253
	s_nop 1
	v_add_f32_dpp v183, v183, v183 quad_perm:[1,0,3,2] row_mask:0xf bank_mask:0xf bound_ctrl:1
	s_nop 1
	v_add_f32_dpp v183, v183, v183 quad_perm:[2,3,0,1] row_mask:0xf bank_mask:0xf bound_ctrl:1
	s_nop 1
	v_add_f32_dpp v183, v183, v183 row_half_mirror row_mask:0xf bank_mask:0xf bound_ctrl:1
	s_nop 1
	v_add_f32_dpp v183, v183, v183 row_mirror row_mask:0xf bank_mask:0xf bound_ctrl:1
	s_nop 1
	v_readlane_b32 s98, v183, 0
	v_readlane_b32 s99, v183, 16
	v_readlane_b32 s100, v183, 32
	v_readlane_b32 s101, v183, 48
	s_nop 1
	v_mov_b32_e32 v183, s98
	v_add_f32_e32 v183, s99, v183
	v_add_f32_e32 v183, s100, v183
	v_add_f32_e32 v183, s101, v183
	v_fmamk_f32 v183, v183, 0x3a800000, v182
	v_cmp_gt_f32_e32 vcc, 0x800000, v183
	v_mul_f32_e32 v181, 0x4b800000, v183
	s_nop 1
	v_cndmask_b32_e32 v183, v183, v181, vcc
	v_rsq_f32_e32 v183, v183
	s_nop 0
	v_mul_f32_e32 v181, 0x45800000, v183
	v_cndmask_b32_e32 v184, v183, v181, vcc
	v_mov_b32_e32 v185, v184
	v_pk_mul_f32 v[160:161], v[160:161], v[184:185]
	v_pk_mul_f32 v[162:163], v[162:163], v[184:185]
	v_pk_mul_f32 v[164:165], v[164:165], v[184:185]
	v_pk_mul_f32 v[166:167], v[166:167], v[184:185]
	v_pk_mul_f32 v[168:169], v[168:169], v[184:185]
	v_pk_mul_f32 v[170:171], v[170:171], v[184:185]
	v_pk_mul_f32 v[172:173], v[172:173], v[184:185]
	v_pk_mul_f32 v[174:175], v[174:175], v[184:185]
	v_pk_fma_f32 v[144:145], v[160:161], v[128:129], v[144:145]
	v_pk_fma_f32 v[146:147], v[162:163], v[130:131], v[146:147]
	v_pk_fma_f32 v[148:149], v[164:165], v[132:133], v[148:149]
	v_pk_fma_f32 v[150:151], v[166:167], v[134:135], v[150:151]
	v_pk_fma_f32 v[152:153], v[168:169], v[136:137], v[152:153]
	v_pk_fma_f32 v[154:155], v[170:171], v[138:139], v[154:155]
	v_pk_fma_f32 v[156:157], v[172:173], v[140:141], v[156:157]
	v_pk_fma_f32 v[158:159], v[174:175], v[142:143], v[158:159]
	v_pk_mul_f32 v[252:253], v[144:145], v[144:145]
	v_pk_mul_f32 v[254:255], v[146:147], v[146:147]
	v_pk_fma_f32 v[252:253], v[148:149], v[148:149], v[252:253]
	v_pk_fma_f32 v[254:255], v[150:151], v[150:151], v[254:255]
	v_pk_fma_f32 v[252:253], v[152:153], v[152:153], v[252:253]
	v_pk_fma_f32 v[254:255], v[154:155], v[154:155], v[254:255]
	v_pk_fma_f32 v[252:253], v[156:157], v[156:157], v[252:253]
	v_pk_fma_f32 v[254:255], v[158:159], v[158:159], v[254:255]
	v_pk_add_f32 v[252:253], v[252:253], v[254:255]
	s_nop 0
	v_add_f32_e32 v183, v252, v253
	s_nop 1
	v_add_f32_dpp v183, v183, v183 quad_perm:[1,0,3,2] row_mask:0xf bank_mask:0xf bound_ctrl:1
	s_nop 1
	v_add_f32_dpp v183, v183, v183 quad_perm:[2,3,0,1] row_mask:0xf bank_mask:0xf bound_ctrl:1
	s_nop 1
	v_add_f32_dpp v183, v183, v183 row_half_mirror row_mask:0xf bank_mask:0xf bound_ctrl:1
	s_nop 1
	v_add_f32_dpp v183, v183, v183 row_mirror row_mask:0xf bank_mask:0xf bound_ctrl:1
	s_nop 1
	v_readlane_b32 s98, v183, 0
	v_readlane_b32 s99, v183, 16
	v_readlane_b32 s100, v183, 32
	v_readlane_b32 s101, v183, 48
	s_nop 1
	v_mov_b32_e32 v183, s98
	v_add_f32_e32 v183, s99, v183
	v_add_f32_e32 v183, s100, v183
	v_add_f32_e32 v183, s101, v183
	v_fmamk_f32 v183, v183, 0x3a800000, v182
	v_cmp_gt_f32_e32 vcc, 0x800000, v183
	v_mul_f32_e32 v181, 0x4b800000, v183
	s_nop 1
	v_cndmask_b32_e32 v183, v183, v181, vcc
	v_rsq_f32_e32 v183, v183
	s_nop 0
	v_mul_f32_e32 v181, 0x45800000, v183
	v_cndmask_b32_e32 v184, v183, v181, vcc
	v_mov_b32_e32 v185, v184
	v_pk_mul_f32 v[144:145], v[144:145], v[184:185]
	v_pk_mul_f32 v[146:147], v[146:147], v[184:185]
	v_pk_mul_f32 v[148:149], v[148:149], v[184:185]
	v_pk_mul_f32 v[150:151], v[150:151], v[184:185]
	v_pk_mul_f32 v[152:153], v[152:153], v[184:185]
	v_pk_mul_f32 v[154:155], v[154:155], v[184:185]
	v_pk_mul_f32 v[156:157], v[156:157], v[184:185]
	v_pk_mul_f32 v[158:159], v[158:159], v[184:185]
	v_pk_mul_f32 v[144:145], v[144:145], v[236:237]
	v_pk_mul_f32 v[146:147], v[146:147], v[238:239]
	v_pk_mul_f32 v[148:149], v[148:149], v[240:241]
	v_pk_mul_f32 v[150:151], v[150:151], v[242:243]
	v_pk_mul_f32 v[152:153], v[152:153], v[244:245]
	v_pk_mul_f32 v[154:155], v[154:155], v[246:247]
	v_pk_mul_f32 v[156:157], v[156:157], v[248:249]
	v_pk_mul_f32 v[158:159], v[158:159], v[250:251]
	v_add_u32_e32 v181, 0x3000000, v178
	global_store_dwordx4 v181, v[144:147], s[76:77]
	global_store_dwordx4 v181, v[148:151], s[76:77] offset:16
	global_store_dwordx4 v181, v[152:155], s[76:77] offset:2048
	global_store_dwordx4 v181, v[156:159], s[76:77] offset:2064
	s_nop 1
	s_waitcnt vmcnt(0)
	v_lshlrev_b32_e32 v144, 16, v112
	v_and_b32_e32 v145, 0xffff0000, v112
	v_lshlrev_b32_e32 v146, 16, v113
	v_and_b32_e32 v147, 0xffff0000, v113
	v_lshlrev_b32_e32 v148, 16, v114
	v_and_b32_e32 v149, 0xffff0000, v114
	v_lshlrev_b32_e32 v150, 16, v115
	v_and_b32_e32 v151, 0xffff0000, v115
	v_lshlrev_b32_e32 v152, 16, v116
	v_and_b32_e32 v153, 0xffff0000, v116
	v_lshlrev_b32_e32 v154, 16, v117
	v_and_b32_e32 v155, 0xffff0000, v117
	v_lshlrev_b32_e32 v156, 16, v118
	v_and_b32_e32 v157, 0xffff0000, v118
	v_lshlrev_b32_e32 v158, 16, v119
	v_and_b32_e32 v159, 0xffff0000, v119
	v_lshlrev_b32_e32 v160, 16, v120
	v_and_b32_e32 v161, 0xffff0000, v120
	v_lshlrev_b32_e32 v162, 16, v121
	v_and_b32_e32 v163, 0xffff0000, v121
	v_lshlrev_b32_e32 v164, 16, v122
	v_and_b32_e32 v165, 0xffff0000, v122
	v_lshlrev_b32_e32 v166, 16, v123
	v_and_b32_e32 v167, 0xffff0000, v123
	v_lshlrev_b32_e32 v168, 16, v124
	v_and_b32_e32 v169, 0xffff0000, v124
	v_lshlrev_b32_e32 v170, 16, v125
	v_and_b32_e32 v171, 0xffff0000, v125
	v_lshlrev_b32_e32 v172, 16, v126
	v_and_b32_e32 v173, 0xffff0000, v126
	v_lshlrev_b32_e32 v174, 16, v127
	v_and_b32_e32 v175, 0xffff0000, v127
	v_pk_mul_f32 v[252:253], v[160:161], v[160:161]
	v_pk_mul_f32 v[254:255], v[162:163], v[162:163]
	v_pk_fma_f32 v[252:253], v[164:165], v[164:165], v[252:253]
	v_pk_fma_f32 v[254:255], v[166:167], v[166:167], v[254:255]
	v_pk_fma_f32 v[252:253], v[168:169], v[168:169], v[252:253]
	v_pk_fma_f32 v[254:255], v[170:171], v[170:171], v[254:255]
	v_pk_fma_f32 v[252:253], v[172:173], v[172:173], v[252:253]
	v_pk_fma_f32 v[254:255], v[174:175], v[174:175], v[254:255]
	v_pk_add_f32 v[252:253], v[252:253], v[254:255]
	s_nop 0
	v_add_f32_e32 v183, v252, v253
	s_nop 1
	v_add_f32_dpp v183, v183, v183 quad_perm:[1,0,3,2] row_mask:0xf bank_mask:0xf bound_ctrl:1
	s_nop 1
	v_add_f32_dpp v183, v183, v183 quad_perm:[2,3,0,1] row_mask:0xf bank_mask:0xf bound_ctrl:1
	s_nop 1
	v_add_f32_dpp v183, v183, v183 row_half_mirror row_mask:0xf bank_mask:0xf bound_ctrl:1
	s_nop 1
	v_add_f32_dpp v183, v183, v183 row_mirror row_mask:0xf bank_mask:0xf bound_ctrl:1
	s_nop 1
	v_readlane_b32 s98, v183, 0
	v_readlane_b32 s99, v183, 16
	v_readlane_b32 s100, v183, 32
	v_readlane_b32 s101, v183, 48
	s_nop 1
	v_mov_b32_e32 v183, s98
	v_add_f32_e32 v183, s99, v183
	v_add_f32_e32 v183, s100, v183
	v_add_f32_e32 v183, s101, v183
	v_fmamk_f32 v183, v183, 0x3a800000, v182
	v_cmp_gt_f32_e32 vcc, 0x800000, v183
	v_mul_f32_e32 v181, 0x4b800000, v183
	s_nop 1
	v_cndmask_b32_e32 v183, v183, v181, vcc
	v_rsq_f32_e32 v183, v183
	s_nop 0
	v_mul_f32_e32 v181, 0x45800000, v183
	v_cndmask_b32_e32 v184, v183, v181, vcc
	v_mov_b32_e32 v185, v184
	v_pk_mul_f32 v[160:161], v[160:161], v[184:185]
	v_pk_mul_f32 v[162:163], v[162:163], v[184:185]
	v_pk_mul_f32 v[164:165], v[164:165], v[184:185]
	v_pk_mul_f32 v[166:167], v[166:167], v[184:185]
	v_pk_mul_f32 v[168:169], v[168:169], v[184:185]
	v_pk_mul_f32 v[170:171], v[170:171], v[184:185]
	v_pk_mul_f32 v[172:173], v[172:173], v[184:185]
	v_pk_mul_f32 v[174:175], v[174:175], v[184:185]
	v_pk_fma_f32 v[144:145], v[160:161], v[128:129], v[144:145]
	v_pk_fma_f32 v[146:147], v[162:163], v[130:131], v[146:147]
	v_pk_fma_f32 v[148:149], v[164:165], v[132:133], v[148:149]
	v_pk_fma_f32 v[150:151], v[166:167], v[134:135], v[150:151]
	v_pk_fma_f32 v[152:153], v[168:169], v[136:137], v[152:153]
	v_pk_fma_f32 v[154:155], v[170:171], v[138:139], v[154:155]
	v_pk_fma_f32 v[156:157], v[172:173], v[140:141], v[156:157]
	v_pk_fma_f32 v[158:159], v[174:175], v[142:143], v[158:159]
	v_pk_mul_f32 v[252:253], v[144:145], v[144:145]
	v_pk_mul_f32 v[254:255], v[146:147], v[146:147]
	v_pk_fma_f32 v[252:253], v[148:149], v[148:149], v[252:253]
	v_pk_fma_f32 v[254:255], v[150:151], v[150:151], v[254:255]
	v_pk_fma_f32 v[252:253], v[152:153], v[152:153], v[252:253]
	v_pk_fma_f32 v[254:255], v[154:155], v[154:155], v[254:255]
	v_pk_fma_f32 v[252:253], v[156:157], v[156:157], v[252:253]
	v_pk_fma_f32 v[254:255], v[158:159], v[158:159], v[254:255]
	v_pk_add_f32 v[252:253], v[252:253], v[254:255]
	s_nop 0
	v_add_f32_e32 v183, v252, v253
	s_nop 1
	v_add_f32_dpp v183, v183, v183 quad_perm:[1,0,3,2] row_mask:0xf bank_mask:0xf bound_ctrl:1
	s_nop 1
	v_add_f32_dpp v183, v183, v183 quad_perm:[2,3,0,1] row_mask:0xf bank_mask:0xf bound_ctrl:1
	s_nop 1
	v_add_f32_dpp v183, v183, v183 row_half_mirror row_mask:0xf bank_mask:0xf bound_ctrl:1
	s_nop 1
	v_add_f32_dpp v183, v183, v183 row_mirror row_mask:0xf bank_mask:0xf bound_ctrl:1
	s_nop 1
	v_readlane_b32 s98, v183, 0
	v_readlane_b32 s99, v183, 16
	v_readlane_b32 s100, v183, 32
	v_readlane_b32 s101, v183, 48
	s_nop 1
	v_mov_b32_e32 v183, s98
	v_add_f32_e32 v183, s99, v183
	v_add_f32_e32 v183, s100, v183
	v_add_f32_e32 v183, s101, v183
	v_fmamk_f32 v183, v183, 0x3a800000, v182
	v_cmp_gt_f32_e32 vcc, 0x800000, v183
	v_mul_f32_e32 v181, 0x4b800000, v183
	s_nop 1
	v_cndmask_b32_e32 v183, v183, v181, vcc
	v_rsq_f32_e32 v183, v183
	s_nop 0
	v_mul_f32_e32 v181, 0x45800000, v183
	v_cndmask_b32_e32 v184, v183, v181, vcc
	v_mov_b32_e32 v185, v184
	v_pk_mul_f32 v[144:145], v[144:145], v[184:185]
	v_pk_mul_f32 v[146:147], v[146:147], v[184:185]
	v_pk_mul_f32 v[148:149], v[148:149], v[184:185]
	v_pk_mul_f32 v[150:151], v[150:151], v[184:185]
	v_pk_mul_f32 v[152:153], v[152:153], v[184:185]
	v_pk_mul_f32 v[154:155], v[154:155], v[184:185]
	v_pk_mul_f32 v[156:157], v[156:157], v[184:185]
	v_pk_mul_f32 v[158:159], v[158:159], v[184:185]
	v_pk_mul_f32 v[144:145], v[144:145], v[236:237]
	v_pk_mul_f32 v[146:147], v[146:147], v[238:239]
	v_pk_mul_f32 v[148:149], v[148:149], v[240:241]
	v_pk_mul_f32 v[150:151], v[150:151], v[242:243]
	v_pk_mul_f32 v[152:153], v[152:153], v[244:245]
	v_pk_mul_f32 v[154:155], v[154:155], v[246:247]
	v_pk_mul_f32 v[156:157], v[156:157], v[248:249]
	v_pk_mul_f32 v[158:159], v[158:159], v[250:251]
	v_add_u32_e32 v181, 0x3800000, v178
	global_store_dwordx4 v181, v[144:147], s[76:77]
	global_store_dwordx4 v181, v[148:151], s[76:77] offset:16
	global_store_dwordx4 v181, v[152:155], s[76:77] offset:2048
	global_store_dwordx4 v181, v[156:159], s[76:77] offset:2064
	s_nop 1
	v_readfirstlane_b32 s98, v179
	s_nop 3
	s_cmp_ge_u32 s98, 512
	s_cbranch_scc1 .Lmyxupd_done_7
	v_lshlrev_b32_e32 v177, 4, v176
	v_lshl_add_u32 v177, v179, 11, v177
	v_lshl_add_u32 v178, v179, 12, v180
	v_add_u32_e32 v181, 0x3800000, v177
	global_load_dwordx4 v[0:3], v181, s[78:79]
	global_load_dwordx4 v[4:7], v181, s[78:79] offset:1024
	v_lshl_add_u32 v183, v179, 12, v180
	v_add_u32_e32 v183, 0xbf00000, v183
	v_add_u32_e32 v181, 0x0, v183
	global_load_dwordx4 v[8:11], v181, s[78:79]
	global_load_dwordx4 v[12:15], v181, s[78:79] offset:16
	global_load_dwordx4 v[16:19], v181, s[78:79] offset:2048
	global_load_dwordx4 v[20:23], v181, s[78:79] offset:2064
	v_add_u32_e32 v181, 0x200000, v183
	global_load_dwordx4 v[24:27], v181, s[78:79]
	global_load_dwordx4 v[28:31], v181, s[78:79] offset:16
	global_load_dwordx4 v[32:35], v181, s[78:79] offset:2048
	global_load_dwordx4 v[36:39], v181, s[78:79] offset:2064
	v_add_u32_e32 v181, 0x400000, v183
	global_load_dwordx4 v[40:43], v181, s[78:79]
	global_load_dwordx4 v[44:47], v181, s[78:79] offset:16
	global_load_dwordx4 v[48:51], v181, s[78:79] offset:2048
	global_load_dwordx4 v[52:55], v181, s[78:79] offset:2064
	v_add_u32_e32 v181, 0x600000, v183
	global_load_dwordx4 v[56:59], v181, s[78:79]
	global_load_dwordx4 v[60:63], v181, s[78:79] offset:16
	global_load_dwordx4 v[64:67], v181, s[78:79] offset:2048
	global_load_dwordx4 v[68:71], v181, s[78:79] offset:2064
	v_add_u32_e32 v181, 0x800000, v183
	global_load_dwordx4 v[72:75], v181, s[78:79]
	global_load_dwordx4 v[76:79], v181, s[78:79] offset:16
	global_load_dwordx4 v[80:83], v181, s[78:79] offset:2048
	global_load_dwordx4 v[84:87], v181, s[78:79] offset:2064
	v_add_u32_e32 v181, 0xa00000, v183
	global_load_dwordx4 v[88:91], v181, s[78:79]
	global_load_dwordx4 v[92:95], v181, s[78:79] offset:16
	global_load_dwordx4 v[96:99], v181, s[78:79] offset:2048
	global_load_dwordx4 v[100:103], v181, s[78:79] offset:2064
	s_waitcnt vmcnt(20)
	v_pk_add_f32 v[160:161], v[8:9], 0 op_sel_hi:[1,0]
	v_pk_add_f32 v[162:163], v[10:11], 0 op_sel_hi:[1,0]
	v_pk_add_f32 v[164:165], v[12:13], 0 op_sel_hi:[1,0]
	v_pk_add_f32 v[166:167], v[14:15], 0 op_sel_hi:[1,0]
	v_pk_add_f32 v[168:169], v[16:17], 0 op_sel_hi:[1,0]
	v_pk_add_f32 v[170:171], v[18:19], 0 op_sel_hi:[1,0]
	v_pk_add_f32 v[172:173], v[20:21], 0 op_sel_hi:[1,0]
	v_pk_add_f32 v[174:175], v[22:23], 0 op_sel_hi:[1,0]
	s_waitcnt vmcnt(16)
	v_pk_add_f32 v[160:161], v[160:161], v[24:25]
	v_pk_add_f32 v[162:163], v[162:163], v[26:27]
	v_pk_add_f32 v[164:165], v[164:165], v[28:29]
	v_pk_add_f32 v[166:167], v[166:167], v[30:31]
	v_pk_add_f32 v[168:169], v[168:169], v[32:33]
	v_pk_add_f32 v[170:171], v[170:171], v[34:35]
	v_pk_add_f32 v[172:173], v[172:173], v[36:37]
	v_pk_add_f32 v[174:175], v[174:175], v[38:39]
	s_waitcnt vmcnt(12)
	v_pk_add_f32 v[160:161], v[160:161], v[40:41]
	v_pk_add_f32 v[162:163], v[162:163], v[42:43]
	v_pk_add_f32 v[164:165], v[164:165], v[44:45]
	v_pk_add_f32 v[166:167], v[166:167], v[46:47]
	v_pk_add_f32 v[168:169], v[168:169], v[48:49]
	v_pk_add_f32 v[170:171], v[170:171], v[50:51]
	v_pk_add_f32 v[172:173], v[172:173], v[52:53]
	v_pk_add_f32 v[174:175], v[174:175], v[54:55]
	s_waitcnt vmcnt(8)
	v_pk_add_f32 v[160:161], v[160:161], v[56:57]
	v_pk_add_f32 v[162:163], v[162:163], v[58:59]
	v_pk_add_f32 v[164:165], v[164:165], v[60:61]
	v_pk_add_f32 v[166:167], v[166:167], v[62:63]
	v_pk_add_f32 v[168:169], v[168:169], v[64:65]
	v_pk_add_f32 v[170:171], v[170:171], v[66:67]
	v_pk_add_f32 v[172:173], v[172:173], v[68:69]
	v_pk_add_f32 v[174:175], v[174:175], v[70:71]
	s_waitcnt vmcnt(4)
	v_pk_add_f32 v[160:161], v[160:161], v[72:73]
	v_pk_add_f32 v[162:163], v[162:163], v[74:75]
	v_pk_add_f32 v[164:165], v[164:165], v[76:77]
	v_pk_add_f32 v[166:167], v[166:167], v[78:79]
	v_pk_add_f32 v[168:169], v[168:169], v[80:81]
	v_pk_add_f32 v[170:171], v[170:171], v[82:83]
	v_pk_add_f32 v[172:173], v[172:173], v[84:85]
	v_pk_add_f32 v[174:175], v[174:175], v[86:87]
	s_waitcnt vmcnt(0)
	v_pk_add_f32 v[160:161], v[160:161], v[88:89]
	v_pk_add_f32 v[162:163], v[162:163], v[90:91]
	v_pk_add_f32 v[164:165], v[164:165], v[92:93]
	v_pk_add_f32 v[166:167], v[166:167], v[94:95]
	v_pk_add_f32 v[168:169], v[168:169], v[96:97]
	v_pk_add_f32 v[170:171], v[170:171], v[98:99]
	v_pk_add_f32 v[172:173], v[172:173], v[100:101]
	v_pk_add_f32 v[174:175], v[174:175], v[102:103]
	v_lshlrev_b32_e32 v144, 16, v0
	v_and_b32_e32 v145, 0xffff0000, v0
	v_lshlrev_b32_e32 v146, 16, v1
	v_and_b32_e32 v147, 0xffff0000, v1
	v_lshlrev_b32_e32 v148, 16, v2
	v_and_b32_e32 v149, 0xffff0000, v2
	v_lshlrev_b32_e32 v150, 16, v3
	v_and_b32_e32 v151, 0xffff0000, v3
	v_lshlrev_b32_e32 v152, 16, v4
	v_and_b32_e32 v153, 0xffff0000, v4
	v_lshlrev_b32_e32 v154, 16, v5
	v_and_b32_e32 v155, 0xffff0000, v5
	v_lshlrev_b32_e32 v156, 16, v6
	v_and_b32_e32 v157, 0xffff0000, v6
	v_lshlrev_b32_e32 v158, 16, v7
	v_and_b32_e32 v159, 0xffff0000, v7
	v_add_u32_e32 v181, 0xc00000, v183
	global_load_dwordx4 v[8:11], v181, s[78:79]
	global_load_dwordx4 v[12:15], v181, s[78:79] offset:16
	global_load_dwordx4 v[16:19], v181, s[78:79] offset:2048
	global_load_dwordx4 v[20:23], v181, s[78:79] offset:2064
	v_add_u32_e32 v181, 0xe00000, v183
	global_load_dwordx4 v[24:27], v181, s[78:79]
	global_load_dwordx4 v[28:31], v181, s[78:79] offset:16
	global_load_dwordx4 v[32:35], v181, s[78:79] offset:2048
	global_load_dwordx4 v[36:39], v181, s[78:79] offset:2064
	v_add_u32_e32 v181, 0x1000000, v183
	global_load_dwordx4 v[40:43], v181, s[78:79]
	global_load_dwordx4 v[44:47], v181, s[78:79] offset:16
	global_load_dwordx4 v[48:51], v181, s[78:79] offset:2048
	global_load_dwordx4 v[52:55], v181, s[78:79] offset:2064
	v_add_u32_e32 v181, 0x1200000, v183
	global_load_dwordx4 v[56:59], v181, s[78:79]
	global_load_dwordx4 v[60:63], v181, s[78:79] offset:16
	global_load_dwordx4 v[64:67], v181, s[78:79] offset:2048
	global_load_dwordx4 v[68:71], v181, s[78:79] offset:2064
	v_add_u32_e32 v181, 0x1400000, v183
	global_load_dwordx4 v[72:75], v181, s[78:79]
	global_load_dwordx4 v[76:79], v181, s[78:79] offset:16
	global_load_dwordx4 v[80:83], v181, s[78:79] offset:2048
	global_load_dwordx4 v[84:87], v181, s[78:79] offset:2064
	s_waitcnt vmcnt(16)
	v_pk_add_f32 v[160:161], v[160:161], v[8:9]
	v_pk_add_f32 v[162:163], v[162:163], v[10:11]
	v_pk_add_f32 v[164:165], v[164:165], v[12:13]
	v_pk_add_f32 v[166:167], v[166:167], v[14:15]
	v_pk_add_f32 v[168:169], v[168:169], v[16:17]
	v_pk_add_f32 v[170:171], v[170:171], v[18:19]
	v_pk_add_f32 v[172:173], v[172:173], v[20:21]
	v_pk_add_f32 v[174:175], v[174:175], v[22:23]
	s_waitcnt vmcnt(12)
	v_pk_add_f32 v[160:161], v[160:161], v[24:25]
	v_pk_add_f32 v[162:163], v[162:163], v[26:27]
	v_pk_add_f32 v[164:165], v[164:165], v[28:29]
	v_pk_add_f32 v[166:167], v[166:167], v[30:31]
	v_pk_add_f32 v[168:169], v[168:169], v[32:33]
	v_pk_add_f32 v[170:171], v[170:171], v[34:35]
	v_pk_add_f32 v[172:173], v[172:173], v[36:37]
	v_pk_add_f32 v[174:175], v[174:175], v[38:39]
	s_waitcnt vmcnt(8)
	v_pk_add_f32 v[160:161], v[160:161], v[40:41]
	v_pk_add_f32 v[162:163], v[162:163], v[42:43]
	v_pk_add_f32 v[164:165], v[164:165], v[44:45]
	v_pk_add_f32 v[166:167], v[166:167], v[46:47]
	v_pk_add_f32 v[168:169], v[168:169], v[48:49]
	v_pk_add_f32 v[170:171], v[170:171], v[50:51]
	v_pk_add_f32 v[172:173], v[172:173], v[52:53]
	v_pk_add_f32 v[174:175], v[174:175], v[54:55]
	s_waitcnt vmcnt(4)
	v_pk_add_f32 v[160:161], v[160:161], v[56:57]
	v_pk_add_f32 v[162:163], v[162:163], v[58:59]
	v_pk_add_f32 v[164:165], v[164:165], v[60:61]
	v_pk_add_f32 v[166:167], v[166:167], v[62:63]
	v_pk_add_f32 v[168:169], v[168:169], v[64:65]
	v_pk_add_f32 v[170:171], v[170:171], v[66:67]
	v_pk_add_f32 v[172:173], v[172:173], v[68:69]
	v_pk_add_f32 v[174:175], v[174:175], v[70:71]
	s_waitcnt vmcnt(0)
	v_pk_add_f32 v[160:161], v[160:161], v[72:73]
	v_pk_add_f32 v[162:163], v[162:163], v[74:75]
	v_pk_add_f32 v[164:165], v[164:165], v[76:77]
	v_pk_add_f32 v[166:167], v[166:167], v[78:79]
	v_pk_add_f32 v[168:169], v[168:169], v[80:81]
	v_pk_add_f32 v[170:171], v[170:171], v[82:83]
	v_pk_add_f32 v[172:173], v[172:173], v[84:85]
	v_pk_add_f32 v[174:175], v[174:175], v[86:87]
	v_pk_mul_f32 v[252:253], v[160:161], v[160:161]
	v_pk_mul_f32 v[254:255], v[162:163], v[162:163]
	v_pk_fma_f32 v[252:253], v[164:165], v[164:165], v[252:253]
	v_pk_fma_f32 v[254:255], v[166:167], v[166:167], v[254:255]
	v_pk_fma_f32 v[252:253], v[168:169], v[168:169], v[252:253]
	v_pk_fma_f32 v[254:255], v[170:171], v[170:171], v[254:255]
	v_pk_fma_f32 v[252:253], v[172:173], v[172:173], v[252:253]
	v_pk_fma_f32 v[254:255], v[174:175], v[174:175], v[254:255]
	v_pk_add_f32 v[252:253], v[252:253], v[254:255]
	s_nop 0
	v_add_f32_e32 v183, v252, v253
	s_nop 1
	v_add_f32_dpp v183, v183, v183 quad_perm:[1,0,3,2] row_mask:0xf bank_mask:0xf bound_ctrl:1
	s_nop 1
	v_add_f32_dpp v183, v183, v183 quad_perm:[2,3,0,1] row_mask:0xf bank_mask:0xf bound_ctrl:1
	s_nop 1
	v_add_f32_dpp v183, v183, v183 row_half_mirror row_mask:0xf bank_mask:0xf bound_ctrl:1
	s_nop 1
	v_add_f32_dpp v183, v183, v183 row_mirror row_mask:0xf bank_mask:0xf bound_ctrl:1
	s_nop 1
	v_readlane_b32 s98, v183, 0
	v_readlane_b32 s99, v183, 16
	v_readlane_b32 s100, v183, 32
	v_readlane_b32 s101, v183, 48
	s_nop 1
	v_mov_b32_e32 v183, s98
	v_add_f32_e32 v183, s99, v183
	v_add_f32_e32 v183, s100, v183
	v_add_f32_e32 v183, s101, v183
	v_fmamk_f32 v183, v183, 0x3a800000, v182
	v_cmp_gt_f32_e32 vcc, 0x800000, v183
	v_mul_f32_e32 v181, 0x4b800000, v183
	s_nop 1
	v_cndmask_b32_e32 v183, v183, v181, vcc
	v_rsq_f32_e32 v183, v183
	s_nop 0
	v_mul_f32_e32 v181, 0x45800000, v183
	v_cndmask_b32_e32 v184, v183, v181, vcc
	v_mov_b32_e32 v185, v184
	v_pk_mul_f32 v[160:161], v[160:161], v[184:185]
	v_pk_mul_f32 v[162:163], v[162:163], v[184:185]
	v_pk_mul_f32 v[164:165], v[164:165], v[184:185]
	v_pk_mul_f32 v[166:167], v[166:167], v[184:185]
	v_pk_mul_f32 v[168:169], v[168:169], v[184:185]
	v_pk_mul_f32 v[170:171], v[170:171], v[184:185]
	v_pk_mul_f32 v[172:173], v[172:173], v[184:185]
	v_pk_mul_f32 v[174:175], v[174:175], v[184:185]
	v_pk_fma_f32 v[144:145], v[160:161], v[128:129], v[144:145]
	v_pk_fma_f32 v[146:147], v[162:163], v[130:131], v[146:147]
	v_pk_fma_f32 v[148:149], v[164:165], v[132:133], v[148:149]
	v_pk_fma_f32 v[150:151], v[166:167], v[134:135], v[150:151]
	v_pk_fma_f32 v[152:153], v[168:169], v[136:137], v[152:153]
	v_pk_fma_f32 v[154:155], v[170:171], v[138:139], v[154:155]
	v_pk_fma_f32 v[156:157], v[172:173], v[140:141], v[156:157]
	v_pk_fma_f32 v[158:159], v[174:175], v[142:143], v[158:159]
	v_pk_mul_f32 v[252:253], v[144:145], v[144:145]
	v_pk_mul_f32 v[254:255], v[146:147], v[146:147]
	v_pk_fma_f32 v[252:253], v[148:149], v[148:149], v[252:253]
	v_pk_fma_f32 v[254:255], v[150:151], v[150:151], v[254:255]
	v_pk_fma_f32 v[252:253], v[152:153], v[152:153], v[252:253]
	v_pk_fma_f32 v[254:255], v[154:155], v[154:155], v[254:255]
	v_pk_fma_f32 v[252:253], v[156:157], v[156:157], v[252:253]
	v_pk_fma_f32 v[254:255], v[158:159], v[158:159], v[254:255]
	v_pk_add_f32 v[252:253], v[252:253], v[254:255]
	s_nop 0
	v_add_f32_e32 v183, v252, v253
	s_nop 1
	v_add_f32_dpp v183, v183, v183 quad_perm:[1,0,3,2] row_mask:0xf bank_mask:0xf bound_ctrl:1
	s_nop 1
	v_add_f32_dpp v183, v183, v183 quad_perm:[2,3,0,1] row_mask:0xf bank_mask:0xf bound_ctrl:1
	s_nop 1
	v_add_f32_dpp v183, v183, v183 row_half_mirror row_mask:0xf bank_mask:0xf bound_ctrl:1
	s_nop 1
	v_add_f32_dpp v183, v183, v183 row_mirror row_mask:0xf bank_mask:0xf bound_ctrl:1
	s_nop 1
	v_readlane_b32 s98, v183, 0
	v_readlane_b32 s99, v183, 16
	v_readlane_b32 s100, v183, 32
	v_readlane_b32 s101, v183, 48
	s_nop 1
	v_mov_b32_e32 v183, s98
	v_add_f32_e32 v183, s99, v183
	v_add_f32_e32 v183, s100, v183
	v_add_f32_e32 v183, s101, v183
	v_fmamk_f32 v183, v183, 0x3a800000, v182
	v_cmp_gt_f32_e32 vcc, 0x800000, v183
	v_mul_f32_e32 v181, 0x4b800000, v183
	s_nop 1
	v_cndmask_b32_e32 v183, v183, v181, vcc
	v_rsq_f32_e32 v183, v183
	s_nop 0
	v_mul_f32_e32 v181, 0x45800000, v183
	v_cndmask_b32_e32 v184, v183, v181, vcc
	v_mov_b32_e32 v185, v184
	v_pk_mul_f32 v[144:145], v[144:145], v[184:185]
	v_pk_mul_f32 v[146:147], v[146:147], v[184:185]
	v_pk_mul_f32 v[148:149], v[148:149], v[184:185]
	v_pk_mul_f32 v[150:151], v[150:151], v[184:185]
	v_pk_mul_f32 v[152:153], v[152:153], v[184:185]
	v_pk_mul_f32 v[154:155], v[154:155], v[184:185]
	v_pk_mul_f32 v[156:157], v[156:157], v[184:185]
	v_pk_mul_f32 v[158:159], v[158:159], v[184:185]
	v_pk_mul_f32 v[144:145], v[144:145], v[236:237]
	v_pk_mul_f32 v[146:147], v[146:147], v[238:239]
	v_pk_mul_f32 v[148:149], v[148:149], v[240:241]
	v_pk_mul_f32 v[150:151], v[150:151], v[242:243]
	v_pk_mul_f32 v[152:153], v[152:153], v[244:245]
	v_pk_mul_f32 v[154:155], v[154:155], v[246:247]
	v_pk_mul_f32 v[156:157], v[156:157], v[248:249]
	v_pk_mul_f32 v[158:159], v[158:159], v[250:251]
	v_add_u32_e32 v181, 0x4000000, v178
	global_store_dwordx4 v181, v[144:147], s[76:77]
	global_store_dwordx4 v181, v[148:151], s[76:77] offset:16
	global_store_dwordx4 v181, v[152:155], s[76:77] offset:2048
	global_store_dwordx4 v181, v[156:159], s[76:77] offset:2064
	s_nop 1
